# c23: c16 + opportunistic MFMA start: each wave issues its first 4 MFMAs (two same-D pairs) at priority 0 before the hand-over barrier, once its load segment's data is in registers
# baseline (speedup 1.0000x reference)
.LBB0_343:
	s_ashr_i32 s11, s10, 31
	s_lshl_b64 s[12:13], s[10:11], 20
	s_add_u32 s12, s26, s12
	s_addc_u32 s13, s27, s13
	s_and_b64 s[14:15], s[2:3], exec
	s_cselect_b32 s11, s13, s21
	s_cselect_b32 s75, s12, s20
	s_ashr_i32 s9, s8, 31
	s_lshl_b64 s[14:15], s[8:9], 20
	s_add_u32 s14, s28, s14
	s_addc_u32 s15, s29, s15
	s_and_b64 s[22:23], s[2:3], exec
	s_cselect_b32 s9, s15, s19
	s_cselect_b32 s76, s14, s18
	s_add_u32 s77, s18, 0x100
	s_addc_u32 s78, s19, 0
	s_add_u32 s18, s20, 0x80080
	s_addc_u32 s19, s21, 0
	s_add_u32 s79, s20, 0x100
	s_addc_u32 s80, s21, 0
	s_mov_b32 s81, -2
	ds_read_b128 v[148:151], v143
	ds_read_b128 v[152:155], v143 offset:1024
	ds_read_b128 v[156:159], v143 offset:2048
	ds_read_b128 v[160:163], v143 offset:3072
	ds_read_b128 v[164:167], v144
	ds_read_b128 v[168:171], v144 offset:1024
	ds_read_b128 v[172:175], v144 offset:2048
	ds_read_b128 v[176:179], v144 offset:3072
	s_cmp_eq_u32 s81, 28
	s_cselect_b32 s21, s9, s78
	s_cselect_b32 s20, s76, s77
	s_cselect_b32 s23, s11, s80
	s_cselect_b32 s22, s75, s79
	ds_read_b128 v[180:183], v145
	ds_read_b128 v[184:187], v145 offset:1024
	ds_read_b128 v[188:191], v145 offset:2048
	ds_read_b128 v[192:195], v145 offset:3072
	ds_read_b128 v[196:199], v145 offset:4096
	ds_read_b128 v[200:203], v145 offset:5120
	ds_read_b128 v[204:207], v145 offset:6144
	ds_read_b128 v[208:211], v145 offset:7168
	s_add_u32 s82, s18, 0xfff80000
	s_addc_u32 s83, s19, -1
	s_mov_b32 s86, m0
	s_mov_b32 m0, s64
	s_nop 0
	global_load_lds_dwordx4 v138, s[82:83]
	s_mov_b32 m0, s86
	s_nop 0
	s_mov_b32 s86, m0
	s_mov_b32 m0, s67
	s_nop 0
	global_load_lds_dwordx4 v140, s[82:83]
	s_mov_b32 m0, s86
	s_mov_b32 s82, m0
	s_mov_b32 m0, s65
	s_nop 0
	global_load_lds_dwordx4 v138, s[18:19]
	s_mov_b32 m0, s82
	s_nop 0
	s_mov_b32 s82, m0
	s_mov_b32 m0, s73
	s_nop 0
	global_load_lds_dwordx4 v140, s[18:19]
	s_mov_b32 m0, s82
	s_waitcnt vmcnt(8)
	s_waitcnt lgkmcnt(0)
	s_waitcnt lgkmcnt(7)
	v_mfma_f32_16x16x32_bf16 v[126:129], v[148:151], v[180:183], 0
	v_mfma_f32_16x16x32_bf16 v[126:129], v[152:155], v[184:187], v[126:129]
	s_waitcnt lgkmcnt(5)
	v_mfma_f32_16x16x32_bf16 v[122:125], v[156:159], v[180:183], 0
	v_mfma_f32_16x16x32_bf16 v[122:125], v[160:163], v[184:187], v[122:125]
	s_barrier
	s_setprio 1
	s_waitcnt lgkmcnt(3)
	v_mfma_f32_16x16x32_bf16 v[106:109], v[156:159], v[188:191], 0
	v_mfma_f32_16x16x32_bf16 v[106:109], v[160:163], v[192:195], v[106:109]
	s_waitcnt lgkmcnt(1)
	v_mfma_f32_16x16x32_bf16 v[110:113], v[148:151], v[188:191], 0
	v_mfma_f32_16x16x32_bf16 v[110:113], v[152:155], v[192:195], v[110:113]
	v_mfma_f32_16x16x32_bf16 v[94:97], v[148:151], v[196:199], 0
	v_mfma_f32_16x16x32_bf16 v[94:97], v[152:155], v[200:203], v[94:97]
	v_mfma_f32_16x16x32_bf16 v[90:93], v[156:159], v[196:199], 0
	v_mfma_f32_16x16x32_bf16 v[90:93], v[160:163], v[200:203], v[90:93]
	v_mfma_f32_16x16x32_bf16 v[74:77], v[156:159], v[204:207], 0
	v_mfma_f32_16x16x32_bf16 v[74:77], v[160:163], v[208:211], v[74:77]
	s_waitcnt lgkmcnt(0)
	v_mfma_f32_16x16x32_bf16 v[78:81], v[148:151], v[204:207], 0
	v_mfma_f32_16x16x32_bf16 v[78:81], v[152:155], v[208:211], v[78:81]
	s_setprio 0
	s_setprio 1
	v_mfma_f32_16x16x32_bf16 v[118:121], v[164:167], v[180:183], 0
	v_mfma_f32_16x16x32_bf16 v[118:121], v[168:171], v[184:187], v[118:121]
	v_mfma_f32_16x16x32_bf16 v[114:117], v[172:175], v[180:183], 0
	v_mfma_f32_16x16x32_bf16 v[114:117], v[176:179], v[184:187], v[114:117]
	v_mfma_f32_16x16x32_bf16 v[98:101], v[172:175], v[188:191], 0
	v_mfma_f32_16x16x32_bf16 v[98:101], v[176:179], v[192:195], v[98:101]
	v_mfma_f32_16x16x32_bf16 v[102:105], v[164:167], v[188:191], 0
	v_mfma_f32_16x16x32_bf16 v[102:105], v[168:171], v[192:195], v[102:105]
	v_mfma_f32_16x16x32_bf16 v[86:89], v[164:167], v[196:199], 0
	v_mfma_f32_16x16x32_bf16 v[86:89], v[168:171], v[200:203], v[86:89]
	v_mfma_f32_16x16x32_bf16 v[82:85], v[172:175], v[196:199], 0
	v_mfma_f32_16x16x32_bf16 v[82:85], v[176:179], v[200:203], v[82:85]
	v_mfma_f32_16x16x32_bf16 v[66:69], v[172:175], v[204:207], 0
	v_mfma_f32_16x16x32_bf16 v[66:69], v[176:179], v[208:211], v[66:69]
	s_setprio 2
	s_barrier
	v_mfma_f32_16x16x32_bf16 v[70:73], v[164:167], v[204:207], 0
	v_mfma_f32_16x16x32_bf16 v[70:73], v[168:171], v[208:211], v[70:73]
	s_setprio 0
	ds_read_b128 v[180:183], v145 offset:16384
	ds_read_b128 v[184:187], v145 offset:17408
	ds_read_b128 v[188:191], v145 offset:18432
	ds_read_b128 v[192:195], v145 offset:19456
	ds_read_b128 v[196:199], v145 offset:20480
	ds_read_b128 v[200:203], v145 offset:21504
	ds_read_b128 v[204:207], v145 offset:22528
	ds_read_b128 v[208:211], v145 offset:23552
	s_mov_b32 s82, m0
	s_mov_b32 m0, s35
	s_nop 0
	global_load_lds_dwordx4 v139, s[20:21]
	s_mov_b32 m0, s82
	s_nop 0
	s_mov_b32 s82, m0
	s_mov_b32 m0, s36
	s_nop 0
	global_load_lds_dwordx4 v141, s[20:21]
	s_mov_b32 m0, s82
	s_add_u32 s82, s20, 0x80000
	s_addc_u32 s83, s21, 0
	s_mov_b32 s86, m0
	s_mov_b32 m0, s37
	s_nop 0
	global_load_lds_dwordx4 v139, s[82:83]
	s_mov_b32 m0, s86
	s_nop 0
	s_mov_b32 s86, m0
	s_mov_b32 m0, s42
	s_nop 0
	global_load_lds_dwordx4 v141, s[82:83]
	s_mov_b32 m0, s86
	s_waitcnt vmcnt(4)
	s_waitcnt lgkmcnt(0)
	s_waitcnt lgkmcnt(7)
	v_mfma_f32_16x16x32_bf16 v[62:65], v[148:151], v[180:183], 0
	v_mfma_f32_16x16x32_bf16 v[62:65], v[152:155], v[184:187], v[62:65]
	s_waitcnt lgkmcnt(5)
	v_mfma_f32_16x16x32_bf16 v[58:61], v[156:159], v[180:183], 0
	v_mfma_f32_16x16x32_bf16 v[58:61], v[160:163], v[184:187], v[58:61]
	s_barrier
	s_setprio 1
	s_waitcnt lgkmcnt(3)
	v_mfma_f32_16x16x32_bf16 v[42:45], v[156:159], v[188:191], 0
	v_mfma_f32_16x16x32_bf16 v[42:45], v[160:163], v[192:195], v[42:45]
	s_waitcnt lgkmcnt(1)
	v_mfma_f32_16x16x32_bf16 v[46:49], v[148:151], v[188:191], 0
	v_mfma_f32_16x16x32_bf16 v[46:49], v[152:155], v[192:195], v[46:49]
	v_mfma_f32_16x16x32_bf16 v[30:33], v[148:151], v[196:199], 0
	v_mfma_f32_16x16x32_bf16 v[30:33], v[152:155], v[200:203], v[30:33]
	v_mfma_f32_16x16x32_bf16 v[26:29], v[156:159], v[196:199], 0
	v_mfma_f32_16x16x32_bf16 v[26:29], v[160:163], v[200:203], v[26:29]
	v_mfma_f32_16x16x32_bf16 v[10:13], v[156:159], v[204:207], 0
	v_mfma_f32_16x16x32_bf16 v[10:13], v[160:163], v[208:211], v[10:13]
	s_waitcnt lgkmcnt(0)
	v_mfma_f32_16x16x32_bf16 v[14:17], v[148:151], v[204:207], 0
	v_mfma_f32_16x16x32_bf16 v[14:17], v[152:155], v[208:211], v[14:17]
	s_setprio 0
	s_setprio 1
	v_mfma_f32_16x16x32_bf16 v[54:57], v[164:167], v[180:183], 0
	v_mfma_f32_16x16x32_bf16 v[54:57], v[168:171], v[184:187], v[54:57]
	v_mfma_f32_16x16x32_bf16 v[50:53], v[172:175], v[180:183], 0
	v_mfma_f32_16x16x32_bf16 v[50:53], v[176:179], v[184:187], v[50:53]
	v_mfma_f32_16x16x32_bf16 v[34:37], v[172:175], v[188:191], 0
	v_mfma_f32_16x16x32_bf16 v[34:37], v[176:179], v[192:195], v[34:37]
	v_mfma_f32_16x16x32_bf16 v[38:41], v[164:167], v[188:191], 0
	v_mfma_f32_16x16x32_bf16 v[38:41], v[168:171], v[192:195], v[38:41]
	v_mfma_f32_16x16x32_bf16 v[22:25], v[164:167], v[196:199], 0
	v_mfma_f32_16x16x32_bf16 v[22:25], v[168:171], v[200:203], v[22:25]
	v_mfma_f32_16x16x32_bf16 v[18:21], v[172:175], v[196:199], 0
	v_mfma_f32_16x16x32_bf16 v[18:21], v[176:179], v[200:203], v[18:21]
	v_mfma_f32_16x16x32_bf16 v[2:5], v[172:175], v[204:207], 0
	v_mfma_f32_16x16x32_bf16 v[2:5], v[176:179], v[208:211], v[2:5]
	s_setprio 2
	s_barrier
	v_mfma_f32_16x16x32_bf16 v[6:9], v[164:167], v[204:207], 0
	v_mfma_f32_16x16x32_bf16 v[6:9], v[168:171], v[208:211], v[6:9]
	s_setprio 0
	ds_read_b128 v[148:151], v146
	ds_read_b128 v[152:155], v146 offset:1024
	ds_read_b128 v[156:159], v146 offset:2048
	ds_read_b128 v[160:163], v146 offset:3072
	ds_read_b128 v[164:167], v147
	ds_read_b128 v[168:171], v147 offset:1024
	ds_read_b128 v[172:175], v147 offset:2048
	ds_read_b128 v[176:179], v147 offset:3072
	ds_read_b128 v[180:183], v145 offset:32768
	ds_read_b128 v[184:187], v145 offset:33792
	ds_read_b128 v[188:191], v145 offset:34816
	ds_read_b128 v[192:195], v145 offset:35840
	ds_read_b128 v[196:199], v145 offset:36864
	ds_read_b128 v[200:203], v145 offset:37888
	ds_read_b128 v[204:207], v145 offset:38912
	ds_read_b128 v[208:211], v145 offset:39936
	s_mov_b32 s82, m0
	s_mov_b32 m0, s31
	s_nop 0
	global_load_lds_dwordx4 v138, s[22:23]
	s_mov_b32 m0, s82
	s_nop 0
	s_mov_b32 s82, m0
	s_mov_b32 m0, s43
	s_nop 0
	global_load_lds_dwordx4 v140, s[22:23]
	s_mov_b32 m0, s82
	s_add_u32 s22, s22, 0x80000
	s_addc_u32 s23, s23, 0
	s_mov_b32 s82, m0
	s_mov_b32 m0, s46
	s_nop 0
	global_load_lds_dwordx4 v138, s[22:23]
	s_mov_b32 m0, s82
	s_nop 0
	s_mov_b32 s82, m0
	s_mov_b32 m0, s47
	s_nop 0
	global_load_lds_dwordx4 v140, s[22:23]
	s_mov_b32 m0, s82
	s_waitcnt vmcnt(8)
	s_waitcnt lgkmcnt(0)
	s_waitcnt lgkmcnt(7)
	v_mfma_f32_16x16x32_bf16 v[126:129], v[148:151], v[180:183], v[126:129]
	v_mfma_f32_16x16x32_bf16 v[126:129], v[152:155], v[184:187], v[126:129]
	s_waitcnt lgkmcnt(5)
	v_mfma_f32_16x16x32_bf16 v[122:125], v[156:159], v[180:183], v[122:125]
	v_mfma_f32_16x16x32_bf16 v[122:125], v[160:163], v[184:187], v[122:125]
	s_barrier
	s_setprio 1
	s_waitcnt lgkmcnt(3)
	v_mfma_f32_16x16x32_bf16 v[106:109], v[156:159], v[188:191], v[106:109]
	v_mfma_f32_16x16x32_bf16 v[106:109], v[160:163], v[192:195], v[106:109]
	s_waitcnt lgkmcnt(1)
	v_mfma_f32_16x16x32_bf16 v[110:113], v[148:151], v[188:191], v[110:113]
	v_mfma_f32_16x16x32_bf16 v[110:113], v[152:155], v[192:195], v[110:113]
	v_mfma_f32_16x16x32_bf16 v[94:97], v[148:151], v[196:199], v[94:97]
	v_mfma_f32_16x16x32_bf16 v[94:97], v[152:155], v[200:203], v[94:97]
	v_mfma_f32_16x16x32_bf16 v[90:93], v[156:159], v[196:199], v[90:93]
	v_mfma_f32_16x16x32_bf16 v[90:93], v[160:163], v[200:203], v[90:93]
	v_mfma_f32_16x16x32_bf16 v[74:77], v[156:159], v[204:207], v[74:77]
	v_mfma_f32_16x16x32_bf16 v[74:77], v[160:163], v[208:211], v[74:77]
	s_waitcnt lgkmcnt(0)
	v_mfma_f32_16x16x32_bf16 v[78:81], v[148:151], v[204:207], v[78:81]
	v_mfma_f32_16x16x32_bf16 v[78:81], v[152:155], v[208:211], v[78:81]
	s_setprio 0
	s_setprio 1
	v_mfma_f32_16x16x32_bf16 v[118:121], v[164:167], v[180:183], v[118:121]
	v_mfma_f32_16x16x32_bf16 v[118:121], v[168:171], v[184:187], v[118:121]
	v_mfma_f32_16x16x32_bf16 v[114:117], v[172:175], v[180:183], v[114:117]
	v_mfma_f32_16x16x32_bf16 v[114:117], v[176:179], v[184:187], v[114:117]
	v_mfma_f32_16x16x32_bf16 v[98:101], v[172:175], v[188:191], v[98:101]
	v_mfma_f32_16x16x32_bf16 v[98:101], v[176:179], v[192:195], v[98:101]
	v_mfma_f32_16x16x32_bf16 v[102:105], v[164:167], v[188:191], v[102:105]
	v_mfma_f32_16x16x32_bf16 v[102:105], v[168:171], v[192:195], v[102:105]
	v_mfma_f32_16x16x32_bf16 v[86:89], v[164:167], v[196:199], v[86:89]
	v_mfma_f32_16x16x32_bf16 v[86:89], v[168:171], v[200:203], v[86:89]
	v_mfma_f32_16x16x32_bf16 v[82:85], v[172:175], v[196:199], v[82:85]
	v_mfma_f32_16x16x32_bf16 v[82:85], v[176:179], v[200:203], v[82:85]
	v_mfma_f32_16x16x32_bf16 v[66:69], v[172:175], v[204:207], v[66:69]
	v_mfma_f32_16x16x32_bf16 v[66:69], v[176:179], v[208:211], v[66:69]
	s_setprio 2
	s_barrier
	v_mfma_f32_16x16x32_bf16 v[70:73], v[164:167], v[204:207], v[70:73]
	v_mfma_f32_16x16x32_bf16 v[70:73], v[168:171], v[208:211], v[70:73]
	s_setprio 0
	ds_read_b128 v[180:183], v145 offset:49152
	ds_read_b128 v[184:187], v145 offset:50176
	ds_read_b128 v[188:191], v145 offset:51200
	ds_read_b128 v[192:195], v145 offset:52224
	ds_read_b128 v[196:199], v145 offset:53248
	ds_read_b128 v[200:203], v145 offset:54272
	ds_read_b128 v[204:207], v145 offset:55296
	ds_read_b128 v[208:211], v145 offset:56320
	s_add_u32 s22, s20, 0x80
	s_addc_u32 s23, s21, 0
	s_mov_b32 s82, m0
	s_mov_b32 m0, s48
	s_nop 0
	global_load_lds_dwordx4 v139, s[22:23]
	s_mov_b32 m0, s82
	s_add_u32 s20, s20, 0x80080
	s_mov_b32 s82, m0
	s_mov_b32 m0, s49
	s_nop 0
	global_load_lds_dwordx4 v141, s[22:23]
	s_mov_b32 m0, s82
	s_addc_u32 s21, s21, 0
	s_mov_b32 s22, m0
	s_mov_b32 m0, s56
	s_nop 0
	global_load_lds_dwordx4 v139, s[20:21]
	s_mov_b32 m0, s22
	s_nop 0
	s_mov_b32 s22, m0
	s_mov_b32 m0, s57
	s_nop 0
	global_load_lds_dwordx4 v141, s[20:21]
	s_mov_b32 m0, s22
	s_waitcnt vmcnt(4)
	s_waitcnt lgkmcnt(0)
	s_waitcnt lgkmcnt(7)
	v_mfma_f32_16x16x32_bf16 v[62:65], v[148:151], v[180:183], v[62:65]
	v_mfma_f32_16x16x32_bf16 v[62:65], v[152:155], v[184:187], v[62:65]
	s_waitcnt lgkmcnt(5)
	v_mfma_f32_16x16x32_bf16 v[58:61], v[156:159], v[180:183], v[58:61]
	v_mfma_f32_16x16x32_bf16 v[58:61], v[160:163], v[184:187], v[58:61]
	s_barrier
	s_setprio 1
	s_waitcnt lgkmcnt(3)
	v_mfma_f32_16x16x32_bf16 v[42:45], v[156:159], v[188:191], v[42:45]
	v_mfma_f32_16x16x32_bf16 v[42:45], v[160:163], v[192:195], v[42:45]
	s_waitcnt lgkmcnt(1)
	v_mfma_f32_16x16x32_bf16 v[46:49], v[148:151], v[188:191], v[46:49]
	v_mfma_f32_16x16x32_bf16 v[46:49], v[152:155], v[192:195], v[46:49]
	v_mfma_f32_16x16x32_bf16 v[30:33], v[148:151], v[196:199], v[30:33]
	v_mfma_f32_16x16x32_bf16 v[30:33], v[152:155], v[200:203], v[30:33]
	v_mfma_f32_16x16x32_bf16 v[26:29], v[156:159], v[196:199], v[26:29]
	v_mfma_f32_16x16x32_bf16 v[26:29], v[160:163], v[200:203], v[26:29]
	v_mfma_f32_16x16x32_bf16 v[10:13], v[156:159], v[204:207], v[10:13]
	v_mfma_f32_16x16x32_bf16 v[10:13], v[160:163], v[208:211], v[10:13]
	s_waitcnt lgkmcnt(0)
	v_mfma_f32_16x16x32_bf16 v[14:17], v[148:151], v[204:207], v[14:17]
	v_mfma_f32_16x16x32_bf16 v[14:17], v[152:155], v[208:211], v[14:17]
	s_setprio 0
	s_setprio 1
	v_mfma_f32_16x16x32_bf16 v[54:57], v[164:167], v[180:183], v[54:57]
	v_mfma_f32_16x16x32_bf16 v[54:57], v[168:171], v[184:187], v[54:57]
	v_mfma_f32_16x16x32_bf16 v[50:53], v[172:175], v[180:183], v[50:53]
	v_mfma_f32_16x16x32_bf16 v[50:53], v[176:179], v[184:187], v[50:53]
	v_mfma_f32_16x16x32_bf16 v[34:37], v[172:175], v[188:191], v[34:37]
	v_mfma_f32_16x16x32_bf16 v[34:37], v[176:179], v[192:195], v[34:37]
	v_mfma_f32_16x16x32_bf16 v[38:41], v[164:167], v[188:191], v[38:41]
	v_mfma_f32_16x16x32_bf16 v[38:41], v[168:171], v[192:195], v[38:41]
	v_mfma_f32_16x16x32_bf16 v[22:25], v[164:167], v[196:199], v[22:25]
	v_mfma_f32_16x16x32_bf16 v[22:25], v[168:171], v[200:203], v[22:25]
	v_mfma_f32_16x16x32_bf16 v[18:21], v[172:175], v[196:199], v[18:21]
	v_mfma_f32_16x16x32_bf16 v[18:21], v[176:179], v[200:203], v[18:21]
	v_mfma_f32_16x16x32_bf16 v[2:5], v[172:175], v[204:207], v[2:5]
	v_mfma_f32_16x16x32_bf16 v[2:5], v[176:179], v[208:211], v[2:5]
	s_setprio 2
	s_barrier
	v_mfma_f32_16x16x32_bf16 v[6:9], v[164:167], v[204:207], v[6:9]
	v_mfma_f32_16x16x32_bf16 v[6:9], v[168:171], v[208:211], v[6:9]
	s_setprio 0
	s_add_i32 s81, s81, 2
	s_add_u32 s77, s77, 0x100
	s_addc_u32 s78, s78, 0
	s_add_u32 s18, s18, 0x100
	s_addc_u32 s19, s19, 0
	s_add_u32 s79, s79, 0x100
	s_addc_u32 s80, s80, 0
	s_cmp_gt_u32 s81, 29
	.p2align 6
.LBB0_344:
	ds_read_b128 v[148:151], v143
	ds_read_b128 v[152:155], v143 offset:1024
	ds_read_b128 v[156:159], v143 offset:2048
	ds_read_b128 v[160:163], v143 offset:3072
	ds_read_b128 v[164:167], v144
	ds_read_b128 v[168:171], v144 offset:1024
	ds_read_b128 v[172:175], v144 offset:2048
	ds_read_b128 v[176:179], v144 offset:3072
	s_cmp_eq_u32 s81, 28
	s_cselect_b32 s21, s9, s78
	s_cselect_b32 s20, s76, s77
	s_cselect_b32 s23, s11, s80
	s_cselect_b32 s22, s75, s79
	ds_read_b128 v[180:183], v145
	ds_read_b128 v[184:187], v145 offset:1024
	ds_read_b128 v[188:191], v145 offset:2048
	ds_read_b128 v[192:195], v145 offset:3072
	ds_read_b128 v[196:199], v145 offset:4096
	ds_read_b128 v[200:203], v145 offset:5120
	ds_read_b128 v[204:207], v145 offset:6144
	ds_read_b128 v[208:211], v145 offset:7168
	s_add_u32 s82, s18, 0xfff80000
	s_addc_u32 s83, s19, -1
	s_mov_b32 s86, m0
	s_mov_b32 m0, s64
	s_nop 0
	global_load_lds_dwordx4 v138, s[82:83]
	s_mov_b32 m0, s86
	s_nop 0
	s_mov_b32 s86, m0
	s_mov_b32 m0, s67
	s_nop 0
	global_load_lds_dwordx4 v140, s[82:83]
	s_mov_b32 m0, s86
	s_mov_b32 s82, m0
	s_mov_b32 m0, s65
	s_nop 0
	global_load_lds_dwordx4 v138, s[18:19]
	s_mov_b32 m0, s82
	s_nop 0
	s_mov_b32 s82, m0
	s_mov_b32 m0, s73
	s_nop 0
	global_load_lds_dwordx4 v140, s[18:19]
	s_mov_b32 m0, s82
	s_waitcnt vmcnt(8)
	s_waitcnt lgkmcnt(0)
	s_waitcnt lgkmcnt(7)
	v_mfma_f32_16x16x32_bf16 v[126:129], v[148:151], v[180:183], v[126:129]
	v_mfma_f32_16x16x32_bf16 v[126:129], v[152:155], v[184:187], v[126:129]
	s_waitcnt lgkmcnt(5)
	v_mfma_f32_16x16x32_bf16 v[122:125], v[156:159], v[180:183], v[122:125]
	v_mfma_f32_16x16x32_bf16 v[122:125], v[160:163], v[184:187], v[122:125]
	s_barrier
	s_setprio 1
	s_waitcnt lgkmcnt(3)
	v_mfma_f32_16x16x32_bf16 v[106:109], v[156:159], v[188:191], v[106:109]
	v_mfma_f32_16x16x32_bf16 v[106:109], v[160:163], v[192:195], v[106:109]
	s_waitcnt lgkmcnt(1)
	v_mfma_f32_16x16x32_bf16 v[110:113], v[148:151], v[188:191], v[110:113]
	v_mfma_f32_16x16x32_bf16 v[110:113], v[152:155], v[192:195], v[110:113]
	v_mfma_f32_16x16x32_bf16 v[94:97], v[148:151], v[196:199], v[94:97]
	v_mfma_f32_16x16x32_bf16 v[94:97], v[152:155], v[200:203], v[94:97]
	v_mfma_f32_16x16x32_bf16 v[90:93], v[156:159], v[196:199], v[90:93]
	v_mfma_f32_16x16x32_bf16 v[90:93], v[160:163], v[200:203], v[90:93]
	v_mfma_f32_16x16x32_bf16 v[74:77], v[156:159], v[204:207], v[74:77]
	v_mfma_f32_16x16x32_bf16 v[74:77], v[160:163], v[208:211], v[74:77]
	s_waitcnt lgkmcnt(0)
	v_mfma_f32_16x16x32_bf16 v[78:81], v[148:151], v[204:207], v[78:81]
	v_mfma_f32_16x16x32_bf16 v[78:81], v[152:155], v[208:211], v[78:81]
	s_setprio 0
	s_setprio 1
	v_mfma_f32_16x16x32_bf16 v[118:121], v[164:167], v[180:183], v[118:121]
	v_mfma_f32_16x16x32_bf16 v[118:121], v[168:171], v[184:187], v[118:121]
	v_mfma_f32_16x16x32_bf16 v[114:117], v[172:175], v[180:183], v[114:117]
	v_mfma_f32_16x16x32_bf16 v[114:117], v[176:179], v[184:187], v[114:117]
	v_mfma_f32_16x16x32_bf16 v[98:101], v[172:175], v[188:191], v[98:101]
	v_mfma_f32_16x16x32_bf16 v[98:101], v[176:179], v[192:195], v[98:101]
	v_mfma_f32_16x16x32_bf16 v[102:105], v[164:167], v[188:191], v[102:105]
	v_mfma_f32_16x16x32_bf16 v[102:105], v[168:171], v[192:195], v[102:105]
	v_mfma_f32_16x16x32_bf16 v[86:89], v[164:167], v[196:199], v[86:89]
	v_mfma_f32_16x16x32_bf16 v[86:89], v[168:171], v[200:203], v[86:89]
	v_mfma_f32_16x16x32_bf16 v[82:85], v[172:175], v[196:199], v[82:85]
	v_mfma_f32_16x16x32_bf16 v[82:85], v[176:179], v[200:203], v[82:85]
	v_mfma_f32_16x16x32_bf16 v[66:69], v[172:175], v[204:207], v[66:69]
	v_mfma_f32_16x16x32_bf16 v[66:69], v[176:179], v[208:211], v[66:69]
	s_setprio 2
	s_barrier
	v_mfma_f32_16x16x32_bf16 v[70:73], v[164:167], v[204:207], v[70:73]
	v_mfma_f32_16x16x32_bf16 v[70:73], v[168:171], v[208:211], v[70:73]
	s_setprio 0
	ds_read_b128 v[180:183], v145 offset:16384
	ds_read_b128 v[184:187], v145 offset:17408
	ds_read_b128 v[188:191], v145 offset:18432
	ds_read_b128 v[192:195], v145 offset:19456
	ds_read_b128 v[196:199], v145 offset:20480
	ds_read_b128 v[200:203], v145 offset:21504
	ds_read_b128 v[204:207], v145 offset:22528
	ds_read_b128 v[208:211], v145 offset:23552
	s_mov_b32 s82, m0
	s_mov_b32 m0, s35
	s_nop 0
	global_load_lds_dwordx4 v139, s[20:21]
	s_mov_b32 m0, s82
	s_nop 0
	s_mov_b32 s82, m0
	s_mov_b32 m0, s36
	s_nop 0
	global_load_lds_dwordx4 v141, s[20:21]
	s_mov_b32 m0, s82
	s_add_u32 s82, s20, 0x80000
	s_addc_u32 s83, s21, 0
	s_mov_b32 s86, m0
	s_mov_b32 m0, s37
	s_nop 0
	global_load_lds_dwordx4 v139, s[82:83]
	s_mov_b32 m0, s86
	s_nop 0
	s_mov_b32 s86, m0
	s_mov_b32 m0, s42
	s_nop 0
	global_load_lds_dwordx4 v141, s[82:83]
	s_mov_b32 m0, s86
	s_waitcnt vmcnt(4)
	s_waitcnt lgkmcnt(0)
	s_waitcnt lgkmcnt(7)
	v_mfma_f32_16x16x32_bf16 v[62:65], v[148:151], v[180:183], v[62:65]
	v_mfma_f32_16x16x32_bf16 v[62:65], v[152:155], v[184:187], v[62:65]
	s_waitcnt lgkmcnt(5)
	v_mfma_f32_16x16x32_bf16 v[58:61], v[156:159], v[180:183], v[58:61]
	v_mfma_f32_16x16x32_bf16 v[58:61], v[160:163], v[184:187], v[58:61]
	s_barrier
	s_setprio 1
	s_waitcnt lgkmcnt(3)
	v_mfma_f32_16x16x32_bf16 v[42:45], v[156:159], v[188:191], v[42:45]
	v_mfma_f32_16x16x32_bf16 v[42:45], v[160:163], v[192:195], v[42:45]
	s_waitcnt lgkmcnt(1)
	v_mfma_f32_16x16x32_bf16 v[46:49], v[148:151], v[188:191], v[46:49]
	v_mfma_f32_16x16x32_bf16 v[46:49], v[152:155], v[192:195], v[46:49]
	v_mfma_f32_16x16x32_bf16 v[30:33], v[148:151], v[196:199], v[30:33]
	v_mfma_f32_16x16x32_bf16 v[30:33], v[152:155], v[200:203], v[30:33]
	v_mfma_f32_16x16x32_bf16 v[26:29], v[156:159], v[196:199], v[26:29]
	v_mfma_f32_16x16x32_bf16 v[26:29], v[160:163], v[200:203], v[26:29]
	v_mfma_f32_16x16x32_bf16 v[10:13], v[156:159], v[204:207], v[10:13]
	v_mfma_f32_16x16x32_bf16 v[10:13], v[160:163], v[208:211], v[10:13]
	s_waitcnt lgkmcnt(0)
	v_mfma_f32_16x16x32_bf16 v[14:17], v[148:151], v[204:207], v[14:17]
	v_mfma_f32_16x16x32_bf16 v[14:17], v[152:155], v[208:211], v[14:17]
	s_setprio 0
	s_setprio 1
	v_mfma_f32_16x16x32_bf16 v[54:57], v[164:167], v[180:183], v[54:57]
	v_mfma_f32_16x16x32_bf16 v[54:57], v[168:171], v[184:187], v[54:57]
	v_mfma_f32_16x16x32_bf16 v[50:53], v[172:175], v[180:183], v[50:53]
	v_mfma_f32_16x16x32_bf16 v[50:53], v[176:179], v[184:187], v[50:53]
	v_mfma_f32_16x16x32_bf16 v[34:37], v[172:175], v[188:191], v[34:37]
	v_mfma_f32_16x16x32_bf16 v[34:37], v[176:179], v[192:195], v[34:37]
	v_mfma_f32_16x16x32_bf16 v[38:41], v[164:167], v[188:191], v[38:41]
	v_mfma_f32_16x16x32_bf16 v[38:41], v[168:171], v[192:195], v[38:41]
	v_mfma_f32_16x16x32_bf16 v[22:25], v[164:167], v[196:199], v[22:25]
	v_mfma_f32_16x16x32_bf16 v[22:25], v[168:171], v[200:203], v[22:25]
	v_mfma_f32_16x16x32_bf16 v[18:21], v[172:175], v[196:199], v[18:21]
	v_mfma_f32_16x16x32_bf16 v[18:21], v[176:179], v[200:203], v[18:21]
	v_mfma_f32_16x16x32_bf16 v[2:5], v[172:175], v[204:207], v[2:5]
	v_mfma_f32_16x16x32_bf16 v[2:5], v[176:179], v[208:211], v[2:5]
	s_setprio 2
	s_barrier
	v_mfma_f32_16x16x32_bf16 v[6:9], v[164:167], v[204:207], v[6:9]
	v_mfma_f32_16x16x32_bf16 v[6:9], v[168:171], v[208:211], v[6:9]
	s_setprio 0
	ds_read_b128 v[148:151], v146
	ds_read_b128 v[152:155], v146 offset:1024
	ds_read_b128 v[156:159], v146 offset:2048
	ds_read_b128 v[160:163], v146 offset:3072
	ds_read_b128 v[164:167], v147
	ds_read_b128 v[168:171], v147 offset:1024
	ds_read_b128 v[172:175], v147 offset:2048
	ds_read_b128 v[176:179], v147 offset:3072
	ds_read_b128 v[180:183], v145 offset:32768
	ds_read_b128 v[184:187], v145 offset:33792
	ds_read_b128 v[188:191], v145 offset:34816
	ds_read_b128 v[192:195], v145 offset:35840
	ds_read_b128 v[196:199], v145 offset:36864
	ds_read_b128 v[200:203], v145 offset:37888
	ds_read_b128 v[204:207], v145 offset:38912
	ds_read_b128 v[208:211], v145 offset:39936
	s_mov_b32 s82, m0
	s_mov_b32 m0, s31
	s_nop 0
	global_load_lds_dwordx4 v138, s[22:23]
	s_mov_b32 m0, s82
	s_nop 0
	s_mov_b32 s82, m0
	s_mov_b32 m0, s43
	s_nop 0
	global_load_lds_dwordx4 v140, s[22:23]
	s_mov_b32 m0, s82
	s_add_u32 s22, s22, 0x80000
	s_addc_u32 s23, s23, 0
	s_mov_b32 s82, m0
	s_mov_b32 m0, s46
	s_nop 0
	global_load_lds_dwordx4 v138, s[22:23]
	s_mov_b32 m0, s82
	s_nop 0
	s_mov_b32 s82, m0
	s_mov_b32 m0, s47
	s_nop 0
	global_load_lds_dwordx4 v140, s[22:23]
	s_mov_b32 m0, s82
	s_waitcnt vmcnt(8)
	s_waitcnt lgkmcnt(0)
	s_waitcnt lgkmcnt(7)
	v_mfma_f32_16x16x32_bf16 v[126:129], v[148:151], v[180:183], v[126:129]
	v_mfma_f32_16x16x32_bf16 v[126:129], v[152:155], v[184:187], v[126:129]
	s_waitcnt lgkmcnt(5)
	v_mfma_f32_16x16x32_bf16 v[122:125], v[156:159], v[180:183], v[122:125]
	v_mfma_f32_16x16x32_bf16 v[122:125], v[160:163], v[184:187], v[122:125]
	s_barrier
	s_setprio 1
	s_waitcnt lgkmcnt(3)
	v_mfma_f32_16x16x32_bf16 v[106:109], v[156:159], v[188:191], v[106:109]
	v_mfma_f32_16x16x32_bf16 v[106:109], v[160:163], v[192:195], v[106:109]
	s_waitcnt lgkmcnt(1)
	v_mfma_f32_16x16x32_bf16 v[110:113], v[148:151], v[188:191], v[110:113]
	v_mfma_f32_16x16x32_bf16 v[110:113], v[152:155], v[192:195], v[110:113]
	v_mfma_f32_16x16x32_bf16 v[94:97], v[148:151], v[196:199], v[94:97]
	v_mfma_f32_16x16x32_bf16 v[94:97], v[152:155], v[200:203], v[94:97]
	v_mfma_f32_16x16x32_bf16 v[90:93], v[156:159], v[196:199], v[90:93]
	v_mfma_f32_16x16x32_bf16 v[90:93], v[160:163], v[200:203], v[90:93]
	v_mfma_f32_16x16x32_bf16 v[74:77], v[156:159], v[204:207], v[74:77]
	v_mfma_f32_16x16x32_bf16 v[74:77], v[160:163], v[208:211], v[74:77]
	s_waitcnt lgkmcnt(0)
	v_mfma_f32_16x16x32_bf16 v[78:81], v[148:151], v[204:207], v[78:81]
	v_mfma_f32_16x16x32_bf16 v[78:81], v[152:155], v[208:211], v[78:81]
	s_setprio 0
	s_setprio 1
	v_mfma_f32_16x16x32_bf16 v[118:121], v[164:167], v[180:183], v[118:121]
	v_mfma_f32_16x16x32_bf16 v[118:121], v[168:171], v[184:187], v[118:121]
	v_mfma_f32_16x16x32_bf16 v[114:117], v[172:175], v[180:183], v[114:117]
	v_mfma_f32_16x16x32_bf16 v[114:117], v[176:179], v[184:187], v[114:117]
	v_mfma_f32_16x16x32_bf16 v[98:101], v[172:175], v[188:191], v[98:101]
	v_mfma_f32_16x16x32_bf16 v[98:101], v[176:179], v[192:195], v[98:101]
	v_mfma_f32_16x16x32_bf16 v[102:105], v[164:167], v[188:191], v[102:105]
	v_mfma_f32_16x16x32_bf16 v[102:105], v[168:171], v[192:195], v[102:105]
	v_mfma_f32_16x16x32_bf16 v[86:89], v[164:167], v[196:199], v[86:89]
	v_mfma_f32_16x16x32_bf16 v[86:89], v[168:171], v[200:203], v[86:89]
	v_mfma_f32_16x16x32_bf16 v[82:85], v[172:175], v[196:199], v[82:85]
	v_mfma_f32_16x16x32_bf16 v[82:85], v[176:179], v[200:203], v[82:85]
	v_mfma_f32_16x16x32_bf16 v[66:69], v[172:175], v[204:207], v[66:69]
	v_mfma_f32_16x16x32_bf16 v[66:69], v[176:179], v[208:211], v[66:69]
	s_setprio 2
	s_barrier
	v_mfma_f32_16x16x32_bf16 v[70:73], v[164:167], v[204:207], v[70:73]
	v_mfma_f32_16x16x32_bf16 v[70:73], v[168:171], v[208:211], v[70:73]
	s_setprio 0
	ds_read_b128 v[180:183], v145 offset:49152
	ds_read_b128 v[184:187], v145 offset:50176
	ds_read_b128 v[188:191], v145 offset:51200
	ds_read_b128 v[192:195], v145 offset:52224
	ds_read_b128 v[196:199], v145 offset:53248
	ds_read_b128 v[200:203], v145 offset:54272
	ds_read_b128 v[204:207], v145 offset:55296
	ds_read_b128 v[208:211], v145 offset:56320
	s_add_u32 s22, s20, 0x80
	s_addc_u32 s23, s21, 0
	s_mov_b32 s82, m0
	s_mov_b32 m0, s48
	s_nop 0
	global_load_lds_dwordx4 v139, s[22:23]
	s_mov_b32 m0, s82
	s_add_u32 s20, s20, 0x80080
	s_mov_b32 s82, m0
	s_mov_b32 m0, s49
	s_nop 0
	global_load_lds_dwordx4 v141, s[22:23]
	s_mov_b32 m0, s82
	s_addc_u32 s21, s21, 0
	s_mov_b32 s22, m0
	s_mov_b32 m0, s56
	s_nop 0
	global_load_lds_dwordx4 v139, s[20:21]
	s_mov_b32 m0, s22
	s_nop 0
	s_mov_b32 s22, m0
	s_mov_b32 m0, s57
	s_nop 0
	global_load_lds_dwordx4 v141, s[20:21]
	s_mov_b32 m0, s22
	s_waitcnt vmcnt(4)
	s_waitcnt lgkmcnt(0)
	s_waitcnt lgkmcnt(7)
	v_mfma_f32_16x16x32_bf16 v[62:65], v[148:151], v[180:183], v[62:65]
	v_mfma_f32_16x16x32_bf16 v[62:65], v[152:155], v[184:187], v[62:65]
	s_waitcnt lgkmcnt(5)
	v_mfma_f32_16x16x32_bf16 v[58:61], v[156:159], v[180:183], v[58:61]
	v_mfma_f32_16x16x32_bf16 v[58:61], v[160:163], v[184:187], v[58:61]
	s_barrier
	s_setprio 1
	s_waitcnt lgkmcnt(3)
	v_mfma_f32_16x16x32_bf16 v[42:45], v[156:159], v[188:191], v[42:45]
	v_mfma_f32_16x16x32_bf16 v[42:45], v[160:163], v[192:195], v[42:45]
	s_waitcnt lgkmcnt(1)
	v_mfma_f32_16x16x32_bf16 v[46:49], v[148:151], v[188:191], v[46:49]
	v_mfma_f32_16x16x32_bf16 v[46:49], v[152:155], v[192:195], v[46:49]
	v_mfma_f32_16x16x32_bf16 v[30:33], v[148:151], v[196:199], v[30:33]
	v_mfma_f32_16x16x32_bf16 v[30:33], v[152:155], v[200:203], v[30:33]
	v_mfma_f32_16x16x32_bf16 v[26:29], v[156:159], v[196:199], v[26:29]
	v_mfma_f32_16x16x32_bf16 v[26:29], v[160:163], v[200:203], v[26:29]
	v_mfma_f32_16x16x32_bf16 v[10:13], v[156:159], v[204:207], v[10:13]
	v_mfma_f32_16x16x32_bf16 v[10:13], v[160:163], v[208:211], v[10:13]
	s_waitcnt lgkmcnt(0)
	v_mfma_f32_16x16x32_bf16 v[14:17], v[148:151], v[204:207], v[14:17]
	v_mfma_f32_16x16x32_bf16 v[14:17], v[152:155], v[208:211], v[14:17]
	s_setprio 0
	s_setprio 1
	v_mfma_f32_16x16x32_bf16 v[54:57], v[164:167], v[180:183], v[54:57]
	v_mfma_f32_16x16x32_bf16 v[54:57], v[168:171], v[184:187], v[54:57]
	v_mfma_f32_16x16x32_bf16 v[50:53], v[172:175], v[180:183], v[50:53]
	v_mfma_f32_16x16x32_bf16 v[50:53], v[176:179], v[184:187], v[50:53]
	v_mfma_f32_16x16x32_bf16 v[34:37], v[172:175], v[188:191], v[34:37]
	v_mfma_f32_16x16x32_bf16 v[34:37], v[176:179], v[192:195], v[34:37]
	v_mfma_f32_16x16x32_bf16 v[38:41], v[164:167], v[188:191], v[38:41]
	v_mfma_f32_16x16x32_bf16 v[38:41], v[168:171], v[192:195], v[38:41]
	v_mfma_f32_16x16x32_bf16 v[22:25], v[164:167], v[196:199], v[22:25]
	v_mfma_f32_16x16x32_bf16 v[22:25], v[168:171], v[200:203], v[22:25]
	v_mfma_f32_16x16x32_bf16 v[18:21], v[172:175], v[196:199], v[18:21]
	v_mfma_f32_16x16x32_bf16 v[18:21], v[176:179], v[200:203], v[18:21]
	v_mfma_f32_16x16x32_bf16 v[2:5], v[172:175], v[204:207], v[2:5]
	v_mfma_f32_16x16x32_bf16 v[2:5], v[176:179], v[208:211], v[2:5]
	s_setprio 2
	s_barrier
	v_mfma_f32_16x16x32_bf16 v[6:9], v[164:167], v[204:207], v[6:9]
	v_mfma_f32_16x16x32_bf16 v[6:9], v[168:171], v[208:211], v[6:9]
	s_setprio 0
	s_add_i32 s81, s81, 2
	s_add_u32 s77, s77, 0x100
	s_addc_u32 s78, s78, 0
	s_add_u32 s18, s18, 0x100
	s_addc_u32 s19, s19, 0
	s_add_u32 s79, s79, 0x100
	s_addc_u32 s80, s80, 0
	s_cmp_gt_u32 s81, 29
	s_cbranch_scc0 .LBB0_344
	s_and_b64 vcc, exec, s[6:7]
	s_cbranch_vccz .LBB0_347
	s_barrier

.LBB0_472:
	s_ashr_i32 s13, s12, 31
	s_lshl_b64 s[14:15], s[12:13], 15
	s_add_u32 s14, s28, s14
	s_addc_u32 s15, s29, s15
	s_and_b64 s[16:17], s[2:3], exec
	s_cselect_b32 s13, s15, s23
	s_cselect_b32 s76, s14, s22
	s_ashr_i32 s11, s10, 31
	s_lshl_b64 s[16:17], s[10:11], 15
	s_add_u32 s16, s30, s16
	s_addc_u32 s17, s31, s17
	s_and_b64 s[24:25], s[2:3], exec
	s_cselect_b32 s11, s17, s21
	s_cselect_b32 s77, s16, s20
	s_add_u32 s78, s20, 0x80000
	s_addc_u32 s79, s21, 0
	s_add_u32 s20, s22, 0x204000
	s_addc_u32 s21, s23, 0
	s_add_u32 s80, s22, 0x400000
	s_addc_u32 s81, s23, 0
	s_mov_b32 s82, -2
	s_waitcnt vmcnt(25)
	s_waitcnt vmcnt(24)
	s_waitcnt vmcnt(23)
	s_waitcnt vmcnt(22)
	s_waitcnt vmcnt(21)
	s_waitcnt vmcnt(20)
	s_waitcnt vmcnt(15)
	s_waitcnt vmcnt(14)
	s_waitcnt vmcnt(13)
	s_waitcnt vmcnt(12)
	s_waitcnt vmcnt(7)
	s_waitcnt vmcnt(6)
	s_waitcnt vmcnt(5)
	s_waitcnt vmcnt(4)
	s_waitcnt vmcnt(3)
	s_waitcnt vmcnt(2)
	s_waitcnt vmcnt(1)
	s_waitcnt vmcnt(0)
	ds_read_b128 v[134:137], v161
	ds_read_b128 v[138:141], v161 offset:1024
	ds_read_b128 v[142:145], v161 offset:2048
	ds_read_b128 v[146:149], v161 offset:3072
	ds_read_b128 v[150:153], v162
	ds_read_b128 v[166:169], v162 offset:1024
	ds_read_b128 v[170:173], v162 offset:2048
	ds_read_b128 v[174:177], v162 offset:3072
	s_cmpk_eq_i32 s82, 0x52
	s_cselect_b32 s23, s11, s79
	s_cselect_b32 s22, s77, s78
	s_cselect_b32 s25, s13, s81
	s_cselect_b32 s24, s76, s80
	ds_read_b128 v[178:181], v163
	ds_read_b128 v[182:185], v163 offset:1024
	ds_read_b128 v[186:189], v163 offset:2048
	ds_read_b128 v[190:193], v163 offset:3072
	ds_read_b128 v[194:197], v163 offset:4096
	ds_read_b128 v[198:201], v163 offset:5120
	ds_read_b128 v[202:205], v163 offset:6144
	ds_read_b128 v[206:209], v163 offset:7168
	s_add_u32 s86, s20, 0xffffc000
	s_addc_u32 s87, s21, -1
	s_mov_b32 s83, m0
	s_mov_b32 m0, s65
	s_nop 0
	global_load_lds_dwordx4 v1, s[86:87]
	s_mov_b32 m0, s83
	s_nop 0
	s_mov_b32 s83, m0
	s_mov_b32 m0, s67
	s_nop 0
	global_load_lds_dwordx4 v157, s[86:87]
	s_mov_b32 m0, s83
	s_nop 0
	s_mov_b32 s83, m0
	s_mov_b32 m0, s66
	s_nop 0
	global_load_lds_dwordx4 v1, s[20:21]
	s_mov_b32 m0, s83
	s_nop 0
	s_mov_b32 s83, m0
	s_mov_b32 m0, s73
	s_nop 0
	global_load_lds_dwordx4 v157, s[20:21]
	s_mov_b32 m0, s83
	s_waitcnt vmcnt(8)
	s_waitcnt lgkmcnt(0)
	s_waitcnt lgkmcnt(7)
	v_mfma_f32_16x16x32_bf16 v[126:129], v[134:137], v[178:181], 0
	v_mfma_f32_16x16x32_bf16 v[126:129], v[138:141], v[182:185], v[126:129]
	s_waitcnt lgkmcnt(5)
	v_mfma_f32_16x16x32_bf16 v[122:125], v[142:145], v[178:181], 0
	v_mfma_f32_16x16x32_bf16 v[122:125], v[146:149], v[182:185], v[122:125]
	s_barrier
	s_setprio 1
	s_waitcnt lgkmcnt(3)
	v_mfma_f32_16x16x32_bf16 v[114:117], v[142:145], v[186:189], 0
	v_mfma_f32_16x16x32_bf16 v[114:117], v[146:149], v[190:193], v[114:117]
	s_waitcnt lgkmcnt(1)
	v_mfma_f32_16x16x32_bf16 v[118:121], v[134:137], v[186:189], 0
	v_mfma_f32_16x16x32_bf16 v[118:121], v[138:141], v[190:193], v[118:121]
	v_mfma_f32_16x16x32_bf16 v[102:105], v[134:137], v[194:197], 0
	v_mfma_f32_16x16x32_bf16 v[102:105], v[138:141], v[198:201], v[102:105]
	v_mfma_f32_16x16x32_bf16 v[94:97], v[142:145], v[194:197], 0
	v_mfma_f32_16x16x32_bf16 v[94:97], v[146:149], v[198:201], v[94:97]
	v_mfma_f32_16x16x32_bf16 v[78:81], v[142:145], v[202:205], 0
	v_mfma_f32_16x16x32_bf16 v[78:81], v[146:149], v[206:209], v[78:81]
	s_waitcnt lgkmcnt(0)
	v_mfma_f32_16x16x32_bf16 v[86:89], v[134:137], v[202:205], 0
	v_mfma_f32_16x16x32_bf16 v[86:89], v[138:141], v[206:209], v[86:89]
	s_setprio 0
	s_setprio 1
	v_mfma_f32_16x16x32_bf16 v[110:113], v[150:153], v[178:181], 0
	v_mfma_f32_16x16x32_bf16 v[110:113], v[166:169], v[182:185], v[110:113]
	v_mfma_f32_16x16x32_bf16 v[106:109], v[170:173], v[178:181], 0
	v_mfma_f32_16x16x32_bf16 v[106:109], v[174:177], v[182:185], v[106:109]
	v_mfma_f32_16x16x32_bf16 v[90:93], v[170:173], v[186:189], 0
	v_mfma_f32_16x16x32_bf16 v[90:93], v[174:177], v[190:193], v[90:93]
	v_mfma_f32_16x16x32_bf16 v[98:101], v[150:153], v[186:189], 0
	v_mfma_f32_16x16x32_bf16 v[98:101], v[166:169], v[190:193], v[98:101]
	v_mfma_f32_16x16x32_bf16 v[82:85], v[150:153], v[194:197], 0
	v_mfma_f32_16x16x32_bf16 v[82:85], v[166:169], v[198:201], v[82:85]
	v_mfma_f32_16x16x32_bf16 v[74:77], v[170:173], v[194:197], 0
	v_mfma_f32_16x16x32_bf16 v[74:77], v[174:177], v[198:201], v[74:77]
	v_mfma_f32_16x16x32_bf16 v[66:69], v[170:173], v[202:205], 0
	v_mfma_f32_16x16x32_bf16 v[66:69], v[174:177], v[206:209], v[66:69]
	s_setprio 2
	s_barrier
	v_mfma_f32_16x16x32_bf16 v[70:73], v[150:153], v[202:205], 0
	v_mfma_f32_16x16x32_bf16 v[70:73], v[166:169], v[206:209], v[70:73]
	s_setprio 0
	ds_read_b128 v[178:181], v163 offset:16384
	ds_read_b128 v[182:185], v163 offset:17408
	ds_read_b128 v[186:189], v163 offset:18432
	ds_read_b128 v[190:193], v163 offset:19456
	ds_read_b128 v[194:197], v163 offset:20480
	ds_read_b128 v[198:201], v163 offset:21504
	ds_read_b128 v[202:205], v163 offset:22528
	ds_read_b128 v[206:209], v163 offset:23552
	s_mov_b32 s83, m0
	s_mov_b32 m0, s19
	s_nop 0
	global_load_lds_dwordx4 v156, s[22:23]
	s_mov_b32 m0, s83
	s_add_u32 s86, s22, 0x4000
	s_mov_b32 s83, m0
	s_mov_b32 m0, s35
	s_nop 0
	global_load_lds_dwordx4 v158, s[22:23]
	s_mov_b32 m0, s83
	s_addc_u32 s87, s23, 0
	s_mov_b32 s83, m0
	s_mov_b32 m0, s36
	s_nop 0
	global_load_lds_dwordx4 v156, s[86:87]
	s_mov_b32 m0, s83
	s_nop 0
	s_mov_b32 s83, m0
	s_mov_b32 m0, s37
	s_nop 0
	global_load_lds_dwordx4 v158, s[86:87]
	s_mov_b32 m0, s83
	s_waitcnt vmcnt(4)
	s_waitcnt lgkmcnt(0)
	s_waitcnt lgkmcnt(7)
	v_mfma_f32_16x16x32_bf16 v[62:65], v[134:137], v[178:181], 0
	v_mfma_f32_16x16x32_bf16 v[62:65], v[138:141], v[182:185], v[62:65]
	s_waitcnt lgkmcnt(5)
	v_mfma_f32_16x16x32_bf16 v[58:61], v[142:145], v[178:181], 0
	v_mfma_f32_16x16x32_bf16 v[58:61], v[146:149], v[182:185], v[58:61]
	s_barrier
	s_setprio 1
	s_waitcnt lgkmcnt(3)
	v_mfma_f32_16x16x32_bf16 v[46:49], v[142:145], v[186:189], 0
	v_mfma_f32_16x16x32_bf16 v[46:49], v[146:149], v[190:193], v[46:49]
	s_waitcnt lgkmcnt(1)
	v_mfma_f32_16x16x32_bf16 v[54:57], v[134:137], v[186:189], 0
	v_mfma_f32_16x16x32_bf16 v[54:57], v[138:141], v[190:193], v[54:57]
	v_mfma_f32_16x16x32_bf16 v[38:41], v[134:137], v[194:197], 0
	v_mfma_f32_16x16x32_bf16 v[38:41], v[138:141], v[198:201], v[38:41]
	v_mfma_f32_16x16x32_bf16 v[30:33], v[142:145], v[194:197], 0
	v_mfma_f32_16x16x32_bf16 v[30:33], v[146:149], v[198:201], v[30:33]
	v_mfma_f32_16x16x32_bf16 v[14:17], v[142:145], v[202:205], 0
	v_mfma_f32_16x16x32_bf16 v[14:17], v[146:149], v[206:209], v[14:17]
	s_waitcnt lgkmcnt(0)
	v_mfma_f32_16x16x32_bf16 v[22:25], v[134:137], v[202:205], 0
	v_mfma_f32_16x16x32_bf16 v[22:25], v[138:141], v[206:209], v[22:25]
	s_setprio 0
	s_setprio 1
	v_mfma_f32_16x16x32_bf16 v[50:53], v[150:153], v[178:181], 0
	v_mfma_f32_16x16x32_bf16 v[50:53], v[166:169], v[182:185], v[50:53]
	v_mfma_f32_16x16x32_bf16 v[42:45], v[170:173], v[178:181], 0
	v_mfma_f32_16x16x32_bf16 v[42:45], v[174:177], v[182:185], v[42:45]
	v_mfma_f32_16x16x32_bf16 v[26:29], v[170:173], v[186:189], 0
	v_mfma_f32_16x16x32_bf16 v[26:29], v[174:177], v[190:193], v[26:29]
	v_mfma_f32_16x16x32_bf16 v[34:37], v[150:153], v[186:189], 0
	v_mfma_f32_16x16x32_bf16 v[34:37], v[166:169], v[190:193], v[34:37]
	v_mfma_f32_16x16x32_bf16 v[18:21], v[150:153], v[194:197], 0
	v_mfma_f32_16x16x32_bf16 v[18:21], v[166:169], v[198:201], v[18:21]
	v_mfma_f32_16x16x32_bf16 v[10:13], v[170:173], v[194:197], 0
	v_mfma_f32_16x16x32_bf16 v[10:13], v[174:177], v[198:201], v[10:13]
	v_mfma_f32_16x16x32_bf16 v[2:5], v[170:173], v[202:205], 0
	v_mfma_f32_16x16x32_bf16 v[2:5], v[174:177], v[206:209], v[2:5]
	s_setprio 2
	s_barrier
	v_mfma_f32_16x16x32_bf16 v[6:9], v[150:153], v[202:205], 0
	v_mfma_f32_16x16x32_bf16 v[6:9], v[166:169], v[206:209], v[6:9]
	s_setprio 0
	ds_read_b128 v[134:137], v164
	ds_read_b128 v[138:141], v164 offset:1024
	ds_read_b128 v[142:145], v164 offset:2048
	ds_read_b128 v[146:149], v164 offset:3072
	ds_read_b128 v[150:153], v165
	ds_read_b128 v[166:169], v165 offset:1024
	ds_read_b128 v[170:173], v165 offset:2048
	ds_read_b128 v[174:177], v165 offset:3072
	ds_read_b128 v[178:181], v163 offset:32768
	ds_read_b128 v[182:185], v163 offset:33792
	ds_read_b128 v[186:189], v163 offset:34816
	ds_read_b128 v[190:193], v163 offset:35840
	ds_read_b128 v[194:197], v163 offset:36864
	ds_read_b128 v[198:201], v163 offset:37888
	ds_read_b128 v[202:205], v163 offset:38912
	ds_read_b128 v[206:209], v163 offset:39936
	s_mov_b32 s83, m0
	s_mov_b32 m0, s34
	s_nop 0
	global_load_lds_dwordx4 v1, s[24:25]
	s_mov_b32 m0, s83
	s_nop 0
	s_mov_b32 s83, m0
	s_mov_b32 m0, s42
	s_nop 0
	global_load_lds_dwordx4 v157, s[24:25]
	s_mov_b32 m0, s83
	s_add_u32 s24, s24, 0x4000
	s_addc_u32 s25, s25, 0
	s_mov_b32 s83, m0
	s_mov_b32 m0, s43
	s_nop 0
	global_load_lds_dwordx4 v1, s[24:25]
	s_mov_b32 m0, s83
	s_nop 0
	s_mov_b32 s83, m0
	s_mov_b32 m0, s46
	s_nop 0
	global_load_lds_dwordx4 v157, s[24:25]
	s_mov_b32 m0, s83
	s_waitcnt vmcnt(8)
	s_waitcnt lgkmcnt(0)
	s_waitcnt lgkmcnt(7)
	v_mfma_f32_16x16x32_bf16 v[126:129], v[134:137], v[178:181], v[126:129]
	v_mfma_f32_16x16x32_bf16 v[126:129], v[138:141], v[182:185], v[126:129]
	s_waitcnt lgkmcnt(5)
	v_mfma_f32_16x16x32_bf16 v[122:125], v[142:145], v[178:181], v[122:125]
	v_mfma_f32_16x16x32_bf16 v[122:125], v[146:149], v[182:185], v[122:125]
	s_barrier
	s_setprio 1
	s_waitcnt lgkmcnt(3)
	v_mfma_f32_16x16x32_bf16 v[114:117], v[142:145], v[186:189], v[114:117]
	v_mfma_f32_16x16x32_bf16 v[114:117], v[146:149], v[190:193], v[114:117]
	s_waitcnt lgkmcnt(1)
	v_mfma_f32_16x16x32_bf16 v[118:121], v[134:137], v[186:189], v[118:121]
	v_mfma_f32_16x16x32_bf16 v[118:121], v[138:141], v[190:193], v[118:121]
	v_mfma_f32_16x16x32_bf16 v[102:105], v[134:137], v[194:197], v[102:105]
	v_mfma_f32_16x16x32_bf16 v[102:105], v[138:141], v[198:201], v[102:105]
	v_mfma_f32_16x16x32_bf16 v[94:97], v[142:145], v[194:197], v[94:97]
	v_mfma_f32_16x16x32_bf16 v[94:97], v[146:149], v[198:201], v[94:97]
	v_mfma_f32_16x16x32_bf16 v[78:81], v[142:145], v[202:205], v[78:81]
	v_mfma_f32_16x16x32_bf16 v[78:81], v[146:149], v[206:209], v[78:81]
	s_waitcnt lgkmcnt(0)
	v_mfma_f32_16x16x32_bf16 v[86:89], v[134:137], v[202:205], v[86:89]
	v_mfma_f32_16x16x32_bf16 v[86:89], v[138:141], v[206:209], v[86:89]
	s_setprio 0
	s_setprio 1
	v_mfma_f32_16x16x32_bf16 v[110:113], v[150:153], v[178:181], v[110:113]
	v_mfma_f32_16x16x32_bf16 v[110:113], v[166:169], v[182:185], v[110:113]
	v_mfma_f32_16x16x32_bf16 v[106:109], v[170:173], v[178:181], v[106:109]
	v_mfma_f32_16x16x32_bf16 v[106:109], v[174:177], v[182:185], v[106:109]
	v_mfma_f32_16x16x32_bf16 v[90:93], v[170:173], v[186:189], v[90:93]
	v_mfma_f32_16x16x32_bf16 v[90:93], v[174:177], v[190:193], v[90:93]
	v_mfma_f32_16x16x32_bf16 v[98:101], v[150:153], v[186:189], v[98:101]
	v_mfma_f32_16x16x32_bf16 v[98:101], v[166:169], v[190:193], v[98:101]
	v_mfma_f32_16x16x32_bf16 v[82:85], v[150:153], v[194:197], v[82:85]
	v_mfma_f32_16x16x32_bf16 v[82:85], v[166:169], v[198:201], v[82:85]
	v_mfma_f32_16x16x32_bf16 v[74:77], v[170:173], v[194:197], v[74:77]
	v_mfma_f32_16x16x32_bf16 v[74:77], v[174:177], v[198:201], v[74:77]
	v_mfma_f32_16x16x32_bf16 v[66:69], v[170:173], v[202:205], v[66:69]
	v_mfma_f32_16x16x32_bf16 v[66:69], v[174:177], v[206:209], v[66:69]
	s_setprio 2
	s_barrier
	v_mfma_f32_16x16x32_bf16 v[70:73], v[150:153], v[202:205], v[70:73]
	v_mfma_f32_16x16x32_bf16 v[70:73], v[166:169], v[206:209], v[70:73]
	s_setprio 0
	ds_read_b128 v[178:181], v163 offset:49152
	ds_read_b128 v[182:185], v163 offset:50176
	ds_read_b128 v[186:189], v163 offset:51200
	ds_read_b128 v[190:193], v163 offset:52224
	ds_read_b128 v[194:197], v163 offset:53248
	ds_read_b128 v[198:201], v163 offset:54272
	ds_read_b128 v[202:205], v163 offset:55296
	ds_read_b128 v[206:209], v163 offset:56320
	s_add_u32 s24, s22, 0x40000
	s_addc_u32 s25, s23, 0
	s_mov_b32 s83, m0
	s_mov_b32 m0, s47
	s_nop 0
	global_load_lds_dwordx4 v156, s[24:25]
	s_mov_b32 m0, s83
	s_add_u32 s22, s22, 0x44000
	s_mov_b32 s83, m0
	s_mov_b32 m0, s48
	s_nop 0
	global_load_lds_dwordx4 v158, s[24:25]
	s_mov_b32 m0, s83
	s_addc_u32 s23, s23, 0
	s_mov_b32 s24, m0
	s_mov_b32 m0, s49
	s_nop 0
	global_load_lds_dwordx4 v156, s[22:23]
	s_mov_b32 m0, s24
	s_nop 0
	s_mov_b32 s24, m0
	s_mov_b32 m0, s56
	s_nop 0
	global_load_lds_dwordx4 v158, s[22:23]
	s_mov_b32 m0, s24
	s_waitcnt vmcnt(4)
	s_waitcnt lgkmcnt(0)
	s_waitcnt lgkmcnt(7)
	v_mfma_f32_16x16x32_bf16 v[62:65], v[134:137], v[178:181], v[62:65]
	v_mfma_f32_16x16x32_bf16 v[62:65], v[138:141], v[182:185], v[62:65]
	s_waitcnt lgkmcnt(5)
	v_mfma_f32_16x16x32_bf16 v[58:61], v[142:145], v[178:181], v[58:61]
	v_mfma_f32_16x16x32_bf16 v[58:61], v[146:149], v[182:185], v[58:61]
	s_barrier
	s_setprio 1
	s_waitcnt lgkmcnt(3)
	v_mfma_f32_16x16x32_bf16 v[46:49], v[142:145], v[186:189], v[46:49]
	v_mfma_f32_16x16x32_bf16 v[46:49], v[146:149], v[190:193], v[46:49]
	s_waitcnt lgkmcnt(1)
	v_mfma_f32_16x16x32_bf16 v[54:57], v[134:137], v[186:189], v[54:57]
	v_mfma_f32_16x16x32_bf16 v[54:57], v[138:141], v[190:193], v[54:57]
	v_mfma_f32_16x16x32_bf16 v[38:41], v[134:137], v[194:197], v[38:41]
	v_mfma_f32_16x16x32_bf16 v[38:41], v[138:141], v[198:201], v[38:41]
	v_mfma_f32_16x16x32_bf16 v[30:33], v[142:145], v[194:197], v[30:33]
	v_mfma_f32_16x16x32_bf16 v[30:33], v[146:149], v[198:201], v[30:33]
	v_mfma_f32_16x16x32_bf16 v[14:17], v[142:145], v[202:205], v[14:17]
	v_mfma_f32_16x16x32_bf16 v[14:17], v[146:149], v[206:209], v[14:17]
	s_waitcnt lgkmcnt(0)
	v_mfma_f32_16x16x32_bf16 v[22:25], v[134:137], v[202:205], v[22:25]
	v_mfma_f32_16x16x32_bf16 v[22:25], v[138:141], v[206:209], v[22:25]
	s_setprio 0
	s_setprio 1
	v_mfma_f32_16x16x32_bf16 v[50:53], v[150:153], v[178:181], v[50:53]
	v_mfma_f32_16x16x32_bf16 v[50:53], v[166:169], v[182:185], v[50:53]
	v_mfma_f32_16x16x32_bf16 v[42:45], v[170:173], v[178:181], v[42:45]
	v_mfma_f32_16x16x32_bf16 v[42:45], v[174:177], v[182:185], v[42:45]
	v_mfma_f32_16x16x32_bf16 v[26:29], v[170:173], v[186:189], v[26:29]
	v_mfma_f32_16x16x32_bf16 v[26:29], v[174:177], v[190:193], v[26:29]
	v_mfma_f32_16x16x32_bf16 v[34:37], v[150:153], v[186:189], v[34:37]
	v_mfma_f32_16x16x32_bf16 v[34:37], v[166:169], v[190:193], v[34:37]
	v_mfma_f32_16x16x32_bf16 v[18:21], v[150:153], v[194:197], v[18:21]
	v_mfma_f32_16x16x32_bf16 v[18:21], v[166:169], v[198:201], v[18:21]
	v_mfma_f32_16x16x32_bf16 v[10:13], v[170:173], v[194:197], v[10:13]
	v_mfma_f32_16x16x32_bf16 v[10:13], v[174:177], v[198:201], v[10:13]
	v_mfma_f32_16x16x32_bf16 v[2:5], v[170:173], v[202:205], v[2:5]
	v_mfma_f32_16x16x32_bf16 v[2:5], v[174:177], v[206:209], v[2:5]
	s_setprio 2
	s_barrier
	v_mfma_f32_16x16x32_bf16 v[6:9], v[150:153], v[202:205], v[6:9]
	v_mfma_f32_16x16x32_bf16 v[6:9], v[166:169], v[206:209], v[6:9]
	s_setprio 0
	s_add_i32 s82, s82, 2
	s_add_u32 s78, s78, 0x80000
	s_addc_u32 s79, s79, 0
	s_add_u32 s20, s20, 0x400000
	s_addc_u32 s21, s21, 0
	s_add_u32 s80, s80, 0x400000
	s_addc_u32 s81, s81, 0
	s_cmpk_gt_u32 s82, 0x53
	.p2align 6
.LBB0_473:
	ds_read_b128 v[134:137], v161
	ds_read_b128 v[138:141], v161 offset:1024
	ds_read_b128 v[142:145], v161 offset:2048
	ds_read_b128 v[146:149], v161 offset:3072
	ds_read_b128 v[150:153], v162
	ds_read_b128 v[166:169], v162 offset:1024
	ds_read_b128 v[170:173], v162 offset:2048
	ds_read_b128 v[174:177], v162 offset:3072
	s_cmpk_eq_i32 s82, 0x52
	s_cselect_b32 s23, s11, s79
	s_cselect_b32 s22, s77, s78
	s_cselect_b32 s25, s13, s81
	s_cselect_b32 s24, s76, s80
	ds_read_b128 v[178:181], v163
	ds_read_b128 v[182:185], v163 offset:1024
	ds_read_b128 v[186:189], v163 offset:2048
	ds_read_b128 v[190:193], v163 offset:3072
	ds_read_b128 v[194:197], v163 offset:4096
	ds_read_b128 v[198:201], v163 offset:5120
	ds_read_b128 v[202:205], v163 offset:6144
	ds_read_b128 v[206:209], v163 offset:7168
	s_add_u32 s86, s20, 0xffffc000
	s_addc_u32 s87, s21, -1
	s_mov_b32 s83, m0
	s_mov_b32 m0, s65
	s_nop 0
	global_load_lds_dwordx4 v1, s[86:87]
	s_mov_b32 m0, s83
	s_nop 0
	s_mov_b32 s83, m0
	s_mov_b32 m0, s67
	s_nop 0
	global_load_lds_dwordx4 v157, s[86:87]
	s_mov_b32 m0, s83
	s_nop 0
	s_mov_b32 s83, m0
	s_mov_b32 m0, s66
	s_nop 0
	global_load_lds_dwordx4 v1, s[20:21]
	s_mov_b32 m0, s83
	s_nop 0
	s_mov_b32 s83, m0
	s_mov_b32 m0, s73
	s_nop 0
	global_load_lds_dwordx4 v157, s[20:21]
	s_mov_b32 m0, s83
	s_waitcnt vmcnt(8)
	s_waitcnt lgkmcnt(0)
	s_waitcnt lgkmcnt(7)
	v_mfma_f32_16x16x32_bf16 v[126:129], v[134:137], v[178:181], v[126:129]
	v_mfma_f32_16x16x32_bf16 v[126:129], v[138:141], v[182:185], v[126:129]
	s_waitcnt lgkmcnt(5)
	v_mfma_f32_16x16x32_bf16 v[122:125], v[142:145], v[178:181], v[122:125]
	v_mfma_f32_16x16x32_bf16 v[122:125], v[146:149], v[182:185], v[122:125]
	s_barrier
	s_setprio 1
	s_waitcnt lgkmcnt(3)
	v_mfma_f32_16x16x32_bf16 v[114:117], v[142:145], v[186:189], v[114:117]
	v_mfma_f32_16x16x32_bf16 v[114:117], v[146:149], v[190:193], v[114:117]
	s_waitcnt lgkmcnt(1)
	v_mfma_f32_16x16x32_bf16 v[118:121], v[134:137], v[186:189], v[118:121]
	v_mfma_f32_16x16x32_bf16 v[118:121], v[138:141], v[190:193], v[118:121]
	v_mfma_f32_16x16x32_bf16 v[102:105], v[134:137], v[194:197], v[102:105]
	v_mfma_f32_16x16x32_bf16 v[102:105], v[138:141], v[198:201], v[102:105]
	v_mfma_f32_16x16x32_bf16 v[94:97], v[142:145], v[194:197], v[94:97]
	v_mfma_f32_16x16x32_bf16 v[94:97], v[146:149], v[198:201], v[94:97]
	v_mfma_f32_16x16x32_bf16 v[78:81], v[142:145], v[202:205], v[78:81]
	v_mfma_f32_16x16x32_bf16 v[78:81], v[146:149], v[206:209], v[78:81]
	s_waitcnt lgkmcnt(0)
	v_mfma_f32_16x16x32_bf16 v[86:89], v[134:137], v[202:205], v[86:89]
	v_mfma_f32_16x16x32_bf16 v[86:89], v[138:141], v[206:209], v[86:89]
	s_setprio 0
	s_setprio 1
	v_mfma_f32_16x16x32_bf16 v[110:113], v[150:153], v[178:181], v[110:113]
	v_mfma_f32_16x16x32_bf16 v[110:113], v[166:169], v[182:185], v[110:113]
	v_mfma_f32_16x16x32_bf16 v[106:109], v[170:173], v[178:181], v[106:109]
	v_mfma_f32_16x16x32_bf16 v[106:109], v[174:177], v[182:185], v[106:109]
	v_mfma_f32_16x16x32_bf16 v[90:93], v[170:173], v[186:189], v[90:93]
	v_mfma_f32_16x16x32_bf16 v[90:93], v[174:177], v[190:193], v[90:93]
	v_mfma_f32_16x16x32_bf16 v[98:101], v[150:153], v[186:189], v[98:101]
	v_mfma_f32_16x16x32_bf16 v[98:101], v[166:169], v[190:193], v[98:101]
	v_mfma_f32_16x16x32_bf16 v[82:85], v[150:153], v[194:197], v[82:85]
	v_mfma_f32_16x16x32_bf16 v[82:85], v[166:169], v[198:201], v[82:85]
	v_mfma_f32_16x16x32_bf16 v[74:77], v[170:173], v[194:197], v[74:77]
	v_mfma_f32_16x16x32_bf16 v[74:77], v[174:177], v[198:201], v[74:77]
	v_mfma_f32_16x16x32_bf16 v[66:69], v[170:173], v[202:205], v[66:69]
	v_mfma_f32_16x16x32_bf16 v[66:69], v[174:177], v[206:209], v[66:69]
	s_setprio 2
	s_barrier
	v_mfma_f32_16x16x32_bf16 v[70:73], v[150:153], v[202:205], v[70:73]
	v_mfma_f32_16x16x32_bf16 v[70:73], v[166:169], v[206:209], v[70:73]
	s_setprio 0
	ds_read_b128 v[178:181], v163 offset:16384
	ds_read_b128 v[182:185], v163 offset:17408
	ds_read_b128 v[186:189], v163 offset:18432
	ds_read_b128 v[190:193], v163 offset:19456
	ds_read_b128 v[194:197], v163 offset:20480
	ds_read_b128 v[198:201], v163 offset:21504
	ds_read_b128 v[202:205], v163 offset:22528
	ds_read_b128 v[206:209], v163 offset:23552
	s_mov_b32 s83, m0
	s_mov_b32 m0, s19
	s_nop 0
	global_load_lds_dwordx4 v156, s[22:23]
	s_mov_b32 m0, s83
	s_add_u32 s86, s22, 0x4000
	s_mov_b32 s83, m0
	s_mov_b32 m0, s35
	s_nop 0
	global_load_lds_dwordx4 v158, s[22:23]
	s_mov_b32 m0, s83
	s_addc_u32 s87, s23, 0
	s_mov_b32 s83, m0
	s_mov_b32 m0, s36
	s_nop 0
	global_load_lds_dwordx4 v156, s[86:87]
	s_mov_b32 m0, s83
	s_nop 0
	s_mov_b32 s83, m0
	s_mov_b32 m0, s37
	s_nop 0
	global_load_lds_dwordx4 v158, s[86:87]
	s_mov_b32 m0, s83
	s_waitcnt vmcnt(4)
	s_waitcnt lgkmcnt(0)
	s_waitcnt lgkmcnt(7)
	v_mfma_f32_16x16x32_bf16 v[62:65], v[134:137], v[178:181], v[62:65]
	v_mfma_f32_16x16x32_bf16 v[62:65], v[138:141], v[182:185], v[62:65]
	s_waitcnt lgkmcnt(5)
	v_mfma_f32_16x16x32_bf16 v[58:61], v[142:145], v[178:181], v[58:61]
	v_mfma_f32_16x16x32_bf16 v[58:61], v[146:149], v[182:185], v[58:61]
	s_barrier
	s_setprio 1
	s_waitcnt lgkmcnt(3)
	v_mfma_f32_16x16x32_bf16 v[46:49], v[142:145], v[186:189], v[46:49]
	v_mfma_f32_16x16x32_bf16 v[46:49], v[146:149], v[190:193], v[46:49]
	s_waitcnt lgkmcnt(1)
	v_mfma_f32_16x16x32_bf16 v[54:57], v[134:137], v[186:189], v[54:57]
	v_mfma_f32_16x16x32_bf16 v[54:57], v[138:141], v[190:193], v[54:57]
	v_mfma_f32_16x16x32_bf16 v[38:41], v[134:137], v[194:197], v[38:41]
	v_mfma_f32_16x16x32_bf16 v[38:41], v[138:141], v[198:201], v[38:41]
	v_mfma_f32_16x16x32_bf16 v[30:33], v[142:145], v[194:197], v[30:33]
	v_mfma_f32_16x16x32_bf16 v[30:33], v[146:149], v[198:201], v[30:33]
	v_mfma_f32_16x16x32_bf16 v[14:17], v[142:145], v[202:205], v[14:17]
	v_mfma_f32_16x16x32_bf16 v[14:17], v[146:149], v[206:209], v[14:17]
	s_waitcnt lgkmcnt(0)
	v_mfma_f32_16x16x32_bf16 v[22:25], v[134:137], v[202:205], v[22:25]
	v_mfma_f32_16x16x32_bf16 v[22:25], v[138:141], v[206:209], v[22:25]
	s_setprio 0
	s_setprio 1
	v_mfma_f32_16x16x32_bf16 v[50:53], v[150:153], v[178:181], v[50:53]
	v_mfma_f32_16x16x32_bf16 v[50:53], v[166:169], v[182:185], v[50:53]
	v_mfma_f32_16x16x32_bf16 v[42:45], v[170:173], v[178:181], v[42:45]
	v_mfma_f32_16x16x32_bf16 v[42:45], v[174:177], v[182:185], v[42:45]
	v_mfma_f32_16x16x32_bf16 v[26:29], v[170:173], v[186:189], v[26:29]
	v_mfma_f32_16x16x32_bf16 v[26:29], v[174:177], v[190:193], v[26:29]
	v_mfma_f32_16x16x32_bf16 v[34:37], v[150:153], v[186:189], v[34:37]
	v_mfma_f32_16x16x32_bf16 v[34:37], v[166:169], v[190:193], v[34:37]
	v_mfma_f32_16x16x32_bf16 v[18:21], v[150:153], v[194:197], v[18:21]
	v_mfma_f32_16x16x32_bf16 v[18:21], v[166:169], v[198:201], v[18:21]
	v_mfma_f32_16x16x32_bf16 v[10:13], v[170:173], v[194:197], v[10:13]
	v_mfma_f32_16x16x32_bf16 v[10:13], v[174:177], v[198:201], v[10:13]
	v_mfma_f32_16x16x32_bf16 v[2:5], v[170:173], v[202:205], v[2:5]
	v_mfma_f32_16x16x32_bf16 v[2:5], v[174:177], v[206:209], v[2:5]
	s_setprio 2
	s_barrier
	v_mfma_f32_16x16x32_bf16 v[6:9], v[150:153], v[202:205], v[6:9]
	v_mfma_f32_16x16x32_bf16 v[6:9], v[166:169], v[206:209], v[6:9]
	s_setprio 0
	ds_read_b128 v[134:137], v164
	ds_read_b128 v[138:141], v164 offset:1024
	ds_read_b128 v[142:145], v164 offset:2048
	ds_read_b128 v[146:149], v164 offset:3072
	ds_read_b128 v[150:153], v165
	ds_read_b128 v[166:169], v165 offset:1024
	ds_read_b128 v[170:173], v165 offset:2048
	ds_read_b128 v[174:177], v165 offset:3072
	ds_read_b128 v[178:181], v163 offset:32768
	ds_read_b128 v[182:185], v163 offset:33792
	ds_read_b128 v[186:189], v163 offset:34816
	ds_read_b128 v[190:193], v163 offset:35840
	ds_read_b128 v[194:197], v163 offset:36864
	ds_read_b128 v[198:201], v163 offset:37888
	ds_read_b128 v[202:205], v163 offset:38912
	ds_read_b128 v[206:209], v163 offset:39936
	s_mov_b32 s83, m0
	s_mov_b32 m0, s34
	s_nop 0
	global_load_lds_dwordx4 v1, s[24:25]
	s_mov_b32 m0, s83
	s_nop 0
	s_mov_b32 s83, m0
	s_mov_b32 m0, s42
	s_nop 0
	global_load_lds_dwordx4 v157, s[24:25]
	s_mov_b32 m0, s83
	s_add_u32 s24, s24, 0x4000
	s_addc_u32 s25, s25, 0
	s_mov_b32 s83, m0
	s_mov_b32 m0, s43
	s_nop 0
	global_load_lds_dwordx4 v1, s[24:25]
	s_mov_b32 m0, s83
	s_nop 0
	s_mov_b32 s83, m0
	s_mov_b32 m0, s46
	s_nop 0
	global_load_lds_dwordx4 v157, s[24:25]
	s_mov_b32 m0, s83
	s_waitcnt vmcnt(8)
	s_waitcnt lgkmcnt(0)
	s_waitcnt lgkmcnt(7)
	v_mfma_f32_16x16x32_bf16 v[126:129], v[134:137], v[178:181], v[126:129]
	v_mfma_f32_16x16x32_bf16 v[126:129], v[138:141], v[182:185], v[126:129]
	s_waitcnt lgkmcnt(5)
	v_mfma_f32_16x16x32_bf16 v[122:125], v[142:145], v[178:181], v[122:125]
	v_mfma_f32_16x16x32_bf16 v[122:125], v[146:149], v[182:185], v[122:125]
	s_barrier
	s_setprio 1
	s_waitcnt lgkmcnt(3)
	v_mfma_f32_16x16x32_bf16 v[114:117], v[142:145], v[186:189], v[114:117]
	v_mfma_f32_16x16x32_bf16 v[114:117], v[146:149], v[190:193], v[114:117]
	s_waitcnt lgkmcnt(1)
	v_mfma_f32_16x16x32_bf16 v[118:121], v[134:137], v[186:189], v[118:121]
	v_mfma_f32_16x16x32_bf16 v[118:121], v[138:141], v[190:193], v[118:121]
	v_mfma_f32_16x16x32_bf16 v[102:105], v[134:137], v[194:197], v[102:105]
	v_mfma_f32_16x16x32_bf16 v[102:105], v[138:141], v[198:201], v[102:105]
	v_mfma_f32_16x16x32_bf16 v[94:97], v[142:145], v[194:197], v[94:97]
	v_mfma_f32_16x16x32_bf16 v[94:97], v[146:149], v[198:201], v[94:97]
	v_mfma_f32_16x16x32_bf16 v[78:81], v[142:145], v[202:205], v[78:81]
	v_mfma_f32_16x16x32_bf16 v[78:81], v[146:149], v[206:209], v[78:81]
	s_waitcnt lgkmcnt(0)
	v_mfma_f32_16x16x32_bf16 v[86:89], v[134:137], v[202:205], v[86:89]
	v_mfma_f32_16x16x32_bf16 v[86:89], v[138:141], v[206:209], v[86:89]
	s_setprio 0
	s_setprio 1
	v_mfma_f32_16x16x32_bf16 v[110:113], v[150:153], v[178:181], v[110:113]
	v_mfma_f32_16x16x32_bf16 v[110:113], v[166:169], v[182:185], v[110:113]
	v_mfma_f32_16x16x32_bf16 v[106:109], v[170:173], v[178:181], v[106:109]
	v_mfma_f32_16x16x32_bf16 v[106:109], v[174:177], v[182:185], v[106:109]
	v_mfma_f32_16x16x32_bf16 v[90:93], v[170:173], v[186:189], v[90:93]
	v_mfma_f32_16x16x32_bf16 v[90:93], v[174:177], v[190:193], v[90:93]
	v_mfma_f32_16x16x32_bf16 v[98:101], v[150:153], v[186:189], v[98:101]
	v_mfma_f32_16x16x32_bf16 v[98:101], v[166:169], v[190:193], v[98:101]
	v_mfma_f32_16x16x32_bf16 v[82:85], v[150:153], v[194:197], v[82:85]
	v_mfma_f32_16x16x32_bf16 v[82:85], v[166:169], v[198:201], v[82:85]
	v_mfma_f32_16x16x32_bf16 v[74:77], v[170:173], v[194:197], v[74:77]
	v_mfma_f32_16x16x32_bf16 v[74:77], v[174:177], v[198:201], v[74:77]
	v_mfma_f32_16x16x32_bf16 v[66:69], v[170:173], v[202:205], v[66:69]
	v_mfma_f32_16x16x32_bf16 v[66:69], v[174:177], v[206:209], v[66:69]
	s_setprio 2
	s_barrier
	v_mfma_f32_16x16x32_bf16 v[70:73], v[150:153], v[202:205], v[70:73]
	v_mfma_f32_16x16x32_bf16 v[70:73], v[166:169], v[206:209], v[70:73]
	s_setprio 0
	ds_read_b128 v[178:181], v163 offset:49152
	ds_read_b128 v[182:185], v163 offset:50176
	ds_read_b128 v[186:189], v163 offset:51200
	ds_read_b128 v[190:193], v163 offset:52224
	ds_read_b128 v[194:197], v163 offset:53248
	ds_read_b128 v[198:201], v163 offset:54272
	ds_read_b128 v[202:205], v163 offset:55296
	ds_read_b128 v[206:209], v163 offset:56320
	s_add_u32 s24, s22, 0x40000
	s_addc_u32 s25, s23, 0
	s_mov_b32 s83, m0
	s_mov_b32 m0, s47
	s_nop 0
	global_load_lds_dwordx4 v156, s[24:25]
	s_mov_b32 m0, s83
	s_add_u32 s22, s22, 0x44000
	s_mov_b32 s83, m0
	s_mov_b32 m0, s48
	s_nop 0
	global_load_lds_dwordx4 v158, s[24:25]
	s_mov_b32 m0, s83
	s_addc_u32 s23, s23, 0
	s_mov_b32 s24, m0
	s_mov_b32 m0, s49
	s_nop 0
	global_load_lds_dwordx4 v156, s[22:23]
	s_mov_b32 m0, s24
	s_nop 0
	s_mov_b32 s24, m0
	s_mov_b32 m0, s56
	s_nop 0
	global_load_lds_dwordx4 v158, s[22:23]
	s_mov_b32 m0, s24
	s_waitcnt vmcnt(4)
	s_waitcnt lgkmcnt(0)
	s_waitcnt lgkmcnt(7)
	v_mfma_f32_16x16x32_bf16 v[62:65], v[134:137], v[178:181], v[62:65]
	v_mfma_f32_16x16x32_bf16 v[62:65], v[138:141], v[182:185], v[62:65]
	s_waitcnt lgkmcnt(5)
	v_mfma_f32_16x16x32_bf16 v[58:61], v[142:145], v[178:181], v[58:61]
	v_mfma_f32_16x16x32_bf16 v[58:61], v[146:149], v[182:185], v[58:61]
	s_barrier
	s_setprio 1
	s_waitcnt lgkmcnt(3)
	v_mfma_f32_16x16x32_bf16 v[46:49], v[142:145], v[186:189], v[46:49]
	v_mfma_f32_16x16x32_bf16 v[46:49], v[146:149], v[190:193], v[46:49]
	s_waitcnt lgkmcnt(1)
	v_mfma_f32_16x16x32_bf16 v[54:57], v[134:137], v[186:189], v[54:57]
	v_mfma_f32_16x16x32_bf16 v[54:57], v[138:141], v[190:193], v[54:57]
	v_mfma_f32_16x16x32_bf16 v[38:41], v[134:137], v[194:197], v[38:41]
	v_mfma_f32_16x16x32_bf16 v[38:41], v[138:141], v[198:201], v[38:41]
	v_mfma_f32_16x16x32_bf16 v[30:33], v[142:145], v[194:197], v[30:33]
	v_mfma_f32_16x16x32_bf16 v[30:33], v[146:149], v[198:201], v[30:33]
	v_mfma_f32_16x16x32_bf16 v[14:17], v[142:145], v[202:205], v[14:17]
	v_mfma_f32_16x16x32_bf16 v[14:17], v[146:149], v[206:209], v[14:17]
	s_waitcnt lgkmcnt(0)
	v_mfma_f32_16x16x32_bf16 v[22:25], v[134:137], v[202:205], v[22:25]
	v_mfma_f32_16x16x32_bf16 v[22:25], v[138:141], v[206:209], v[22:25]
	s_setprio 0
	s_setprio 1
	v_mfma_f32_16x16x32_bf16 v[50:53], v[150:153], v[178:181], v[50:53]
	v_mfma_f32_16x16x32_bf16 v[50:53], v[166:169], v[182:185], v[50:53]
	v_mfma_f32_16x16x32_bf16 v[42:45], v[170:173], v[178:181], v[42:45]
	v_mfma_f32_16x16x32_bf16 v[42:45], v[174:177], v[182:185], v[42:45]
	v_mfma_f32_16x16x32_bf16 v[26:29], v[170:173], v[186:189], v[26:29]
	v_mfma_f32_16x16x32_bf16 v[26:29], v[174:177], v[190:193], v[26:29]
	v_mfma_f32_16x16x32_bf16 v[34:37], v[150:153], v[186:189], v[34:37]
	v_mfma_f32_16x16x32_bf16 v[34:37], v[166:169], v[190:193], v[34:37]
	v_mfma_f32_16x16x32_bf16 v[18:21], v[150:153], v[194:197], v[18:21]
	v_mfma_f32_16x16x32_bf16 v[18:21], v[166:169], v[198:201], v[18:21]
	v_mfma_f32_16x16x32_bf16 v[10:13], v[170:173], v[194:197], v[10:13]
	v_mfma_f32_16x16x32_bf16 v[10:13], v[174:177], v[198:201], v[10:13]
	v_mfma_f32_16x16x32_bf16 v[2:5], v[170:173], v[202:205], v[2:5]
	v_mfma_f32_16x16x32_bf16 v[2:5], v[174:177], v[206:209], v[2:5]
	s_setprio 2
	s_barrier
	v_mfma_f32_16x16x32_bf16 v[6:9], v[150:153], v[202:205], v[6:9]
	v_mfma_f32_16x16x32_bf16 v[6:9], v[166:169], v[206:209], v[6:9]
	s_setprio 0
	s_add_i32 s82, s82, 2
	s_add_u32 s78, s78, 0x80000
	s_addc_u32 s79, s79, 0
	s_add_u32 s20, s20, 0x400000
	s_addc_u32 s21, s21, 0
	s_add_u32 s80, s80, 0x400000
	s_addc_u32 s81, s81, 0
	s_cmpk_gt_u32 s82, 0x53
	s_cbranch_scc0 .LBB0_473
	s_and_b64 vcc, exec, s[8:9]
	s_cbranch_vccz .LBB0_476
	s_barrier

.LBB0_653:
	s_ashr_i32 s23, s22, 31
	s_lshl_b64 s[24:25], s[22:23], 20
	s_add_u32 s24, s35, s24
	s_addc_u32 s25, s36, s25
	s_and_b64 s[26:27], s[2:3], exec
	s_cselect_b32 s7, s25, s11
	s_cselect_b32 s9, s24, s10
	s_ashr_i32 s21, s20, 31
	s_lshl_b64 s[26:27], s[20:21], 20
	s_add_u32 s26, s37, s26
	s_addc_u32 s27, s40, s27
	s_and_b64 s[28:29], s[2:3], exec
	s_cselect_b32 s21, s27, s5
	s_cselect_b32 s23, s26, s4
	s_add_u32 s30, s4, 0x100
	s_addc_u32 s31, s5, 0
	s_add_u32 s4, s10, 0x80080
	s_addc_u32 s5, s11, 0
	s_add_u32 s33, s10, 0x100
	s_addc_u32 s73, s11, 0
	s_mov_b32 s74, -2
	s_waitcnt vmcnt(25)
	s_waitcnt vmcnt(24)
	s_waitcnt vmcnt(15)
	s_waitcnt vmcnt(14)
	s_waitcnt vmcnt(13)
	s_waitcnt vmcnt(12)
	s_waitcnt vmcnt(11)
	s_waitcnt vmcnt(10)
	s_waitcnt vmcnt(9)
	s_waitcnt vmcnt(8)
	s_waitcnt vmcnt(7)
	s_waitcnt vmcnt(6)
	s_waitcnt vmcnt(5)
	s_waitcnt vmcnt(4)
	s_waitcnt vmcnt(3)
	s_waitcnt vmcnt(2)
	s_waitcnt vmcnt(1)
	s_waitcnt vmcnt(0)
	ds_read_b128 v[130:133], v161
	ds_read_b128 v[138:141], v161 offset:1024
	ds_read_b128 v[142:145], v161 offset:2048
	ds_read_b128 v[146:149], v161 offset:3072
	ds_read_b128 v[150:153], v162
	ds_read_b128 v[168:171], v162 offset:1024
	ds_read_b128 v[172:175], v162 offset:2048
	ds_read_b128 v[176:179], v162 offset:3072
	s_cmp_eq_u32 s74, 28
	s_cselect_b32 s11, s21, s31
	s_cselect_b32 s10, s23, s30
	s_cselect_b32 s29, s7, s73
	s_cselect_b32 s28, s9, s33
	ds_read_b128 v[180:183], v163
	ds_read_b128 v[184:187], v163 offset:1024
	ds_read_b128 v[188:191], v163 offset:2048
	ds_read_b128 v[192:195], v163 offset:3072
	ds_read_b128 v[196:199], v163 offset:4096
	ds_read_b128 v[200:203], v163 offset:5120
	ds_read_b128 v[204:207], v163 offset:6144
	ds_read_b128 v[208:211], v163 offset:7168
	s_add_u32 s76, s4, 0xfff80000
	s_addc_u32 s77, s5, -1
	s_mov_b32 s75, m0
	s_mov_b32 m0, s80
	s_nop 0
	global_load_lds_dwordx4 v1, s[76:77]
	s_mov_b32 m0, s75
	s_nop 0
	s_mov_b32 s75, m0
	s_mov_b32 m0, s82
	s_nop 0
	global_load_lds_dwordx4 v157, s[76:77]
	s_mov_b32 m0, s75
	s_nop 0
	s_mov_b32 s75, m0
	s_mov_b32 m0, s81
	s_nop 0
	global_load_lds_dwordx4 v1, s[4:5]
	s_mov_b32 m0, s75
	s_nop 0
	s_mov_b32 s75, m0
	s_mov_b32 m0, s83
	s_nop 0
	global_load_lds_dwordx4 v157, s[4:5]
	s_mov_b32 m0, s75
	s_waitcnt vmcnt(8)
	s_waitcnt lgkmcnt(0)
	s_waitcnt lgkmcnt(7)
	v_mfma_f32_16x16x32_bf16 v[126:129], v[130:133], v[180:183], 0
	v_mfma_f32_16x16x32_bf16 v[126:129], v[138:141], v[184:187], v[126:129]
	s_waitcnt lgkmcnt(5)
	v_mfma_f32_16x16x32_bf16 v[122:125], v[142:145], v[180:183], 0
	v_mfma_f32_16x16x32_bf16 v[122:125], v[146:149], v[184:187], v[122:125]
	s_barrier
	s_setprio 1
	s_waitcnt lgkmcnt(3)
	v_mfma_f32_16x16x32_bf16 v[106:109], v[142:145], v[188:191], 0
	v_mfma_f32_16x16x32_bf16 v[106:109], v[146:149], v[192:195], v[106:109]
	s_waitcnt lgkmcnt(1)
	v_mfma_f32_16x16x32_bf16 v[110:113], v[130:133], v[188:191], 0
	v_mfma_f32_16x16x32_bf16 v[110:113], v[138:141], v[192:195], v[110:113]
	v_mfma_f32_16x16x32_bf16 v[94:97], v[130:133], v[196:199], 0
	v_mfma_f32_16x16x32_bf16 v[94:97], v[138:141], v[200:203], v[94:97]
	v_mfma_f32_16x16x32_bf16 v[90:93], v[142:145], v[196:199], 0
	v_mfma_f32_16x16x32_bf16 v[90:93], v[146:149], v[200:203], v[90:93]
	v_mfma_f32_16x16x32_bf16 v[74:77], v[142:145], v[204:207], 0
	v_mfma_f32_16x16x32_bf16 v[74:77], v[146:149], v[208:211], v[74:77]
	s_waitcnt lgkmcnt(0)
	v_mfma_f32_16x16x32_bf16 v[78:81], v[130:133], v[204:207], 0
	v_mfma_f32_16x16x32_bf16 v[78:81], v[138:141], v[208:211], v[78:81]
	s_setprio 0
	s_setprio 1
	v_mfma_f32_16x16x32_bf16 v[118:121], v[150:153], v[180:183], 0
	v_mfma_f32_16x16x32_bf16 v[118:121], v[168:171], v[184:187], v[118:121]
	v_mfma_f32_16x16x32_bf16 v[114:117], v[172:175], v[180:183], 0
	v_mfma_f32_16x16x32_bf16 v[114:117], v[176:179], v[184:187], v[114:117]
	v_mfma_f32_16x16x32_bf16 v[98:101], v[172:175], v[188:191], 0
	v_mfma_f32_16x16x32_bf16 v[98:101], v[176:179], v[192:195], v[98:101]
	v_mfma_f32_16x16x32_bf16 v[102:105], v[150:153], v[188:191], 0
	v_mfma_f32_16x16x32_bf16 v[102:105], v[168:171], v[192:195], v[102:105]
	v_mfma_f32_16x16x32_bf16 v[86:89], v[150:153], v[196:199], 0
	v_mfma_f32_16x16x32_bf16 v[86:89], v[168:171], v[200:203], v[86:89]
	v_mfma_f32_16x16x32_bf16 v[82:85], v[172:175], v[196:199], 0
	v_mfma_f32_16x16x32_bf16 v[82:85], v[176:179], v[200:203], v[82:85]
	v_mfma_f32_16x16x32_bf16 v[66:69], v[172:175], v[204:207], 0
	v_mfma_f32_16x16x32_bf16 v[66:69], v[176:179], v[208:211], v[66:69]
	s_setprio 2
	s_barrier
	v_mfma_f32_16x16x32_bf16 v[70:73], v[150:153], v[204:207], 0
	v_mfma_f32_16x16x32_bf16 v[70:73], v[168:171], v[208:211], v[70:73]
	s_setprio 0
	ds_read_b128 v[180:183], v163 offset:16384
	ds_read_b128 v[184:187], v163 offset:17408
	ds_read_b128 v[188:191], v163 offset:18432
	ds_read_b128 v[192:195], v163 offset:19456
	ds_read_b128 v[196:199], v163 offset:20480
	ds_read_b128 v[200:203], v163 offset:21504
	ds_read_b128 v[204:207], v163 offset:22528
	ds_read_b128 v[208:211], v163 offset:23552
	s_mov_b32 s75, m0
	s_mov_b32 m0, s43
	s_nop 0
	global_load_lds_dwordx4 v156, s[10:11]
	s_mov_b32 m0, s75
	s_add_u32 s76, s10, 0x80000
	s_mov_b32 s75, m0
	s_mov_b32 m0, s46
	s_nop 0
	global_load_lds_dwordx4 v158, s[10:11]
	s_mov_b32 m0, s75
	s_addc_u32 s77, s11, 0
	s_mov_b32 s75, m0
	s_mov_b32 m0, s47
	s_nop 0
	global_load_lds_dwordx4 v156, s[76:77]
	s_mov_b32 m0, s75
	s_nop 0
	s_mov_b32 s75, m0
	s_mov_b32 m0, s48
	s_nop 0
	global_load_lds_dwordx4 v158, s[76:77]
	s_mov_b32 m0, s75
	s_waitcnt vmcnt(4)
	s_waitcnt lgkmcnt(0)
	s_waitcnt lgkmcnt(7)
	v_mfma_f32_16x16x32_bf16 v[62:65], v[130:133], v[180:183], 0
	v_mfma_f32_16x16x32_bf16 v[62:65], v[138:141], v[184:187], v[62:65]
	s_waitcnt lgkmcnt(5)
	v_mfma_f32_16x16x32_bf16 v[58:61], v[142:145], v[180:183], 0
	v_mfma_f32_16x16x32_bf16 v[58:61], v[146:149], v[184:187], v[58:61]
	s_barrier
	s_setprio 1
	s_waitcnt lgkmcnt(3)
	v_mfma_f32_16x16x32_bf16 v[42:45], v[142:145], v[188:191], 0
	v_mfma_f32_16x16x32_bf16 v[42:45], v[146:149], v[192:195], v[42:45]
	s_waitcnt lgkmcnt(1)
	v_mfma_f32_16x16x32_bf16 v[46:49], v[130:133], v[188:191], 0
	v_mfma_f32_16x16x32_bf16 v[46:49], v[138:141], v[192:195], v[46:49]
	v_mfma_f32_16x16x32_bf16 v[30:33], v[130:133], v[196:199], 0
	v_mfma_f32_16x16x32_bf16 v[30:33], v[138:141], v[200:203], v[30:33]
	v_mfma_f32_16x16x32_bf16 v[26:29], v[142:145], v[196:199], 0
	v_mfma_f32_16x16x32_bf16 v[26:29], v[146:149], v[200:203], v[26:29]
	v_mfma_f32_16x16x32_bf16 v[10:13], v[142:145], v[204:207], 0
	v_mfma_f32_16x16x32_bf16 v[10:13], v[146:149], v[208:211], v[10:13]
	s_waitcnt lgkmcnt(0)
	v_mfma_f32_16x16x32_bf16 v[14:17], v[130:133], v[204:207], 0
	v_mfma_f32_16x16x32_bf16 v[14:17], v[138:141], v[208:211], v[14:17]
	s_setprio 0
	s_setprio 1
	v_mfma_f32_16x16x32_bf16 v[54:57], v[150:153], v[180:183], 0
	v_mfma_f32_16x16x32_bf16 v[54:57], v[168:171], v[184:187], v[54:57]
	v_mfma_f32_16x16x32_bf16 v[50:53], v[172:175], v[180:183], 0
	v_mfma_f32_16x16x32_bf16 v[50:53], v[176:179], v[184:187], v[50:53]
	v_mfma_f32_16x16x32_bf16 v[34:37], v[172:175], v[188:191], 0
	v_mfma_f32_16x16x32_bf16 v[34:37], v[176:179], v[192:195], v[34:37]
	v_mfma_f32_16x16x32_bf16 v[38:41], v[150:153], v[188:191], 0
	v_mfma_f32_16x16x32_bf16 v[38:41], v[168:171], v[192:195], v[38:41]
	v_mfma_f32_16x16x32_bf16 v[22:25], v[150:153], v[196:199], 0
	v_mfma_f32_16x16x32_bf16 v[22:25], v[168:171], v[200:203], v[22:25]
	v_mfma_f32_16x16x32_bf16 v[18:21], v[172:175], v[196:199], 0
	v_mfma_f32_16x16x32_bf16 v[18:21], v[176:179], v[200:203], v[18:21]
	v_mfma_f32_16x16x32_bf16 v[2:5], v[172:175], v[204:207], 0
	v_mfma_f32_16x16x32_bf16 v[2:5], v[176:179], v[208:211], v[2:5]
	s_setprio 2
	s_barrier
	v_mfma_f32_16x16x32_bf16 v[6:9], v[150:153], v[204:207], 0
	v_mfma_f32_16x16x32_bf16 v[6:9], v[168:171], v[208:211], v[6:9]
	s_setprio 0
	ds_read_b128 v[130:133], v164
	ds_read_b128 v[138:141], v164 offset:1024
	ds_read_b128 v[142:145], v164 offset:2048
	ds_read_b128 v[146:149], v164 offset:3072
	ds_read_b128 v[150:153], v165
	ds_read_b128 v[168:171], v165 offset:1024
	ds_read_b128 v[172:175], v165 offset:2048
	ds_read_b128 v[176:179], v165 offset:3072
	ds_read_b128 v[180:183], v163 offset:32768
	ds_read_b128 v[184:187], v163 offset:33792
	ds_read_b128 v[188:191], v163 offset:34816
	ds_read_b128 v[192:195], v163 offset:35840
	ds_read_b128 v[196:199], v163 offset:36864
	ds_read_b128 v[200:203], v163 offset:37888
	ds_read_b128 v[204:207], v163 offset:38912
	ds_read_b128 v[208:211], v163 offset:39936
	s_mov_b32 s75, m0
	s_mov_b32 m0, s42
	s_nop 0
	global_load_lds_dwordx4 v1, s[28:29]
	s_mov_b32 m0, s75
	s_nop 0
	s_mov_b32 s75, m0
	s_mov_b32 m0, s49
	s_nop 0
	global_load_lds_dwordx4 v157, s[28:29]
	s_mov_b32 m0, s75
	s_add_u32 s28, s28, 0x80000
	s_addc_u32 s29, s29, 0
	s_mov_b32 s75, m0
	s_mov_b32 m0, s56
	s_nop 0
	global_load_lds_dwordx4 v1, s[28:29]
	s_mov_b32 m0, s75
	s_nop 0
	s_mov_b32 s75, m0
	s_mov_b32 m0, s57
	s_nop 0
	global_load_lds_dwordx4 v157, s[28:29]
	s_mov_b32 m0, s75
	s_waitcnt vmcnt(8)
	s_waitcnt lgkmcnt(0)
	s_waitcnt lgkmcnt(7)
	v_mfma_f32_16x16x32_bf16 v[126:129], v[130:133], v[180:183], v[126:129]
	v_mfma_f32_16x16x32_bf16 v[126:129], v[138:141], v[184:187], v[126:129]
	s_waitcnt lgkmcnt(5)
	v_mfma_f32_16x16x32_bf16 v[122:125], v[142:145], v[180:183], v[122:125]
	v_mfma_f32_16x16x32_bf16 v[122:125], v[146:149], v[184:187], v[122:125]
	s_barrier
	s_setprio 1
	s_waitcnt lgkmcnt(3)
	v_mfma_f32_16x16x32_bf16 v[106:109], v[142:145], v[188:191], v[106:109]
	v_mfma_f32_16x16x32_bf16 v[106:109], v[146:149], v[192:195], v[106:109]
	s_waitcnt lgkmcnt(1)
	v_mfma_f32_16x16x32_bf16 v[110:113], v[130:133], v[188:191], v[110:113]
	v_mfma_f32_16x16x32_bf16 v[110:113], v[138:141], v[192:195], v[110:113]
	v_mfma_f32_16x16x32_bf16 v[94:97], v[130:133], v[196:199], v[94:97]
	v_mfma_f32_16x16x32_bf16 v[94:97], v[138:141], v[200:203], v[94:97]
	v_mfma_f32_16x16x32_bf16 v[90:93], v[142:145], v[196:199], v[90:93]
	v_mfma_f32_16x16x32_bf16 v[90:93], v[146:149], v[200:203], v[90:93]
	v_mfma_f32_16x16x32_bf16 v[74:77], v[142:145], v[204:207], v[74:77]
	v_mfma_f32_16x16x32_bf16 v[74:77], v[146:149], v[208:211], v[74:77]
	s_waitcnt lgkmcnt(0)
	v_mfma_f32_16x16x32_bf16 v[78:81], v[130:133], v[204:207], v[78:81]
	v_mfma_f32_16x16x32_bf16 v[78:81], v[138:141], v[208:211], v[78:81]
	s_setprio 0
	s_setprio 1
	v_mfma_f32_16x16x32_bf16 v[118:121], v[150:153], v[180:183], v[118:121]
	v_mfma_f32_16x16x32_bf16 v[118:121], v[168:171], v[184:187], v[118:121]
	v_mfma_f32_16x16x32_bf16 v[114:117], v[172:175], v[180:183], v[114:117]
	v_mfma_f32_16x16x32_bf16 v[114:117], v[176:179], v[184:187], v[114:117]
	v_mfma_f32_16x16x32_bf16 v[98:101], v[172:175], v[188:191], v[98:101]
	v_mfma_f32_16x16x32_bf16 v[98:101], v[176:179], v[192:195], v[98:101]
	v_mfma_f32_16x16x32_bf16 v[102:105], v[150:153], v[188:191], v[102:105]
	v_mfma_f32_16x16x32_bf16 v[102:105], v[168:171], v[192:195], v[102:105]
	v_mfma_f32_16x16x32_bf16 v[86:89], v[150:153], v[196:199], v[86:89]
	v_mfma_f32_16x16x32_bf16 v[86:89], v[168:171], v[200:203], v[86:89]
	v_mfma_f32_16x16x32_bf16 v[82:85], v[172:175], v[196:199], v[82:85]
	v_mfma_f32_16x16x32_bf16 v[82:85], v[176:179], v[200:203], v[82:85]
	v_mfma_f32_16x16x32_bf16 v[66:69], v[172:175], v[204:207], v[66:69]
	v_mfma_f32_16x16x32_bf16 v[66:69], v[176:179], v[208:211], v[66:69]
	s_setprio 2
	s_barrier
	v_mfma_f32_16x16x32_bf16 v[70:73], v[150:153], v[204:207], v[70:73]
	v_mfma_f32_16x16x32_bf16 v[70:73], v[168:171], v[208:211], v[70:73]
	s_setprio 0
	ds_read_b128 v[180:183], v163 offset:49152
	ds_read_b128 v[184:187], v163 offset:50176
	ds_read_b128 v[188:191], v163 offset:51200
	ds_read_b128 v[192:195], v163 offset:52224
	ds_read_b128 v[196:199], v163 offset:53248
	ds_read_b128 v[200:203], v163 offset:54272
	ds_read_b128 v[204:207], v163 offset:55296
	ds_read_b128 v[208:211], v163 offset:56320
	s_add_u32 s28, s10, 0x80
	s_addc_u32 s29, s11, 0
	s_mov_b32 s75, m0
	s_mov_b32 m0, s64
	s_nop 0
	global_load_lds_dwordx4 v156, s[28:29]
	s_mov_b32 m0, s75
	s_add_u32 s10, s10, 0x80080
	s_mov_b32 s75, m0
	s_mov_b32 m0, s65
	s_nop 0
	global_load_lds_dwordx4 v158, s[28:29]
	s_mov_b32 m0, s75
	s_addc_u32 s11, s11, 0
	s_mov_b32 s28, m0
	s_mov_b32 m0, s66
	s_nop 0
	global_load_lds_dwordx4 v156, s[10:11]
	s_mov_b32 m0, s28
	s_nop 0
	s_mov_b32 s28, m0
	s_mov_b32 m0, s67
	s_nop 0
	global_load_lds_dwordx4 v158, s[10:11]
	s_mov_b32 m0, s28
	s_waitcnt vmcnt(4)
	s_waitcnt lgkmcnt(0)
	s_waitcnt lgkmcnt(7)
	v_mfma_f32_16x16x32_bf16 v[62:65], v[130:133], v[180:183], v[62:65]
	v_mfma_f32_16x16x32_bf16 v[62:65], v[138:141], v[184:187], v[62:65]
	s_waitcnt lgkmcnt(5)
	v_mfma_f32_16x16x32_bf16 v[58:61], v[142:145], v[180:183], v[58:61]
	v_mfma_f32_16x16x32_bf16 v[58:61], v[146:149], v[184:187], v[58:61]
	s_barrier
	s_setprio 1
	s_waitcnt lgkmcnt(3)
	v_mfma_f32_16x16x32_bf16 v[42:45], v[142:145], v[188:191], v[42:45]
	v_mfma_f32_16x16x32_bf16 v[42:45], v[146:149], v[192:195], v[42:45]
	s_waitcnt lgkmcnt(1)
	v_mfma_f32_16x16x32_bf16 v[46:49], v[130:133], v[188:191], v[46:49]
	v_mfma_f32_16x16x32_bf16 v[46:49], v[138:141], v[192:195], v[46:49]
	v_mfma_f32_16x16x32_bf16 v[30:33], v[130:133], v[196:199], v[30:33]
	v_mfma_f32_16x16x32_bf16 v[30:33], v[138:141], v[200:203], v[30:33]
	v_mfma_f32_16x16x32_bf16 v[26:29], v[142:145], v[196:199], v[26:29]
	v_mfma_f32_16x16x32_bf16 v[26:29], v[146:149], v[200:203], v[26:29]
	v_mfma_f32_16x16x32_bf16 v[10:13], v[142:145], v[204:207], v[10:13]
	v_mfma_f32_16x16x32_bf16 v[10:13], v[146:149], v[208:211], v[10:13]
	s_waitcnt lgkmcnt(0)
	v_mfma_f32_16x16x32_bf16 v[14:17], v[130:133], v[204:207], v[14:17]
	v_mfma_f32_16x16x32_bf16 v[14:17], v[138:141], v[208:211], v[14:17]
	s_setprio 0
	s_setprio 1
	v_mfma_f32_16x16x32_bf16 v[54:57], v[150:153], v[180:183], v[54:57]
	v_mfma_f32_16x16x32_bf16 v[54:57], v[168:171], v[184:187], v[54:57]
	v_mfma_f32_16x16x32_bf16 v[50:53], v[172:175], v[180:183], v[50:53]
	v_mfma_f32_16x16x32_bf16 v[50:53], v[176:179], v[184:187], v[50:53]
	v_mfma_f32_16x16x32_bf16 v[34:37], v[172:175], v[188:191], v[34:37]
	v_mfma_f32_16x16x32_bf16 v[34:37], v[176:179], v[192:195], v[34:37]
	v_mfma_f32_16x16x32_bf16 v[38:41], v[150:153], v[188:191], v[38:41]
	v_mfma_f32_16x16x32_bf16 v[38:41], v[168:171], v[192:195], v[38:41]
	v_mfma_f32_16x16x32_bf16 v[22:25], v[150:153], v[196:199], v[22:25]
	v_mfma_f32_16x16x32_bf16 v[22:25], v[168:171], v[200:203], v[22:25]
	v_mfma_f32_16x16x32_bf16 v[18:21], v[172:175], v[196:199], v[18:21]
	v_mfma_f32_16x16x32_bf16 v[18:21], v[176:179], v[200:203], v[18:21]
	v_mfma_f32_16x16x32_bf16 v[2:5], v[172:175], v[204:207], v[2:5]
	v_mfma_f32_16x16x32_bf16 v[2:5], v[176:179], v[208:211], v[2:5]
	s_setprio 2
	s_barrier
	v_mfma_f32_16x16x32_bf16 v[6:9], v[150:153], v[204:207], v[6:9]
	v_mfma_f32_16x16x32_bf16 v[6:9], v[168:171], v[208:211], v[6:9]
	s_setprio 0
	s_add_i32 s74, s74, 2
	s_add_u32 s30, s30, 0x100
	s_addc_u32 s31, s31, 0
	s_add_u32 s4, s4, 0x100
	s_addc_u32 s5, s5, 0
	s_add_u32 s33, s33, 0x100
	s_addc_u32 s73, s73, 0
	s_cmp_gt_u32 s74, 29
	.p2align 6
.LBB0_654:
	ds_read_b128 v[130:133], v161
	ds_read_b128 v[138:141], v161 offset:1024
	ds_read_b128 v[142:145], v161 offset:2048
	ds_read_b128 v[146:149], v161 offset:3072
	ds_read_b128 v[150:153], v162
	ds_read_b128 v[168:171], v162 offset:1024
	ds_read_b128 v[172:175], v162 offset:2048
	ds_read_b128 v[176:179], v162 offset:3072
	s_cmp_eq_u32 s74, 28
	s_cselect_b32 s11, s21, s31
	s_cselect_b32 s10, s23, s30
	s_cselect_b32 s29, s7, s73
	s_cselect_b32 s28, s9, s33
	ds_read_b128 v[180:183], v163
	ds_read_b128 v[184:187], v163 offset:1024
	ds_read_b128 v[188:191], v163 offset:2048
	ds_read_b128 v[192:195], v163 offset:3072
	ds_read_b128 v[196:199], v163 offset:4096
	ds_read_b128 v[200:203], v163 offset:5120
	ds_read_b128 v[204:207], v163 offset:6144
	ds_read_b128 v[208:211], v163 offset:7168
	s_add_u32 s76, s4, 0xfff80000
	s_addc_u32 s77, s5, -1
	s_mov_b32 s75, m0
	s_mov_b32 m0, s80
	s_nop 0
	global_load_lds_dwordx4 v1, s[76:77]
	s_mov_b32 m0, s75
	s_nop 0
	s_mov_b32 s75, m0
	s_mov_b32 m0, s82
	s_nop 0
	global_load_lds_dwordx4 v157, s[76:77]
	s_mov_b32 m0, s75
	s_nop 0
	s_mov_b32 s75, m0
	s_mov_b32 m0, s81
	s_nop 0
	global_load_lds_dwordx4 v1, s[4:5]
	s_mov_b32 m0, s75
	s_nop 0
	s_mov_b32 s75, m0
	s_mov_b32 m0, s83
	s_nop 0
	global_load_lds_dwordx4 v157, s[4:5]
	s_mov_b32 m0, s75
	s_waitcnt vmcnt(8)
	s_waitcnt lgkmcnt(0)
	s_waitcnt lgkmcnt(7)
	v_mfma_f32_16x16x32_bf16 v[126:129], v[130:133], v[180:183], v[126:129]
	v_mfma_f32_16x16x32_bf16 v[126:129], v[138:141], v[184:187], v[126:129]
	s_waitcnt lgkmcnt(5)
	v_mfma_f32_16x16x32_bf16 v[122:125], v[142:145], v[180:183], v[122:125]
	v_mfma_f32_16x16x32_bf16 v[122:125], v[146:149], v[184:187], v[122:125]
	s_barrier
	s_setprio 1
	s_waitcnt lgkmcnt(3)
	v_mfma_f32_16x16x32_bf16 v[106:109], v[142:145], v[188:191], v[106:109]
	v_mfma_f32_16x16x32_bf16 v[106:109], v[146:149], v[192:195], v[106:109]
	s_waitcnt lgkmcnt(1)
	v_mfma_f32_16x16x32_bf16 v[110:113], v[130:133], v[188:191], v[110:113]
	v_mfma_f32_16x16x32_bf16 v[110:113], v[138:141], v[192:195], v[110:113]
	v_mfma_f32_16x16x32_bf16 v[94:97], v[130:133], v[196:199], v[94:97]
	v_mfma_f32_16x16x32_bf16 v[94:97], v[138:141], v[200:203], v[94:97]
	v_mfma_f32_16x16x32_bf16 v[90:93], v[142:145], v[196:199], v[90:93]
	v_mfma_f32_16x16x32_bf16 v[90:93], v[146:149], v[200:203], v[90:93]
	v_mfma_f32_16x16x32_bf16 v[74:77], v[142:145], v[204:207], v[74:77]
	v_mfma_f32_16x16x32_bf16 v[74:77], v[146:149], v[208:211], v[74:77]
	s_waitcnt lgkmcnt(0)
	v_mfma_f32_16x16x32_bf16 v[78:81], v[130:133], v[204:207], v[78:81]
	v_mfma_f32_16x16x32_bf16 v[78:81], v[138:141], v[208:211], v[78:81]
	s_setprio 0
	s_setprio 1
	v_mfma_f32_16x16x32_bf16 v[118:121], v[150:153], v[180:183], v[118:121]
	v_mfma_f32_16x16x32_bf16 v[118:121], v[168:171], v[184:187], v[118:121]
	v_mfma_f32_16x16x32_bf16 v[114:117], v[172:175], v[180:183], v[114:117]
	v_mfma_f32_16x16x32_bf16 v[114:117], v[176:179], v[184:187], v[114:117]
	v_mfma_f32_16x16x32_bf16 v[98:101], v[172:175], v[188:191], v[98:101]
	v_mfma_f32_16x16x32_bf16 v[98:101], v[176:179], v[192:195], v[98:101]
	v_mfma_f32_16x16x32_bf16 v[102:105], v[150:153], v[188:191], v[102:105]
	v_mfma_f32_16x16x32_bf16 v[102:105], v[168:171], v[192:195], v[102:105]
	v_mfma_f32_16x16x32_bf16 v[86:89], v[150:153], v[196:199], v[86:89]
	v_mfma_f32_16x16x32_bf16 v[86:89], v[168:171], v[200:203], v[86:89]
	v_mfma_f32_16x16x32_bf16 v[82:85], v[172:175], v[196:199], v[82:85]
	v_mfma_f32_16x16x32_bf16 v[82:85], v[176:179], v[200:203], v[82:85]
	v_mfma_f32_16x16x32_bf16 v[66:69], v[172:175], v[204:207], v[66:69]
	v_mfma_f32_16x16x32_bf16 v[66:69], v[176:179], v[208:211], v[66:69]
	s_setprio 2
	s_barrier
	v_mfma_f32_16x16x32_bf16 v[70:73], v[150:153], v[204:207], v[70:73]
	v_mfma_f32_16x16x32_bf16 v[70:73], v[168:171], v[208:211], v[70:73]
	s_setprio 0
	ds_read_b128 v[180:183], v163 offset:16384
	ds_read_b128 v[184:187], v163 offset:17408
	ds_read_b128 v[188:191], v163 offset:18432
	ds_read_b128 v[192:195], v163 offset:19456
	ds_read_b128 v[196:199], v163 offset:20480
	ds_read_b128 v[200:203], v163 offset:21504
	ds_read_b128 v[204:207], v163 offset:22528
	ds_read_b128 v[208:211], v163 offset:23552
	s_mov_b32 s75, m0
	s_mov_b32 m0, s43
	s_nop 0
	global_load_lds_dwordx4 v156, s[10:11]
	s_mov_b32 m0, s75
	s_add_u32 s76, s10, 0x80000
	s_mov_b32 s75, m0
	s_mov_b32 m0, s46
	s_nop 0
	global_load_lds_dwordx4 v158, s[10:11]
	s_mov_b32 m0, s75
	s_addc_u32 s77, s11, 0
	s_mov_b32 s75, m0
	s_mov_b32 m0, s47
	s_nop 0
	global_load_lds_dwordx4 v156, s[76:77]
	s_mov_b32 m0, s75
	s_nop 0
	s_mov_b32 s75, m0
	s_mov_b32 m0, s48
	s_nop 0
	global_load_lds_dwordx4 v158, s[76:77]
	s_mov_b32 m0, s75
	s_waitcnt vmcnt(4)
	s_waitcnt lgkmcnt(0)
	s_waitcnt lgkmcnt(7)
	v_mfma_f32_16x16x32_bf16 v[62:65], v[130:133], v[180:183], v[62:65]
	v_mfma_f32_16x16x32_bf16 v[62:65], v[138:141], v[184:187], v[62:65]
	s_waitcnt lgkmcnt(5)
	v_mfma_f32_16x16x32_bf16 v[58:61], v[142:145], v[180:183], v[58:61]
	v_mfma_f32_16x16x32_bf16 v[58:61], v[146:149], v[184:187], v[58:61]
	s_barrier
	s_setprio 1
	s_waitcnt lgkmcnt(3)
	v_mfma_f32_16x16x32_bf16 v[42:45], v[142:145], v[188:191], v[42:45]
	v_mfma_f32_16x16x32_bf16 v[42:45], v[146:149], v[192:195], v[42:45]
	s_waitcnt lgkmcnt(1)
	v_mfma_f32_16x16x32_bf16 v[46:49], v[130:133], v[188:191], v[46:49]
	v_mfma_f32_16x16x32_bf16 v[46:49], v[138:141], v[192:195], v[46:49]
	v_mfma_f32_16x16x32_bf16 v[30:33], v[130:133], v[196:199], v[30:33]
	v_mfma_f32_16x16x32_bf16 v[30:33], v[138:141], v[200:203], v[30:33]
	v_mfma_f32_16x16x32_bf16 v[26:29], v[142:145], v[196:199], v[26:29]
	v_mfma_f32_16x16x32_bf16 v[26:29], v[146:149], v[200:203], v[26:29]
	v_mfma_f32_16x16x32_bf16 v[10:13], v[142:145], v[204:207], v[10:13]
	v_mfma_f32_16x16x32_bf16 v[10:13], v[146:149], v[208:211], v[10:13]
	s_waitcnt lgkmcnt(0)
	v_mfma_f32_16x16x32_bf16 v[14:17], v[130:133], v[204:207], v[14:17]
	v_mfma_f32_16x16x32_bf16 v[14:17], v[138:141], v[208:211], v[14:17]
	s_setprio 0
	s_setprio 1
	v_mfma_f32_16x16x32_bf16 v[54:57], v[150:153], v[180:183], v[54:57]
	v_mfma_f32_16x16x32_bf16 v[54:57], v[168:171], v[184:187], v[54:57]
	v_mfma_f32_16x16x32_bf16 v[50:53], v[172:175], v[180:183], v[50:53]
	v_mfma_f32_16x16x32_bf16 v[50:53], v[176:179], v[184:187], v[50:53]
	v_mfma_f32_16x16x32_bf16 v[34:37], v[172:175], v[188:191], v[34:37]
	v_mfma_f32_16x16x32_bf16 v[34:37], v[176:179], v[192:195], v[34:37]
	v_mfma_f32_16x16x32_bf16 v[38:41], v[150:153], v[188:191], v[38:41]
	v_mfma_f32_16x16x32_bf16 v[38:41], v[168:171], v[192:195], v[38:41]
	v_mfma_f32_16x16x32_bf16 v[22:25], v[150:153], v[196:199], v[22:25]
	v_mfma_f32_16x16x32_bf16 v[22:25], v[168:171], v[200:203], v[22:25]
	v_mfma_f32_16x16x32_bf16 v[18:21], v[172:175], v[196:199], v[18:21]
	v_mfma_f32_16x16x32_bf16 v[18:21], v[176:179], v[200:203], v[18:21]
	v_mfma_f32_16x16x32_bf16 v[2:5], v[172:175], v[204:207], v[2:5]
	v_mfma_f32_16x16x32_bf16 v[2:5], v[176:179], v[208:211], v[2:5]
	s_setprio 2
	s_barrier
	v_mfma_f32_16x16x32_bf16 v[6:9], v[150:153], v[204:207], v[6:9]
	v_mfma_f32_16x16x32_bf16 v[6:9], v[168:171], v[208:211], v[6:9]
	s_setprio 0
	ds_read_b128 v[130:133], v164
	ds_read_b128 v[138:141], v164 offset:1024
	ds_read_b128 v[142:145], v164 offset:2048
	ds_read_b128 v[146:149], v164 offset:3072
	ds_read_b128 v[150:153], v165
	ds_read_b128 v[168:171], v165 offset:1024
	ds_read_b128 v[172:175], v165 offset:2048
	ds_read_b128 v[176:179], v165 offset:3072
	ds_read_b128 v[180:183], v163 offset:32768
	ds_read_b128 v[184:187], v163 offset:33792
	ds_read_b128 v[188:191], v163 offset:34816
	ds_read_b128 v[192:195], v163 offset:35840
	ds_read_b128 v[196:199], v163 offset:36864
	ds_read_b128 v[200:203], v163 offset:37888
	ds_read_b128 v[204:207], v163 offset:38912
	ds_read_b128 v[208:211], v163 offset:39936
	s_mov_b32 s75, m0
	s_mov_b32 m0, s42
	s_nop 0
	global_load_lds_dwordx4 v1, s[28:29]
	s_mov_b32 m0, s75
	s_nop 0
	s_mov_b32 s75, m0
	s_mov_b32 m0, s49
	s_nop 0
	global_load_lds_dwordx4 v157, s[28:29]
	s_mov_b32 m0, s75
	s_add_u32 s28, s28, 0x80000
	s_addc_u32 s29, s29, 0
	s_mov_b32 s75, m0
	s_mov_b32 m0, s56
	s_nop 0
	global_load_lds_dwordx4 v1, s[28:29]
	s_mov_b32 m0, s75
	s_nop 0
	s_mov_b32 s75, m0
	s_mov_b32 m0, s57
	s_nop 0
	global_load_lds_dwordx4 v157, s[28:29]
	s_mov_b32 m0, s75
	s_waitcnt vmcnt(8)
	s_waitcnt lgkmcnt(0)
	s_waitcnt lgkmcnt(7)
	v_mfma_f32_16x16x32_bf16 v[126:129], v[130:133], v[180:183], v[126:129]
	v_mfma_f32_16x16x32_bf16 v[126:129], v[138:141], v[184:187], v[126:129]
	s_waitcnt lgkmcnt(5)
	v_mfma_f32_16x16x32_bf16 v[122:125], v[142:145], v[180:183], v[122:125]
	v_mfma_f32_16x16x32_bf16 v[122:125], v[146:149], v[184:187], v[122:125]
	s_barrier
	s_setprio 1
	s_waitcnt lgkmcnt(3)
	v_mfma_f32_16x16x32_bf16 v[106:109], v[142:145], v[188:191], v[106:109]
	v_mfma_f32_16x16x32_bf16 v[106:109], v[146:149], v[192:195], v[106:109]
	s_waitcnt lgkmcnt(1)
	v_mfma_f32_16x16x32_bf16 v[110:113], v[130:133], v[188:191], v[110:113]
	v_mfma_f32_16x16x32_bf16 v[110:113], v[138:141], v[192:195], v[110:113]
	v_mfma_f32_16x16x32_bf16 v[94:97], v[130:133], v[196:199], v[94:97]
	v_mfma_f32_16x16x32_bf16 v[94:97], v[138:141], v[200:203], v[94:97]
	v_mfma_f32_16x16x32_bf16 v[90:93], v[142:145], v[196:199], v[90:93]
	v_mfma_f32_16x16x32_bf16 v[90:93], v[146:149], v[200:203], v[90:93]
	v_mfma_f32_16x16x32_bf16 v[74:77], v[142:145], v[204:207], v[74:77]
	v_mfma_f32_16x16x32_bf16 v[74:77], v[146:149], v[208:211], v[74:77]
	s_waitcnt lgkmcnt(0)
	v_mfma_f32_16x16x32_bf16 v[78:81], v[130:133], v[204:207], v[78:81]
	v_mfma_f32_16x16x32_bf16 v[78:81], v[138:141], v[208:211], v[78:81]
	s_setprio 0
	s_setprio 1
	v_mfma_f32_16x16x32_bf16 v[118:121], v[150:153], v[180:183], v[118:121]
	v_mfma_f32_16x16x32_bf16 v[118:121], v[168:171], v[184:187], v[118:121]
	v_mfma_f32_16x16x32_bf16 v[114:117], v[172:175], v[180:183], v[114:117]
	v_mfma_f32_16x16x32_bf16 v[114:117], v[176:179], v[184:187], v[114:117]
	v_mfma_f32_16x16x32_bf16 v[98:101], v[172:175], v[188:191], v[98:101]
	v_mfma_f32_16x16x32_bf16 v[98:101], v[176:179], v[192:195], v[98:101]
	v_mfma_f32_16x16x32_bf16 v[102:105], v[150:153], v[188:191], v[102:105]
	v_mfma_f32_16x16x32_bf16 v[102:105], v[168:171], v[192:195], v[102:105]
	v_mfma_f32_16x16x32_bf16 v[86:89], v[150:153], v[196:199], v[86:89]
	v_mfma_f32_16x16x32_bf16 v[86:89], v[168:171], v[200:203], v[86:89]
	v_mfma_f32_16x16x32_bf16 v[82:85], v[172:175], v[196:199], v[82:85]
	v_mfma_f32_16x16x32_bf16 v[82:85], v[176:179], v[200:203], v[82:85]
	v_mfma_f32_16x16x32_bf16 v[66:69], v[172:175], v[204:207], v[66:69]
	v_mfma_f32_16x16x32_bf16 v[66:69], v[176:179], v[208:211], v[66:69]
	s_setprio 2
	s_barrier
	v_mfma_f32_16x16x32_bf16 v[70:73], v[150:153], v[204:207], v[70:73]
	v_mfma_f32_16x16x32_bf16 v[70:73], v[168:171], v[208:211], v[70:73]
	s_setprio 0
	ds_read_b128 v[180:183], v163 offset:49152
	ds_read_b128 v[184:187], v163 offset:50176
	ds_read_b128 v[188:191], v163 offset:51200
	ds_read_b128 v[192:195], v163 offset:52224
	ds_read_b128 v[196:199], v163 offset:53248
	ds_read_b128 v[200:203], v163 offset:54272
	ds_read_b128 v[204:207], v163 offset:55296
	ds_read_b128 v[208:211], v163 offset:56320
	s_add_u32 s28, s10, 0x80
	s_addc_u32 s29, s11, 0
	s_mov_b32 s75, m0
	s_mov_b32 m0, s64
	s_nop 0
	global_load_lds_dwordx4 v156, s[28:29]
	s_mov_b32 m0, s75
	s_add_u32 s10, s10, 0x80080
	s_mov_b32 s75, m0
	s_mov_b32 m0, s65
	s_nop 0
	global_load_lds_dwordx4 v158, s[28:29]
	s_mov_b32 m0, s75
	s_addc_u32 s11, s11, 0
	s_mov_b32 s28, m0
	s_mov_b32 m0, s66
	s_nop 0
	global_load_lds_dwordx4 v156, s[10:11]
	s_mov_b32 m0, s28
	s_nop 0
	s_mov_b32 s28, m0
	s_mov_b32 m0, s67
	s_nop 0
	global_load_lds_dwordx4 v158, s[10:11]
	s_mov_b32 m0, s28
	s_waitcnt vmcnt(4)
	s_waitcnt lgkmcnt(0)
	s_waitcnt lgkmcnt(7)
	v_mfma_f32_16x16x32_bf16 v[62:65], v[130:133], v[180:183], v[62:65]
	v_mfma_f32_16x16x32_bf16 v[62:65], v[138:141], v[184:187], v[62:65]
	s_waitcnt lgkmcnt(5)
	v_mfma_f32_16x16x32_bf16 v[58:61], v[142:145], v[180:183], v[58:61]
	v_mfma_f32_16x16x32_bf16 v[58:61], v[146:149], v[184:187], v[58:61]
	s_barrier
	s_setprio 1
	s_waitcnt lgkmcnt(3)
	v_mfma_f32_16x16x32_bf16 v[42:45], v[142:145], v[188:191], v[42:45]
	v_mfma_f32_16x16x32_bf16 v[42:45], v[146:149], v[192:195], v[42:45]
	s_waitcnt lgkmcnt(1)
	v_mfma_f32_16x16x32_bf16 v[46:49], v[130:133], v[188:191], v[46:49]
	v_mfma_f32_16x16x32_bf16 v[46:49], v[138:141], v[192:195], v[46:49]
	v_mfma_f32_16x16x32_bf16 v[30:33], v[130:133], v[196:199], v[30:33]
	v_mfma_f32_16x16x32_bf16 v[30:33], v[138:141], v[200:203], v[30:33]
	v_mfma_f32_16x16x32_bf16 v[26:29], v[142:145], v[196:199], v[26:29]
	v_mfma_f32_16x16x32_bf16 v[26:29], v[146:149], v[200:203], v[26:29]
	v_mfma_f32_16x16x32_bf16 v[10:13], v[142:145], v[204:207], v[10:13]
	v_mfma_f32_16x16x32_bf16 v[10:13], v[146:149], v[208:211], v[10:13]
	s_waitcnt lgkmcnt(0)
	v_mfma_f32_16x16x32_bf16 v[14:17], v[130:133], v[204:207], v[14:17]
	v_mfma_f32_16x16x32_bf16 v[14:17], v[138:141], v[208:211], v[14:17]
	s_setprio 0
	s_setprio 1
	v_mfma_f32_16x16x32_bf16 v[54:57], v[150:153], v[180:183], v[54:57]
	v_mfma_f32_16x16x32_bf16 v[54:57], v[168:171], v[184:187], v[54:57]
	v_mfma_f32_16x16x32_bf16 v[50:53], v[172:175], v[180:183], v[50:53]
	v_mfma_f32_16x16x32_bf16 v[50:53], v[176:179], v[184:187], v[50:53]
	v_mfma_f32_16x16x32_bf16 v[34:37], v[172:175], v[188:191], v[34:37]
	v_mfma_f32_16x16x32_bf16 v[34:37], v[176:179], v[192:195], v[34:37]
	v_mfma_f32_16x16x32_bf16 v[38:41], v[150:153], v[188:191], v[38:41]
	v_mfma_f32_16x16x32_bf16 v[38:41], v[168:171], v[192:195], v[38:41]
	v_mfma_f32_16x16x32_bf16 v[22:25], v[150:153], v[196:199], v[22:25]
	v_mfma_f32_16x16x32_bf16 v[22:25], v[168:171], v[200:203], v[22:25]
	v_mfma_f32_16x16x32_bf16 v[18:21], v[172:175], v[196:199], v[18:21]
	v_mfma_f32_16x16x32_bf16 v[18:21], v[176:179], v[200:203], v[18:21]
	v_mfma_f32_16x16x32_bf16 v[2:5], v[172:175], v[204:207], v[2:5]
	v_mfma_f32_16x16x32_bf16 v[2:5], v[176:179], v[208:211], v[2:5]
	s_setprio 2
	s_barrier
	v_mfma_f32_16x16x32_bf16 v[6:9], v[150:153], v[204:207], v[6:9]
	v_mfma_f32_16x16x32_bf16 v[6:9], v[168:171], v[208:211], v[6:9]
	s_setprio 0
	s_add_i32 s74, s74, 2
	s_add_u32 s30, s30, 0x100
	s_addc_u32 s31, s31, 0
	s_add_u32 s4, s4, 0x100
	s_addc_u32 s5, s5, 0
	s_add_u32 s33, s33, 0x100
	s_addc_u32 s73, s73, 0
	s_cmp_gt_u32 s74, 29
	s_cbranch_scc0 .LBB0_654
	s_and_b64 vcc, exec, s[18:19]
	s_cbranch_vccz .LBB0_657
	s_barrier

.LBB0_1052:
	s_ashr_i32 s13, s12, 31
	s_lshl_b64 s[14:15], s[12:13], 20
	s_add_u32 s14, s28, s14
	s_addc_u32 s15, s29, s15
	s_and_b64 s[16:17], s[2:3], exec
	s_cselect_b32 s13, s15, s23
	s_cselect_b32 s67, s14, s22
	s_ashr_i32 s11, s10, 31
	s_lshl_b64 s[16:17], s[10:11], 20
	s_add_u32 s16, s30, s16
	s_addc_u32 s17, s31, s17
	s_and_b64 s[24:25], s[2:3], exec
	s_cselect_b32 s11, s17, s21
	s_cselect_b32 s73, s16, s20
	s_add_u32 s74, s20, 0x100
	s_addc_u32 s75, s21, 0
	s_add_u32 s20, s22, 0x80080
	s_addc_u32 s21, s23, 0
	s_add_u32 s76, s22, 0x100
	s_addc_u32 s77, s23, 0
	s_mov_b32 s78, -2
	s_waitcnt vmcnt(25)
	s_waitcnt vmcnt(24)
	s_waitcnt vmcnt(15)
	s_waitcnt vmcnt(14)
	s_waitcnt vmcnt(13)
	s_waitcnt vmcnt(12)
	s_waitcnt vmcnt(11)
	s_waitcnt vmcnt(10)
	s_waitcnt vmcnt(9)
	s_waitcnt vmcnt(8)
	s_waitcnt vmcnt(7)
	s_waitcnt vmcnt(6)
	s_waitcnt vmcnt(5)
	s_waitcnt vmcnt(4)
	s_waitcnt vmcnt(3)
	s_waitcnt vmcnt(2)
	s_waitcnt vmcnt(1)
	s_waitcnt vmcnt(0)
	ds_read_b128 v[130:133], v181
	ds_read_b128 v[134:137], v181 offset:1024
	ds_read_b128 v[138:141], v181 offset:2048
	ds_read_b128 v[142:145], v181 offset:3072
	ds_read_b128 v[146:149], v182
	ds_read_b128 v[150:153], v182 offset:1024
	ds_read_b128 v[154:157], v182 offset:2048
	ds_read_b128 v[158:161], v182 offset:3072
	s_cmp_eq_u32 s78, 28
	s_cselect_b32 s23, s11, s75
	s_cselect_b32 s22, s73, s74
	s_cselect_b32 s25, s13, s77
	s_cselect_b32 s24, s67, s76
	ds_read_b128 v[166:169], v183
	ds_read_b128 v[170:173], v183 offset:1024
	ds_read_b128 v[186:189], v183 offset:2048
	ds_read_b128 v[190:193], v183 offset:3072
	ds_read_b128 v[194:197], v183 offset:4096
	ds_read_b128 v[198:201], v183 offset:5120
	ds_read_b128 v[202:205], v183 offset:6144
	ds_read_b128 v[206:209], v183 offset:7168
	s_add_u32 s80, s20, 0xfff80000
	s_addc_u32 s81, s21, -1
	s_mov_b32 s79, m0
	s_mov_b32 m0, s58
	s_nop 0
	global_load_lds_dwordx4 v1, s[80:81]
	s_mov_b32 m0, s79
	s_nop 0
	s_mov_b32 s79, m0
	s_mov_b32 m0, s64
	s_nop 0
	global_load_lds_dwordx4 v177, s[80:81]
	s_mov_b32 m0, s79
	s_nop 0
	s_mov_b32 s79, m0
	s_mov_b32 m0, s59
	s_nop 0
	global_load_lds_dwordx4 v1, s[20:21]
	s_mov_b32 m0, s79
	s_nop 0
	s_mov_b32 s79, m0
	s_mov_b32 m0, s65
	s_nop 0
	global_load_lds_dwordx4 v177, s[20:21]
	s_mov_b32 m0, s79
	s_waitcnt vmcnt(8)
	s_waitcnt lgkmcnt(0)
	s_waitcnt lgkmcnt(7)
	v_mfma_f32_16x16x32_bf16 v[126:129], v[130:133], v[166:169], 0
	v_mfma_f32_16x16x32_bf16 v[126:129], v[134:137], v[170:173], v[126:129]
	s_waitcnt lgkmcnt(5)
	v_mfma_f32_16x16x32_bf16 v[122:125], v[138:141], v[166:169], 0
	v_mfma_f32_16x16x32_bf16 v[122:125], v[142:145], v[170:173], v[122:125]
	s_barrier
	s_setprio 1
	s_waitcnt lgkmcnt(3)
	v_mfma_f32_16x16x32_bf16 v[114:117], v[138:141], v[186:189], 0
	v_mfma_f32_16x16x32_bf16 v[114:117], v[142:145], v[190:193], v[114:117]
	s_waitcnt lgkmcnt(1)
	v_mfma_f32_16x16x32_bf16 v[118:121], v[130:133], v[186:189], 0
	v_mfma_f32_16x16x32_bf16 v[118:121], v[134:137], v[190:193], v[118:121]
	v_mfma_f32_16x16x32_bf16 v[94:97], v[130:133], v[194:197], 0
	v_mfma_f32_16x16x32_bf16 v[94:97], v[134:137], v[198:201], v[94:97]
	v_mfma_f32_16x16x32_bf16 v[90:93], v[138:141], v[194:197], 0
	v_mfma_f32_16x16x32_bf16 v[90:93], v[142:145], v[198:201], v[90:93]
	v_mfma_f32_16x16x32_bf16 v[78:81], v[138:141], v[202:205], 0
	v_mfma_f32_16x16x32_bf16 v[78:81], v[142:145], v[206:209], v[78:81]
	s_waitcnt lgkmcnt(0)
	v_mfma_f32_16x16x32_bf16 v[86:89], v[130:133], v[202:205], 0
	v_mfma_f32_16x16x32_bf16 v[86:89], v[134:137], v[206:209], v[86:89]
	s_setprio 0
	s_setprio 1
	v_mfma_f32_16x16x32_bf16 v[110:113], v[146:149], v[166:169], 0
	v_mfma_f32_16x16x32_bf16 v[110:113], v[150:153], v[170:173], v[110:113]
	v_mfma_f32_16x16x32_bf16 v[106:109], v[154:157], v[166:169], 0
	v_mfma_f32_16x16x32_bf16 v[106:109], v[158:161], v[170:173], v[106:109]
	v_mfma_f32_16x16x32_bf16 v[98:101], v[154:157], v[186:189], 0
	v_mfma_f32_16x16x32_bf16 v[98:101], v[158:161], v[190:193], v[98:101]
	v_mfma_f32_16x16x32_bf16 v[102:105], v[146:149], v[186:189], 0
	v_mfma_f32_16x16x32_bf16 v[102:105], v[150:153], v[190:193], v[102:105]
	v_mfma_f32_16x16x32_bf16 v[82:85], v[146:149], v[194:197], 0
	v_mfma_f32_16x16x32_bf16 v[82:85], v[150:153], v[198:201], v[82:85]
	v_mfma_f32_16x16x32_bf16 v[74:77], v[154:157], v[194:197], 0
	v_mfma_f32_16x16x32_bf16 v[74:77], v[158:161], v[198:201], v[74:77]
	v_mfma_f32_16x16x32_bf16 v[66:69], v[154:157], v[202:205], 0
	v_mfma_f32_16x16x32_bf16 v[66:69], v[158:161], v[206:209], v[66:69]
	s_setprio 2
	s_barrier
	v_mfma_f32_16x16x32_bf16 v[70:73], v[146:149], v[202:205], 0
	v_mfma_f32_16x16x32_bf16 v[70:73], v[150:153], v[206:209], v[70:73]
	s_setprio 0
	ds_read_b128 v[166:169], v183 offset:16384
	ds_read_b128 v[170:173], v183 offset:17408
	ds_read_b128 v[186:189], v183 offset:18432
	ds_read_b128 v[190:193], v183 offset:19456
	ds_read_b128 v[194:197], v183 offset:20480
	ds_read_b128 v[198:201], v183 offset:21504
	ds_read_b128 v[202:205], v183 offset:22528
	ds_read_b128 v[206:209], v183 offset:23552
	s_mov_b32 s79, m0
	s_mov_b32 m0, s35
	s_nop 0
	global_load_lds_dwordx4 v176, s[22:23]
	s_mov_b32 m0, s79
	s_add_u32 s80, s22, 0x80000
	s_mov_b32 s79, m0
	s_mov_b32 m0, s36
	s_nop 0
	global_load_lds_dwordx4 v178, s[22:23]
	s_mov_b32 m0, s79
	s_addc_u32 s81, s23, 0
	s_mov_b32 s79, m0
	s_mov_b32 m0, s37
	s_nop 0
	global_load_lds_dwordx4 v176, s[80:81]
	s_mov_b32 m0, s79
	s_nop 0
	s_mov_b32 s79, m0
	s_mov_b32 m0, s40
	s_nop 0
	global_load_lds_dwordx4 v178, s[80:81]
	s_mov_b32 m0, s79
	s_waitcnt vmcnt(4)
	s_waitcnt lgkmcnt(0)
	s_waitcnt lgkmcnt(7)
	v_mfma_f32_16x16x32_bf16 v[62:65], v[130:133], v[166:169], 0
	v_mfma_f32_16x16x32_bf16 v[62:65], v[134:137], v[170:173], v[62:65]
	s_waitcnt lgkmcnt(5)
	v_mfma_f32_16x16x32_bf16 v[58:61], v[138:141], v[166:169], 0
	v_mfma_f32_16x16x32_bf16 v[58:61], v[142:145], v[170:173], v[58:61]
	s_barrier
	s_setprio 1
	s_waitcnt lgkmcnt(3)
	v_mfma_f32_16x16x32_bf16 v[42:45], v[138:141], v[186:189], 0
	v_mfma_f32_16x16x32_bf16 v[42:45], v[142:145], v[190:193], v[42:45]
	s_waitcnt lgkmcnt(1)
	v_mfma_f32_16x16x32_bf16 v[46:49], v[130:133], v[186:189], 0
	v_mfma_f32_16x16x32_bf16 v[46:49], v[134:137], v[190:193], v[46:49]
	v_mfma_f32_16x16x32_bf16 v[30:33], v[130:133], v[194:197], 0
	v_mfma_f32_16x16x32_bf16 v[30:33], v[134:137], v[198:201], v[30:33]
	v_mfma_f32_16x16x32_bf16 v[26:29], v[138:141], v[194:197], 0
	v_mfma_f32_16x16x32_bf16 v[26:29], v[142:145], v[198:201], v[26:29]
	v_mfma_f32_16x16x32_bf16 v[10:13], v[138:141], v[202:205], 0
	v_mfma_f32_16x16x32_bf16 v[10:13], v[142:145], v[206:209], v[10:13]
	s_waitcnt lgkmcnt(0)
	v_mfma_f32_16x16x32_bf16 v[14:17], v[130:133], v[202:205], 0
	v_mfma_f32_16x16x32_bf16 v[14:17], v[134:137], v[206:209], v[14:17]
	s_setprio 0
	s_setprio 1
	v_mfma_f32_16x16x32_bf16 v[54:57], v[146:149], v[166:169], 0
	v_mfma_f32_16x16x32_bf16 v[54:57], v[150:153], v[170:173], v[54:57]
	v_mfma_f32_16x16x32_bf16 v[50:53], v[154:157], v[166:169], 0
	v_mfma_f32_16x16x32_bf16 v[50:53], v[158:161], v[170:173], v[50:53]
	v_mfma_f32_16x16x32_bf16 v[34:37], v[154:157], v[186:189], 0
	v_mfma_f32_16x16x32_bf16 v[34:37], v[158:161], v[190:193], v[34:37]
	v_mfma_f32_16x16x32_bf16 v[38:41], v[146:149], v[186:189], 0
	v_mfma_f32_16x16x32_bf16 v[38:41], v[150:153], v[190:193], v[38:41]
	v_mfma_f32_16x16x32_bf16 v[22:25], v[146:149], v[194:197], 0
	v_mfma_f32_16x16x32_bf16 v[22:25], v[150:153], v[198:201], v[22:25]
	v_mfma_f32_16x16x32_bf16 v[18:21], v[154:157], v[194:197], 0
	v_mfma_f32_16x16x32_bf16 v[18:21], v[158:161], v[198:201], v[18:21]
	v_mfma_f32_16x16x32_bf16 v[2:5], v[154:157], v[202:205], 0
	v_mfma_f32_16x16x32_bf16 v[2:5], v[158:161], v[206:209], v[2:5]
	s_setprio 2
	s_barrier
	v_mfma_f32_16x16x32_bf16 v[6:9], v[146:149], v[202:205], 0
	v_mfma_f32_16x16x32_bf16 v[6:9], v[150:153], v[206:209], v[6:9]
	s_setprio 0
	ds_read_b128 v[130:133], v184
	ds_read_b128 v[134:137], v184 offset:1024
	ds_read_b128 v[138:141], v184 offset:2048
	ds_read_b128 v[142:145], v184 offset:3072
	ds_read_b128 v[146:149], v185
	ds_read_b128 v[150:153], v185 offset:1024
	ds_read_b128 v[154:157], v185 offset:2048
	ds_read_b128 v[158:161], v185 offset:3072
	ds_read_b128 v[166:169], v183 offset:32768
	ds_read_b128 v[170:173], v183 offset:33792
	ds_read_b128 v[186:189], v183 offset:34816
	ds_read_b128 v[190:193], v183 offset:35840
	ds_read_b128 v[194:197], v183 offset:36864
	ds_read_b128 v[198:201], v183 offset:37888
	ds_read_b128 v[202:205], v183 offset:38912
	ds_read_b128 v[206:209], v183 offset:39936
	s_mov_b32 s79, m0
	s_mov_b32 m0, s34
	s_nop 0
	global_load_lds_dwordx4 v1, s[24:25]
	s_mov_b32 m0, s79
	s_nop 0
	s_mov_b32 s79, m0
	s_mov_b32 m0, s41
	s_nop 0
	global_load_lds_dwordx4 v177, s[24:25]
	s_mov_b32 m0, s79
	s_add_u32 s24, s24, 0x80000
	s_addc_u32 s25, s25, 0
	s_mov_b32 s79, m0
	s_mov_b32 m0, s42
	s_nop 0
	global_load_lds_dwordx4 v1, s[24:25]
	s_mov_b32 m0, s79
	s_nop 0
	s_mov_b32 s79, m0
	s_mov_b32 m0, s43
	s_nop 0
	global_load_lds_dwordx4 v177, s[24:25]
	s_mov_b32 m0, s79
	s_waitcnt vmcnt(8)
	s_waitcnt lgkmcnt(0)
	s_waitcnt lgkmcnt(7)
	v_mfma_f32_16x16x32_bf16 v[126:129], v[130:133], v[166:169], v[126:129]
	v_mfma_f32_16x16x32_bf16 v[126:129], v[134:137], v[170:173], v[126:129]
	s_waitcnt lgkmcnt(5)
	v_mfma_f32_16x16x32_bf16 v[122:125], v[138:141], v[166:169], v[122:125]
	v_mfma_f32_16x16x32_bf16 v[122:125], v[142:145], v[170:173], v[122:125]
	s_barrier
	s_setprio 1
	s_waitcnt lgkmcnt(3)
	v_mfma_f32_16x16x32_bf16 v[114:117], v[138:141], v[186:189], v[114:117]
	v_mfma_f32_16x16x32_bf16 v[114:117], v[142:145], v[190:193], v[114:117]
	s_waitcnt lgkmcnt(1)
	v_mfma_f32_16x16x32_bf16 v[118:121], v[130:133], v[186:189], v[118:121]
	v_mfma_f32_16x16x32_bf16 v[118:121], v[134:137], v[190:193], v[118:121]
	v_mfma_f32_16x16x32_bf16 v[94:97], v[130:133], v[194:197], v[94:97]
	v_mfma_f32_16x16x32_bf16 v[94:97], v[134:137], v[198:201], v[94:97]
	v_mfma_f32_16x16x32_bf16 v[90:93], v[138:141], v[194:197], v[90:93]
	v_mfma_f32_16x16x32_bf16 v[90:93], v[142:145], v[198:201], v[90:93]
	v_mfma_f32_16x16x32_bf16 v[78:81], v[138:141], v[202:205], v[78:81]
	v_mfma_f32_16x16x32_bf16 v[78:81], v[142:145], v[206:209], v[78:81]
	s_waitcnt lgkmcnt(0)
	v_mfma_f32_16x16x32_bf16 v[86:89], v[130:133], v[202:205], v[86:89]
	v_mfma_f32_16x16x32_bf16 v[86:89], v[134:137], v[206:209], v[86:89]
	s_setprio 0
	s_setprio 1
	v_mfma_f32_16x16x32_bf16 v[110:113], v[146:149], v[166:169], v[110:113]
	v_mfma_f32_16x16x32_bf16 v[110:113], v[150:153], v[170:173], v[110:113]
	v_mfma_f32_16x16x32_bf16 v[106:109], v[154:157], v[166:169], v[106:109]
	v_mfma_f32_16x16x32_bf16 v[106:109], v[158:161], v[170:173], v[106:109]
	v_mfma_f32_16x16x32_bf16 v[98:101], v[154:157], v[186:189], v[98:101]
	v_mfma_f32_16x16x32_bf16 v[98:101], v[158:161], v[190:193], v[98:101]
	v_mfma_f32_16x16x32_bf16 v[102:105], v[146:149], v[186:189], v[102:105]
	v_mfma_f32_16x16x32_bf16 v[102:105], v[150:153], v[190:193], v[102:105]
	v_mfma_f32_16x16x32_bf16 v[82:85], v[146:149], v[194:197], v[82:85]
	v_mfma_f32_16x16x32_bf16 v[82:85], v[150:153], v[198:201], v[82:85]
	v_mfma_f32_16x16x32_bf16 v[74:77], v[154:157], v[194:197], v[74:77]
	v_mfma_f32_16x16x32_bf16 v[74:77], v[158:161], v[198:201], v[74:77]
	v_mfma_f32_16x16x32_bf16 v[66:69], v[154:157], v[202:205], v[66:69]
	v_mfma_f32_16x16x32_bf16 v[66:69], v[158:161], v[206:209], v[66:69]
	s_setprio 2
	s_barrier
	v_mfma_f32_16x16x32_bf16 v[70:73], v[146:149], v[202:205], v[70:73]
	v_mfma_f32_16x16x32_bf16 v[70:73], v[150:153], v[206:209], v[70:73]
	s_setprio 0
	ds_read_b128 v[166:169], v183 offset:49152
	ds_read_b128 v[170:173], v183 offset:50176
	ds_read_b128 v[186:189], v183 offset:51200
	ds_read_b128 v[190:193], v183 offset:52224
	ds_read_b128 v[194:197], v183 offset:53248
	ds_read_b128 v[198:201], v183 offset:54272
	ds_read_b128 v[202:205], v183 offset:55296
	ds_read_b128 v[206:209], v183 offset:56320
	s_add_u32 s24, s22, 0x80
	s_addc_u32 s25, s23, 0
	s_mov_b32 s79, m0
	s_mov_b32 m0, s46
	s_nop 0
	global_load_lds_dwordx4 v176, s[24:25]
	s_mov_b32 m0, s79
	s_add_u32 s22, s22, 0x80080
	s_mov_b32 s79, m0
	s_mov_b32 m0, s47
	s_nop 0
	global_load_lds_dwordx4 v178, s[24:25]
	s_mov_b32 m0, s79
	s_addc_u32 s23, s23, 0
	s_mov_b32 s24, m0
	s_mov_b32 m0, s48
	s_nop 0
	global_load_lds_dwordx4 v176, s[22:23]
	s_mov_b32 m0, s24
	s_nop 0
	s_mov_b32 s24, m0
	s_mov_b32 m0, s49
	s_nop 0
	global_load_lds_dwordx4 v178, s[22:23]
	s_mov_b32 m0, s24
	s_waitcnt vmcnt(4)
	s_waitcnt lgkmcnt(0)
	s_waitcnt lgkmcnt(7)
	v_mfma_f32_16x16x32_bf16 v[62:65], v[130:133], v[166:169], v[62:65]
	v_mfma_f32_16x16x32_bf16 v[62:65], v[134:137], v[170:173], v[62:65]
	s_waitcnt lgkmcnt(5)
	v_mfma_f32_16x16x32_bf16 v[58:61], v[138:141], v[166:169], v[58:61]
	v_mfma_f32_16x16x32_bf16 v[58:61], v[142:145], v[170:173], v[58:61]
	s_barrier
	s_setprio 1
	s_waitcnt lgkmcnt(3)
	v_mfma_f32_16x16x32_bf16 v[42:45], v[138:141], v[186:189], v[42:45]
	v_mfma_f32_16x16x32_bf16 v[42:45], v[142:145], v[190:193], v[42:45]
	s_waitcnt lgkmcnt(1)
	v_mfma_f32_16x16x32_bf16 v[46:49], v[130:133], v[186:189], v[46:49]
	v_mfma_f32_16x16x32_bf16 v[46:49], v[134:137], v[190:193], v[46:49]
	v_mfma_f32_16x16x32_bf16 v[30:33], v[130:133], v[194:197], v[30:33]
	v_mfma_f32_16x16x32_bf16 v[30:33], v[134:137], v[198:201], v[30:33]
	v_mfma_f32_16x16x32_bf16 v[26:29], v[138:141], v[194:197], v[26:29]
	v_mfma_f32_16x16x32_bf16 v[26:29], v[142:145], v[198:201], v[26:29]
	v_mfma_f32_16x16x32_bf16 v[10:13], v[138:141], v[202:205], v[10:13]
	v_mfma_f32_16x16x32_bf16 v[10:13], v[142:145], v[206:209], v[10:13]
	s_waitcnt lgkmcnt(0)
	v_mfma_f32_16x16x32_bf16 v[14:17], v[130:133], v[202:205], v[14:17]
	v_mfma_f32_16x16x32_bf16 v[14:17], v[134:137], v[206:209], v[14:17]
	s_setprio 0
	s_setprio 1
	v_mfma_f32_16x16x32_bf16 v[54:57], v[146:149], v[166:169], v[54:57]
	v_mfma_f32_16x16x32_bf16 v[54:57], v[150:153], v[170:173], v[54:57]
	v_mfma_f32_16x16x32_bf16 v[50:53], v[154:157], v[166:169], v[50:53]
	v_mfma_f32_16x16x32_bf16 v[50:53], v[158:161], v[170:173], v[50:53]
	v_mfma_f32_16x16x32_bf16 v[34:37], v[154:157], v[186:189], v[34:37]
	v_mfma_f32_16x16x32_bf16 v[34:37], v[158:161], v[190:193], v[34:37]
	v_mfma_f32_16x16x32_bf16 v[38:41], v[146:149], v[186:189], v[38:41]
	v_mfma_f32_16x16x32_bf16 v[38:41], v[150:153], v[190:193], v[38:41]
	v_mfma_f32_16x16x32_bf16 v[22:25], v[146:149], v[194:197], v[22:25]
	v_mfma_f32_16x16x32_bf16 v[22:25], v[150:153], v[198:201], v[22:25]
	v_mfma_f32_16x16x32_bf16 v[18:21], v[154:157], v[194:197], v[18:21]
	v_mfma_f32_16x16x32_bf16 v[18:21], v[158:161], v[198:201], v[18:21]
	v_mfma_f32_16x16x32_bf16 v[2:5], v[154:157], v[202:205], v[2:5]
	v_mfma_f32_16x16x32_bf16 v[2:5], v[158:161], v[206:209], v[2:5]
	s_setprio 2
	s_barrier
	v_mfma_f32_16x16x32_bf16 v[6:9], v[146:149], v[202:205], v[6:9]
	v_mfma_f32_16x16x32_bf16 v[6:9], v[150:153], v[206:209], v[6:9]
	s_setprio 0
	s_add_i32 s78, s78, 2
	s_add_u32 s74, s74, 0x100
	s_addc_u32 s75, s75, 0
	s_add_u32 s20, s20, 0x100
	s_addc_u32 s21, s21, 0
	s_add_u32 s76, s76, 0x100
	s_addc_u32 s77, s77, 0
	s_cmp_gt_u32 s78, 29
	.p2align 6
.LBB0_1053:
	ds_read_b128 v[130:133], v181
	ds_read_b128 v[134:137], v181 offset:1024
	ds_read_b128 v[138:141], v181 offset:2048
	ds_read_b128 v[142:145], v181 offset:3072
	ds_read_b128 v[146:149], v182
	ds_read_b128 v[150:153], v182 offset:1024
	ds_read_b128 v[154:157], v182 offset:2048
	ds_read_b128 v[158:161], v182 offset:3072
	s_cmp_eq_u32 s78, 28
	s_cselect_b32 s23, s11, s75
	s_cselect_b32 s22, s73, s74
	s_cselect_b32 s25, s13, s77
	s_cselect_b32 s24, s67, s76
	ds_read_b128 v[166:169], v183
	ds_read_b128 v[170:173], v183 offset:1024
	ds_read_b128 v[186:189], v183 offset:2048
	ds_read_b128 v[190:193], v183 offset:3072
	ds_read_b128 v[194:197], v183 offset:4096
	ds_read_b128 v[198:201], v183 offset:5120
	ds_read_b128 v[202:205], v183 offset:6144
	ds_read_b128 v[206:209], v183 offset:7168
	s_add_u32 s80, s20, 0xfff80000
	s_addc_u32 s81, s21, -1
	s_mov_b32 s79, m0
	s_mov_b32 m0, s58
	s_nop 0
	global_load_lds_dwordx4 v1, s[80:81]
	s_mov_b32 m0, s79
	s_nop 0
	s_mov_b32 s79, m0
	s_mov_b32 m0, s64
	s_nop 0
	global_load_lds_dwordx4 v177, s[80:81]
	s_mov_b32 m0, s79
	s_nop 0
	s_mov_b32 s79, m0
	s_mov_b32 m0, s59
	s_nop 0
	global_load_lds_dwordx4 v1, s[20:21]
	s_mov_b32 m0, s79
	s_nop 0
	s_mov_b32 s79, m0
	s_mov_b32 m0, s65
	s_nop 0
	global_load_lds_dwordx4 v177, s[20:21]
	s_mov_b32 m0, s79
	s_waitcnt vmcnt(8)
	s_waitcnt lgkmcnt(0)
	s_waitcnt lgkmcnt(7)
	v_mfma_f32_16x16x32_bf16 v[126:129], v[130:133], v[166:169], v[126:129]
	v_mfma_f32_16x16x32_bf16 v[126:129], v[134:137], v[170:173], v[126:129]
	s_waitcnt lgkmcnt(5)
	v_mfma_f32_16x16x32_bf16 v[122:125], v[138:141], v[166:169], v[122:125]
	v_mfma_f32_16x16x32_bf16 v[122:125], v[142:145], v[170:173], v[122:125]
	s_barrier
	s_setprio 1
	s_waitcnt lgkmcnt(3)
	v_mfma_f32_16x16x32_bf16 v[114:117], v[138:141], v[186:189], v[114:117]
	v_mfma_f32_16x16x32_bf16 v[114:117], v[142:145], v[190:193], v[114:117]
	s_waitcnt lgkmcnt(1)
	v_mfma_f32_16x16x32_bf16 v[118:121], v[130:133], v[186:189], v[118:121]
	v_mfma_f32_16x16x32_bf16 v[118:121], v[134:137], v[190:193], v[118:121]
	v_mfma_f32_16x16x32_bf16 v[94:97], v[130:133], v[194:197], v[94:97]
	v_mfma_f32_16x16x32_bf16 v[94:97], v[134:137], v[198:201], v[94:97]
	v_mfma_f32_16x16x32_bf16 v[90:93], v[138:141], v[194:197], v[90:93]
	v_mfma_f32_16x16x32_bf16 v[90:93], v[142:145], v[198:201], v[90:93]
	v_mfma_f32_16x16x32_bf16 v[78:81], v[138:141], v[202:205], v[78:81]
	v_mfma_f32_16x16x32_bf16 v[78:81], v[142:145], v[206:209], v[78:81]
	s_waitcnt lgkmcnt(0)
	v_mfma_f32_16x16x32_bf16 v[86:89], v[130:133], v[202:205], v[86:89]
	v_mfma_f32_16x16x32_bf16 v[86:89], v[134:137], v[206:209], v[86:89]
	s_setprio 0
	s_setprio 1
	v_mfma_f32_16x16x32_bf16 v[110:113], v[146:149], v[166:169], v[110:113]
	v_mfma_f32_16x16x32_bf16 v[110:113], v[150:153], v[170:173], v[110:113]
	v_mfma_f32_16x16x32_bf16 v[106:109], v[154:157], v[166:169], v[106:109]
	v_mfma_f32_16x16x32_bf16 v[106:109], v[158:161], v[170:173], v[106:109]
	v_mfma_f32_16x16x32_bf16 v[98:101], v[154:157], v[186:189], v[98:101]
	v_mfma_f32_16x16x32_bf16 v[98:101], v[158:161], v[190:193], v[98:101]
	v_mfma_f32_16x16x32_bf16 v[102:105], v[146:149], v[186:189], v[102:105]
	v_mfma_f32_16x16x32_bf16 v[102:105], v[150:153], v[190:193], v[102:105]
	v_mfma_f32_16x16x32_bf16 v[82:85], v[146:149], v[194:197], v[82:85]
	v_mfma_f32_16x16x32_bf16 v[82:85], v[150:153], v[198:201], v[82:85]
	v_mfma_f32_16x16x32_bf16 v[74:77], v[154:157], v[194:197], v[74:77]
	v_mfma_f32_16x16x32_bf16 v[74:77], v[158:161], v[198:201], v[74:77]
	v_mfma_f32_16x16x32_bf16 v[66:69], v[154:157], v[202:205], v[66:69]
	v_mfma_f32_16x16x32_bf16 v[66:69], v[158:161], v[206:209], v[66:69]
	s_setprio 2
	s_barrier
	v_mfma_f32_16x16x32_bf16 v[70:73], v[146:149], v[202:205], v[70:73]
	v_mfma_f32_16x16x32_bf16 v[70:73], v[150:153], v[206:209], v[70:73]
	s_setprio 0
	ds_read_b128 v[166:169], v183 offset:16384
	ds_read_b128 v[170:173], v183 offset:17408
	ds_read_b128 v[186:189], v183 offset:18432
	ds_read_b128 v[190:193], v183 offset:19456
	ds_read_b128 v[194:197], v183 offset:20480
	ds_read_b128 v[198:201], v183 offset:21504
	ds_read_b128 v[202:205], v183 offset:22528
	ds_read_b128 v[206:209], v183 offset:23552
	s_mov_b32 s79, m0
	s_mov_b32 m0, s35
	s_nop 0
	global_load_lds_dwordx4 v176, s[22:23]
	s_mov_b32 m0, s79
	s_add_u32 s80, s22, 0x80000
	s_mov_b32 s79, m0
	s_mov_b32 m0, s36
	s_nop 0
	global_load_lds_dwordx4 v178, s[22:23]
	s_mov_b32 m0, s79
	s_addc_u32 s81, s23, 0
	s_mov_b32 s79, m0
	s_mov_b32 m0, s37
	s_nop 0
	global_load_lds_dwordx4 v176, s[80:81]
	s_mov_b32 m0, s79
	s_nop 0
	s_mov_b32 s79, m0
	s_mov_b32 m0, s40
	s_nop 0
	global_load_lds_dwordx4 v178, s[80:81]
	s_mov_b32 m0, s79
	s_waitcnt vmcnt(4)
	s_waitcnt lgkmcnt(0)
	s_waitcnt lgkmcnt(7)
	v_mfma_f32_16x16x32_bf16 v[62:65], v[130:133], v[166:169], v[62:65]
	v_mfma_f32_16x16x32_bf16 v[62:65], v[134:137], v[170:173], v[62:65]
	s_waitcnt lgkmcnt(5)
	v_mfma_f32_16x16x32_bf16 v[58:61], v[138:141], v[166:169], v[58:61]
	v_mfma_f32_16x16x32_bf16 v[58:61], v[142:145], v[170:173], v[58:61]
	s_barrier
	s_setprio 1
	s_waitcnt lgkmcnt(3)
	v_mfma_f32_16x16x32_bf16 v[42:45], v[138:141], v[186:189], v[42:45]
	v_mfma_f32_16x16x32_bf16 v[42:45], v[142:145], v[190:193], v[42:45]
	s_waitcnt lgkmcnt(1)
	v_mfma_f32_16x16x32_bf16 v[46:49], v[130:133], v[186:189], v[46:49]
	v_mfma_f32_16x16x32_bf16 v[46:49], v[134:137], v[190:193], v[46:49]
	v_mfma_f32_16x16x32_bf16 v[30:33], v[130:133], v[194:197], v[30:33]
	v_mfma_f32_16x16x32_bf16 v[30:33], v[134:137], v[198:201], v[30:33]
	v_mfma_f32_16x16x32_bf16 v[26:29], v[138:141], v[194:197], v[26:29]
	v_mfma_f32_16x16x32_bf16 v[26:29], v[142:145], v[198:201], v[26:29]
	v_mfma_f32_16x16x32_bf16 v[10:13], v[138:141], v[202:205], v[10:13]
	v_mfma_f32_16x16x32_bf16 v[10:13], v[142:145], v[206:209], v[10:13]
	s_waitcnt lgkmcnt(0)
	v_mfma_f32_16x16x32_bf16 v[14:17], v[130:133], v[202:205], v[14:17]
	v_mfma_f32_16x16x32_bf16 v[14:17], v[134:137], v[206:209], v[14:17]
	s_setprio 0
	s_setprio 1
	v_mfma_f32_16x16x32_bf16 v[54:57], v[146:149], v[166:169], v[54:57]
	v_mfma_f32_16x16x32_bf16 v[54:57], v[150:153], v[170:173], v[54:57]
	v_mfma_f32_16x16x32_bf16 v[50:53], v[154:157], v[166:169], v[50:53]
	v_mfma_f32_16x16x32_bf16 v[50:53], v[158:161], v[170:173], v[50:53]
	v_mfma_f32_16x16x32_bf16 v[34:37], v[154:157], v[186:189], v[34:37]
	v_mfma_f32_16x16x32_bf16 v[34:37], v[158:161], v[190:193], v[34:37]
	v_mfma_f32_16x16x32_bf16 v[38:41], v[146:149], v[186:189], v[38:41]
	v_mfma_f32_16x16x32_bf16 v[38:41], v[150:153], v[190:193], v[38:41]
	v_mfma_f32_16x16x32_bf16 v[22:25], v[146:149], v[194:197], v[22:25]
	v_mfma_f32_16x16x32_bf16 v[22:25], v[150:153], v[198:201], v[22:25]
	v_mfma_f32_16x16x32_bf16 v[18:21], v[154:157], v[194:197], v[18:21]
	v_mfma_f32_16x16x32_bf16 v[18:21], v[158:161], v[198:201], v[18:21]
	v_mfma_f32_16x16x32_bf16 v[2:5], v[154:157], v[202:205], v[2:5]
	v_mfma_f32_16x16x32_bf16 v[2:5], v[158:161], v[206:209], v[2:5]
	s_setprio 2
	s_barrier
	v_mfma_f32_16x16x32_bf16 v[6:9], v[146:149], v[202:205], v[6:9]
	v_mfma_f32_16x16x32_bf16 v[6:9], v[150:153], v[206:209], v[6:9]
	s_setprio 0
	ds_read_b128 v[130:133], v184
	ds_read_b128 v[134:137], v184 offset:1024
	ds_read_b128 v[138:141], v184 offset:2048
	ds_read_b128 v[142:145], v184 offset:3072
	ds_read_b128 v[146:149], v185
	ds_read_b128 v[150:153], v185 offset:1024
	ds_read_b128 v[154:157], v185 offset:2048
	ds_read_b128 v[158:161], v185 offset:3072
	ds_read_b128 v[166:169], v183 offset:32768
	ds_read_b128 v[170:173], v183 offset:33792
	ds_read_b128 v[186:189], v183 offset:34816
	ds_read_b128 v[190:193], v183 offset:35840
	ds_read_b128 v[194:197], v183 offset:36864
	ds_read_b128 v[198:201], v183 offset:37888
	ds_read_b128 v[202:205], v183 offset:38912
	ds_read_b128 v[206:209], v183 offset:39936
	s_mov_b32 s79, m0
	s_mov_b32 m0, s34
	s_nop 0
	global_load_lds_dwordx4 v1, s[24:25]
	s_mov_b32 m0, s79
	s_nop 0
	s_mov_b32 s79, m0
	s_mov_b32 m0, s41
	s_nop 0
	global_load_lds_dwordx4 v177, s[24:25]
	s_mov_b32 m0, s79
	s_add_u32 s24, s24, 0x80000
	s_addc_u32 s25, s25, 0
	s_mov_b32 s79, m0
	s_mov_b32 m0, s42
	s_nop 0
	global_load_lds_dwordx4 v1, s[24:25]
	s_mov_b32 m0, s79
	s_nop 0
	s_mov_b32 s79, m0
	s_mov_b32 m0, s43
	s_nop 0
	global_load_lds_dwordx4 v177, s[24:25]
	s_mov_b32 m0, s79
	s_waitcnt vmcnt(8)
	s_waitcnt lgkmcnt(0)
	s_waitcnt lgkmcnt(7)
	v_mfma_f32_16x16x32_bf16 v[126:129], v[130:133], v[166:169], v[126:129]
	v_mfma_f32_16x16x32_bf16 v[126:129], v[134:137], v[170:173], v[126:129]
	s_waitcnt lgkmcnt(5)
	v_mfma_f32_16x16x32_bf16 v[122:125], v[138:141], v[166:169], v[122:125]
	v_mfma_f32_16x16x32_bf16 v[122:125], v[142:145], v[170:173], v[122:125]
	s_barrier
	s_setprio 1
	s_waitcnt lgkmcnt(3)
	v_mfma_f32_16x16x32_bf16 v[114:117], v[138:141], v[186:189], v[114:117]
	v_mfma_f32_16x16x32_bf16 v[114:117], v[142:145], v[190:193], v[114:117]
	s_waitcnt lgkmcnt(1)
	v_mfma_f32_16x16x32_bf16 v[118:121], v[130:133], v[186:189], v[118:121]
	v_mfma_f32_16x16x32_bf16 v[118:121], v[134:137], v[190:193], v[118:121]
	v_mfma_f32_16x16x32_bf16 v[94:97], v[130:133], v[194:197], v[94:97]
	v_mfma_f32_16x16x32_bf16 v[94:97], v[134:137], v[198:201], v[94:97]
	v_mfma_f32_16x16x32_bf16 v[90:93], v[138:141], v[194:197], v[90:93]
	v_mfma_f32_16x16x32_bf16 v[90:93], v[142:145], v[198:201], v[90:93]
	v_mfma_f32_16x16x32_bf16 v[78:81], v[138:141], v[202:205], v[78:81]
	v_mfma_f32_16x16x32_bf16 v[78:81], v[142:145], v[206:209], v[78:81]
	s_waitcnt lgkmcnt(0)
	v_mfma_f32_16x16x32_bf16 v[86:89], v[130:133], v[202:205], v[86:89]
	v_mfma_f32_16x16x32_bf16 v[86:89], v[134:137], v[206:209], v[86:89]
	s_setprio 0
	s_setprio 1
	v_mfma_f32_16x16x32_bf16 v[110:113], v[146:149], v[166:169], v[110:113]
	v_mfma_f32_16x16x32_bf16 v[110:113], v[150:153], v[170:173], v[110:113]
	v_mfma_f32_16x16x32_bf16 v[106:109], v[154:157], v[166:169], v[106:109]
	v_mfma_f32_16x16x32_bf16 v[106:109], v[158:161], v[170:173], v[106:109]
	v_mfma_f32_16x16x32_bf16 v[98:101], v[154:157], v[186:189], v[98:101]
	v_mfma_f32_16x16x32_bf16 v[98:101], v[158:161], v[190:193], v[98:101]
	v_mfma_f32_16x16x32_bf16 v[102:105], v[146:149], v[186:189], v[102:105]
	v_mfma_f32_16x16x32_bf16 v[102:105], v[150:153], v[190:193], v[102:105]
	v_mfma_f32_16x16x32_bf16 v[82:85], v[146:149], v[194:197], v[82:85]
	v_mfma_f32_16x16x32_bf16 v[82:85], v[150:153], v[198:201], v[82:85]
	v_mfma_f32_16x16x32_bf16 v[74:77], v[154:157], v[194:197], v[74:77]
	v_mfma_f32_16x16x32_bf16 v[74:77], v[158:161], v[198:201], v[74:77]
	v_mfma_f32_16x16x32_bf16 v[66:69], v[154:157], v[202:205], v[66:69]
	v_mfma_f32_16x16x32_bf16 v[66:69], v[158:161], v[206:209], v[66:69]
	s_setprio 2
	s_barrier
	v_mfma_f32_16x16x32_bf16 v[70:73], v[146:149], v[202:205], v[70:73]
	v_mfma_f32_16x16x32_bf16 v[70:73], v[150:153], v[206:209], v[70:73]
	s_setprio 0
	ds_read_b128 v[166:169], v183 offset:49152
	ds_read_b128 v[170:173], v183 offset:50176
	ds_read_b128 v[186:189], v183 offset:51200
	ds_read_b128 v[190:193], v183 offset:52224
	ds_read_b128 v[194:197], v183 offset:53248
	ds_read_b128 v[198:201], v183 offset:54272
	ds_read_b128 v[202:205], v183 offset:55296
	ds_read_b128 v[206:209], v183 offset:56320
	s_add_u32 s24, s22, 0x80
	s_addc_u32 s25, s23, 0
	s_mov_b32 s79, m0
	s_mov_b32 m0, s46
	s_nop 0
	global_load_lds_dwordx4 v176, s[24:25]
	s_mov_b32 m0, s79
	s_add_u32 s22, s22, 0x80080
	s_mov_b32 s79, m0
	s_mov_b32 m0, s47
	s_nop 0
	global_load_lds_dwordx4 v178, s[24:25]
	s_mov_b32 m0, s79
	s_addc_u32 s23, s23, 0
	s_mov_b32 s24, m0
	s_mov_b32 m0, s48
	s_nop 0
	global_load_lds_dwordx4 v176, s[22:23]
	s_mov_b32 m0, s24
	s_nop 0
	s_mov_b32 s24, m0
	s_mov_b32 m0, s49
	s_nop 0
	global_load_lds_dwordx4 v178, s[22:23]
	s_mov_b32 m0, s24
	s_waitcnt vmcnt(4)
	s_waitcnt lgkmcnt(0)
	s_waitcnt lgkmcnt(7)
	v_mfma_f32_16x16x32_bf16 v[62:65], v[130:133], v[166:169], v[62:65]
	v_mfma_f32_16x16x32_bf16 v[62:65], v[134:137], v[170:173], v[62:65]
	s_waitcnt lgkmcnt(5)
	v_mfma_f32_16x16x32_bf16 v[58:61], v[138:141], v[166:169], v[58:61]
	v_mfma_f32_16x16x32_bf16 v[58:61], v[142:145], v[170:173], v[58:61]
	s_barrier
	s_setprio 1
	s_waitcnt lgkmcnt(3)
	v_mfma_f32_16x16x32_bf16 v[42:45], v[138:141], v[186:189], v[42:45]
	v_mfma_f32_16x16x32_bf16 v[42:45], v[142:145], v[190:193], v[42:45]
	s_waitcnt lgkmcnt(1)
	v_mfma_f32_16x16x32_bf16 v[46:49], v[130:133], v[186:189], v[46:49]
	v_mfma_f32_16x16x32_bf16 v[46:49], v[134:137], v[190:193], v[46:49]
	v_mfma_f32_16x16x32_bf16 v[30:33], v[130:133], v[194:197], v[30:33]
	v_mfma_f32_16x16x32_bf16 v[30:33], v[134:137], v[198:201], v[30:33]
	v_mfma_f32_16x16x32_bf16 v[26:29], v[138:141], v[194:197], v[26:29]
	v_mfma_f32_16x16x32_bf16 v[26:29], v[142:145], v[198:201], v[26:29]
	v_mfma_f32_16x16x32_bf16 v[10:13], v[138:141], v[202:205], v[10:13]
	v_mfma_f32_16x16x32_bf16 v[10:13], v[142:145], v[206:209], v[10:13]
	s_waitcnt lgkmcnt(0)
	v_mfma_f32_16x16x32_bf16 v[14:17], v[130:133], v[202:205], v[14:17]
	v_mfma_f32_16x16x32_bf16 v[14:17], v[134:137], v[206:209], v[14:17]
	s_setprio 0
	s_setprio 1
	v_mfma_f32_16x16x32_bf16 v[54:57], v[146:149], v[166:169], v[54:57]
	v_mfma_f32_16x16x32_bf16 v[54:57], v[150:153], v[170:173], v[54:57]
	v_mfma_f32_16x16x32_bf16 v[50:53], v[154:157], v[166:169], v[50:53]
	v_mfma_f32_16x16x32_bf16 v[50:53], v[158:161], v[170:173], v[50:53]
	v_mfma_f32_16x16x32_bf16 v[34:37], v[154:157], v[186:189], v[34:37]
	v_mfma_f32_16x16x32_bf16 v[34:37], v[158:161], v[190:193], v[34:37]
	v_mfma_f32_16x16x32_bf16 v[38:41], v[146:149], v[186:189], v[38:41]
	v_mfma_f32_16x16x32_bf16 v[38:41], v[150:153], v[190:193], v[38:41]
	v_mfma_f32_16x16x32_bf16 v[22:25], v[146:149], v[194:197], v[22:25]
	v_mfma_f32_16x16x32_bf16 v[22:25], v[150:153], v[198:201], v[22:25]
	v_mfma_f32_16x16x32_bf16 v[18:21], v[154:157], v[194:197], v[18:21]
	v_mfma_f32_16x16x32_bf16 v[18:21], v[158:161], v[198:201], v[18:21]
	v_mfma_f32_16x16x32_bf16 v[2:5], v[154:157], v[202:205], v[2:5]
	v_mfma_f32_16x16x32_bf16 v[2:5], v[158:161], v[206:209], v[2:5]
	s_setprio 2
	s_barrier
	v_mfma_f32_16x16x32_bf16 v[6:9], v[146:149], v[202:205], v[6:9]
	v_mfma_f32_16x16x32_bf16 v[6:9], v[150:153], v[206:209], v[6:9]
	s_setprio 0
	s_add_i32 s78, s78, 2
	s_add_u32 s74, s74, 0x100
	s_addc_u32 s75, s75, 0
	s_add_u32 s20, s20, 0x100
	s_addc_u32 s21, s21, 0
	s_add_u32 s76, s76, 0x100
	s_addc_u32 s77, s77, 0
	s_cmp_gt_u32 s78, 29
	s_cbranch_scc0 .LBB0_1053
	s_and_b64 vcc, exec, s[8:9]
	s_cbranch_vccz .LBB0_1056
	s_barrier

.LBB0_1223:
	s_ashr_i32 s11, s10, 31
	s_lshl_b64 s[12:13], s[10:11], 20
	s_add_u32 s12, s26, s12
	s_addc_u32 s13, s27, s13
	s_and_b64 s[14:15], s[2:3], exec
	s_cselect_b32 s11, s13, s21
	s_cselect_b32 s66, s12, s20
	s_ashr_i32 s9, s8, 31
	s_lshl_b64 s[14:15], s[8:9], 20
	s_add_u32 s14, s28, s14
	s_addc_u32 s15, s29, s15
	s_and_b64 s[22:23], s[2:3], exec
	s_cselect_b32 s9, s15, s19
	s_cselect_b32 s67, s14, s18
	s_add_u32 s73, s18, 0x100
	s_addc_u32 s74, s19, 0
	s_add_u32 s18, s20, 0x80080
	s_addc_u32 s19, s21, 0
	s_add_u32 s75, s20, 0x100
	s_addc_u32 s76, s21, 0
	s_mov_b32 s77, -2
	ds_read_b128 v[148:151], v143
	ds_read_b128 v[152:155], v143 offset:1024
	ds_read_b128 v[156:159], v143 offset:2048
	ds_read_b128 v[160:163], v143 offset:3072
	ds_read_b128 v[164:167], v144
	ds_read_b128 v[168:171], v144 offset:1024
	ds_read_b128 v[172:175], v144 offset:2048
	ds_read_b128 v[176:179], v144 offset:3072
	s_cmp_eq_u32 s77, 28
	s_cselect_b32 s21, s9, s74
	s_cselect_b32 s20, s67, s73
	s_cselect_b32 s23, s11, s76
	s_cselect_b32 s22, s66, s75
	ds_read_b128 v[180:183], v145
	ds_read_b128 v[184:187], v145 offset:1024
	ds_read_b128 v[188:191], v145 offset:2048
	ds_read_b128 v[192:195], v145 offset:3072
	ds_read_b128 v[196:199], v145 offset:4096
	ds_read_b128 v[200:203], v145 offset:5120
	ds_read_b128 v[204:207], v145 offset:6144
	ds_read_b128 v[208:211], v145 offset:7168
	s_add_u32 s78, s18, 0xfff80000
	s_addc_u32 s79, s19, -1
	s_mov_b32 s80, m0
	s_mov_b32 m0, s56
	s_nop 0
	global_load_lds_dwordx4 v138, s[78:79]
	s_mov_b32 m0, s80
	s_nop 0
	s_mov_b32 s80, m0
	s_mov_b32 m0, s59
	s_nop 0
	global_load_lds_dwordx4 v140, s[78:79]
	s_mov_b32 m0, s80
	s_mov_b32 s78, m0
	s_mov_b32 m0, s57
	s_nop 0
	global_load_lds_dwordx4 v138, s[18:19]
	s_mov_b32 m0, s78
	s_nop 0
	s_mov_b32 s78, m0
	s_mov_b32 m0, s64
	s_nop 0
	global_load_lds_dwordx4 v140, s[18:19]
	s_mov_b32 m0, s78
	s_waitcnt vmcnt(8)
	s_waitcnt lgkmcnt(0)
	s_waitcnt lgkmcnt(7)
	v_mfma_f32_16x16x32_bf16 v[126:129], v[148:151], v[180:183], 0
	v_mfma_f32_16x16x32_bf16 v[126:129], v[152:155], v[184:187], v[126:129]
	s_waitcnt lgkmcnt(5)
	v_mfma_f32_16x16x32_bf16 v[122:125], v[156:159], v[180:183], 0
	v_mfma_f32_16x16x32_bf16 v[122:125], v[160:163], v[184:187], v[122:125]
	s_barrier
	s_setprio 1
	s_waitcnt lgkmcnt(3)
	v_mfma_f32_16x16x32_bf16 v[106:109], v[156:159], v[188:191], 0
	v_mfma_f32_16x16x32_bf16 v[106:109], v[160:163], v[192:195], v[106:109]
	s_waitcnt lgkmcnt(1)
	v_mfma_f32_16x16x32_bf16 v[110:113], v[148:151], v[188:191], 0
	v_mfma_f32_16x16x32_bf16 v[110:113], v[152:155], v[192:195], v[110:113]
	v_mfma_f32_16x16x32_bf16 v[94:97], v[148:151], v[196:199], 0
	v_mfma_f32_16x16x32_bf16 v[94:97], v[152:155], v[200:203], v[94:97]
	v_mfma_f32_16x16x32_bf16 v[90:93], v[156:159], v[196:199], 0
	v_mfma_f32_16x16x32_bf16 v[90:93], v[160:163], v[200:203], v[90:93]
	v_mfma_f32_16x16x32_bf16 v[74:77], v[156:159], v[204:207], 0
	v_mfma_f32_16x16x32_bf16 v[74:77], v[160:163], v[208:211], v[74:77]
	s_waitcnt lgkmcnt(0)
	v_mfma_f32_16x16x32_bf16 v[78:81], v[148:151], v[204:207], 0
	v_mfma_f32_16x16x32_bf16 v[78:81], v[152:155], v[208:211], v[78:81]
	s_setprio 0
	s_setprio 1
	v_mfma_f32_16x16x32_bf16 v[118:121], v[164:167], v[180:183], 0
	v_mfma_f32_16x16x32_bf16 v[118:121], v[168:171], v[184:187], v[118:121]
	v_mfma_f32_16x16x32_bf16 v[114:117], v[172:175], v[180:183], 0
	v_mfma_f32_16x16x32_bf16 v[114:117], v[176:179], v[184:187], v[114:117]
	v_mfma_f32_16x16x32_bf16 v[98:101], v[172:175], v[188:191], 0
	v_mfma_f32_16x16x32_bf16 v[98:101], v[176:179], v[192:195], v[98:101]
	v_mfma_f32_16x16x32_bf16 v[102:105], v[164:167], v[188:191], 0
	v_mfma_f32_16x16x32_bf16 v[102:105], v[168:171], v[192:195], v[102:105]
	v_mfma_f32_16x16x32_bf16 v[86:89], v[164:167], v[196:199], 0
	v_mfma_f32_16x16x32_bf16 v[86:89], v[168:171], v[200:203], v[86:89]
	v_mfma_f32_16x16x32_bf16 v[82:85], v[172:175], v[196:199], 0
	v_mfma_f32_16x16x32_bf16 v[82:85], v[176:179], v[200:203], v[82:85]
	v_mfma_f32_16x16x32_bf16 v[66:69], v[172:175], v[204:207], 0
	v_mfma_f32_16x16x32_bf16 v[66:69], v[176:179], v[208:211], v[66:69]
	s_setprio 2
	s_barrier
	v_mfma_f32_16x16x32_bf16 v[70:73], v[164:167], v[204:207], 0
	v_mfma_f32_16x16x32_bf16 v[70:73], v[168:171], v[208:211], v[70:73]
	s_setprio 0
	ds_read_b128 v[180:183], v145 offset:16384
	ds_read_b128 v[184:187], v145 offset:17408
	ds_read_b128 v[188:191], v145 offset:18432
	ds_read_b128 v[192:195], v145 offset:19456
	ds_read_b128 v[196:199], v145 offset:20480
	ds_read_b128 v[200:203], v145 offset:21504
	ds_read_b128 v[204:207], v145 offset:22528
	ds_read_b128 v[208:211], v145 offset:23552
	s_mov_b32 s78, m0
	s_mov_b32 m0, s35
	s_nop 0
	global_load_lds_dwordx4 v139, s[20:21]
	s_mov_b32 m0, s78
	s_nop 0
	s_mov_b32 s78, m0
	s_mov_b32 m0, s36
	s_nop 0
	global_load_lds_dwordx4 v141, s[20:21]
	s_mov_b32 m0, s78
	s_add_u32 s78, s20, 0x80000
	s_addc_u32 s79, s21, 0
	s_mov_b32 s80, m0
	s_mov_b32 m0, s37
	s_nop 0
	global_load_lds_dwordx4 v139, s[78:79]
	s_mov_b32 m0, s80
	s_nop 0
	s_mov_b32 s80, m0
	s_mov_b32 m0, s40
	s_nop 0
	global_load_lds_dwordx4 v141, s[78:79]
	s_mov_b32 m0, s80
	s_waitcnt vmcnt(4)
	s_waitcnt lgkmcnt(0)
	s_waitcnt lgkmcnt(7)
	v_mfma_f32_16x16x32_bf16 v[62:65], v[148:151], v[180:183], 0
	v_mfma_f32_16x16x32_bf16 v[62:65], v[152:155], v[184:187], v[62:65]
	s_waitcnt lgkmcnt(5)
	v_mfma_f32_16x16x32_bf16 v[58:61], v[156:159], v[180:183], 0
	v_mfma_f32_16x16x32_bf16 v[58:61], v[160:163], v[184:187], v[58:61]
	s_barrier
	s_setprio 1
	s_waitcnt lgkmcnt(3)
	v_mfma_f32_16x16x32_bf16 v[42:45], v[156:159], v[188:191], 0
	v_mfma_f32_16x16x32_bf16 v[42:45], v[160:163], v[192:195], v[42:45]
	s_waitcnt lgkmcnt(1)
	v_mfma_f32_16x16x32_bf16 v[46:49], v[148:151], v[188:191], 0
	v_mfma_f32_16x16x32_bf16 v[46:49], v[152:155], v[192:195], v[46:49]
	v_mfma_f32_16x16x32_bf16 v[30:33], v[148:151], v[196:199], 0
	v_mfma_f32_16x16x32_bf16 v[30:33], v[152:155], v[200:203], v[30:33]
	v_mfma_f32_16x16x32_bf16 v[26:29], v[156:159], v[196:199], 0
	v_mfma_f32_16x16x32_bf16 v[26:29], v[160:163], v[200:203], v[26:29]
	v_mfma_f32_16x16x32_bf16 v[10:13], v[156:159], v[204:207], 0
	v_mfma_f32_16x16x32_bf16 v[10:13], v[160:163], v[208:211], v[10:13]
	s_waitcnt lgkmcnt(0)
	v_mfma_f32_16x16x32_bf16 v[14:17], v[148:151], v[204:207], 0
	v_mfma_f32_16x16x32_bf16 v[14:17], v[152:155], v[208:211], v[14:17]
	s_setprio 0
	s_setprio 1
	v_mfma_f32_16x16x32_bf16 v[54:57], v[164:167], v[180:183], 0
	v_mfma_f32_16x16x32_bf16 v[54:57], v[168:171], v[184:187], v[54:57]
	v_mfma_f32_16x16x32_bf16 v[50:53], v[172:175], v[180:183], 0
	v_mfma_f32_16x16x32_bf16 v[50:53], v[176:179], v[184:187], v[50:53]
	v_mfma_f32_16x16x32_bf16 v[34:37], v[172:175], v[188:191], 0
	v_mfma_f32_16x16x32_bf16 v[34:37], v[176:179], v[192:195], v[34:37]
	v_mfma_f32_16x16x32_bf16 v[38:41], v[164:167], v[188:191], 0
	v_mfma_f32_16x16x32_bf16 v[38:41], v[168:171], v[192:195], v[38:41]
	v_mfma_f32_16x16x32_bf16 v[22:25], v[164:167], v[196:199], 0
	v_mfma_f32_16x16x32_bf16 v[22:25], v[168:171], v[200:203], v[22:25]
	v_mfma_f32_16x16x32_bf16 v[18:21], v[172:175], v[196:199], 0
	v_mfma_f32_16x16x32_bf16 v[18:21], v[176:179], v[200:203], v[18:21]
	v_mfma_f32_16x16x32_bf16 v[2:5], v[172:175], v[204:207], 0
	v_mfma_f32_16x16x32_bf16 v[2:5], v[176:179], v[208:211], v[2:5]
	s_setprio 2
	s_barrier
	v_mfma_f32_16x16x32_bf16 v[6:9], v[164:167], v[204:207], 0
	v_mfma_f32_16x16x32_bf16 v[6:9], v[168:171], v[208:211], v[6:9]
	s_setprio 0
	ds_read_b128 v[148:151], v146
	ds_read_b128 v[152:155], v146 offset:1024
	ds_read_b128 v[156:159], v146 offset:2048
	ds_read_b128 v[160:163], v146 offset:3072
	ds_read_b128 v[164:167], v147
	ds_read_b128 v[168:171], v147 offset:1024
	ds_read_b128 v[172:175], v147 offset:2048
	ds_read_b128 v[176:179], v147 offset:3072
	ds_read_b128 v[180:183], v145 offset:32768
	ds_read_b128 v[184:187], v145 offset:33792
	ds_read_b128 v[188:191], v145 offset:34816
	ds_read_b128 v[192:195], v145 offset:35840
	ds_read_b128 v[196:199], v145 offset:36864
	ds_read_b128 v[200:203], v145 offset:37888
	ds_read_b128 v[204:207], v145 offset:38912
	ds_read_b128 v[208:211], v145 offset:39936
	s_mov_b32 s78, m0
	s_mov_b32 m0, s31
	s_nop 0
	global_load_lds_dwordx4 v138, s[22:23]
	s_mov_b32 m0, s78
	s_nop 0
	s_mov_b32 s78, m0
	s_mov_b32 m0, s41
	s_nop 0
	global_load_lds_dwordx4 v140, s[22:23]
	s_mov_b32 m0, s78
	s_add_u32 s22, s22, 0x80000
	s_addc_u32 s23, s23, 0
	s_mov_b32 s78, m0
	s_mov_b32 m0, s42
	s_nop 0
	global_load_lds_dwordx4 v138, s[22:23]
	s_mov_b32 m0, s78
	s_nop 0
	s_mov_b32 s78, m0
	s_mov_b32 m0, s43
	s_nop 0
	global_load_lds_dwordx4 v140, s[22:23]
	s_mov_b32 m0, s78
	s_waitcnt vmcnt(8)
	s_waitcnt lgkmcnt(0)
	s_waitcnt lgkmcnt(7)
	v_mfma_f32_16x16x32_bf16 v[126:129], v[148:151], v[180:183], v[126:129]
	v_mfma_f32_16x16x32_bf16 v[126:129], v[152:155], v[184:187], v[126:129]
	s_waitcnt lgkmcnt(5)
	v_mfma_f32_16x16x32_bf16 v[122:125], v[156:159], v[180:183], v[122:125]
	v_mfma_f32_16x16x32_bf16 v[122:125], v[160:163], v[184:187], v[122:125]
	s_barrier
	s_setprio 1
	s_waitcnt lgkmcnt(3)
	v_mfma_f32_16x16x32_bf16 v[106:109], v[156:159], v[188:191], v[106:109]
	v_mfma_f32_16x16x32_bf16 v[106:109], v[160:163], v[192:195], v[106:109]
	s_waitcnt lgkmcnt(1)
	v_mfma_f32_16x16x32_bf16 v[110:113], v[148:151], v[188:191], v[110:113]
	v_mfma_f32_16x16x32_bf16 v[110:113], v[152:155], v[192:195], v[110:113]
	v_mfma_f32_16x16x32_bf16 v[94:97], v[148:151], v[196:199], v[94:97]
	v_mfma_f32_16x16x32_bf16 v[94:97], v[152:155], v[200:203], v[94:97]
	v_mfma_f32_16x16x32_bf16 v[90:93], v[156:159], v[196:199], v[90:93]
	v_mfma_f32_16x16x32_bf16 v[90:93], v[160:163], v[200:203], v[90:93]
	v_mfma_f32_16x16x32_bf16 v[74:77], v[156:159], v[204:207], v[74:77]
	v_mfma_f32_16x16x32_bf16 v[74:77], v[160:163], v[208:211], v[74:77]
	s_waitcnt lgkmcnt(0)
	v_mfma_f32_16x16x32_bf16 v[78:81], v[148:151], v[204:207], v[78:81]
	v_mfma_f32_16x16x32_bf16 v[78:81], v[152:155], v[208:211], v[78:81]
	s_setprio 0
	s_setprio 1
	v_mfma_f32_16x16x32_bf16 v[118:121], v[164:167], v[180:183], v[118:121]
	v_mfma_f32_16x16x32_bf16 v[118:121], v[168:171], v[184:187], v[118:121]
	v_mfma_f32_16x16x32_bf16 v[114:117], v[172:175], v[180:183], v[114:117]
	v_mfma_f32_16x16x32_bf16 v[114:117], v[176:179], v[184:187], v[114:117]
	v_mfma_f32_16x16x32_bf16 v[98:101], v[172:175], v[188:191], v[98:101]
	v_mfma_f32_16x16x32_bf16 v[98:101], v[176:179], v[192:195], v[98:101]
	v_mfma_f32_16x16x32_bf16 v[102:105], v[164:167], v[188:191], v[102:105]
	v_mfma_f32_16x16x32_bf16 v[102:105], v[168:171], v[192:195], v[102:105]
	v_mfma_f32_16x16x32_bf16 v[86:89], v[164:167], v[196:199], v[86:89]
	v_mfma_f32_16x16x32_bf16 v[86:89], v[168:171], v[200:203], v[86:89]
	v_mfma_f32_16x16x32_bf16 v[82:85], v[172:175], v[196:199], v[82:85]
	v_mfma_f32_16x16x32_bf16 v[82:85], v[176:179], v[200:203], v[82:85]
	v_mfma_f32_16x16x32_bf16 v[66:69], v[172:175], v[204:207], v[66:69]
	v_mfma_f32_16x16x32_bf16 v[66:69], v[176:179], v[208:211], v[66:69]
	s_setprio 2
	s_barrier
	v_mfma_f32_16x16x32_bf16 v[70:73], v[164:167], v[204:207], v[70:73]
	v_mfma_f32_16x16x32_bf16 v[70:73], v[168:171], v[208:211], v[70:73]
	s_setprio 0
	ds_read_b128 v[180:183], v145 offset:49152
	ds_read_b128 v[184:187], v145 offset:50176
	ds_read_b128 v[188:191], v145 offset:51200
	ds_read_b128 v[192:195], v145 offset:52224
	ds_read_b128 v[196:199], v145 offset:53248
	ds_read_b128 v[200:203], v145 offset:54272
	ds_read_b128 v[204:207], v145 offset:55296
	ds_read_b128 v[208:211], v145 offset:56320
	s_add_u32 s22, s20, 0x80
	s_addc_u32 s23, s21, 0
	s_mov_b32 s78, m0
	s_mov_b32 m0, s46
	s_nop 0
	global_load_lds_dwordx4 v139, s[22:23]
	s_mov_b32 m0, s78
	s_add_u32 s20, s20, 0x80080
	s_mov_b32 s78, m0
	s_mov_b32 m0, s47
	s_nop 0
	global_load_lds_dwordx4 v141, s[22:23]
	s_mov_b32 m0, s78
	s_addc_u32 s21, s21, 0
	s_mov_b32 s22, m0
	s_mov_b32 m0, s48
	s_nop 0
	global_load_lds_dwordx4 v139, s[20:21]
	s_mov_b32 m0, s22
	s_nop 0
	s_mov_b32 s22, m0
	s_mov_b32 m0, s49
	s_nop 0
	global_load_lds_dwordx4 v141, s[20:21]
	s_mov_b32 m0, s22
	s_waitcnt vmcnt(4)
	s_waitcnt lgkmcnt(0)
	s_waitcnt lgkmcnt(7)
	v_mfma_f32_16x16x32_bf16 v[62:65], v[148:151], v[180:183], v[62:65]
	v_mfma_f32_16x16x32_bf16 v[62:65], v[152:155], v[184:187], v[62:65]
	s_waitcnt lgkmcnt(5)
	v_mfma_f32_16x16x32_bf16 v[58:61], v[156:159], v[180:183], v[58:61]
	v_mfma_f32_16x16x32_bf16 v[58:61], v[160:163], v[184:187], v[58:61]
	s_barrier
	s_setprio 1
	s_waitcnt lgkmcnt(3)
	v_mfma_f32_16x16x32_bf16 v[42:45], v[156:159], v[188:191], v[42:45]
	v_mfma_f32_16x16x32_bf16 v[42:45], v[160:163], v[192:195], v[42:45]
	s_waitcnt lgkmcnt(1)
	v_mfma_f32_16x16x32_bf16 v[46:49], v[148:151], v[188:191], v[46:49]
	v_mfma_f32_16x16x32_bf16 v[46:49], v[152:155], v[192:195], v[46:49]
	v_mfma_f32_16x16x32_bf16 v[30:33], v[148:151], v[196:199], v[30:33]
	v_mfma_f32_16x16x32_bf16 v[30:33], v[152:155], v[200:203], v[30:33]
	v_mfma_f32_16x16x32_bf16 v[26:29], v[156:159], v[196:199], v[26:29]
	v_mfma_f32_16x16x32_bf16 v[26:29], v[160:163], v[200:203], v[26:29]
	v_mfma_f32_16x16x32_bf16 v[10:13], v[156:159], v[204:207], v[10:13]
	v_mfma_f32_16x16x32_bf16 v[10:13], v[160:163], v[208:211], v[10:13]
	s_waitcnt lgkmcnt(0)
	v_mfma_f32_16x16x32_bf16 v[14:17], v[148:151], v[204:207], v[14:17]
	v_mfma_f32_16x16x32_bf16 v[14:17], v[152:155], v[208:211], v[14:17]
	s_setprio 0
	s_setprio 1
	v_mfma_f32_16x16x32_bf16 v[54:57], v[164:167], v[180:183], v[54:57]
	v_mfma_f32_16x16x32_bf16 v[54:57], v[168:171], v[184:187], v[54:57]
	v_mfma_f32_16x16x32_bf16 v[50:53], v[172:175], v[180:183], v[50:53]
	v_mfma_f32_16x16x32_bf16 v[50:53], v[176:179], v[184:187], v[50:53]
	v_mfma_f32_16x16x32_bf16 v[34:37], v[172:175], v[188:191], v[34:37]
	v_mfma_f32_16x16x32_bf16 v[34:37], v[176:179], v[192:195], v[34:37]
	v_mfma_f32_16x16x32_bf16 v[38:41], v[164:167], v[188:191], v[38:41]
	v_mfma_f32_16x16x32_bf16 v[38:41], v[168:171], v[192:195], v[38:41]
	v_mfma_f32_16x16x32_bf16 v[22:25], v[164:167], v[196:199], v[22:25]
	v_mfma_f32_16x16x32_bf16 v[22:25], v[168:171], v[200:203], v[22:25]
	v_mfma_f32_16x16x32_bf16 v[18:21], v[172:175], v[196:199], v[18:21]
	v_mfma_f32_16x16x32_bf16 v[18:21], v[176:179], v[200:203], v[18:21]
	v_mfma_f32_16x16x32_bf16 v[2:5], v[172:175], v[204:207], v[2:5]
	v_mfma_f32_16x16x32_bf16 v[2:5], v[176:179], v[208:211], v[2:5]
	s_setprio 2
	s_barrier
	v_mfma_f32_16x16x32_bf16 v[6:9], v[164:167], v[204:207], v[6:9]
	v_mfma_f32_16x16x32_bf16 v[6:9], v[168:171], v[208:211], v[6:9]
	s_setprio 0
	s_add_i32 s77, s77, 2
	s_add_u32 s73, s73, 0x100
	s_addc_u32 s74, s74, 0
	s_add_u32 s18, s18, 0x100
	s_addc_u32 s19, s19, 0
	s_add_u32 s75, s75, 0x100
	s_addc_u32 s76, s76, 0
	s_cmp_gt_u32 s77, 29
	.p2align 6
.LBB0_1224:
	ds_read_b128 v[148:151], v143
	ds_read_b128 v[152:155], v143 offset:1024
	ds_read_b128 v[156:159], v143 offset:2048
	ds_read_b128 v[160:163], v143 offset:3072
	ds_read_b128 v[164:167], v144
	ds_read_b128 v[168:171], v144 offset:1024
	ds_read_b128 v[172:175], v144 offset:2048
	ds_read_b128 v[176:179], v144 offset:3072
	s_cmp_eq_u32 s77, 28
	s_cselect_b32 s21, s9, s74
	s_cselect_b32 s20, s67, s73
	s_cselect_b32 s23, s11, s76
	s_cselect_b32 s22, s66, s75
	ds_read_b128 v[180:183], v145
	ds_read_b128 v[184:187], v145 offset:1024
	ds_read_b128 v[188:191], v145 offset:2048
	ds_read_b128 v[192:195], v145 offset:3072
	ds_read_b128 v[196:199], v145 offset:4096
	ds_read_b128 v[200:203], v145 offset:5120
	ds_read_b128 v[204:207], v145 offset:6144
	ds_read_b128 v[208:211], v145 offset:7168
	s_add_u32 s78, s18, 0xfff80000
	s_addc_u32 s79, s19, -1
	s_mov_b32 s80, m0
	s_mov_b32 m0, s56
	s_nop 0
	global_load_lds_dwordx4 v138, s[78:79]
	s_mov_b32 m0, s80
	s_nop 0
	s_mov_b32 s80, m0
	s_mov_b32 m0, s59
	s_nop 0
	global_load_lds_dwordx4 v140, s[78:79]
	s_mov_b32 m0, s80
	s_mov_b32 s78, m0
	s_mov_b32 m0, s57
	s_nop 0
	global_load_lds_dwordx4 v138, s[18:19]
	s_mov_b32 m0, s78
	s_nop 0
	s_mov_b32 s78, m0
	s_mov_b32 m0, s64
	s_nop 0
	global_load_lds_dwordx4 v140, s[18:19]
	s_mov_b32 m0, s78
	s_waitcnt vmcnt(8)
	s_waitcnt lgkmcnt(0)
	s_waitcnt lgkmcnt(7)
	v_mfma_f32_16x16x32_bf16 v[126:129], v[148:151], v[180:183], v[126:129]
	v_mfma_f32_16x16x32_bf16 v[126:129], v[152:155], v[184:187], v[126:129]
	s_waitcnt lgkmcnt(5)
	v_mfma_f32_16x16x32_bf16 v[122:125], v[156:159], v[180:183], v[122:125]
	v_mfma_f32_16x16x32_bf16 v[122:125], v[160:163], v[184:187], v[122:125]
	s_barrier
	s_setprio 1
	s_waitcnt lgkmcnt(3)
	v_mfma_f32_16x16x32_bf16 v[106:109], v[156:159], v[188:191], v[106:109]
	v_mfma_f32_16x16x32_bf16 v[106:109], v[160:163], v[192:195], v[106:109]
	s_waitcnt lgkmcnt(1)
	v_mfma_f32_16x16x32_bf16 v[110:113], v[148:151], v[188:191], v[110:113]
	v_mfma_f32_16x16x32_bf16 v[110:113], v[152:155], v[192:195], v[110:113]
	v_mfma_f32_16x16x32_bf16 v[94:97], v[148:151], v[196:199], v[94:97]
	v_mfma_f32_16x16x32_bf16 v[94:97], v[152:155], v[200:203], v[94:97]
	v_mfma_f32_16x16x32_bf16 v[90:93], v[156:159], v[196:199], v[90:93]
	v_mfma_f32_16x16x32_bf16 v[90:93], v[160:163], v[200:203], v[90:93]
	v_mfma_f32_16x16x32_bf16 v[74:77], v[156:159], v[204:207], v[74:77]
	v_mfma_f32_16x16x32_bf16 v[74:77], v[160:163], v[208:211], v[74:77]
	s_waitcnt lgkmcnt(0)
	v_mfma_f32_16x16x32_bf16 v[78:81], v[148:151], v[204:207], v[78:81]
	v_mfma_f32_16x16x32_bf16 v[78:81], v[152:155], v[208:211], v[78:81]
	s_setprio 0
	s_setprio 1
	v_mfma_f32_16x16x32_bf16 v[118:121], v[164:167], v[180:183], v[118:121]
	v_mfma_f32_16x16x32_bf16 v[118:121], v[168:171], v[184:187], v[118:121]
	v_mfma_f32_16x16x32_bf16 v[114:117], v[172:175], v[180:183], v[114:117]
	v_mfma_f32_16x16x32_bf16 v[114:117], v[176:179], v[184:187], v[114:117]
	v_mfma_f32_16x16x32_bf16 v[98:101], v[172:175], v[188:191], v[98:101]
	v_mfma_f32_16x16x32_bf16 v[98:101], v[176:179], v[192:195], v[98:101]
	v_mfma_f32_16x16x32_bf16 v[102:105], v[164:167], v[188:191], v[102:105]
	v_mfma_f32_16x16x32_bf16 v[102:105], v[168:171], v[192:195], v[102:105]
	v_mfma_f32_16x16x32_bf16 v[86:89], v[164:167], v[196:199], v[86:89]
	v_mfma_f32_16x16x32_bf16 v[86:89], v[168:171], v[200:203], v[86:89]
	v_mfma_f32_16x16x32_bf16 v[82:85], v[172:175], v[196:199], v[82:85]
	v_mfma_f32_16x16x32_bf16 v[82:85], v[176:179], v[200:203], v[82:85]
	v_mfma_f32_16x16x32_bf16 v[66:69], v[172:175], v[204:207], v[66:69]
	v_mfma_f32_16x16x32_bf16 v[66:69], v[176:179], v[208:211], v[66:69]
	s_setprio 2
	s_barrier
	v_mfma_f32_16x16x32_bf16 v[70:73], v[164:167], v[204:207], v[70:73]
	v_mfma_f32_16x16x32_bf16 v[70:73], v[168:171], v[208:211], v[70:73]
	s_setprio 0
	ds_read_b128 v[180:183], v145 offset:16384
	ds_read_b128 v[184:187], v145 offset:17408
	ds_read_b128 v[188:191], v145 offset:18432
	ds_read_b128 v[192:195], v145 offset:19456
	ds_read_b128 v[196:199], v145 offset:20480
	ds_read_b128 v[200:203], v145 offset:21504
	ds_read_b128 v[204:207], v145 offset:22528
	ds_read_b128 v[208:211], v145 offset:23552
	s_mov_b32 s78, m0
	s_mov_b32 m0, s35
	s_nop 0
	global_load_lds_dwordx4 v139, s[20:21]
	s_mov_b32 m0, s78
	s_nop 0
	s_mov_b32 s78, m0
	s_mov_b32 m0, s36
	s_nop 0
	global_load_lds_dwordx4 v141, s[20:21]
	s_mov_b32 m0, s78
	s_add_u32 s78, s20, 0x80000
	s_addc_u32 s79, s21, 0
	s_mov_b32 s80, m0
	s_mov_b32 m0, s37
	s_nop 0
	global_load_lds_dwordx4 v139, s[78:79]
	s_mov_b32 m0, s80
	s_nop 0
	s_mov_b32 s80, m0
	s_mov_b32 m0, s40
	s_nop 0
	global_load_lds_dwordx4 v141, s[78:79]
	s_mov_b32 m0, s80
	s_waitcnt vmcnt(4)
	s_waitcnt lgkmcnt(0)
	s_waitcnt lgkmcnt(7)
	v_mfma_f32_16x16x32_bf16 v[62:65], v[148:151], v[180:183], v[62:65]
	v_mfma_f32_16x16x32_bf16 v[62:65], v[152:155], v[184:187], v[62:65]
	s_waitcnt lgkmcnt(5)
	v_mfma_f32_16x16x32_bf16 v[58:61], v[156:159], v[180:183], v[58:61]
	v_mfma_f32_16x16x32_bf16 v[58:61], v[160:163], v[184:187], v[58:61]
	s_barrier
	s_setprio 1
	s_waitcnt lgkmcnt(3)
	v_mfma_f32_16x16x32_bf16 v[42:45], v[156:159], v[188:191], v[42:45]
	v_mfma_f32_16x16x32_bf16 v[42:45], v[160:163], v[192:195], v[42:45]
	s_waitcnt lgkmcnt(1)
	v_mfma_f32_16x16x32_bf16 v[46:49], v[148:151], v[188:191], v[46:49]
	v_mfma_f32_16x16x32_bf16 v[46:49], v[152:155], v[192:195], v[46:49]
	v_mfma_f32_16x16x32_bf16 v[30:33], v[148:151], v[196:199], v[30:33]
	v_mfma_f32_16x16x32_bf16 v[30:33], v[152:155], v[200:203], v[30:33]
	v_mfma_f32_16x16x32_bf16 v[26:29], v[156:159], v[196:199], v[26:29]
	v_mfma_f32_16x16x32_bf16 v[26:29], v[160:163], v[200:203], v[26:29]
	v_mfma_f32_16x16x32_bf16 v[10:13], v[156:159], v[204:207], v[10:13]
	v_mfma_f32_16x16x32_bf16 v[10:13], v[160:163], v[208:211], v[10:13]
	s_waitcnt lgkmcnt(0)
	v_mfma_f32_16x16x32_bf16 v[14:17], v[148:151], v[204:207], v[14:17]
	v_mfma_f32_16x16x32_bf16 v[14:17], v[152:155], v[208:211], v[14:17]
	s_setprio 0
	s_setprio 1
	v_mfma_f32_16x16x32_bf16 v[54:57], v[164:167], v[180:183], v[54:57]
	v_mfma_f32_16x16x32_bf16 v[54:57], v[168:171], v[184:187], v[54:57]
	v_mfma_f32_16x16x32_bf16 v[50:53], v[172:175], v[180:183], v[50:53]
	v_mfma_f32_16x16x32_bf16 v[50:53], v[176:179], v[184:187], v[50:53]
	v_mfma_f32_16x16x32_bf16 v[34:37], v[172:175], v[188:191], v[34:37]
	v_mfma_f32_16x16x32_bf16 v[34:37], v[176:179], v[192:195], v[34:37]
	v_mfma_f32_16x16x32_bf16 v[38:41], v[164:167], v[188:191], v[38:41]
	v_mfma_f32_16x16x32_bf16 v[38:41], v[168:171], v[192:195], v[38:41]
	v_mfma_f32_16x16x32_bf16 v[22:25], v[164:167], v[196:199], v[22:25]
	v_mfma_f32_16x16x32_bf16 v[22:25], v[168:171], v[200:203], v[22:25]
	v_mfma_f32_16x16x32_bf16 v[18:21], v[172:175], v[196:199], v[18:21]
	v_mfma_f32_16x16x32_bf16 v[18:21], v[176:179], v[200:203], v[18:21]
	v_mfma_f32_16x16x32_bf16 v[2:5], v[172:175], v[204:207], v[2:5]
	v_mfma_f32_16x16x32_bf16 v[2:5], v[176:179], v[208:211], v[2:5]
	s_setprio 2
	s_barrier
	v_mfma_f32_16x16x32_bf16 v[6:9], v[164:167], v[204:207], v[6:9]
	v_mfma_f32_16x16x32_bf16 v[6:9], v[168:171], v[208:211], v[6:9]
	s_setprio 0
	ds_read_b128 v[148:151], v146
	ds_read_b128 v[152:155], v146 offset:1024
	ds_read_b128 v[156:159], v146 offset:2048
	ds_read_b128 v[160:163], v146 offset:3072
	ds_read_b128 v[164:167], v147
	ds_read_b128 v[168:171], v147 offset:1024
	ds_read_b128 v[172:175], v147 offset:2048
	ds_read_b128 v[176:179], v147 offset:3072
	ds_read_b128 v[180:183], v145 offset:32768
	ds_read_b128 v[184:187], v145 offset:33792
	ds_read_b128 v[188:191], v145 offset:34816
	ds_read_b128 v[192:195], v145 offset:35840
	ds_read_b128 v[196:199], v145 offset:36864
	ds_read_b128 v[200:203], v145 offset:37888
	ds_read_b128 v[204:207], v145 offset:38912
	ds_read_b128 v[208:211], v145 offset:39936
	s_mov_b32 s78, m0
	s_mov_b32 m0, s31
	s_nop 0
	global_load_lds_dwordx4 v138, s[22:23]
	s_mov_b32 m0, s78
	s_nop 0
	s_mov_b32 s78, m0
	s_mov_b32 m0, s41
	s_nop 0
	global_load_lds_dwordx4 v140, s[22:23]
	s_mov_b32 m0, s78
	s_add_u32 s22, s22, 0x80000
	s_addc_u32 s23, s23, 0
	s_mov_b32 s78, m0
	s_mov_b32 m0, s42
	s_nop 0
	global_load_lds_dwordx4 v138, s[22:23]
	s_mov_b32 m0, s78
	s_nop 0
	s_mov_b32 s78, m0
	s_mov_b32 m0, s43
	s_nop 0
	global_load_lds_dwordx4 v140, s[22:23]
	s_mov_b32 m0, s78
	s_waitcnt vmcnt(8)
	s_waitcnt lgkmcnt(0)
	s_waitcnt lgkmcnt(7)
	v_mfma_f32_16x16x32_bf16 v[126:129], v[148:151], v[180:183], v[126:129]
	v_mfma_f32_16x16x32_bf16 v[126:129], v[152:155], v[184:187], v[126:129]
	s_waitcnt lgkmcnt(5)
	v_mfma_f32_16x16x32_bf16 v[122:125], v[156:159], v[180:183], v[122:125]
	v_mfma_f32_16x16x32_bf16 v[122:125], v[160:163], v[184:187], v[122:125]
	s_barrier
	s_setprio 1
	s_waitcnt lgkmcnt(3)
	v_mfma_f32_16x16x32_bf16 v[106:109], v[156:159], v[188:191], v[106:109]
	v_mfma_f32_16x16x32_bf16 v[106:109], v[160:163], v[192:195], v[106:109]
	s_waitcnt lgkmcnt(1)
	v_mfma_f32_16x16x32_bf16 v[110:113], v[148:151], v[188:191], v[110:113]
	v_mfma_f32_16x16x32_bf16 v[110:113], v[152:155], v[192:195], v[110:113]
	v_mfma_f32_16x16x32_bf16 v[94:97], v[148:151], v[196:199], v[94:97]
	v_mfma_f32_16x16x32_bf16 v[94:97], v[152:155], v[200:203], v[94:97]
	v_mfma_f32_16x16x32_bf16 v[90:93], v[156:159], v[196:199], v[90:93]
	v_mfma_f32_16x16x32_bf16 v[90:93], v[160:163], v[200:203], v[90:93]
	v_mfma_f32_16x16x32_bf16 v[74:77], v[156:159], v[204:207], v[74:77]
	v_mfma_f32_16x16x32_bf16 v[74:77], v[160:163], v[208:211], v[74:77]
	s_waitcnt lgkmcnt(0)
	v_mfma_f32_16x16x32_bf16 v[78:81], v[148:151], v[204:207], v[78:81]
	v_mfma_f32_16x16x32_bf16 v[78:81], v[152:155], v[208:211], v[78:81]
	s_setprio 0
	s_setprio 1
	v_mfma_f32_16x16x32_bf16 v[118:121], v[164:167], v[180:183], v[118:121]
	v_mfma_f32_16x16x32_bf16 v[118:121], v[168:171], v[184:187], v[118:121]
	v_mfma_f32_16x16x32_bf16 v[114:117], v[172:175], v[180:183], v[114:117]
	v_mfma_f32_16x16x32_bf16 v[114:117], v[176:179], v[184:187], v[114:117]
	v_mfma_f32_16x16x32_bf16 v[98:101], v[172:175], v[188:191], v[98:101]
	v_mfma_f32_16x16x32_bf16 v[98:101], v[176:179], v[192:195], v[98:101]
	v_mfma_f32_16x16x32_bf16 v[102:105], v[164:167], v[188:191], v[102:105]
	v_mfma_f32_16x16x32_bf16 v[102:105], v[168:171], v[192:195], v[102:105]
	v_mfma_f32_16x16x32_bf16 v[86:89], v[164:167], v[196:199], v[86:89]
	v_mfma_f32_16x16x32_bf16 v[86:89], v[168:171], v[200:203], v[86:89]
	v_mfma_f32_16x16x32_bf16 v[82:85], v[172:175], v[196:199], v[82:85]
	v_mfma_f32_16x16x32_bf16 v[82:85], v[176:179], v[200:203], v[82:85]
	v_mfma_f32_16x16x32_bf16 v[66:69], v[172:175], v[204:207], v[66:69]
	v_mfma_f32_16x16x32_bf16 v[66:69], v[176:179], v[208:211], v[66:69]
	s_setprio 2
	s_barrier
	v_mfma_f32_16x16x32_bf16 v[70:73], v[164:167], v[204:207], v[70:73]
	v_mfma_f32_16x16x32_bf16 v[70:73], v[168:171], v[208:211], v[70:73]
	s_setprio 0
	ds_read_b128 v[180:183], v145 offset:49152
	ds_read_b128 v[184:187], v145 offset:50176
	ds_read_b128 v[188:191], v145 offset:51200
	ds_read_b128 v[192:195], v145 offset:52224
	ds_read_b128 v[196:199], v145 offset:53248
	ds_read_b128 v[200:203], v145 offset:54272
	ds_read_b128 v[204:207], v145 offset:55296
	ds_read_b128 v[208:211], v145 offset:56320
	s_add_u32 s22, s20, 0x80
	s_addc_u32 s23, s21, 0
	s_mov_b32 s78, m0
	s_mov_b32 m0, s46
	s_nop 0
	global_load_lds_dwordx4 v139, s[22:23]
	s_mov_b32 m0, s78
	s_add_u32 s20, s20, 0x80080
	s_mov_b32 s78, m0
	s_mov_b32 m0, s47
	s_nop 0
	global_load_lds_dwordx4 v141, s[22:23]
	s_mov_b32 m0, s78
	s_addc_u32 s21, s21, 0
	s_mov_b32 s22, m0
	s_mov_b32 m0, s48
	s_nop 0
	global_load_lds_dwordx4 v139, s[20:21]
	s_mov_b32 m0, s22
	s_nop 0
	s_mov_b32 s22, m0
	s_mov_b32 m0, s49
	s_nop 0
	global_load_lds_dwordx4 v141, s[20:21]
	s_mov_b32 m0, s22
	s_waitcnt vmcnt(4)
	s_waitcnt lgkmcnt(0)
	s_waitcnt lgkmcnt(7)
	v_mfma_f32_16x16x32_bf16 v[62:65], v[148:151], v[180:183], v[62:65]
	v_mfma_f32_16x16x32_bf16 v[62:65], v[152:155], v[184:187], v[62:65]
	s_waitcnt lgkmcnt(5)
	v_mfma_f32_16x16x32_bf16 v[58:61], v[156:159], v[180:183], v[58:61]
	v_mfma_f32_16x16x32_bf16 v[58:61], v[160:163], v[184:187], v[58:61]
	s_barrier
	s_setprio 1
	s_waitcnt lgkmcnt(3)
	v_mfma_f32_16x16x32_bf16 v[42:45], v[156:159], v[188:191], v[42:45]
	v_mfma_f32_16x16x32_bf16 v[42:45], v[160:163], v[192:195], v[42:45]
	s_waitcnt lgkmcnt(1)
	v_mfma_f32_16x16x32_bf16 v[46:49], v[148:151], v[188:191], v[46:49]
	v_mfma_f32_16x16x32_bf16 v[46:49], v[152:155], v[192:195], v[46:49]
	v_mfma_f32_16x16x32_bf16 v[30:33], v[148:151], v[196:199], v[30:33]
	v_mfma_f32_16x16x32_bf16 v[30:33], v[152:155], v[200:203], v[30:33]
	v_mfma_f32_16x16x32_bf16 v[26:29], v[156:159], v[196:199], v[26:29]
	v_mfma_f32_16x16x32_bf16 v[26:29], v[160:163], v[200:203], v[26:29]
	v_mfma_f32_16x16x32_bf16 v[10:13], v[156:159], v[204:207], v[10:13]
	v_mfma_f32_16x16x32_bf16 v[10:13], v[160:163], v[208:211], v[10:13]
	s_waitcnt lgkmcnt(0)
	v_mfma_f32_16x16x32_bf16 v[14:17], v[148:151], v[204:207], v[14:17]
	v_mfma_f32_16x16x32_bf16 v[14:17], v[152:155], v[208:211], v[14:17]
	s_setprio 0
	s_setprio 1
	v_mfma_f32_16x16x32_bf16 v[54:57], v[164:167], v[180:183], v[54:57]
	v_mfma_f32_16x16x32_bf16 v[54:57], v[168:171], v[184:187], v[54:57]
	v_mfma_f32_16x16x32_bf16 v[50:53], v[172:175], v[180:183], v[50:53]
	v_mfma_f32_16x16x32_bf16 v[50:53], v[176:179], v[184:187], v[50:53]
	v_mfma_f32_16x16x32_bf16 v[34:37], v[172:175], v[188:191], v[34:37]
	v_mfma_f32_16x16x32_bf16 v[34:37], v[176:179], v[192:195], v[34:37]
	v_mfma_f32_16x16x32_bf16 v[38:41], v[164:167], v[188:191], v[38:41]
	v_mfma_f32_16x16x32_bf16 v[38:41], v[168:171], v[192:195], v[38:41]
	v_mfma_f32_16x16x32_bf16 v[22:25], v[164:167], v[196:199], v[22:25]
	v_mfma_f32_16x16x32_bf16 v[22:25], v[168:171], v[200:203], v[22:25]
	v_mfma_f32_16x16x32_bf16 v[18:21], v[172:175], v[196:199], v[18:21]
	v_mfma_f32_16x16x32_bf16 v[18:21], v[176:179], v[200:203], v[18:21]
	v_mfma_f32_16x16x32_bf16 v[2:5], v[172:175], v[204:207], v[2:5]
	v_mfma_f32_16x16x32_bf16 v[2:5], v[176:179], v[208:211], v[2:5]
	s_setprio 2
	s_barrier
	v_mfma_f32_16x16x32_bf16 v[6:9], v[164:167], v[204:207], v[6:9]
	v_mfma_f32_16x16x32_bf16 v[6:9], v[168:171], v[208:211], v[6:9]
	s_setprio 0
	s_add_i32 s77, s77, 2
	s_add_u32 s73, s73, 0x100
	s_addc_u32 s74, s74, 0
	s_add_u32 s18, s18, 0x100
	s_addc_u32 s19, s19, 0
	s_add_u32 s75, s75, 0x100
	s_addc_u32 s76, s76, 0
	s_cmp_gt_u32 s77, 29
	s_cbranch_scc0 .LBB0_1224
	s_and_b64 vcc, exec, s[6:7]
	s_cbranch_vccz .LBB0_1227
	s_barrier

.LBB0_1356:
	s_ashr_i32 s13, s12, 31
	s_lshl_b64 s[14:15], s[12:13], 15
	s_add_u32 s14, s28, s14
	s_addc_u32 s15, s29, s15
	s_and_b64 s[16:17], s[2:3], exec
	s_cselect_b32 s13, s15, s23
	s_cselect_b32 s67, s14, s22
	s_ashr_i32 s11, s10, 31
	s_lshl_b64 s[16:17], s[10:11], 15
	s_add_u32 s16, s30, s16
	s_addc_u32 s17, s31, s17
	s_and_b64 s[24:25], s[2:3], exec
	s_cselect_b32 s11, s17, s21
	s_cselect_b32 s73, s16, s20
	s_add_u32 s74, s20, 0x80000
	s_addc_u32 s75, s21, 0
	s_add_u32 s20, s22, 0x204000
	s_addc_u32 s21, s23, 0
	s_add_u32 s76, s22, 0x400000
	s_addc_u32 s77, s23, 0
	s_mov_b32 s78, -2
	s_waitcnt vmcnt(25)
	s_waitcnt vmcnt(24)
	s_waitcnt vmcnt(15)
	s_waitcnt vmcnt(14)
	s_waitcnt vmcnt(13)
	s_waitcnt vmcnt(12)
	s_waitcnt vmcnt(11)
	s_waitcnt vmcnt(10)
	s_waitcnt vmcnt(9)
	s_waitcnt vmcnt(8)
	s_waitcnt vmcnt(7)
	s_waitcnt vmcnt(6)
	s_waitcnt vmcnt(5)
	s_waitcnt vmcnt(4)
	s_waitcnt vmcnt(3)
	s_waitcnt vmcnt(2)
	s_waitcnt vmcnt(1)
	s_waitcnt vmcnt(0)
	ds_read_b128 v[130:133], v181
	ds_read_b128 v[134:137], v181 offset:1024
	ds_read_b128 v[138:141], v181 offset:2048
	ds_read_b128 v[142:145], v181 offset:3072
	ds_read_b128 v[150:153], v182
	ds_read_b128 v[154:157], v182 offset:1024
	ds_read_b128 v[158:161], v182 offset:2048
	ds_read_b128 v[162:165], v182 offset:3072
	s_cmpk_eq_i32 s78, 0x52
	s_cselect_b32 s23, s11, s75
	s_cselect_b32 s22, s73, s74
	s_cselect_b32 s25, s13, s77
	s_cselect_b32 s24, s67, s76
	ds_read_b128 v[166:169], v183
	ds_read_b128 v[170:173], v183 offset:1024
	ds_read_b128 v[186:189], v183 offset:2048
	ds_read_b128 v[190:193], v183 offset:3072
	ds_read_b128 v[194:197], v183 offset:4096
	ds_read_b128 v[198:201], v183 offset:5120
	ds_read_b128 v[202:205], v183 offset:6144
	ds_read_b128 v[206:209], v183 offset:7168
	s_add_u32 s80, s20, 0xffffc000
	s_addc_u32 s81, s21, -1
	s_mov_b32 s79, m0
	s_mov_b32 m0, s58
	s_nop 0
	global_load_lds_dwordx4 v1, s[80:81]
	s_mov_b32 m0, s79
	s_nop 0
	s_mov_b32 s79, m0
	s_mov_b32 m0, s64
	s_nop 0
	global_load_lds_dwordx4 v177, s[80:81]
	s_mov_b32 m0, s79
	s_nop 0
	s_mov_b32 s79, m0
	s_mov_b32 m0, s59
	s_nop 0
	global_load_lds_dwordx4 v1, s[20:21]
	s_mov_b32 m0, s79
	s_nop 0
	s_mov_b32 s79, m0
	s_mov_b32 m0, s65
	s_nop 0
	global_load_lds_dwordx4 v177, s[20:21]
	s_mov_b32 m0, s79
	s_waitcnt vmcnt(8)
	s_waitcnt lgkmcnt(0)
	s_waitcnt lgkmcnt(7)
	v_mfma_f32_16x16x32_bf16 v[126:129], v[130:133], v[166:169], 0
	v_mfma_f32_16x16x32_bf16 v[126:129], v[134:137], v[170:173], v[126:129]
	s_waitcnt lgkmcnt(5)
	v_mfma_f32_16x16x32_bf16 v[122:125], v[138:141], v[166:169], 0
	v_mfma_f32_16x16x32_bf16 v[122:125], v[142:145], v[170:173], v[122:125]
	s_barrier
	s_setprio 1
	s_waitcnt lgkmcnt(3)
	v_mfma_f32_16x16x32_bf16 v[110:113], v[138:141], v[186:189], 0
	v_mfma_f32_16x16x32_bf16 v[110:113], v[142:145], v[190:193], v[110:113]
	s_waitcnt lgkmcnt(1)
	v_mfma_f32_16x16x32_bf16 v[118:121], v[130:133], v[186:189], 0
	v_mfma_f32_16x16x32_bf16 v[118:121], v[134:137], v[190:193], v[118:121]
	v_mfma_f32_16x16x32_bf16 v[94:97], v[130:133], v[194:197], 0
	v_mfma_f32_16x16x32_bf16 v[94:97], v[134:137], v[198:201], v[94:97]
	v_mfma_f32_16x16x32_bf16 v[90:93], v[138:141], v[194:197], 0
	v_mfma_f32_16x16x32_bf16 v[90:93], v[142:145], v[198:201], v[90:93]
	v_mfma_f32_16x16x32_bf16 v[78:81], v[138:141], v[202:205], 0
	v_mfma_f32_16x16x32_bf16 v[78:81], v[142:145], v[206:209], v[78:81]
	s_waitcnt lgkmcnt(0)
	v_mfma_f32_16x16x32_bf16 v[86:89], v[130:133], v[202:205], 0
	v_mfma_f32_16x16x32_bf16 v[86:89], v[134:137], v[206:209], v[86:89]
	s_setprio 0
	s_setprio 1
	v_mfma_f32_16x16x32_bf16 v[114:117], v[150:153], v[166:169], 0
	v_mfma_f32_16x16x32_bf16 v[114:117], v[154:157], v[170:173], v[114:117]
	v_mfma_f32_16x16x32_bf16 v[106:109], v[158:161], v[166:169], 0
	v_mfma_f32_16x16x32_bf16 v[106:109], v[162:165], v[170:173], v[106:109]
	v_mfma_f32_16x16x32_bf16 v[98:101], v[158:161], v[186:189], 0
	v_mfma_f32_16x16x32_bf16 v[98:101], v[162:165], v[190:193], v[98:101]
	v_mfma_f32_16x16x32_bf16 v[102:105], v[150:153], v[186:189], 0
	v_mfma_f32_16x16x32_bf16 v[102:105], v[154:157], v[190:193], v[102:105]
	v_mfma_f32_16x16x32_bf16 v[82:85], v[150:153], v[194:197], 0
	v_mfma_f32_16x16x32_bf16 v[82:85], v[154:157], v[198:201], v[82:85]
	v_mfma_f32_16x16x32_bf16 v[74:77], v[158:161], v[194:197], 0
	v_mfma_f32_16x16x32_bf16 v[74:77], v[162:165], v[198:201], v[74:77]
	v_mfma_f32_16x16x32_bf16 v[66:69], v[158:161], v[202:205], 0
	v_mfma_f32_16x16x32_bf16 v[66:69], v[162:165], v[206:209], v[66:69]
	s_setprio 2
	s_barrier
	v_mfma_f32_16x16x32_bf16 v[70:73], v[150:153], v[202:205], 0
	v_mfma_f32_16x16x32_bf16 v[70:73], v[154:157], v[206:209], v[70:73]
	s_setprio 0
	ds_read_b128 v[166:169], v183 offset:16384
	ds_read_b128 v[170:173], v183 offset:17408
	ds_read_b128 v[186:189], v183 offset:18432
	ds_read_b128 v[190:193], v183 offset:19456
	ds_read_b128 v[194:197], v183 offset:20480
	ds_read_b128 v[198:201], v183 offset:21504
	ds_read_b128 v[202:205], v183 offset:22528
	ds_read_b128 v[206:209], v183 offset:23552
	s_mov_b32 s79, m0
	s_mov_b32 m0, s35
	s_nop 0
	global_load_lds_dwordx4 v176, s[22:23]
	s_mov_b32 m0, s79
	s_add_u32 s80, s22, 0x4000
	s_mov_b32 s79, m0
	s_mov_b32 m0, s36
	s_nop 0
	global_load_lds_dwordx4 v178, s[22:23]
	s_mov_b32 m0, s79
	s_addc_u32 s81, s23, 0
	s_mov_b32 s79, m0
	s_mov_b32 m0, s37
	s_nop 0
	global_load_lds_dwordx4 v176, s[80:81]
	s_mov_b32 m0, s79
	s_nop 0
	s_mov_b32 s79, m0
	s_mov_b32 m0, s40
	s_nop 0
	global_load_lds_dwordx4 v178, s[80:81]
	s_mov_b32 m0, s79
	s_waitcnt vmcnt(4)
	s_waitcnt lgkmcnt(0)
	s_waitcnt lgkmcnt(7)
	v_mfma_f32_16x16x32_bf16 v[62:65], v[130:133], v[166:169], 0
	v_mfma_f32_16x16x32_bf16 v[62:65], v[134:137], v[170:173], v[62:65]
	s_waitcnt lgkmcnt(5)
	v_mfma_f32_16x16x32_bf16 v[58:61], v[138:141], v[166:169], 0
	v_mfma_f32_16x16x32_bf16 v[58:61], v[142:145], v[170:173], v[58:61]
	s_barrier
	s_setprio 1
	s_waitcnt lgkmcnt(3)
	v_mfma_f32_16x16x32_bf16 v[42:45], v[138:141], v[186:189], 0
	v_mfma_f32_16x16x32_bf16 v[42:45], v[142:145], v[190:193], v[42:45]
	s_waitcnt lgkmcnt(1)
	v_mfma_f32_16x16x32_bf16 v[46:49], v[130:133], v[186:189], 0
	v_mfma_f32_16x16x32_bf16 v[46:49], v[134:137], v[190:193], v[46:49]
	v_mfma_f32_16x16x32_bf16 v[30:33], v[130:133], v[194:197], 0
	v_mfma_f32_16x16x32_bf16 v[30:33], v[134:137], v[198:201], v[30:33]
	v_mfma_f32_16x16x32_bf16 v[26:29], v[138:141], v[194:197], 0
	v_mfma_f32_16x16x32_bf16 v[26:29], v[142:145], v[198:201], v[26:29]
	v_mfma_f32_16x16x32_bf16 v[10:13], v[138:141], v[202:205], 0
	v_mfma_f32_16x16x32_bf16 v[10:13], v[142:145], v[206:209], v[10:13]
	s_waitcnt lgkmcnt(0)
	v_mfma_f32_16x16x32_bf16 v[14:17], v[130:133], v[202:205], 0
	v_mfma_f32_16x16x32_bf16 v[14:17], v[134:137], v[206:209], v[14:17]
	s_setprio 0
	s_setprio 1
	v_mfma_f32_16x16x32_bf16 v[54:57], v[150:153], v[166:169], 0
	v_mfma_f32_16x16x32_bf16 v[54:57], v[154:157], v[170:173], v[54:57]
	v_mfma_f32_16x16x32_bf16 v[50:53], v[158:161], v[166:169], 0
	v_mfma_f32_16x16x32_bf16 v[50:53], v[162:165], v[170:173], v[50:53]
	v_mfma_f32_16x16x32_bf16 v[34:37], v[158:161], v[186:189], 0
	v_mfma_f32_16x16x32_bf16 v[34:37], v[162:165], v[190:193], v[34:37]
	v_mfma_f32_16x16x32_bf16 v[38:41], v[150:153], v[186:189], 0
	v_mfma_f32_16x16x32_bf16 v[38:41], v[154:157], v[190:193], v[38:41]
	v_mfma_f32_16x16x32_bf16 v[22:25], v[150:153], v[194:197], 0
	v_mfma_f32_16x16x32_bf16 v[22:25], v[154:157], v[198:201], v[22:25]
	v_mfma_f32_16x16x32_bf16 v[18:21], v[158:161], v[194:197], 0
	v_mfma_f32_16x16x32_bf16 v[18:21], v[162:165], v[198:201], v[18:21]
	v_mfma_f32_16x16x32_bf16 v[2:5], v[158:161], v[202:205], 0
	v_mfma_f32_16x16x32_bf16 v[2:5], v[162:165], v[206:209], v[2:5]
	s_setprio 2
	s_barrier
	v_mfma_f32_16x16x32_bf16 v[6:9], v[150:153], v[202:205], 0
	v_mfma_f32_16x16x32_bf16 v[6:9], v[154:157], v[206:209], v[6:9]
	s_setprio 0
	ds_read_b128 v[130:133], v184
	ds_read_b128 v[134:137], v184 offset:1024
	ds_read_b128 v[138:141], v184 offset:2048
	ds_read_b128 v[142:145], v184 offset:3072
	ds_read_b128 v[150:153], v185
	ds_read_b128 v[154:157], v185 offset:1024
	ds_read_b128 v[158:161], v185 offset:2048
	ds_read_b128 v[162:165], v185 offset:3072
	ds_read_b128 v[166:169], v183 offset:32768
	ds_read_b128 v[170:173], v183 offset:33792
	ds_read_b128 v[186:189], v183 offset:34816
	ds_read_b128 v[190:193], v183 offset:35840
	ds_read_b128 v[194:197], v183 offset:36864
	ds_read_b128 v[198:201], v183 offset:37888
	ds_read_b128 v[202:205], v183 offset:38912
	ds_read_b128 v[206:209], v183 offset:39936
	s_mov_b32 s79, m0
	s_mov_b32 m0, s34
	s_nop 0
	global_load_lds_dwordx4 v1, s[24:25]
	s_mov_b32 m0, s79
	s_nop 0
	s_mov_b32 s79, m0
	s_mov_b32 m0, s41
	s_nop 0
	global_load_lds_dwordx4 v177, s[24:25]
	s_mov_b32 m0, s79
	s_add_u32 s24, s24, 0x4000
	s_addc_u32 s25, s25, 0
	s_mov_b32 s79, m0
	s_mov_b32 m0, s42
	s_nop 0
	global_load_lds_dwordx4 v1, s[24:25]
	s_mov_b32 m0, s79
	s_nop 0
	s_mov_b32 s79, m0
	s_mov_b32 m0, s43
	s_nop 0
	global_load_lds_dwordx4 v177, s[24:25]
	s_mov_b32 m0, s79
	s_waitcnt vmcnt(8)
	s_waitcnt lgkmcnt(0)
	s_waitcnt lgkmcnt(7)
	v_mfma_f32_16x16x32_bf16 v[126:129], v[130:133], v[166:169], v[126:129]
	v_mfma_f32_16x16x32_bf16 v[126:129], v[134:137], v[170:173], v[126:129]
	s_waitcnt lgkmcnt(5)
	v_mfma_f32_16x16x32_bf16 v[122:125], v[138:141], v[166:169], v[122:125]
	v_mfma_f32_16x16x32_bf16 v[122:125], v[142:145], v[170:173], v[122:125]
	s_barrier
	s_setprio 1
	s_waitcnt lgkmcnt(3)
	v_mfma_f32_16x16x32_bf16 v[110:113], v[138:141], v[186:189], v[110:113]
	v_mfma_f32_16x16x32_bf16 v[110:113], v[142:145], v[190:193], v[110:113]
	s_waitcnt lgkmcnt(1)
	v_mfma_f32_16x16x32_bf16 v[118:121], v[130:133], v[186:189], v[118:121]
	v_mfma_f32_16x16x32_bf16 v[118:121], v[134:137], v[190:193], v[118:121]
	v_mfma_f32_16x16x32_bf16 v[94:97], v[130:133], v[194:197], v[94:97]
	v_mfma_f32_16x16x32_bf16 v[94:97], v[134:137], v[198:201], v[94:97]
	v_mfma_f32_16x16x32_bf16 v[90:93], v[138:141], v[194:197], v[90:93]
	v_mfma_f32_16x16x32_bf16 v[90:93], v[142:145], v[198:201], v[90:93]
	v_mfma_f32_16x16x32_bf16 v[78:81], v[138:141], v[202:205], v[78:81]
	v_mfma_f32_16x16x32_bf16 v[78:81], v[142:145], v[206:209], v[78:81]
	s_waitcnt lgkmcnt(0)
	v_mfma_f32_16x16x32_bf16 v[86:89], v[130:133], v[202:205], v[86:89]
	v_mfma_f32_16x16x32_bf16 v[86:89], v[134:137], v[206:209], v[86:89]
	s_setprio 0
	s_setprio 1
	v_mfma_f32_16x16x32_bf16 v[114:117], v[150:153], v[166:169], v[114:117]
	v_mfma_f32_16x16x32_bf16 v[114:117], v[154:157], v[170:173], v[114:117]
	v_mfma_f32_16x16x32_bf16 v[106:109], v[158:161], v[166:169], v[106:109]
	v_mfma_f32_16x16x32_bf16 v[106:109], v[162:165], v[170:173], v[106:109]
	v_mfma_f32_16x16x32_bf16 v[98:101], v[158:161], v[186:189], v[98:101]
	v_mfma_f32_16x16x32_bf16 v[98:101], v[162:165], v[190:193], v[98:101]
	v_mfma_f32_16x16x32_bf16 v[102:105], v[150:153], v[186:189], v[102:105]
	v_mfma_f32_16x16x32_bf16 v[102:105], v[154:157], v[190:193], v[102:105]
	v_mfma_f32_16x16x32_bf16 v[82:85], v[150:153], v[194:197], v[82:85]
	v_mfma_f32_16x16x32_bf16 v[82:85], v[154:157], v[198:201], v[82:85]
	v_mfma_f32_16x16x32_bf16 v[74:77], v[158:161], v[194:197], v[74:77]
	v_mfma_f32_16x16x32_bf16 v[74:77], v[162:165], v[198:201], v[74:77]
	v_mfma_f32_16x16x32_bf16 v[66:69], v[158:161], v[202:205], v[66:69]
	v_mfma_f32_16x16x32_bf16 v[66:69], v[162:165], v[206:209], v[66:69]
	s_setprio 2
	s_barrier
	v_mfma_f32_16x16x32_bf16 v[70:73], v[150:153], v[202:205], v[70:73]
	v_mfma_f32_16x16x32_bf16 v[70:73], v[154:157], v[206:209], v[70:73]
	s_setprio 0
	ds_read_b128 v[166:169], v183 offset:49152
	ds_read_b128 v[170:173], v183 offset:50176
	ds_read_b128 v[186:189], v183 offset:51200
	ds_read_b128 v[190:193], v183 offset:52224
	ds_read_b128 v[194:197], v183 offset:53248
	ds_read_b128 v[198:201], v183 offset:54272
	ds_read_b128 v[202:205], v183 offset:55296
	ds_read_b128 v[206:209], v183 offset:56320
	s_add_u32 s24, s22, 0x40000
	s_addc_u32 s25, s23, 0
	s_mov_b32 s79, m0
	s_mov_b32 m0, s46
	s_nop 0
	global_load_lds_dwordx4 v176, s[24:25]
	s_mov_b32 m0, s79
	s_add_u32 s22, s22, 0x44000
	s_mov_b32 s79, m0
	s_mov_b32 m0, s47
	s_nop 0
	global_load_lds_dwordx4 v178, s[24:25]
	s_mov_b32 m0, s79
	s_addc_u32 s23, s23, 0
	s_mov_b32 s24, m0
	s_mov_b32 m0, s48
	s_nop 0
	global_load_lds_dwordx4 v176, s[22:23]
	s_mov_b32 m0, s24
	s_nop 0
	s_mov_b32 s24, m0
	s_mov_b32 m0, s49
	s_nop 0
	global_load_lds_dwordx4 v178, s[22:23]
	s_mov_b32 m0, s24
	s_waitcnt vmcnt(4)
	s_waitcnt lgkmcnt(0)
	s_waitcnt lgkmcnt(7)
	v_mfma_f32_16x16x32_bf16 v[62:65], v[130:133], v[166:169], v[62:65]
	v_mfma_f32_16x16x32_bf16 v[62:65], v[134:137], v[170:173], v[62:65]
	s_waitcnt lgkmcnt(5)
	v_mfma_f32_16x16x32_bf16 v[58:61], v[138:141], v[166:169], v[58:61]
	v_mfma_f32_16x16x32_bf16 v[58:61], v[142:145], v[170:173], v[58:61]
	s_barrier
	s_setprio 1
	s_waitcnt lgkmcnt(3)
	v_mfma_f32_16x16x32_bf16 v[42:45], v[138:141], v[186:189], v[42:45]
	v_mfma_f32_16x16x32_bf16 v[42:45], v[142:145], v[190:193], v[42:45]
	s_waitcnt lgkmcnt(1)
	v_mfma_f32_16x16x32_bf16 v[46:49], v[130:133], v[186:189], v[46:49]
	v_mfma_f32_16x16x32_bf16 v[46:49], v[134:137], v[190:193], v[46:49]
	v_mfma_f32_16x16x32_bf16 v[30:33], v[130:133], v[194:197], v[30:33]
	v_mfma_f32_16x16x32_bf16 v[30:33], v[134:137], v[198:201], v[30:33]
	v_mfma_f32_16x16x32_bf16 v[26:29], v[138:141], v[194:197], v[26:29]
	v_mfma_f32_16x16x32_bf16 v[26:29], v[142:145], v[198:201], v[26:29]
	v_mfma_f32_16x16x32_bf16 v[10:13], v[138:141], v[202:205], v[10:13]
	v_mfma_f32_16x16x32_bf16 v[10:13], v[142:145], v[206:209], v[10:13]
	s_waitcnt lgkmcnt(0)
	v_mfma_f32_16x16x32_bf16 v[14:17], v[130:133], v[202:205], v[14:17]
	v_mfma_f32_16x16x32_bf16 v[14:17], v[134:137], v[206:209], v[14:17]
	s_setprio 0
	s_setprio 1
	v_mfma_f32_16x16x32_bf16 v[54:57], v[150:153], v[166:169], v[54:57]
	v_mfma_f32_16x16x32_bf16 v[54:57], v[154:157], v[170:173], v[54:57]
	v_mfma_f32_16x16x32_bf16 v[50:53], v[158:161], v[166:169], v[50:53]
	v_mfma_f32_16x16x32_bf16 v[50:53], v[162:165], v[170:173], v[50:53]
	v_mfma_f32_16x16x32_bf16 v[34:37], v[158:161], v[186:189], v[34:37]
	v_mfma_f32_16x16x32_bf16 v[34:37], v[162:165], v[190:193], v[34:37]
	v_mfma_f32_16x16x32_bf16 v[38:41], v[150:153], v[186:189], v[38:41]
	v_mfma_f32_16x16x32_bf16 v[38:41], v[154:157], v[190:193], v[38:41]
	v_mfma_f32_16x16x32_bf16 v[22:25], v[150:153], v[194:197], v[22:25]
	v_mfma_f32_16x16x32_bf16 v[22:25], v[154:157], v[198:201], v[22:25]
	v_mfma_f32_16x16x32_bf16 v[18:21], v[158:161], v[194:197], v[18:21]
	v_mfma_f32_16x16x32_bf16 v[18:21], v[162:165], v[198:201], v[18:21]
	v_mfma_f32_16x16x32_bf16 v[2:5], v[158:161], v[202:205], v[2:5]
	v_mfma_f32_16x16x32_bf16 v[2:5], v[162:165], v[206:209], v[2:5]
	s_setprio 2
	s_barrier
	v_mfma_f32_16x16x32_bf16 v[6:9], v[150:153], v[202:205], v[6:9]
	v_mfma_f32_16x16x32_bf16 v[6:9], v[154:157], v[206:209], v[6:9]
	s_setprio 0
	s_add_i32 s78, s78, 2
	s_add_u32 s74, s74, 0x80000
	s_addc_u32 s75, s75, 0
	s_add_u32 s20, s20, 0x400000
	s_addc_u32 s21, s21, 0
	s_add_u32 s76, s76, 0x400000
	s_addc_u32 s77, s77, 0
	s_cmpk_gt_u32 s78, 0x53
	.p2align 6
.LBB0_1357:
	ds_read_b128 v[130:133], v181
	ds_read_b128 v[134:137], v181 offset:1024
	ds_read_b128 v[138:141], v181 offset:2048
	ds_read_b128 v[142:145], v181 offset:3072
	ds_read_b128 v[150:153], v182
	ds_read_b128 v[154:157], v182 offset:1024
	ds_read_b128 v[158:161], v182 offset:2048
	ds_read_b128 v[162:165], v182 offset:3072
	s_cmpk_eq_i32 s78, 0x52
	s_cselect_b32 s23, s11, s75
	s_cselect_b32 s22, s73, s74
	s_cselect_b32 s25, s13, s77
	s_cselect_b32 s24, s67, s76
	ds_read_b128 v[166:169], v183
	ds_read_b128 v[170:173], v183 offset:1024
	ds_read_b128 v[186:189], v183 offset:2048
	ds_read_b128 v[190:193], v183 offset:3072
	ds_read_b128 v[194:197], v183 offset:4096
	ds_read_b128 v[198:201], v183 offset:5120
	ds_read_b128 v[202:205], v183 offset:6144
	ds_read_b128 v[206:209], v183 offset:7168
	s_add_u32 s80, s20, 0xffffc000
	s_addc_u32 s81, s21, -1
	s_mov_b32 s79, m0
	s_mov_b32 m0, s58
	s_nop 0
	global_load_lds_dwordx4 v1, s[80:81]
	s_mov_b32 m0, s79
	s_nop 0
	s_mov_b32 s79, m0
	s_mov_b32 m0, s64
	s_nop 0
	global_load_lds_dwordx4 v177, s[80:81]
	s_mov_b32 m0, s79
	s_nop 0
	s_mov_b32 s79, m0
	s_mov_b32 m0, s59
	s_nop 0
	global_load_lds_dwordx4 v1, s[20:21]
	s_mov_b32 m0, s79
	s_nop 0
	s_mov_b32 s79, m0
	s_mov_b32 m0, s65
	s_nop 0
	global_load_lds_dwordx4 v177, s[20:21]
	s_mov_b32 m0, s79
	s_waitcnt vmcnt(8)
	s_waitcnt lgkmcnt(0)
	s_waitcnt lgkmcnt(7)
	v_mfma_f32_16x16x32_bf16 v[126:129], v[130:133], v[166:169], v[126:129]
	v_mfma_f32_16x16x32_bf16 v[126:129], v[134:137], v[170:173], v[126:129]
	s_waitcnt lgkmcnt(5)
	v_mfma_f32_16x16x32_bf16 v[122:125], v[138:141], v[166:169], v[122:125]
	v_mfma_f32_16x16x32_bf16 v[122:125], v[142:145], v[170:173], v[122:125]
	s_barrier
	s_setprio 1
	s_waitcnt lgkmcnt(3)
	v_mfma_f32_16x16x32_bf16 v[110:113], v[138:141], v[186:189], v[110:113]
	v_mfma_f32_16x16x32_bf16 v[110:113], v[142:145], v[190:193], v[110:113]
	s_waitcnt lgkmcnt(1)
	v_mfma_f32_16x16x32_bf16 v[118:121], v[130:133], v[186:189], v[118:121]
	v_mfma_f32_16x16x32_bf16 v[118:121], v[134:137], v[190:193], v[118:121]
	v_mfma_f32_16x16x32_bf16 v[94:97], v[130:133], v[194:197], v[94:97]
	v_mfma_f32_16x16x32_bf16 v[94:97], v[134:137], v[198:201], v[94:97]
	v_mfma_f32_16x16x32_bf16 v[90:93], v[138:141], v[194:197], v[90:93]
	v_mfma_f32_16x16x32_bf16 v[90:93], v[142:145], v[198:201], v[90:93]
	v_mfma_f32_16x16x32_bf16 v[78:81], v[138:141], v[202:205], v[78:81]
	v_mfma_f32_16x16x32_bf16 v[78:81], v[142:145], v[206:209], v[78:81]
	s_waitcnt lgkmcnt(0)
	v_mfma_f32_16x16x32_bf16 v[86:89], v[130:133], v[202:205], v[86:89]
	v_mfma_f32_16x16x32_bf16 v[86:89], v[134:137], v[206:209], v[86:89]
	s_setprio 0
	s_setprio 1
	v_mfma_f32_16x16x32_bf16 v[114:117], v[150:153], v[166:169], v[114:117]
	v_mfma_f32_16x16x32_bf16 v[114:117], v[154:157], v[170:173], v[114:117]
	v_mfma_f32_16x16x32_bf16 v[106:109], v[158:161], v[166:169], v[106:109]
	v_mfma_f32_16x16x32_bf16 v[106:109], v[162:165], v[170:173], v[106:109]
	v_mfma_f32_16x16x32_bf16 v[98:101], v[158:161], v[186:189], v[98:101]
	v_mfma_f32_16x16x32_bf16 v[98:101], v[162:165], v[190:193], v[98:101]
	v_mfma_f32_16x16x32_bf16 v[102:105], v[150:153], v[186:189], v[102:105]
	v_mfma_f32_16x16x32_bf16 v[102:105], v[154:157], v[190:193], v[102:105]
	v_mfma_f32_16x16x32_bf16 v[82:85], v[150:153], v[194:197], v[82:85]
	v_mfma_f32_16x16x32_bf16 v[82:85], v[154:157], v[198:201], v[82:85]
	v_mfma_f32_16x16x32_bf16 v[74:77], v[158:161], v[194:197], v[74:77]
	v_mfma_f32_16x16x32_bf16 v[74:77], v[162:165], v[198:201], v[74:77]
	v_mfma_f32_16x16x32_bf16 v[66:69], v[158:161], v[202:205], v[66:69]
	v_mfma_f32_16x16x32_bf16 v[66:69], v[162:165], v[206:209], v[66:69]
	s_setprio 2
	s_barrier
	v_mfma_f32_16x16x32_bf16 v[70:73], v[150:153], v[202:205], v[70:73]
	v_mfma_f32_16x16x32_bf16 v[70:73], v[154:157], v[206:209], v[70:73]
	s_setprio 0
	ds_read_b128 v[166:169], v183 offset:16384
	ds_read_b128 v[170:173], v183 offset:17408
	ds_read_b128 v[186:189], v183 offset:18432
	ds_read_b128 v[190:193], v183 offset:19456
	ds_read_b128 v[194:197], v183 offset:20480
	ds_read_b128 v[198:201], v183 offset:21504
	ds_read_b128 v[202:205], v183 offset:22528
	ds_read_b128 v[206:209], v183 offset:23552
	s_mov_b32 s79, m0
	s_mov_b32 m0, s35
	s_nop 0
	global_load_lds_dwordx4 v176, s[22:23]
	s_mov_b32 m0, s79
	s_add_u32 s80, s22, 0x4000
	s_mov_b32 s79, m0
	s_mov_b32 m0, s36
	s_nop 0
	global_load_lds_dwordx4 v178, s[22:23]
	s_mov_b32 m0, s79
	s_addc_u32 s81, s23, 0
	s_mov_b32 s79, m0
	s_mov_b32 m0, s37
	s_nop 0
	global_load_lds_dwordx4 v176, s[80:81]
	s_mov_b32 m0, s79
	s_nop 0
	s_mov_b32 s79, m0
	s_mov_b32 m0, s40
	s_nop 0
	global_load_lds_dwordx4 v178, s[80:81]
	s_mov_b32 m0, s79
	s_waitcnt vmcnt(4)
	s_waitcnt lgkmcnt(0)
	s_waitcnt lgkmcnt(7)
	v_mfma_f32_16x16x32_bf16 v[62:65], v[130:133], v[166:169], v[62:65]
	v_mfma_f32_16x16x32_bf16 v[62:65], v[134:137], v[170:173], v[62:65]
	s_waitcnt lgkmcnt(5)
	v_mfma_f32_16x16x32_bf16 v[58:61], v[138:141], v[166:169], v[58:61]
	v_mfma_f32_16x16x32_bf16 v[58:61], v[142:145], v[170:173], v[58:61]
	s_barrier
	s_setprio 1
	s_waitcnt lgkmcnt(3)
	v_mfma_f32_16x16x32_bf16 v[42:45], v[138:141], v[186:189], v[42:45]
	v_mfma_f32_16x16x32_bf16 v[42:45], v[142:145], v[190:193], v[42:45]
	s_waitcnt lgkmcnt(1)
	v_mfma_f32_16x16x32_bf16 v[46:49], v[130:133], v[186:189], v[46:49]
	v_mfma_f32_16x16x32_bf16 v[46:49], v[134:137], v[190:193], v[46:49]
	v_mfma_f32_16x16x32_bf16 v[30:33], v[130:133], v[194:197], v[30:33]
	v_mfma_f32_16x16x32_bf16 v[30:33], v[134:137], v[198:201], v[30:33]
	v_mfma_f32_16x16x32_bf16 v[26:29], v[138:141], v[194:197], v[26:29]
	v_mfma_f32_16x16x32_bf16 v[26:29], v[142:145], v[198:201], v[26:29]
	v_mfma_f32_16x16x32_bf16 v[10:13], v[138:141], v[202:205], v[10:13]
	v_mfma_f32_16x16x32_bf16 v[10:13], v[142:145], v[206:209], v[10:13]
	s_waitcnt lgkmcnt(0)
	v_mfma_f32_16x16x32_bf16 v[14:17], v[130:133], v[202:205], v[14:17]
	v_mfma_f32_16x16x32_bf16 v[14:17], v[134:137], v[206:209], v[14:17]
	s_setprio 0
	s_setprio 1
	v_mfma_f32_16x16x32_bf16 v[54:57], v[150:153], v[166:169], v[54:57]
	v_mfma_f32_16x16x32_bf16 v[54:57], v[154:157], v[170:173], v[54:57]
	v_mfma_f32_16x16x32_bf16 v[50:53], v[158:161], v[166:169], v[50:53]
	v_mfma_f32_16x16x32_bf16 v[50:53], v[162:165], v[170:173], v[50:53]
	v_mfma_f32_16x16x32_bf16 v[34:37], v[158:161], v[186:189], v[34:37]
	v_mfma_f32_16x16x32_bf16 v[34:37], v[162:165], v[190:193], v[34:37]
	v_mfma_f32_16x16x32_bf16 v[38:41], v[150:153], v[186:189], v[38:41]
	v_mfma_f32_16x16x32_bf16 v[38:41], v[154:157], v[190:193], v[38:41]
	v_mfma_f32_16x16x32_bf16 v[22:25], v[150:153], v[194:197], v[22:25]
	v_mfma_f32_16x16x32_bf16 v[22:25], v[154:157], v[198:201], v[22:25]
	v_mfma_f32_16x16x32_bf16 v[18:21], v[158:161], v[194:197], v[18:21]
	v_mfma_f32_16x16x32_bf16 v[18:21], v[162:165], v[198:201], v[18:21]
	v_mfma_f32_16x16x32_bf16 v[2:5], v[158:161], v[202:205], v[2:5]
	v_mfma_f32_16x16x32_bf16 v[2:5], v[162:165], v[206:209], v[2:5]
	s_setprio 2
	s_barrier
	v_mfma_f32_16x16x32_bf16 v[6:9], v[150:153], v[202:205], v[6:9]
	v_mfma_f32_16x16x32_bf16 v[6:9], v[154:157], v[206:209], v[6:9]
	s_setprio 0
	ds_read_b128 v[130:133], v184
	ds_read_b128 v[134:137], v184 offset:1024
	ds_read_b128 v[138:141], v184 offset:2048
	ds_read_b128 v[142:145], v184 offset:3072
	ds_read_b128 v[150:153], v185
	ds_read_b128 v[154:157], v185 offset:1024
	ds_read_b128 v[158:161], v185 offset:2048
	ds_read_b128 v[162:165], v185 offset:3072
	ds_read_b128 v[166:169], v183 offset:32768
	ds_read_b128 v[170:173], v183 offset:33792
	ds_read_b128 v[186:189], v183 offset:34816
	ds_read_b128 v[190:193], v183 offset:35840
	ds_read_b128 v[194:197], v183 offset:36864
	ds_read_b128 v[198:201], v183 offset:37888
	ds_read_b128 v[202:205], v183 offset:38912
	ds_read_b128 v[206:209], v183 offset:39936
	s_mov_b32 s79, m0
	s_mov_b32 m0, s34
	s_nop 0
	global_load_lds_dwordx4 v1, s[24:25]
	s_mov_b32 m0, s79
	s_nop 0
	s_mov_b32 s79, m0
	s_mov_b32 m0, s41
	s_nop 0
	global_load_lds_dwordx4 v177, s[24:25]
	s_mov_b32 m0, s79
	s_add_u32 s24, s24, 0x4000
	s_addc_u32 s25, s25, 0
	s_mov_b32 s79, m0
	s_mov_b32 m0, s42
	s_nop 0
	global_load_lds_dwordx4 v1, s[24:25]
	s_mov_b32 m0, s79
	s_nop 0
	s_mov_b32 s79, m0
	s_mov_b32 m0, s43
	s_nop 0
	global_load_lds_dwordx4 v177, s[24:25]
	s_mov_b32 m0, s79
	s_waitcnt vmcnt(8)
	s_waitcnt lgkmcnt(0)
	s_waitcnt lgkmcnt(7)
	v_mfma_f32_16x16x32_bf16 v[126:129], v[130:133], v[166:169], v[126:129]
	v_mfma_f32_16x16x32_bf16 v[126:129], v[134:137], v[170:173], v[126:129]
	s_waitcnt lgkmcnt(5)
	v_mfma_f32_16x16x32_bf16 v[122:125], v[138:141], v[166:169], v[122:125]
	v_mfma_f32_16x16x32_bf16 v[122:125], v[142:145], v[170:173], v[122:125]
	s_barrier
	s_setprio 1
	s_waitcnt lgkmcnt(3)
	v_mfma_f32_16x16x32_bf16 v[110:113], v[138:141], v[186:189], v[110:113]
	v_mfma_f32_16x16x32_bf16 v[110:113], v[142:145], v[190:193], v[110:113]
	s_waitcnt lgkmcnt(1)
	v_mfma_f32_16x16x32_bf16 v[118:121], v[130:133], v[186:189], v[118:121]
	v_mfma_f32_16x16x32_bf16 v[118:121], v[134:137], v[190:193], v[118:121]
	v_mfma_f32_16x16x32_bf16 v[94:97], v[130:133], v[194:197], v[94:97]
	v_mfma_f32_16x16x32_bf16 v[94:97], v[134:137], v[198:201], v[94:97]
	v_mfma_f32_16x16x32_bf16 v[90:93], v[138:141], v[194:197], v[90:93]
	v_mfma_f32_16x16x32_bf16 v[90:93], v[142:145], v[198:201], v[90:93]
	v_mfma_f32_16x16x32_bf16 v[78:81], v[138:141], v[202:205], v[78:81]
	v_mfma_f32_16x16x32_bf16 v[78:81], v[142:145], v[206:209], v[78:81]
	s_waitcnt lgkmcnt(0)
	v_mfma_f32_16x16x32_bf16 v[86:89], v[130:133], v[202:205], v[86:89]
	v_mfma_f32_16x16x32_bf16 v[86:89], v[134:137], v[206:209], v[86:89]
	s_setprio 0
	s_setprio 1
	v_mfma_f32_16x16x32_bf16 v[114:117], v[150:153], v[166:169], v[114:117]
	v_mfma_f32_16x16x32_bf16 v[114:117], v[154:157], v[170:173], v[114:117]
	v_mfma_f32_16x16x32_bf16 v[106:109], v[158:161], v[166:169], v[106:109]
	v_mfma_f32_16x16x32_bf16 v[106:109], v[162:165], v[170:173], v[106:109]
	v_mfma_f32_16x16x32_bf16 v[98:101], v[158:161], v[186:189], v[98:101]
	v_mfma_f32_16x16x32_bf16 v[98:101], v[162:165], v[190:193], v[98:101]
	v_mfma_f32_16x16x32_bf16 v[102:105], v[150:153], v[186:189], v[102:105]
	v_mfma_f32_16x16x32_bf16 v[102:105], v[154:157], v[190:193], v[102:105]
	v_mfma_f32_16x16x32_bf16 v[82:85], v[150:153], v[194:197], v[82:85]
	v_mfma_f32_16x16x32_bf16 v[82:85], v[154:157], v[198:201], v[82:85]
	v_mfma_f32_16x16x32_bf16 v[74:77], v[158:161], v[194:197], v[74:77]
	v_mfma_f32_16x16x32_bf16 v[74:77], v[162:165], v[198:201], v[74:77]
	v_mfma_f32_16x16x32_bf16 v[66:69], v[158:161], v[202:205], v[66:69]
	v_mfma_f32_16x16x32_bf16 v[66:69], v[162:165], v[206:209], v[66:69]
	s_setprio 2
	s_barrier
	v_mfma_f32_16x16x32_bf16 v[70:73], v[150:153], v[202:205], v[70:73]
	v_mfma_f32_16x16x32_bf16 v[70:73], v[154:157], v[206:209], v[70:73]
	s_setprio 0
	ds_read_b128 v[166:169], v183 offset:49152
	ds_read_b128 v[170:173], v183 offset:50176
	ds_read_b128 v[186:189], v183 offset:51200
	ds_read_b128 v[190:193], v183 offset:52224
	ds_read_b128 v[194:197], v183 offset:53248
	ds_read_b128 v[198:201], v183 offset:54272
	ds_read_b128 v[202:205], v183 offset:55296
	ds_read_b128 v[206:209], v183 offset:56320
	s_add_u32 s24, s22, 0x40000
	s_addc_u32 s25, s23, 0
	s_mov_b32 s79, m0
	s_mov_b32 m0, s46
	s_nop 0
	global_load_lds_dwordx4 v176, s[24:25]
	s_mov_b32 m0, s79
	s_add_u32 s22, s22, 0x44000
	s_mov_b32 s79, m0
	s_mov_b32 m0, s47
	s_nop 0
	global_load_lds_dwordx4 v178, s[24:25]
	s_mov_b32 m0, s79
	s_addc_u32 s23, s23, 0
	s_mov_b32 s24, m0
	s_mov_b32 m0, s48
	s_nop 0
	global_load_lds_dwordx4 v176, s[22:23]
	s_mov_b32 m0, s24
	s_nop 0
	s_mov_b32 s24, m0
	s_mov_b32 m0, s49
	s_nop 0
	global_load_lds_dwordx4 v178, s[22:23]
	s_mov_b32 m0, s24
	s_waitcnt vmcnt(4)
	s_waitcnt lgkmcnt(0)
	s_waitcnt lgkmcnt(7)
	v_mfma_f32_16x16x32_bf16 v[62:65], v[130:133], v[166:169], v[62:65]
	v_mfma_f32_16x16x32_bf16 v[62:65], v[134:137], v[170:173], v[62:65]
	s_waitcnt lgkmcnt(5)
	v_mfma_f32_16x16x32_bf16 v[58:61], v[138:141], v[166:169], v[58:61]
	v_mfma_f32_16x16x32_bf16 v[58:61], v[142:145], v[170:173], v[58:61]
	s_barrier
	s_setprio 1
	s_waitcnt lgkmcnt(3)
	v_mfma_f32_16x16x32_bf16 v[42:45], v[138:141], v[186:189], v[42:45]
	v_mfma_f32_16x16x32_bf16 v[42:45], v[142:145], v[190:193], v[42:45]
	s_waitcnt lgkmcnt(1)
	v_mfma_f32_16x16x32_bf16 v[46:49], v[130:133], v[186:189], v[46:49]
	v_mfma_f32_16x16x32_bf16 v[46:49], v[134:137], v[190:193], v[46:49]
	v_mfma_f32_16x16x32_bf16 v[30:33], v[130:133], v[194:197], v[30:33]
	v_mfma_f32_16x16x32_bf16 v[30:33], v[134:137], v[198:201], v[30:33]
	v_mfma_f32_16x16x32_bf16 v[26:29], v[138:141], v[194:197], v[26:29]
	v_mfma_f32_16x16x32_bf16 v[26:29], v[142:145], v[198:201], v[26:29]
	v_mfma_f32_16x16x32_bf16 v[10:13], v[138:141], v[202:205], v[10:13]
	v_mfma_f32_16x16x32_bf16 v[10:13], v[142:145], v[206:209], v[10:13]
	s_waitcnt lgkmcnt(0)
	v_mfma_f32_16x16x32_bf16 v[14:17], v[130:133], v[202:205], v[14:17]
	v_mfma_f32_16x16x32_bf16 v[14:17], v[134:137], v[206:209], v[14:17]
	s_setprio 0
	s_setprio 1
	v_mfma_f32_16x16x32_bf16 v[54:57], v[150:153], v[166:169], v[54:57]
	v_mfma_f32_16x16x32_bf16 v[54:57], v[154:157], v[170:173], v[54:57]
	v_mfma_f32_16x16x32_bf16 v[50:53], v[158:161], v[166:169], v[50:53]
	v_mfma_f32_16x16x32_bf16 v[50:53], v[162:165], v[170:173], v[50:53]
	v_mfma_f32_16x16x32_bf16 v[34:37], v[158:161], v[186:189], v[34:37]
	v_mfma_f32_16x16x32_bf16 v[34:37], v[162:165], v[190:193], v[34:37]
	v_mfma_f32_16x16x32_bf16 v[38:41], v[150:153], v[186:189], v[38:41]
	v_mfma_f32_16x16x32_bf16 v[38:41], v[154:157], v[190:193], v[38:41]
	v_mfma_f32_16x16x32_bf16 v[22:25], v[150:153], v[194:197], v[22:25]
	v_mfma_f32_16x16x32_bf16 v[22:25], v[154:157], v[198:201], v[22:25]
	v_mfma_f32_16x16x32_bf16 v[18:21], v[158:161], v[194:197], v[18:21]
	v_mfma_f32_16x16x32_bf16 v[18:21], v[162:165], v[198:201], v[18:21]
	v_mfma_f32_16x16x32_bf16 v[2:5], v[158:161], v[202:205], v[2:5]
	v_mfma_f32_16x16x32_bf16 v[2:5], v[162:165], v[206:209], v[2:5]
	s_setprio 2
	s_barrier
	v_mfma_f32_16x16x32_bf16 v[6:9], v[150:153], v[202:205], v[6:9]
	v_mfma_f32_16x16x32_bf16 v[6:9], v[154:157], v[206:209], v[6:9]
	s_setprio 0
	s_add_i32 s78, s78, 2
	s_add_u32 s74, s74, 0x80000
	s_addc_u32 s75, s75, 0
	s_add_u32 s20, s20, 0x400000
	s_addc_u32 s21, s21, 0
	s_add_u32 s76, s76, 0x400000
	s_addc_u32 s77, s77, 0
	s_cmpk_gt_u32 s78, 0x53
	s_cbranch_scc0 .LBB0_1357
	s_and_b64 vcc, exec, s[8:9]
	s_cbranch_vccz .LBB0_1360
	s_barrier

.LBB0_1537:
	s_ashr_i32 s23, s22, 31
	s_lshl_b64 s[24:25], s[22:23], 20
	s_add_u32 s24, s41, s24
	s_addc_u32 s25, s42, s25
	s_and_b64 s[26:27], s[4:5], exec
	s_cselect_b32 s7, s25, s35
	s_cselect_b32 s23, s24, s34
	s_ashr_i32 s21, s20, 31
	s_lshl_b64 s[26:27], s[20:21], 20
	s_add_u32 s26, s43, s26
	s_addc_u32 s27, s46, s27
	s_and_b64 s[36:37], s[4:5], exec
	s_cselect_b32 s21, s27, s31
	s_cselect_b32 s29, s26, s30
	s_add_u32 s79, s30, 0x100
	s_addc_u32 s80, s31, 0
	s_add_u32 s30, s34, 0x80080
	s_addc_u32 s31, s35, 0
	s_add_u32 s81, s34, 0x100
	s_addc_u32 s82, s35, 0
	s_mov_b32 s83, -2
	s_waitcnt vmcnt(25)
	s_waitcnt vmcnt(24)
	s_waitcnt vmcnt(4)
	s_waitcnt vmcnt(14)
	s_waitcnt vmcnt(13)
	s_waitcnt vmcnt(12)
	s_waitcnt vmcnt(2)
	s_waitcnt vmcnt(10)
	s_waitcnt vmcnt(9)
	s_waitcnt vmcnt(8)
	s_waitcnt vmcnt(7)
	s_waitcnt vmcnt(6)
	s_waitcnt vmcnt(5)
	s_waitcnt vmcnt(4)
	s_waitcnt vmcnt(3)
	s_waitcnt vmcnt(2)
	s_waitcnt vmcnt(1)
	s_waitcnt vmcnt(0)
	ds_read_b128 v[46:49], v182
	ds_read_b128 v[54:57], v182 offset:1024
	ds_read_b128 v[58:61], v182 offset:2048
	ds_read_b128 v[62:65], v182 offset:3072
	ds_read_b128 v[146:149], v183
	ds_read_b128 v[150:153], v183 offset:1024
	ds_read_b128 v[154:157], v183 offset:2048
	ds_read_b128 v[158:161], v183 offset:3072
	s_cmp_eq_u32 s83, 28
	s_cselect_b32 s35, s21, s80
	s_cselect_b32 s34, s29, s79
	s_cselect_b32 s37, s7, s82
	s_cselect_b32 s36, s23, s81
	ds_read_b128 v[170:173], v184
	ds_read_b128 v[188:191], v184 offset:1024
	ds_read_b128 v[192:195], v184 offset:2048
	ds_read_b128 v[196:199], v184 offset:3072
	ds_read_b128 v[200:203], v184 offset:4096
	ds_read_b128 v[204:207], v184 offset:5120
	ds_read_b128 v[208:211], v184 offset:6144
	ds_read_b128 v[212:215], v184 offset:7168
	s_add_u32 s86, s30, 0xfff80000
	s_addc_u32 s87, s31, -1
	s_mov_b32 s92, m0
	s_mov_b32 m0, s73
	s_nop 0
	global_load_lds_dwordx4 v176, s[86:87]
	s_mov_b32 m0, s92
	s_nop 0
	s_mov_b32 s92, m0
	s_mov_b32 m0, s75
	s_nop 0
	global_load_lds_dwordx4 v178, s[86:87]
	s_mov_b32 m0, s92
	s_mov_b32 s86, m0
	s_mov_b32 m0, s74
	s_nop 0
	global_load_lds_dwordx4 v176, s[30:31]
	s_mov_b32 m0, s86
	s_nop 0
	s_mov_b32 s86, m0
	s_mov_b32 m0, s76
	s_nop 0
	global_load_lds_dwordx4 v178, s[30:31]
	s_mov_b32 m0, s86
	s_waitcnt vmcnt(8)
	s_waitcnt lgkmcnt(0)
	s_waitcnt lgkmcnt(7)
	v_mfma_f32_16x16x32_bf16 v[142:145], v[46:49], v[170:173], 0
	v_mfma_f32_16x16x32_bf16 v[142:145], v[54:57], v[188:191], v[142:145]
	s_waitcnt lgkmcnt(5)
	v_mfma_f32_16x16x32_bf16 v[138:141], v[58:61], v[170:173], 0
	v_mfma_f32_16x16x32_bf16 v[138:141], v[62:65], v[188:191], v[138:141]
	s_barrier
	s_setprio 1
	s_waitcnt lgkmcnt(3)
	v_mfma_f32_16x16x32_bf16 v[126:129], v[46:49], v[192:195], 0
	v_mfma_f32_16x16x32_bf16 v[126:129], v[54:57], v[196:199], v[126:129]
	s_waitcnt lgkmcnt(1)
	v_mfma_f32_16x16x32_bf16 v[122:125], v[58:61], v[192:195], 0
	v_mfma_f32_16x16x32_bf16 v[122:125], v[62:65], v[196:199], v[122:125]
	v_mfma_f32_16x16x32_bf16 v[110:113], v[46:49], v[200:203], 0
	v_mfma_f32_16x16x32_bf16 v[110:113], v[54:57], v[204:207], v[110:113]
	v_mfma_f32_16x16x32_bf16 v[106:109], v[58:61], v[200:203], 0
	v_mfma_f32_16x16x32_bf16 v[106:109], v[62:65], v[204:207], v[106:109]
	v_mfma_f32_16x16x32_bf16 v[94:97], v[46:49], v[208:211], 0
	v_mfma_f32_16x16x32_bf16 v[94:97], v[54:57], v[212:215], v[94:97]
	s_waitcnt lgkmcnt(0)
	v_mfma_f32_16x16x32_bf16 v[90:93], v[58:61], v[208:211], 0
	v_mfma_f32_16x16x32_bf16 v[90:93], v[62:65], v[212:215], v[90:93]
	s_setprio 0
	s_setprio 1
	v_mfma_f32_16x16x32_bf16 v[134:137], v[146:149], v[170:173], 0
	v_mfma_f32_16x16x32_bf16 v[134:137], v[150:153], v[188:191], v[134:137]
	v_mfma_f32_16x16x32_bf16 v[130:133], v[154:157], v[170:173], 0
	v_mfma_f32_16x16x32_bf16 v[130:133], v[158:161], v[188:191], v[130:133]
	v_mfma_f32_16x16x32_bf16 v[118:121], v[146:149], v[192:195], 0
	v_mfma_f32_16x16x32_bf16 v[118:121], v[150:153], v[196:199], v[118:121]
	v_mfma_f32_16x16x32_bf16 v[114:117], v[154:157], v[192:195], 0
	v_mfma_f32_16x16x32_bf16 v[114:117], v[158:161], v[196:199], v[114:117]
	v_mfma_f32_16x16x32_bf16 v[102:105], v[146:149], v[200:203], 0
	v_mfma_f32_16x16x32_bf16 v[102:105], v[150:153], v[204:207], v[102:105]
	v_mfma_f32_16x16x32_bf16 v[98:101], v[154:157], v[200:203], 0
	v_mfma_f32_16x16x32_bf16 v[98:101], v[158:161], v[204:207], v[98:101]
	v_mfma_f32_16x16x32_bf16 v[86:89], v[146:149], v[208:211], 0
	v_mfma_f32_16x16x32_bf16 v[86:89], v[150:153], v[212:215], v[86:89]
	s_setprio 2
	s_barrier
	v_mfma_f32_16x16x32_bf16 v[82:85], v[154:157], v[208:211], 0
	v_mfma_f32_16x16x32_bf16 v[82:85], v[158:161], v[212:215], v[82:85]
	s_setprio 0
	ds_read_b128 v[170:173], v184 offset:16384
	ds_read_b128 v[188:191], v184 offset:17408
	ds_read_b128 v[192:195], v184 offset:18432
	ds_read_b128 v[196:199], v184 offset:19456
	ds_read_b128 v[200:203], v184 offset:20480
	ds_read_b128 v[204:207], v184 offset:21504
	ds_read_b128 v[208:211], v184 offset:22528
	ds_read_b128 v[212:215], v184 offset:23552
	s_mov_b32 s86, m0
	s_mov_b32 m0, s49
	s_nop 0
	global_load_lds_dwordx4 v177, s[34:35]
	s_mov_b32 m0, s86
	s_nop 0
	s_mov_b32 s86, m0
	s_mov_b32 m0, s56
	s_nop 0
	global_load_lds_dwordx4 v179, s[34:35]
	s_mov_b32 m0, s86
	s_add_u32 s86, s34, 0x80000
	s_addc_u32 s87, s35, 0
	s_mov_b32 s92, m0
	s_mov_b32 m0, s57
	s_nop 0
	global_load_lds_dwordx4 v177, s[86:87]
	s_mov_b32 m0, s92
	s_nop 0
	s_mov_b32 s92, m0
	s_mov_b32 m0, s58
	s_nop 0
	global_load_lds_dwordx4 v179, s[86:87]
	s_mov_b32 m0, s92
	s_waitcnt vmcnt(4)
	s_waitcnt lgkmcnt(0)
	s_waitcnt lgkmcnt(7)
	v_mfma_f32_16x16x32_bf16 v[78:81], v[46:49], v[170:173], 0
	v_mfma_f32_16x16x32_bf16 v[78:81], v[54:57], v[188:191], v[78:81]
	s_waitcnt lgkmcnt(5)
	v_mfma_f32_16x16x32_bf16 v[74:77], v[58:61], v[170:173], 0
	v_mfma_f32_16x16x32_bf16 v[74:77], v[62:65], v[188:191], v[74:77]
	s_barrier
	s_setprio 1
	s_waitcnt lgkmcnt(3)
	v_mfma_f32_16x16x32_bf16 v[50:53], v[46:49], v[192:195], 0
	v_mfma_f32_16x16x32_bf16 v[50:53], v[54:57], v[196:199], v[50:53]
	s_waitcnt lgkmcnt(1)
	v_mfma_f32_16x16x32_bf16 v[42:45], v[58:61], v[192:195], 0
	v_mfma_f32_16x16x32_bf16 v[42:45], v[62:65], v[196:199], v[42:45]
	v_mfma_f32_16x16x32_bf16 v[30:33], v[46:49], v[200:203], 0
	v_mfma_f32_16x16x32_bf16 v[30:33], v[54:57], v[204:207], v[30:33]
	v_mfma_f32_16x16x32_bf16 v[26:29], v[58:61], v[200:203], 0
	v_mfma_f32_16x16x32_bf16 v[26:29], v[62:65], v[204:207], v[26:29]
	v_mfma_f32_16x16x32_bf16 v[14:17], v[46:49], v[208:211], 0
	v_mfma_f32_16x16x32_bf16 v[14:17], v[54:57], v[212:215], v[14:17]
	s_waitcnt lgkmcnt(0)
	v_mfma_f32_16x16x32_bf16 v[10:13], v[58:61], v[208:211], 0
	v_mfma_f32_16x16x32_bf16 v[10:13], v[62:65], v[212:215], v[10:13]
	s_setprio 0
	s_setprio 1
	v_mfma_f32_16x16x32_bf16 v[38:41], v[146:149], v[192:195], 0
	v_mfma_f32_16x16x32_bf16 v[38:41], v[150:153], v[196:199], v[38:41]
	v_mfma_f32_16x16x32_bf16 v[34:37], v[154:157], v[192:195], 0
	v_mfma_f32_16x16x32_bf16 v[34:37], v[158:161], v[196:199], v[34:37]
	v_mfma_f32_16x16x32_bf16 v[22:25], v[146:149], v[200:203], 0
	v_mfma_f32_16x16x32_bf16 v[22:25], v[150:153], v[204:207], v[22:25]
	v_mfma_f32_16x16x32_bf16 v[18:21], v[154:157], v[200:203], 0
	v_mfma_f32_16x16x32_bf16 v[18:21], v[158:161], v[204:207], v[18:21]
	v_mfma_f32_16x16x32_bf16 v[6:9], v[146:149], v[208:211], 0
	v_mfma_f32_16x16x32_bf16 v[6:9], v[150:153], v[212:215], v[6:9]
	v_mfma_f32_16x16x32_bf16 v[2:5], v[154:157], v[208:211], 0
	v_mfma_f32_16x16x32_bf16 v[2:5], v[158:161], v[212:215], v[2:5]
	v_mfma_f32_16x16x32_bf16 v[46:49], v[146:149], v[170:173], 0
	v_mfma_f32_16x16x32_bf16 v[46:49], v[150:153], v[188:191], v[46:49]
	s_setprio 2
	s_barrier
	v_mfma_f32_16x16x32_bf16 v[54:57], v[154:157], v[170:173], 0
	v_mfma_f32_16x16x32_bf16 v[54:57], v[158:161], v[188:191], v[54:57]
	s_setprio 0
	ds_read_b128 v[58:61], v185
	ds_read_b128 v[62:65], v185 offset:1024
	ds_read_b128 v[66:69], v185 offset:2048
	ds_read_b128 v[70:73], v185 offset:3072
	ds_read_b128 v[146:149], v186
	ds_read_b128 v[150:153], v186 offset:1024
	ds_read_b128 v[154:157], v186 offset:2048
	ds_read_b128 v[158:161], v186 offset:3072
	ds_read_b128 v[170:173], v184 offset:32768
	ds_read_b128 v[188:191], v184 offset:33792
	ds_read_b128 v[192:195], v184 offset:34816
	ds_read_b128 v[196:199], v184 offset:35840
	ds_read_b128 v[200:203], v184 offset:36864
	ds_read_b128 v[204:207], v184 offset:37888
	ds_read_b128 v[208:211], v184 offset:38912
	ds_read_b128 v[212:215], v184 offset:39936
	s_mov_b32 s86, m0
	s_mov_b32 m0, s48
	s_nop 0
	global_load_lds_dwordx4 v176, s[36:37]
	s_mov_b32 m0, s86
	s_nop 0
	s_mov_b32 s86, m0
	s_mov_b32 m0, s59
	s_nop 0
	global_load_lds_dwordx4 v178, s[36:37]
	s_mov_b32 m0, s86
	s_add_u32 s36, s36, 0x80000
	s_addc_u32 s37, s37, 0
	s_mov_b32 s86, m0
	s_mov_b32 m0, s62
	s_nop 0
	global_load_lds_dwordx4 v176, s[36:37]
	s_mov_b32 m0, s86
	s_nop 0
	s_mov_b32 s86, m0
	s_mov_b32 m0, s63
	s_nop 0
	global_load_lds_dwordx4 v178, s[36:37]
	s_mov_b32 m0, s86
	s_waitcnt vmcnt(8)
	s_waitcnt lgkmcnt(0)
	s_waitcnt lgkmcnt(7)
	v_mfma_f32_16x16x32_bf16 v[142:145], v[58:61], v[170:173], v[142:145]
	v_mfma_f32_16x16x32_bf16 v[142:145], v[62:65], v[188:191], v[142:145]
	s_waitcnt lgkmcnt(5)
	v_mfma_f32_16x16x32_bf16 v[138:141], v[66:69], v[170:173], v[138:141]
	v_mfma_f32_16x16x32_bf16 v[138:141], v[70:73], v[188:191], v[138:141]
	s_barrier
	s_setprio 1
	s_waitcnt lgkmcnt(3)
	v_mfma_f32_16x16x32_bf16 v[126:129], v[58:61], v[192:195], v[126:129]
	v_mfma_f32_16x16x32_bf16 v[126:129], v[62:65], v[196:199], v[126:129]
	s_waitcnt lgkmcnt(1)
	v_mfma_f32_16x16x32_bf16 v[122:125], v[66:69], v[192:195], v[122:125]
	v_mfma_f32_16x16x32_bf16 v[122:125], v[70:73], v[196:199], v[122:125]
	v_mfma_f32_16x16x32_bf16 v[110:113], v[58:61], v[200:203], v[110:113]
	v_mfma_f32_16x16x32_bf16 v[110:113], v[62:65], v[204:207], v[110:113]
	v_mfma_f32_16x16x32_bf16 v[106:109], v[66:69], v[200:203], v[106:109]
	v_mfma_f32_16x16x32_bf16 v[106:109], v[70:73], v[204:207], v[106:109]
	v_mfma_f32_16x16x32_bf16 v[94:97], v[58:61], v[208:211], v[94:97]
	v_mfma_f32_16x16x32_bf16 v[94:97], v[62:65], v[212:215], v[94:97]
	s_waitcnt lgkmcnt(0)
	v_mfma_f32_16x16x32_bf16 v[90:93], v[66:69], v[208:211], v[90:93]
	v_mfma_f32_16x16x32_bf16 v[90:93], v[70:73], v[212:215], v[90:93]
	s_setprio 0
	s_setprio 1
	v_mfma_f32_16x16x32_bf16 v[134:137], v[146:149], v[170:173], v[134:137]
	v_mfma_f32_16x16x32_bf16 v[134:137], v[150:153], v[188:191], v[134:137]
	v_mfma_f32_16x16x32_bf16 v[130:133], v[154:157], v[170:173], v[130:133]
	v_mfma_f32_16x16x32_bf16 v[130:133], v[158:161], v[188:191], v[130:133]
	v_mfma_f32_16x16x32_bf16 v[118:121], v[146:149], v[192:195], v[118:121]
	v_mfma_f32_16x16x32_bf16 v[118:121], v[150:153], v[196:199], v[118:121]
	v_mfma_f32_16x16x32_bf16 v[114:117], v[154:157], v[192:195], v[114:117]
	v_mfma_f32_16x16x32_bf16 v[114:117], v[158:161], v[196:199], v[114:117]
	v_mfma_f32_16x16x32_bf16 v[102:105], v[146:149], v[200:203], v[102:105]
	v_mfma_f32_16x16x32_bf16 v[102:105], v[150:153], v[204:207], v[102:105]
	v_mfma_f32_16x16x32_bf16 v[98:101], v[154:157], v[200:203], v[98:101]
	v_mfma_f32_16x16x32_bf16 v[98:101], v[158:161], v[204:207], v[98:101]
	v_mfma_f32_16x16x32_bf16 v[86:89], v[146:149], v[208:211], v[86:89]
	v_mfma_f32_16x16x32_bf16 v[86:89], v[150:153], v[212:215], v[86:89]
	s_setprio 2
	s_barrier
	v_mfma_f32_16x16x32_bf16 v[82:85], v[154:157], v[208:211], v[82:85]
	v_mfma_f32_16x16x32_bf16 v[82:85], v[158:161], v[212:215], v[82:85]
	s_setprio 0
	ds_read_b128 v[170:173], v184 offset:49152
	ds_read_b128 v[188:191], v184 offset:50176
	ds_read_b128 v[192:195], v184 offset:51200
	ds_read_b128 v[196:199], v184 offset:52224
	ds_read_b128 v[200:203], v184 offset:53248
	ds_read_b128 v[204:207], v184 offset:54272
	ds_read_b128 v[208:211], v184 offset:55296
	ds_read_b128 v[212:215], v184 offset:56320
	s_add_u32 s36, s34, 0x80
	s_addc_u32 s37, s35, 0
	s_mov_b32 s86, m0
	s_mov_b32 m0, s64
	s_nop 0
	global_load_lds_dwordx4 v177, s[36:37]
	s_mov_b32 m0, s86
	s_add_u32 s34, s34, 0x80080
	s_mov_b32 s86, m0
	s_mov_b32 m0, s65
	s_nop 0
	global_load_lds_dwordx4 v179, s[36:37]
	s_mov_b32 m0, s86
	s_addc_u32 s35, s35, 0
	s_mov_b32 s36, m0
	s_mov_b32 m0, s66
	s_nop 0
	global_load_lds_dwordx4 v177, s[34:35]
	s_mov_b32 m0, s36
	s_nop 0
	s_mov_b32 s36, m0
	s_mov_b32 m0, s67
	s_nop 0
	global_load_lds_dwordx4 v179, s[34:35]
	s_mov_b32 m0, s36
	s_waitcnt vmcnt(4)
	s_waitcnt lgkmcnt(0)
	s_waitcnt lgkmcnt(7)
	v_mfma_f32_16x16x32_bf16 v[78:81], v[58:61], v[170:173], v[78:81]
	v_mfma_f32_16x16x32_bf16 v[78:81], v[62:65], v[188:191], v[78:81]
	s_waitcnt lgkmcnt(5)
	v_mfma_f32_16x16x32_bf16 v[74:77], v[66:69], v[170:173], v[74:77]
	v_mfma_f32_16x16x32_bf16 v[74:77], v[70:73], v[188:191], v[74:77]
	s_barrier
	s_setprio 1
	s_waitcnt lgkmcnt(3)
	v_mfma_f32_16x16x32_bf16 v[50:53], v[58:61], v[192:195], v[50:53]
	v_mfma_f32_16x16x32_bf16 v[50:53], v[62:65], v[196:199], v[50:53]
	s_waitcnt lgkmcnt(1)
	v_mfma_f32_16x16x32_bf16 v[42:45], v[66:69], v[192:195], v[42:45]
	v_mfma_f32_16x16x32_bf16 v[42:45], v[70:73], v[196:199], v[42:45]
	v_mfma_f32_16x16x32_bf16 v[30:33], v[58:61], v[200:203], v[30:33]
	v_mfma_f32_16x16x32_bf16 v[30:33], v[62:65], v[204:207], v[30:33]
	v_mfma_f32_16x16x32_bf16 v[26:29], v[66:69], v[200:203], v[26:29]
	v_mfma_f32_16x16x32_bf16 v[26:29], v[70:73], v[204:207], v[26:29]
	v_mfma_f32_16x16x32_bf16 v[14:17], v[58:61], v[208:211], v[14:17]
	v_mfma_f32_16x16x32_bf16 v[14:17], v[62:65], v[212:215], v[14:17]
	s_waitcnt lgkmcnt(0)
	v_mfma_f32_16x16x32_bf16 v[10:13], v[66:69], v[208:211], v[10:13]
	v_mfma_f32_16x16x32_bf16 v[10:13], v[70:73], v[212:215], v[10:13]
	s_setprio 0
	s_setprio 1
	v_mfma_f32_16x16x32_bf16 v[46:49], v[146:149], v[170:173], v[46:49]
	v_mfma_f32_16x16x32_bf16 v[70:73], v[150:153], v[188:191], v[46:49]
	v_mfma_f32_16x16x32_bf16 v[46:49], v[154:157], v[170:173], v[54:57]
	v_mfma_f32_16x16x32_bf16 v[66:69], v[158:161], v[188:191], v[46:49]
	v_mfma_f32_16x16x32_bf16 v[38:41], v[146:149], v[192:195], v[38:41]
	v_mfma_f32_16x16x32_bf16 v[38:41], v[150:153], v[196:199], v[38:41]
	v_mfma_f32_16x16x32_bf16 v[34:37], v[154:157], v[192:195], v[34:37]
	v_mfma_f32_16x16x32_bf16 v[34:37], v[158:161], v[196:199], v[34:37]
	v_mfma_f32_16x16x32_bf16 v[22:25], v[146:149], v[200:203], v[22:25]
	v_mfma_f32_16x16x32_bf16 v[22:25], v[150:153], v[204:207], v[22:25]
	v_mfma_f32_16x16x32_bf16 v[18:21], v[154:157], v[200:203], v[18:21]
	v_mfma_f32_16x16x32_bf16 v[18:21], v[158:161], v[204:207], v[18:21]
	v_mfma_f32_16x16x32_bf16 v[6:9], v[146:149], v[208:211], v[6:9]
	v_mfma_f32_16x16x32_bf16 v[6:9], v[150:153], v[212:215], v[6:9]
	s_setprio 2
	s_barrier
	v_mfma_f32_16x16x32_bf16 v[2:5], v[154:157], v[208:211], v[2:5]
	v_mfma_f32_16x16x32_bf16 v[2:5], v[158:161], v[212:215], v[2:5]
	s_setprio 0
	s_add_i32 s83, s83, 2
	s_add_u32 s79, s79, 0x100
	s_addc_u32 s80, s80, 0
	s_add_u32 s30, s30, 0x100
	s_addc_u32 s31, s31, 0
	s_add_u32 s81, s81, 0x100
	s_addc_u32 s82, s82, 0
	s_cmp_gt_u32 s83, 29
	.p2align 6
.LBB0_1538:
	ds_read_b128 v[46:49], v182
	ds_read_b128 v[54:57], v182 offset:1024
	ds_read_b128 v[58:61], v182 offset:2048
	ds_read_b128 v[62:65], v182 offset:3072
	ds_read_b128 v[146:149], v183
	ds_read_b128 v[150:153], v183 offset:1024
	ds_read_b128 v[154:157], v183 offset:2048
	ds_read_b128 v[158:161], v183 offset:3072
	s_cmp_eq_u32 s83, 28
	s_cselect_b32 s35, s21, s80
	s_cselect_b32 s34, s29, s79
	s_cselect_b32 s37, s7, s82
	s_cselect_b32 s36, s23, s81
	ds_read_b128 v[170:173], v184
	ds_read_b128 v[188:191], v184 offset:1024
	ds_read_b128 v[192:195], v184 offset:2048
	ds_read_b128 v[196:199], v184 offset:3072
	ds_read_b128 v[200:203], v184 offset:4096
	ds_read_b128 v[204:207], v184 offset:5120
	ds_read_b128 v[208:211], v184 offset:6144
	ds_read_b128 v[212:215], v184 offset:7168
	s_add_u32 s86, s30, 0xfff80000
	s_addc_u32 s87, s31, -1
	s_mov_b32 s92, m0
	s_mov_b32 m0, s73
	s_nop 0
	global_load_lds_dwordx4 v176, s[86:87]
	s_mov_b32 m0, s92
	s_nop 0
	s_mov_b32 s92, m0
	s_mov_b32 m0, s75
	s_nop 0
	global_load_lds_dwordx4 v178, s[86:87]
	s_mov_b32 m0, s92
	s_mov_b32 s86, m0
	s_mov_b32 m0, s74
	s_nop 0
	global_load_lds_dwordx4 v176, s[30:31]
	s_mov_b32 m0, s86
	s_nop 0
	s_mov_b32 s86, m0
	s_mov_b32 m0, s76
	s_nop 0
	global_load_lds_dwordx4 v178, s[30:31]
	s_mov_b32 m0, s86
	s_waitcnt vmcnt(8)
	s_waitcnt lgkmcnt(0)
	s_waitcnt lgkmcnt(7)
	v_mfma_f32_16x16x32_bf16 v[142:145], v[46:49], v[170:173], v[142:145]
	v_mfma_f32_16x16x32_bf16 v[142:145], v[54:57], v[188:191], v[142:145]
	s_waitcnt lgkmcnt(5)
	v_mfma_f32_16x16x32_bf16 v[138:141], v[58:61], v[170:173], v[138:141]
	v_mfma_f32_16x16x32_bf16 v[138:141], v[62:65], v[188:191], v[138:141]
	s_barrier
	s_setprio 1
	s_waitcnt lgkmcnt(3)
	v_mfma_f32_16x16x32_bf16 v[126:129], v[46:49], v[192:195], v[126:129]
	v_mfma_f32_16x16x32_bf16 v[126:129], v[54:57], v[196:199], v[126:129]
	s_waitcnt lgkmcnt(1)
	v_mfma_f32_16x16x32_bf16 v[122:125], v[58:61], v[192:195], v[122:125]
	v_mfma_f32_16x16x32_bf16 v[122:125], v[62:65], v[196:199], v[122:125]
	v_mfma_f32_16x16x32_bf16 v[110:113], v[46:49], v[200:203], v[110:113]
	v_mfma_f32_16x16x32_bf16 v[110:113], v[54:57], v[204:207], v[110:113]
	v_mfma_f32_16x16x32_bf16 v[106:109], v[58:61], v[200:203], v[106:109]
	v_mfma_f32_16x16x32_bf16 v[106:109], v[62:65], v[204:207], v[106:109]
	v_mfma_f32_16x16x32_bf16 v[94:97], v[46:49], v[208:211], v[94:97]
	v_mfma_f32_16x16x32_bf16 v[94:97], v[54:57], v[212:215], v[94:97]
	s_waitcnt lgkmcnt(0)
	v_mfma_f32_16x16x32_bf16 v[90:93], v[58:61], v[208:211], v[90:93]
	v_mfma_f32_16x16x32_bf16 v[90:93], v[62:65], v[212:215], v[90:93]
	s_setprio 0
	s_setprio 1
	v_mfma_f32_16x16x32_bf16 v[134:137], v[146:149], v[170:173], v[134:137]
	v_mfma_f32_16x16x32_bf16 v[134:137], v[150:153], v[188:191], v[134:137]
	v_mfma_f32_16x16x32_bf16 v[130:133], v[154:157], v[170:173], v[130:133]
	v_mfma_f32_16x16x32_bf16 v[130:133], v[158:161], v[188:191], v[130:133]
	v_mfma_f32_16x16x32_bf16 v[118:121], v[146:149], v[192:195], v[118:121]
	v_mfma_f32_16x16x32_bf16 v[118:121], v[150:153], v[196:199], v[118:121]
	v_mfma_f32_16x16x32_bf16 v[114:117], v[154:157], v[192:195], v[114:117]
	v_mfma_f32_16x16x32_bf16 v[114:117], v[158:161], v[196:199], v[114:117]
	v_mfma_f32_16x16x32_bf16 v[102:105], v[146:149], v[200:203], v[102:105]
	v_mfma_f32_16x16x32_bf16 v[102:105], v[150:153], v[204:207], v[102:105]
	v_mfma_f32_16x16x32_bf16 v[98:101], v[154:157], v[200:203], v[98:101]
	v_mfma_f32_16x16x32_bf16 v[98:101], v[158:161], v[204:207], v[98:101]
	v_mfma_f32_16x16x32_bf16 v[86:89], v[146:149], v[208:211], v[86:89]
	v_mfma_f32_16x16x32_bf16 v[86:89], v[150:153], v[212:215], v[86:89]
	s_setprio 2
	s_barrier
	v_mfma_f32_16x16x32_bf16 v[82:85], v[154:157], v[208:211], v[82:85]
	v_mfma_f32_16x16x32_bf16 v[82:85], v[158:161], v[212:215], v[82:85]
	s_setprio 0
	ds_read_b128 v[170:173], v184 offset:16384
	ds_read_b128 v[188:191], v184 offset:17408
	ds_read_b128 v[192:195], v184 offset:18432
	ds_read_b128 v[196:199], v184 offset:19456
	ds_read_b128 v[200:203], v184 offset:20480
	ds_read_b128 v[204:207], v184 offset:21504
	ds_read_b128 v[208:211], v184 offset:22528
	ds_read_b128 v[212:215], v184 offset:23552
	s_mov_b32 s86, m0
	s_mov_b32 m0, s49
	s_nop 0
	global_load_lds_dwordx4 v177, s[34:35]
	s_mov_b32 m0, s86
	s_nop 0
	s_mov_b32 s86, m0
	s_mov_b32 m0, s56
	s_nop 0
	global_load_lds_dwordx4 v179, s[34:35]
	s_mov_b32 m0, s86
	s_add_u32 s86, s34, 0x80000
	s_addc_u32 s87, s35, 0
	s_mov_b32 s92, m0
	s_mov_b32 m0, s57
	s_nop 0
	global_load_lds_dwordx4 v177, s[86:87]
	s_mov_b32 m0, s92
	s_nop 0
	s_mov_b32 s92, m0
	s_mov_b32 m0, s58
	s_nop 0
	global_load_lds_dwordx4 v179, s[86:87]
	s_mov_b32 m0, s92
	s_waitcnt vmcnt(4)
	s_waitcnt lgkmcnt(0)
	s_waitcnt lgkmcnt(7)
	v_mfma_f32_16x16x32_bf16 v[78:81], v[46:49], v[170:173], v[78:81]
	v_mfma_f32_16x16x32_bf16 v[78:81], v[54:57], v[188:191], v[78:81]
	s_waitcnt lgkmcnt(5)
	v_mfma_f32_16x16x32_bf16 v[74:77], v[58:61], v[170:173], v[74:77]
	v_mfma_f32_16x16x32_bf16 v[74:77], v[62:65], v[188:191], v[74:77]
	s_barrier
	s_setprio 1
	s_waitcnt lgkmcnt(3)
	v_mfma_f32_16x16x32_bf16 v[50:53], v[46:49], v[192:195], v[50:53]
	v_mfma_f32_16x16x32_bf16 v[50:53], v[54:57], v[196:199], v[50:53]
	s_waitcnt lgkmcnt(1)
	v_mfma_f32_16x16x32_bf16 v[42:45], v[58:61], v[192:195], v[42:45]
	v_mfma_f32_16x16x32_bf16 v[42:45], v[62:65], v[196:199], v[42:45]
	v_mfma_f32_16x16x32_bf16 v[30:33], v[46:49], v[200:203], v[30:33]
	v_mfma_f32_16x16x32_bf16 v[30:33], v[54:57], v[204:207], v[30:33]
	v_mfma_f32_16x16x32_bf16 v[26:29], v[58:61], v[200:203], v[26:29]
	v_mfma_f32_16x16x32_bf16 v[26:29], v[62:65], v[204:207], v[26:29]
	v_mfma_f32_16x16x32_bf16 v[14:17], v[46:49], v[208:211], v[14:17]
	v_mfma_f32_16x16x32_bf16 v[14:17], v[54:57], v[212:215], v[14:17]
	s_waitcnt lgkmcnt(0)
	v_mfma_f32_16x16x32_bf16 v[10:13], v[58:61], v[208:211], v[10:13]
	v_mfma_f32_16x16x32_bf16 v[10:13], v[62:65], v[212:215], v[10:13]
	s_setprio 0
	s_setprio 1
	v_mfma_f32_16x16x32_bf16 v[38:41], v[146:149], v[192:195], v[38:41]
	v_mfma_f32_16x16x32_bf16 v[38:41], v[150:153], v[196:199], v[38:41]
	v_mfma_f32_16x16x32_bf16 v[34:37], v[154:157], v[192:195], v[34:37]
	v_mfma_f32_16x16x32_bf16 v[34:37], v[158:161], v[196:199], v[34:37]
	v_mfma_f32_16x16x32_bf16 v[22:25], v[146:149], v[200:203], v[22:25]
	v_mfma_f32_16x16x32_bf16 v[22:25], v[150:153], v[204:207], v[22:25]
	v_mfma_f32_16x16x32_bf16 v[18:21], v[154:157], v[200:203], v[18:21]
	v_mfma_f32_16x16x32_bf16 v[18:21], v[158:161], v[204:207], v[18:21]
	v_mfma_f32_16x16x32_bf16 v[6:9], v[146:149], v[208:211], v[6:9]
	v_mfma_f32_16x16x32_bf16 v[6:9], v[150:153], v[212:215], v[6:9]
	v_mfma_f32_16x16x32_bf16 v[2:5], v[154:157], v[208:211], v[2:5]
	v_mfma_f32_16x16x32_bf16 v[2:5], v[158:161], v[212:215], v[2:5]
	v_mfma_f32_16x16x32_bf16 v[46:49], v[146:149], v[170:173], v[70:73]
	v_mfma_f32_16x16x32_bf16 v[46:49], v[150:153], v[188:191], v[46:49]
	s_setprio 2
	s_barrier
	v_mfma_f32_16x16x32_bf16 v[54:57], v[154:157], v[170:173], v[66:69]
	v_mfma_f32_16x16x32_bf16 v[54:57], v[158:161], v[188:191], v[54:57]
	s_setprio 0
	ds_read_b128 v[58:61], v185
	ds_read_b128 v[62:65], v185 offset:1024
	ds_read_b128 v[66:69], v185 offset:2048
	ds_read_b128 v[70:73], v185 offset:3072
	ds_read_b128 v[146:149], v186
	ds_read_b128 v[150:153], v186 offset:1024
	ds_read_b128 v[154:157], v186 offset:2048
	ds_read_b128 v[158:161], v186 offset:3072
	ds_read_b128 v[170:173], v184 offset:32768
	ds_read_b128 v[188:191], v184 offset:33792
	ds_read_b128 v[192:195], v184 offset:34816
	ds_read_b128 v[196:199], v184 offset:35840
	ds_read_b128 v[200:203], v184 offset:36864
	ds_read_b128 v[204:207], v184 offset:37888
	ds_read_b128 v[208:211], v184 offset:38912
	ds_read_b128 v[212:215], v184 offset:39936
	s_mov_b32 s86, m0
	s_mov_b32 m0, s48
	s_nop 0
	global_load_lds_dwordx4 v176, s[36:37]
	s_mov_b32 m0, s86
	s_nop 0
	s_mov_b32 s86, m0
	s_mov_b32 m0, s59
	s_nop 0
	global_load_lds_dwordx4 v178, s[36:37]
	s_mov_b32 m0, s86
	s_add_u32 s36, s36, 0x80000
	s_addc_u32 s37, s37, 0
	s_mov_b32 s86, m0
	s_mov_b32 m0, s62
	s_nop 0
	global_load_lds_dwordx4 v176, s[36:37]
	s_mov_b32 m0, s86
	s_nop 0
	s_mov_b32 s86, m0
	s_mov_b32 m0, s63
	s_nop 0
	global_load_lds_dwordx4 v178, s[36:37]
	s_mov_b32 m0, s86
	s_waitcnt vmcnt(8)
	s_waitcnt lgkmcnt(0)
	s_waitcnt lgkmcnt(7)
	v_mfma_f32_16x16x32_bf16 v[142:145], v[58:61], v[170:173], v[142:145]
	v_mfma_f32_16x16x32_bf16 v[142:145], v[62:65], v[188:191], v[142:145]
	s_waitcnt lgkmcnt(5)
	v_mfma_f32_16x16x32_bf16 v[138:141], v[66:69], v[170:173], v[138:141]
	v_mfma_f32_16x16x32_bf16 v[138:141], v[70:73], v[188:191], v[138:141]
	s_barrier
	s_setprio 1
	s_waitcnt lgkmcnt(3)
	v_mfma_f32_16x16x32_bf16 v[126:129], v[58:61], v[192:195], v[126:129]
	v_mfma_f32_16x16x32_bf16 v[126:129], v[62:65], v[196:199], v[126:129]
	s_waitcnt lgkmcnt(1)
	v_mfma_f32_16x16x32_bf16 v[122:125], v[66:69], v[192:195], v[122:125]
	v_mfma_f32_16x16x32_bf16 v[122:125], v[70:73], v[196:199], v[122:125]
	v_mfma_f32_16x16x32_bf16 v[110:113], v[58:61], v[200:203], v[110:113]
	v_mfma_f32_16x16x32_bf16 v[110:113], v[62:65], v[204:207], v[110:113]
	v_mfma_f32_16x16x32_bf16 v[106:109], v[66:69], v[200:203], v[106:109]
	v_mfma_f32_16x16x32_bf16 v[106:109], v[70:73], v[204:207], v[106:109]
	v_mfma_f32_16x16x32_bf16 v[94:97], v[58:61], v[208:211], v[94:97]
	v_mfma_f32_16x16x32_bf16 v[94:97], v[62:65], v[212:215], v[94:97]
	s_waitcnt lgkmcnt(0)
	v_mfma_f32_16x16x32_bf16 v[90:93], v[66:69], v[208:211], v[90:93]
	v_mfma_f32_16x16x32_bf16 v[90:93], v[70:73], v[212:215], v[90:93]
	s_setprio 0
	s_setprio 1
	v_mfma_f32_16x16x32_bf16 v[134:137], v[146:149], v[170:173], v[134:137]
	v_mfma_f32_16x16x32_bf16 v[134:137], v[150:153], v[188:191], v[134:137]
	v_mfma_f32_16x16x32_bf16 v[130:133], v[154:157], v[170:173], v[130:133]
	v_mfma_f32_16x16x32_bf16 v[130:133], v[158:161], v[188:191], v[130:133]
	v_mfma_f32_16x16x32_bf16 v[118:121], v[146:149], v[192:195], v[118:121]
	v_mfma_f32_16x16x32_bf16 v[118:121], v[150:153], v[196:199], v[118:121]
	v_mfma_f32_16x16x32_bf16 v[114:117], v[154:157], v[192:195], v[114:117]
	v_mfma_f32_16x16x32_bf16 v[114:117], v[158:161], v[196:199], v[114:117]
	v_mfma_f32_16x16x32_bf16 v[102:105], v[146:149], v[200:203], v[102:105]
	v_mfma_f32_16x16x32_bf16 v[102:105], v[150:153], v[204:207], v[102:105]
	v_mfma_f32_16x16x32_bf16 v[98:101], v[154:157], v[200:203], v[98:101]
	v_mfma_f32_16x16x32_bf16 v[98:101], v[158:161], v[204:207], v[98:101]
	v_mfma_f32_16x16x32_bf16 v[86:89], v[146:149], v[208:211], v[86:89]
	v_mfma_f32_16x16x32_bf16 v[86:89], v[150:153], v[212:215], v[86:89]
	s_setprio 2
	s_barrier
	v_mfma_f32_16x16x32_bf16 v[82:85], v[154:157], v[208:211], v[82:85]
	v_mfma_f32_16x16x32_bf16 v[82:85], v[158:161], v[212:215], v[82:85]
	s_setprio 0
	ds_read_b128 v[170:173], v184 offset:49152
	ds_read_b128 v[188:191], v184 offset:50176
	ds_read_b128 v[192:195], v184 offset:51200
	ds_read_b128 v[196:199], v184 offset:52224
	ds_read_b128 v[200:203], v184 offset:53248
	ds_read_b128 v[204:207], v184 offset:54272
	ds_read_b128 v[208:211], v184 offset:55296
	ds_read_b128 v[212:215], v184 offset:56320
	s_add_u32 s36, s34, 0x80
	s_addc_u32 s37, s35, 0
	s_mov_b32 s86, m0
	s_mov_b32 m0, s64
	s_nop 0
	global_load_lds_dwordx4 v177, s[36:37]
	s_mov_b32 m0, s86
	s_add_u32 s34, s34, 0x80080
	s_mov_b32 s86, m0
	s_mov_b32 m0, s65
	s_nop 0
	global_load_lds_dwordx4 v179, s[36:37]
	s_mov_b32 m0, s86
	s_addc_u32 s35, s35, 0
	s_mov_b32 s36, m0
	s_mov_b32 m0, s66
	s_nop 0
	global_load_lds_dwordx4 v177, s[34:35]
	s_mov_b32 m0, s36
	s_nop 0
	s_mov_b32 s36, m0
	s_mov_b32 m0, s67
	s_nop 0
	global_load_lds_dwordx4 v179, s[34:35]
	s_mov_b32 m0, s36
	s_waitcnt vmcnt(4)
	s_waitcnt lgkmcnt(0)
	s_waitcnt lgkmcnt(7)
	v_mfma_f32_16x16x32_bf16 v[78:81], v[58:61], v[170:173], v[78:81]
	v_mfma_f32_16x16x32_bf16 v[78:81], v[62:65], v[188:191], v[78:81]
	s_waitcnt lgkmcnt(5)
	v_mfma_f32_16x16x32_bf16 v[74:77], v[66:69], v[170:173], v[74:77]
	v_mfma_f32_16x16x32_bf16 v[74:77], v[70:73], v[188:191], v[74:77]
	s_barrier
	s_setprio 1
	s_waitcnt lgkmcnt(3)
	v_mfma_f32_16x16x32_bf16 v[50:53], v[58:61], v[192:195], v[50:53]
	v_mfma_f32_16x16x32_bf16 v[50:53], v[62:65], v[196:199], v[50:53]
	s_waitcnt lgkmcnt(1)
	v_mfma_f32_16x16x32_bf16 v[42:45], v[66:69], v[192:195], v[42:45]
	v_mfma_f32_16x16x32_bf16 v[42:45], v[70:73], v[196:199], v[42:45]
	v_mfma_f32_16x16x32_bf16 v[30:33], v[58:61], v[200:203], v[30:33]
	v_mfma_f32_16x16x32_bf16 v[30:33], v[62:65], v[204:207], v[30:33]
	v_mfma_f32_16x16x32_bf16 v[26:29], v[66:69], v[200:203], v[26:29]
	v_mfma_f32_16x16x32_bf16 v[26:29], v[70:73], v[204:207], v[26:29]
	v_mfma_f32_16x16x32_bf16 v[14:17], v[58:61], v[208:211], v[14:17]
	v_mfma_f32_16x16x32_bf16 v[14:17], v[62:65], v[212:215], v[14:17]
	s_waitcnt lgkmcnt(0)
	v_mfma_f32_16x16x32_bf16 v[10:13], v[66:69], v[208:211], v[10:13]
	v_mfma_f32_16x16x32_bf16 v[10:13], v[70:73], v[212:215], v[10:13]
	s_setprio 0
	s_setprio 1
	v_mfma_f32_16x16x32_bf16 v[46:49], v[146:149], v[170:173], v[46:49]
	v_mfma_f32_16x16x32_bf16 v[70:73], v[150:153], v[188:191], v[46:49]
	v_mfma_f32_16x16x32_bf16 v[46:49], v[154:157], v[170:173], v[54:57]
	v_mfma_f32_16x16x32_bf16 v[66:69], v[158:161], v[188:191], v[46:49]
	v_mfma_f32_16x16x32_bf16 v[38:41], v[146:149], v[192:195], v[38:41]
	v_mfma_f32_16x16x32_bf16 v[38:41], v[150:153], v[196:199], v[38:41]
	v_mfma_f32_16x16x32_bf16 v[34:37], v[154:157], v[192:195], v[34:37]
	v_mfma_f32_16x16x32_bf16 v[34:37], v[158:161], v[196:199], v[34:37]
	v_mfma_f32_16x16x32_bf16 v[22:25], v[146:149], v[200:203], v[22:25]
	v_mfma_f32_16x16x32_bf16 v[22:25], v[150:153], v[204:207], v[22:25]
	v_mfma_f32_16x16x32_bf16 v[18:21], v[154:157], v[200:203], v[18:21]
	v_mfma_f32_16x16x32_bf16 v[18:21], v[158:161], v[204:207], v[18:21]
	v_mfma_f32_16x16x32_bf16 v[6:9], v[146:149], v[208:211], v[6:9]
	v_mfma_f32_16x16x32_bf16 v[6:9], v[150:153], v[212:215], v[6:9]
	s_setprio 2
	s_barrier
	v_mfma_f32_16x16x32_bf16 v[2:5], v[154:157], v[208:211], v[2:5]
	v_mfma_f32_16x16x32_bf16 v[2:5], v[158:161], v[212:215], v[2:5]
	s_setprio 0
	s_add_i32 s83, s83, 2
	s_add_u32 s79, s79, 0x100
	s_addc_u32 s80, s80, 0
	s_add_u32 s30, s30, 0x100
	s_addc_u32 s31, s31, 0
	s_add_u32 s81, s81, 0x100
	s_addc_u32 s82, s82, 0
	s_cmp_gt_u32 s83, 29
	s_cbranch_scc0 .LBB0_1538
	s_and_b64 vcc, exec, s[16:17]
	s_cbranch_vccz .LBB0_1541
	s_barrier

.LBB0_1784:
	s_ashr_i32 s11, s10, 31
	s_lshl_b64 s[12:13], s[10:11], 20
	s_add_u32 s12, s26, s12
	s_addc_u32 s13, s27, s13
	s_and_b64 s[14:15], s[2:3], exec
	s_cselect_b32 s11, s13, s21
	s_cselect_b32 s64, s12, s20
	s_ashr_i32 s9, s8, 31
	s_lshl_b64 s[14:15], s[8:9], 20
	s_add_u32 s14, s28, s14
	s_addc_u32 s15, s29, s15
	s_and_b64 s[22:23], s[2:3], exec
	s_cselect_b32 s9, s15, s19
	s_cselect_b32 s65, s14, s18
	s_add_u32 s66, s18, 0x100
	s_addc_u32 s67, s19, 0
	s_add_u32 s18, s20, 0x80080
	s_addc_u32 s19, s21, 0
	s_add_u32 s70, s20, 0x100
	s_addc_u32 s71, s21, 0
	s_mov_b32 s73, -2
	ds_read_b128 v[148:151], v143
	ds_read_b128 v[152:155], v143 offset:1024
	ds_read_b128 v[156:159], v143 offset:2048
	ds_read_b128 v[160:163], v143 offset:3072
	ds_read_b128 v[164:167], v144
	ds_read_b128 v[168:171], v144 offset:1024
	ds_read_b128 v[172:175], v144 offset:2048
	ds_read_b128 v[176:179], v144 offset:3072
	s_cmp_eq_u32 s73, 28
	s_cselect_b32 s21, s9, s67
	s_cselect_b32 s20, s65, s66
	s_cselect_b32 s23, s11, s71
	s_cselect_b32 s22, s64, s70
	ds_read_b128 v[180:183], v145
	ds_read_b128 v[184:187], v145 offset:1024
	ds_read_b128 v[188:191], v145 offset:2048
	ds_read_b128 v[192:195], v145 offset:3072
	ds_read_b128 v[196:199], v145 offset:4096
	ds_read_b128 v[200:203], v145 offset:5120
	ds_read_b128 v[204:207], v145 offset:6144
	ds_read_b128 v[208:211], v145 offset:7168
	s_add_u32 s74, s18, 0xfff80000
	s_addc_u32 s75, s19, -1
	s_mov_b32 s76, m0
	s_mov_b32 m0, s56
	s_nop 0
	global_load_lds_dwordx4 v138, s[74:75]
	s_mov_b32 m0, s76
	s_nop 0
	s_mov_b32 s76, m0
	s_mov_b32 m0, s59
	s_nop 0
	global_load_lds_dwordx4 v140, s[74:75]
	s_mov_b32 m0, s76
	s_mov_b32 s74, m0
	s_mov_b32 m0, s57
	s_nop 0
	global_load_lds_dwordx4 v138, s[18:19]
	s_mov_b32 m0, s74
	s_nop 0
	s_mov_b32 s74, m0
	s_mov_b32 m0, s62
	s_nop 0
	global_load_lds_dwordx4 v140, s[18:19]
	s_mov_b32 m0, s74
	s_waitcnt vmcnt(8)
	s_waitcnt lgkmcnt(0)
	s_waitcnt lgkmcnt(7)
	v_mfma_f32_16x16x32_bf16 v[126:129], v[148:151], v[180:183], 0
	v_mfma_f32_16x16x32_bf16 v[126:129], v[152:155], v[184:187], v[126:129]
	s_waitcnt lgkmcnt(5)
	v_mfma_f32_16x16x32_bf16 v[122:125], v[156:159], v[180:183], 0
	v_mfma_f32_16x16x32_bf16 v[122:125], v[160:163], v[184:187], v[122:125]
	s_barrier
	s_setprio 1
	s_waitcnt lgkmcnt(3)
	v_mfma_f32_16x16x32_bf16 v[106:109], v[156:159], v[188:191], 0
	v_mfma_f32_16x16x32_bf16 v[106:109], v[160:163], v[192:195], v[106:109]
	s_waitcnt lgkmcnt(1)
	v_mfma_f32_16x16x32_bf16 v[110:113], v[148:151], v[188:191], 0
	v_mfma_f32_16x16x32_bf16 v[110:113], v[152:155], v[192:195], v[110:113]
	v_mfma_f32_16x16x32_bf16 v[94:97], v[148:151], v[196:199], 0
	v_mfma_f32_16x16x32_bf16 v[94:97], v[152:155], v[200:203], v[94:97]
	v_mfma_f32_16x16x32_bf16 v[90:93], v[156:159], v[196:199], 0
	v_mfma_f32_16x16x32_bf16 v[90:93], v[160:163], v[200:203], v[90:93]
	v_mfma_f32_16x16x32_bf16 v[74:77], v[156:159], v[204:207], 0
	v_mfma_f32_16x16x32_bf16 v[74:77], v[160:163], v[208:211], v[74:77]
	s_waitcnt lgkmcnt(0)
	v_mfma_f32_16x16x32_bf16 v[78:81], v[148:151], v[204:207], 0
	v_mfma_f32_16x16x32_bf16 v[78:81], v[152:155], v[208:211], v[78:81]
	s_setprio 0
	s_setprio 1
	v_mfma_f32_16x16x32_bf16 v[118:121], v[164:167], v[180:183], 0
	v_mfma_f32_16x16x32_bf16 v[118:121], v[168:171], v[184:187], v[118:121]
	v_mfma_f32_16x16x32_bf16 v[114:117], v[172:175], v[180:183], 0
	v_mfma_f32_16x16x32_bf16 v[114:117], v[176:179], v[184:187], v[114:117]
	v_mfma_f32_16x16x32_bf16 v[98:101], v[172:175], v[188:191], 0
	v_mfma_f32_16x16x32_bf16 v[98:101], v[176:179], v[192:195], v[98:101]
	v_mfma_f32_16x16x32_bf16 v[102:105], v[164:167], v[188:191], 0
	v_mfma_f32_16x16x32_bf16 v[102:105], v[168:171], v[192:195], v[102:105]
	v_mfma_f32_16x16x32_bf16 v[86:89], v[164:167], v[196:199], 0
	v_mfma_f32_16x16x32_bf16 v[86:89], v[168:171], v[200:203], v[86:89]
	v_mfma_f32_16x16x32_bf16 v[82:85], v[172:175], v[196:199], 0
	v_mfma_f32_16x16x32_bf16 v[82:85], v[176:179], v[200:203], v[82:85]
	v_mfma_f32_16x16x32_bf16 v[66:69], v[172:175], v[204:207], 0
	v_mfma_f32_16x16x32_bf16 v[66:69], v[176:179], v[208:211], v[66:69]
	s_setprio 2
	s_barrier
	v_mfma_f32_16x16x32_bf16 v[70:73], v[164:167], v[204:207], 0
	v_mfma_f32_16x16x32_bf16 v[70:73], v[168:171], v[208:211], v[70:73]
	s_setprio 0
	ds_read_b128 v[180:183], v145 offset:16384
	ds_read_b128 v[184:187], v145 offset:17408
	ds_read_b128 v[188:191], v145 offset:18432
	ds_read_b128 v[192:195], v145 offset:19456
	ds_read_b128 v[196:199], v145 offset:20480
	ds_read_b128 v[200:203], v145 offset:21504
	ds_read_b128 v[204:207], v145 offset:22528
	ds_read_b128 v[208:211], v145 offset:23552
	s_mov_b32 s74, m0
	s_mov_b32 m0, s35
	s_nop 0
	global_load_lds_dwordx4 v139, s[20:21]
	s_mov_b32 m0, s74
	s_nop 0
	s_mov_b32 s74, m0
	s_mov_b32 m0, s36
	s_nop 0
	global_load_lds_dwordx4 v141, s[20:21]
	s_mov_b32 m0, s74
	s_add_u32 s74, s20, 0x80000
	s_addc_u32 s75, s21, 0
	s_mov_b32 s76, m0
	s_mov_b32 m0, s37
	s_nop 0
	global_load_lds_dwordx4 v139, s[74:75]
	s_mov_b32 m0, s76
	s_nop 0
	s_mov_b32 s76, m0
	s_mov_b32 m0, s40
	s_nop 0
	global_load_lds_dwordx4 v141, s[74:75]
	s_mov_b32 m0, s76
	s_waitcnt vmcnt(4)
	s_waitcnt lgkmcnt(0)
	s_waitcnt lgkmcnt(7)
	v_mfma_f32_16x16x32_bf16 v[62:65], v[148:151], v[180:183], 0
	v_mfma_f32_16x16x32_bf16 v[62:65], v[152:155], v[184:187], v[62:65]
	s_waitcnt lgkmcnt(5)
	v_mfma_f32_16x16x32_bf16 v[58:61], v[156:159], v[180:183], 0
	v_mfma_f32_16x16x32_bf16 v[58:61], v[160:163], v[184:187], v[58:61]
	s_barrier
	s_setprio 1
	s_waitcnt lgkmcnt(3)
	v_mfma_f32_16x16x32_bf16 v[42:45], v[156:159], v[188:191], 0
	v_mfma_f32_16x16x32_bf16 v[42:45], v[160:163], v[192:195], v[42:45]
	s_waitcnt lgkmcnt(1)
	v_mfma_f32_16x16x32_bf16 v[46:49], v[148:151], v[188:191], 0
	v_mfma_f32_16x16x32_bf16 v[46:49], v[152:155], v[192:195], v[46:49]
	v_mfma_f32_16x16x32_bf16 v[30:33], v[148:151], v[196:199], 0
	v_mfma_f32_16x16x32_bf16 v[30:33], v[152:155], v[200:203], v[30:33]
	v_mfma_f32_16x16x32_bf16 v[26:29], v[156:159], v[196:199], 0
	v_mfma_f32_16x16x32_bf16 v[26:29], v[160:163], v[200:203], v[26:29]
	v_mfma_f32_16x16x32_bf16 v[10:13], v[156:159], v[204:207], 0
	v_mfma_f32_16x16x32_bf16 v[10:13], v[160:163], v[208:211], v[10:13]
	s_waitcnt lgkmcnt(0)
	v_mfma_f32_16x16x32_bf16 v[14:17], v[148:151], v[204:207], 0
	v_mfma_f32_16x16x32_bf16 v[14:17], v[152:155], v[208:211], v[14:17]
	s_setprio 0
	s_setprio 1
	v_mfma_f32_16x16x32_bf16 v[54:57], v[164:167], v[180:183], 0
	v_mfma_f32_16x16x32_bf16 v[54:57], v[168:171], v[184:187], v[54:57]
	v_mfma_f32_16x16x32_bf16 v[50:53], v[172:175], v[180:183], 0
	v_mfma_f32_16x16x32_bf16 v[50:53], v[176:179], v[184:187], v[50:53]
	v_mfma_f32_16x16x32_bf16 v[34:37], v[172:175], v[188:191], 0
	v_mfma_f32_16x16x32_bf16 v[34:37], v[176:179], v[192:195], v[34:37]
	v_mfma_f32_16x16x32_bf16 v[38:41], v[164:167], v[188:191], 0
	v_mfma_f32_16x16x32_bf16 v[38:41], v[168:171], v[192:195], v[38:41]
	v_mfma_f32_16x16x32_bf16 v[22:25], v[164:167], v[196:199], 0
	v_mfma_f32_16x16x32_bf16 v[22:25], v[168:171], v[200:203], v[22:25]
	v_mfma_f32_16x16x32_bf16 v[18:21], v[172:175], v[196:199], 0
	v_mfma_f32_16x16x32_bf16 v[18:21], v[176:179], v[200:203], v[18:21]
	v_mfma_f32_16x16x32_bf16 v[2:5], v[172:175], v[204:207], 0
	v_mfma_f32_16x16x32_bf16 v[2:5], v[176:179], v[208:211], v[2:5]
	s_setprio 2
	s_barrier
	v_mfma_f32_16x16x32_bf16 v[6:9], v[164:167], v[204:207], 0
	v_mfma_f32_16x16x32_bf16 v[6:9], v[168:171], v[208:211], v[6:9]
	s_setprio 0
	ds_read_b128 v[148:151], v146
	ds_read_b128 v[152:155], v146 offset:1024
	ds_read_b128 v[156:159], v146 offset:2048
	ds_read_b128 v[160:163], v146 offset:3072
	ds_read_b128 v[164:167], v147
	ds_read_b128 v[168:171], v147 offset:1024
	ds_read_b128 v[172:175], v147 offset:2048
	ds_read_b128 v[176:179], v147 offset:3072
	ds_read_b128 v[180:183], v145 offset:32768
	ds_read_b128 v[184:187], v145 offset:33792
	ds_read_b128 v[188:191], v145 offset:34816
	ds_read_b128 v[192:195], v145 offset:35840
	ds_read_b128 v[196:199], v145 offset:36864
	ds_read_b128 v[200:203], v145 offset:37888
	ds_read_b128 v[204:207], v145 offset:38912
	ds_read_b128 v[208:211], v145 offset:39936
	s_mov_b32 s74, m0
	s_mov_b32 m0, s31
	s_nop 0
	global_load_lds_dwordx4 v138, s[22:23]
	s_mov_b32 m0, s74
	s_nop 0
	s_mov_b32 s74, m0
	s_mov_b32 m0, s41
	s_nop 0
	global_load_lds_dwordx4 v140, s[22:23]
	s_mov_b32 m0, s74
	s_add_u32 s22, s22, 0x80000
	s_addc_u32 s23, s23, 0
	s_mov_b32 s74, m0
	s_mov_b32 m0, s42
	s_nop 0
	global_load_lds_dwordx4 v138, s[22:23]
	s_mov_b32 m0, s74
	s_nop 0
	s_mov_b32 s74, m0
	s_mov_b32 m0, s43
	s_nop 0
	global_load_lds_dwordx4 v140, s[22:23]
	s_mov_b32 m0, s74
	s_waitcnt vmcnt(8)
	s_waitcnt lgkmcnt(0)
	s_waitcnt lgkmcnt(7)
	v_mfma_f32_16x16x32_bf16 v[126:129], v[148:151], v[180:183], v[126:129]
	v_mfma_f32_16x16x32_bf16 v[126:129], v[152:155], v[184:187], v[126:129]
	s_waitcnt lgkmcnt(5)
	v_mfma_f32_16x16x32_bf16 v[122:125], v[156:159], v[180:183], v[122:125]
	v_mfma_f32_16x16x32_bf16 v[122:125], v[160:163], v[184:187], v[122:125]
	s_barrier
	s_setprio 1
	s_waitcnt lgkmcnt(3)
	v_mfma_f32_16x16x32_bf16 v[106:109], v[156:159], v[188:191], v[106:109]
	v_mfma_f32_16x16x32_bf16 v[106:109], v[160:163], v[192:195], v[106:109]
	s_waitcnt lgkmcnt(1)
	v_mfma_f32_16x16x32_bf16 v[110:113], v[148:151], v[188:191], v[110:113]
	v_mfma_f32_16x16x32_bf16 v[110:113], v[152:155], v[192:195], v[110:113]
	v_mfma_f32_16x16x32_bf16 v[94:97], v[148:151], v[196:199], v[94:97]
	v_mfma_f32_16x16x32_bf16 v[94:97], v[152:155], v[200:203], v[94:97]
	v_mfma_f32_16x16x32_bf16 v[90:93], v[156:159], v[196:199], v[90:93]
	v_mfma_f32_16x16x32_bf16 v[90:93], v[160:163], v[200:203], v[90:93]
	v_mfma_f32_16x16x32_bf16 v[74:77], v[156:159], v[204:207], v[74:77]
	v_mfma_f32_16x16x32_bf16 v[74:77], v[160:163], v[208:211], v[74:77]
	s_waitcnt lgkmcnt(0)
	v_mfma_f32_16x16x32_bf16 v[78:81], v[148:151], v[204:207], v[78:81]
	v_mfma_f32_16x16x32_bf16 v[78:81], v[152:155], v[208:211], v[78:81]
	s_setprio 0
	s_setprio 1
	v_mfma_f32_16x16x32_bf16 v[118:121], v[164:167], v[180:183], v[118:121]
	v_mfma_f32_16x16x32_bf16 v[118:121], v[168:171], v[184:187], v[118:121]
	v_mfma_f32_16x16x32_bf16 v[114:117], v[172:175], v[180:183], v[114:117]
	v_mfma_f32_16x16x32_bf16 v[114:117], v[176:179], v[184:187], v[114:117]
	v_mfma_f32_16x16x32_bf16 v[98:101], v[172:175], v[188:191], v[98:101]
	v_mfma_f32_16x16x32_bf16 v[98:101], v[176:179], v[192:195], v[98:101]
	v_mfma_f32_16x16x32_bf16 v[102:105], v[164:167], v[188:191], v[102:105]
	v_mfma_f32_16x16x32_bf16 v[102:105], v[168:171], v[192:195], v[102:105]
	v_mfma_f32_16x16x32_bf16 v[86:89], v[164:167], v[196:199], v[86:89]
	v_mfma_f32_16x16x32_bf16 v[86:89], v[168:171], v[200:203], v[86:89]
	v_mfma_f32_16x16x32_bf16 v[82:85], v[172:175], v[196:199], v[82:85]
	v_mfma_f32_16x16x32_bf16 v[82:85], v[176:179], v[200:203], v[82:85]
	v_mfma_f32_16x16x32_bf16 v[66:69], v[172:175], v[204:207], v[66:69]
	v_mfma_f32_16x16x32_bf16 v[66:69], v[176:179], v[208:211], v[66:69]
	s_setprio 2
	s_barrier
	v_mfma_f32_16x16x32_bf16 v[70:73], v[164:167], v[204:207], v[70:73]
	v_mfma_f32_16x16x32_bf16 v[70:73], v[168:171], v[208:211], v[70:73]
	s_setprio 0
	ds_read_b128 v[180:183], v145 offset:49152
	ds_read_b128 v[184:187], v145 offset:50176
	ds_read_b128 v[188:191], v145 offset:51200
	ds_read_b128 v[192:195], v145 offset:52224
	ds_read_b128 v[196:199], v145 offset:53248
	ds_read_b128 v[200:203], v145 offset:54272
	ds_read_b128 v[204:207], v145 offset:55296
	ds_read_b128 v[208:211], v145 offset:56320
	s_add_u32 s22, s20, 0x80
	s_addc_u32 s23, s21, 0
	s_mov_b32 s74, m0
	s_mov_b32 m0, s46
	s_nop 0
	global_load_lds_dwordx4 v139, s[22:23]
	s_mov_b32 m0, s74
	s_add_u32 s20, s20, 0x80080
	s_mov_b32 s74, m0
	s_mov_b32 m0, s47
	s_nop 0
	global_load_lds_dwordx4 v141, s[22:23]
	s_mov_b32 m0, s74
	s_addc_u32 s21, s21, 0
	s_mov_b32 s22, m0
	s_mov_b32 m0, s48
	s_nop 0
	global_load_lds_dwordx4 v139, s[20:21]
	s_mov_b32 m0, s22
	s_nop 0
	s_mov_b32 s22, m0
	s_mov_b32 m0, s49
	s_nop 0
	global_load_lds_dwordx4 v141, s[20:21]
	s_mov_b32 m0, s22
	s_waitcnt vmcnt(4)
	s_waitcnt lgkmcnt(0)
	s_waitcnt lgkmcnt(7)
	v_mfma_f32_16x16x32_bf16 v[62:65], v[148:151], v[180:183], v[62:65]
	v_mfma_f32_16x16x32_bf16 v[62:65], v[152:155], v[184:187], v[62:65]
	s_waitcnt lgkmcnt(5)
	v_mfma_f32_16x16x32_bf16 v[58:61], v[156:159], v[180:183], v[58:61]
	v_mfma_f32_16x16x32_bf16 v[58:61], v[160:163], v[184:187], v[58:61]
	s_barrier
	s_setprio 1
	s_waitcnt lgkmcnt(3)
	v_mfma_f32_16x16x32_bf16 v[42:45], v[156:159], v[188:191], v[42:45]
	v_mfma_f32_16x16x32_bf16 v[42:45], v[160:163], v[192:195], v[42:45]
	s_waitcnt lgkmcnt(1)
	v_mfma_f32_16x16x32_bf16 v[46:49], v[148:151], v[188:191], v[46:49]
	v_mfma_f32_16x16x32_bf16 v[46:49], v[152:155], v[192:195], v[46:49]
	v_mfma_f32_16x16x32_bf16 v[30:33], v[148:151], v[196:199], v[30:33]
	v_mfma_f32_16x16x32_bf16 v[30:33], v[152:155], v[200:203], v[30:33]
	v_mfma_f32_16x16x32_bf16 v[26:29], v[156:159], v[196:199], v[26:29]
	v_mfma_f32_16x16x32_bf16 v[26:29], v[160:163], v[200:203], v[26:29]
	v_mfma_f32_16x16x32_bf16 v[10:13], v[156:159], v[204:207], v[10:13]
	v_mfma_f32_16x16x32_bf16 v[10:13], v[160:163], v[208:211], v[10:13]
	s_waitcnt lgkmcnt(0)
	v_mfma_f32_16x16x32_bf16 v[14:17], v[148:151], v[204:207], v[14:17]
	v_mfma_f32_16x16x32_bf16 v[14:17], v[152:155], v[208:211], v[14:17]
	s_setprio 0
	s_setprio 1
	v_mfma_f32_16x16x32_bf16 v[54:57], v[164:167], v[180:183], v[54:57]
	v_mfma_f32_16x16x32_bf16 v[54:57], v[168:171], v[184:187], v[54:57]
	v_mfma_f32_16x16x32_bf16 v[50:53], v[172:175], v[180:183], v[50:53]
	v_mfma_f32_16x16x32_bf16 v[50:53], v[176:179], v[184:187], v[50:53]
	v_mfma_f32_16x16x32_bf16 v[34:37], v[172:175], v[188:191], v[34:37]
	v_mfma_f32_16x16x32_bf16 v[34:37], v[176:179], v[192:195], v[34:37]
	v_mfma_f32_16x16x32_bf16 v[38:41], v[164:167], v[188:191], v[38:41]
	v_mfma_f32_16x16x32_bf16 v[38:41], v[168:171], v[192:195], v[38:41]
	v_mfma_f32_16x16x32_bf16 v[22:25], v[164:167], v[196:199], v[22:25]
	v_mfma_f32_16x16x32_bf16 v[22:25], v[168:171], v[200:203], v[22:25]
	v_mfma_f32_16x16x32_bf16 v[18:21], v[172:175], v[196:199], v[18:21]
	v_mfma_f32_16x16x32_bf16 v[18:21], v[176:179], v[200:203], v[18:21]
	v_mfma_f32_16x16x32_bf16 v[2:5], v[172:175], v[204:207], v[2:5]
	v_mfma_f32_16x16x32_bf16 v[2:5], v[176:179], v[208:211], v[2:5]
	s_setprio 2
	s_barrier
	v_mfma_f32_16x16x32_bf16 v[6:9], v[164:167], v[204:207], v[6:9]
	v_mfma_f32_16x16x32_bf16 v[6:9], v[168:171], v[208:211], v[6:9]
	s_setprio 0
	s_add_i32 s73, s73, 2
	s_add_u32 s66, s66, 0x100
	s_addc_u32 s67, s67, 0
	s_add_u32 s18, s18, 0x100
	s_addc_u32 s19, s19, 0
	s_add_u32 s70, s70, 0x100
	s_addc_u32 s71, s71, 0
	s_cmp_gt_u32 s73, 29
	.p2align 6
.LBB0_1785:
	ds_read_b128 v[148:151], v143
	ds_read_b128 v[152:155], v143 offset:1024
	ds_read_b128 v[156:159], v143 offset:2048
	ds_read_b128 v[160:163], v143 offset:3072
	ds_read_b128 v[164:167], v144
	ds_read_b128 v[168:171], v144 offset:1024
	ds_read_b128 v[172:175], v144 offset:2048
	ds_read_b128 v[176:179], v144 offset:3072
	s_cmp_eq_u32 s73, 28
	s_cselect_b32 s21, s9, s67
	s_cselect_b32 s20, s65, s66
	s_cselect_b32 s23, s11, s71
	s_cselect_b32 s22, s64, s70
	ds_read_b128 v[180:183], v145
	ds_read_b128 v[184:187], v145 offset:1024
	ds_read_b128 v[188:191], v145 offset:2048
	ds_read_b128 v[192:195], v145 offset:3072
	ds_read_b128 v[196:199], v145 offset:4096
	ds_read_b128 v[200:203], v145 offset:5120
	ds_read_b128 v[204:207], v145 offset:6144
	ds_read_b128 v[208:211], v145 offset:7168
	s_add_u32 s74, s18, 0xfff80000
	s_addc_u32 s75, s19, -1
	s_mov_b32 s76, m0
	s_mov_b32 m0, s56
	s_nop 0
	global_load_lds_dwordx4 v138, s[74:75]
	s_mov_b32 m0, s76
	s_nop 0
	s_mov_b32 s76, m0
	s_mov_b32 m0, s59
	s_nop 0
	global_load_lds_dwordx4 v140, s[74:75]
	s_mov_b32 m0, s76
	s_mov_b32 s74, m0
	s_mov_b32 m0, s57
	s_nop 0
	global_load_lds_dwordx4 v138, s[18:19]
	s_mov_b32 m0, s74
	s_nop 0
	s_mov_b32 s74, m0
	s_mov_b32 m0, s62
	s_nop 0
	global_load_lds_dwordx4 v140, s[18:19]
	s_mov_b32 m0, s74
	s_waitcnt vmcnt(8)
	s_waitcnt lgkmcnt(0)
	s_waitcnt lgkmcnt(7)
	v_mfma_f32_16x16x32_bf16 v[126:129], v[148:151], v[180:183], v[126:129]
	v_mfma_f32_16x16x32_bf16 v[126:129], v[152:155], v[184:187], v[126:129]
	s_waitcnt lgkmcnt(5)
	v_mfma_f32_16x16x32_bf16 v[122:125], v[156:159], v[180:183], v[122:125]
	v_mfma_f32_16x16x32_bf16 v[122:125], v[160:163], v[184:187], v[122:125]
	s_barrier
	s_setprio 1
	s_waitcnt lgkmcnt(3)
	v_mfma_f32_16x16x32_bf16 v[106:109], v[156:159], v[188:191], v[106:109]
	v_mfma_f32_16x16x32_bf16 v[106:109], v[160:163], v[192:195], v[106:109]
	s_waitcnt lgkmcnt(1)
	v_mfma_f32_16x16x32_bf16 v[110:113], v[148:151], v[188:191], v[110:113]
	v_mfma_f32_16x16x32_bf16 v[110:113], v[152:155], v[192:195], v[110:113]
	v_mfma_f32_16x16x32_bf16 v[94:97], v[148:151], v[196:199], v[94:97]
	v_mfma_f32_16x16x32_bf16 v[94:97], v[152:155], v[200:203], v[94:97]
	v_mfma_f32_16x16x32_bf16 v[90:93], v[156:159], v[196:199], v[90:93]
	v_mfma_f32_16x16x32_bf16 v[90:93], v[160:163], v[200:203], v[90:93]
	v_mfma_f32_16x16x32_bf16 v[74:77], v[156:159], v[204:207], v[74:77]
	v_mfma_f32_16x16x32_bf16 v[74:77], v[160:163], v[208:211], v[74:77]
	s_waitcnt lgkmcnt(0)
	v_mfma_f32_16x16x32_bf16 v[78:81], v[148:151], v[204:207], v[78:81]
	v_mfma_f32_16x16x32_bf16 v[78:81], v[152:155], v[208:211], v[78:81]
	s_setprio 0
	s_setprio 1
	v_mfma_f32_16x16x32_bf16 v[118:121], v[164:167], v[180:183], v[118:121]
	v_mfma_f32_16x16x32_bf16 v[118:121], v[168:171], v[184:187], v[118:121]
	v_mfma_f32_16x16x32_bf16 v[114:117], v[172:175], v[180:183], v[114:117]
	v_mfma_f32_16x16x32_bf16 v[114:117], v[176:179], v[184:187], v[114:117]
	v_mfma_f32_16x16x32_bf16 v[98:101], v[172:175], v[188:191], v[98:101]
	v_mfma_f32_16x16x32_bf16 v[98:101], v[176:179], v[192:195], v[98:101]
	v_mfma_f32_16x16x32_bf16 v[102:105], v[164:167], v[188:191], v[102:105]
	v_mfma_f32_16x16x32_bf16 v[102:105], v[168:171], v[192:195], v[102:105]
	v_mfma_f32_16x16x32_bf16 v[86:89], v[164:167], v[196:199], v[86:89]
	v_mfma_f32_16x16x32_bf16 v[86:89], v[168:171], v[200:203], v[86:89]
	v_mfma_f32_16x16x32_bf16 v[82:85], v[172:175], v[196:199], v[82:85]
	v_mfma_f32_16x16x32_bf16 v[82:85], v[176:179], v[200:203], v[82:85]
	v_mfma_f32_16x16x32_bf16 v[66:69], v[172:175], v[204:207], v[66:69]
	v_mfma_f32_16x16x32_bf16 v[66:69], v[176:179], v[208:211], v[66:69]
	s_setprio 2
	s_barrier
	v_mfma_f32_16x16x32_bf16 v[70:73], v[164:167], v[204:207], v[70:73]
	v_mfma_f32_16x16x32_bf16 v[70:73], v[168:171], v[208:211], v[70:73]
	s_setprio 0
	ds_read_b128 v[180:183], v145 offset:16384
	ds_read_b128 v[184:187], v145 offset:17408
	ds_read_b128 v[188:191], v145 offset:18432
	ds_read_b128 v[192:195], v145 offset:19456
	ds_read_b128 v[196:199], v145 offset:20480
	ds_read_b128 v[200:203], v145 offset:21504
	ds_read_b128 v[204:207], v145 offset:22528
	ds_read_b128 v[208:211], v145 offset:23552
	s_mov_b32 s74, m0
	s_mov_b32 m0, s35
	s_nop 0
	global_load_lds_dwordx4 v139, s[20:21]
	s_mov_b32 m0, s74
	s_nop 0
	s_mov_b32 s74, m0
	s_mov_b32 m0, s36
	s_nop 0
	global_load_lds_dwordx4 v141, s[20:21]
	s_mov_b32 m0, s74
	s_add_u32 s74, s20, 0x80000
	s_addc_u32 s75, s21, 0
	s_mov_b32 s76, m0
	s_mov_b32 m0, s37
	s_nop 0
	global_load_lds_dwordx4 v139, s[74:75]
	s_mov_b32 m0, s76
	s_nop 0
	s_mov_b32 s76, m0
	s_mov_b32 m0, s40
	s_nop 0
	global_load_lds_dwordx4 v141, s[74:75]
	s_mov_b32 m0, s76
	s_waitcnt vmcnt(4)
	s_waitcnt lgkmcnt(0)
	s_waitcnt lgkmcnt(7)
	v_mfma_f32_16x16x32_bf16 v[62:65], v[148:151], v[180:183], v[62:65]
	v_mfma_f32_16x16x32_bf16 v[62:65], v[152:155], v[184:187], v[62:65]
	s_waitcnt lgkmcnt(5)
	v_mfma_f32_16x16x32_bf16 v[58:61], v[156:159], v[180:183], v[58:61]
	v_mfma_f32_16x16x32_bf16 v[58:61], v[160:163], v[184:187], v[58:61]
	s_barrier
	s_setprio 1
	s_waitcnt lgkmcnt(3)
	v_mfma_f32_16x16x32_bf16 v[42:45], v[156:159], v[188:191], v[42:45]
	v_mfma_f32_16x16x32_bf16 v[42:45], v[160:163], v[192:195], v[42:45]
	s_waitcnt lgkmcnt(1)
	v_mfma_f32_16x16x32_bf16 v[46:49], v[148:151], v[188:191], v[46:49]
	v_mfma_f32_16x16x32_bf16 v[46:49], v[152:155], v[192:195], v[46:49]
	v_mfma_f32_16x16x32_bf16 v[30:33], v[148:151], v[196:199], v[30:33]
	v_mfma_f32_16x16x32_bf16 v[30:33], v[152:155], v[200:203], v[30:33]
	v_mfma_f32_16x16x32_bf16 v[26:29], v[156:159], v[196:199], v[26:29]
	v_mfma_f32_16x16x32_bf16 v[26:29], v[160:163], v[200:203], v[26:29]
	v_mfma_f32_16x16x32_bf16 v[10:13], v[156:159], v[204:207], v[10:13]
	v_mfma_f32_16x16x32_bf16 v[10:13], v[160:163], v[208:211], v[10:13]
	s_waitcnt lgkmcnt(0)
	v_mfma_f32_16x16x32_bf16 v[14:17], v[148:151], v[204:207], v[14:17]
	v_mfma_f32_16x16x32_bf16 v[14:17], v[152:155], v[208:211], v[14:17]
	s_setprio 0
	s_setprio 1
	v_mfma_f32_16x16x32_bf16 v[54:57], v[164:167], v[180:183], v[54:57]
	v_mfma_f32_16x16x32_bf16 v[54:57], v[168:171], v[184:187], v[54:57]
	v_mfma_f32_16x16x32_bf16 v[50:53], v[172:175], v[180:183], v[50:53]
	v_mfma_f32_16x16x32_bf16 v[50:53], v[176:179], v[184:187], v[50:53]
	v_mfma_f32_16x16x32_bf16 v[34:37], v[172:175], v[188:191], v[34:37]
	v_mfma_f32_16x16x32_bf16 v[34:37], v[176:179], v[192:195], v[34:37]
	v_mfma_f32_16x16x32_bf16 v[38:41], v[164:167], v[188:191], v[38:41]
	v_mfma_f32_16x16x32_bf16 v[38:41], v[168:171], v[192:195], v[38:41]
	v_mfma_f32_16x16x32_bf16 v[22:25], v[164:167], v[196:199], v[22:25]
	v_mfma_f32_16x16x32_bf16 v[22:25], v[168:171], v[200:203], v[22:25]
	v_mfma_f32_16x16x32_bf16 v[18:21], v[172:175], v[196:199], v[18:21]
	v_mfma_f32_16x16x32_bf16 v[18:21], v[176:179], v[200:203], v[18:21]
	v_mfma_f32_16x16x32_bf16 v[2:5], v[172:175], v[204:207], v[2:5]
	v_mfma_f32_16x16x32_bf16 v[2:5], v[176:179], v[208:211], v[2:5]
	s_setprio 2
	s_barrier
	v_mfma_f32_16x16x32_bf16 v[6:9], v[164:167], v[204:207], v[6:9]
	v_mfma_f32_16x16x32_bf16 v[6:9], v[168:171], v[208:211], v[6:9]
	s_setprio 0
	ds_read_b128 v[148:151], v146
	ds_read_b128 v[152:155], v146 offset:1024
	ds_read_b128 v[156:159], v146 offset:2048
	ds_read_b128 v[160:163], v146 offset:3072
	ds_read_b128 v[164:167], v147
	ds_read_b128 v[168:171], v147 offset:1024
	ds_read_b128 v[172:175], v147 offset:2048
	ds_read_b128 v[176:179], v147 offset:3072
	ds_read_b128 v[180:183], v145 offset:32768
	ds_read_b128 v[184:187], v145 offset:33792
	ds_read_b128 v[188:191], v145 offset:34816
	ds_read_b128 v[192:195], v145 offset:35840
	ds_read_b128 v[196:199], v145 offset:36864
	ds_read_b128 v[200:203], v145 offset:37888
	ds_read_b128 v[204:207], v145 offset:38912
	ds_read_b128 v[208:211], v145 offset:39936
	s_mov_b32 s74, m0
	s_mov_b32 m0, s31
	s_nop 0
	global_load_lds_dwordx4 v138, s[22:23]
	s_mov_b32 m0, s74
	s_nop 0
	s_mov_b32 s74, m0
	s_mov_b32 m0, s41
	s_nop 0
	global_load_lds_dwordx4 v140, s[22:23]
	s_mov_b32 m0, s74
	s_add_u32 s22, s22, 0x80000
	s_addc_u32 s23, s23, 0
	s_mov_b32 s74, m0
	s_mov_b32 m0, s42
	s_nop 0
	global_load_lds_dwordx4 v138, s[22:23]
	s_mov_b32 m0, s74
	s_nop 0
	s_mov_b32 s74, m0
	s_mov_b32 m0, s43
	s_nop 0
	global_load_lds_dwordx4 v140, s[22:23]
	s_mov_b32 m0, s74
	s_waitcnt vmcnt(8)
	s_waitcnt lgkmcnt(0)
	s_waitcnt lgkmcnt(7)
	v_mfma_f32_16x16x32_bf16 v[126:129], v[148:151], v[180:183], v[126:129]
	v_mfma_f32_16x16x32_bf16 v[126:129], v[152:155], v[184:187], v[126:129]
	s_waitcnt lgkmcnt(5)
	v_mfma_f32_16x16x32_bf16 v[122:125], v[156:159], v[180:183], v[122:125]
	v_mfma_f32_16x16x32_bf16 v[122:125], v[160:163], v[184:187], v[122:125]
	s_barrier
	s_setprio 1
	s_waitcnt lgkmcnt(3)
	v_mfma_f32_16x16x32_bf16 v[106:109], v[156:159], v[188:191], v[106:109]
	v_mfma_f32_16x16x32_bf16 v[106:109], v[160:163], v[192:195], v[106:109]
	s_waitcnt lgkmcnt(1)
	v_mfma_f32_16x16x32_bf16 v[110:113], v[148:151], v[188:191], v[110:113]
	v_mfma_f32_16x16x32_bf16 v[110:113], v[152:155], v[192:195], v[110:113]
	v_mfma_f32_16x16x32_bf16 v[94:97], v[148:151], v[196:199], v[94:97]
	v_mfma_f32_16x16x32_bf16 v[94:97], v[152:155], v[200:203], v[94:97]
	v_mfma_f32_16x16x32_bf16 v[90:93], v[156:159], v[196:199], v[90:93]
	v_mfma_f32_16x16x32_bf16 v[90:93], v[160:163], v[200:203], v[90:93]
	v_mfma_f32_16x16x32_bf16 v[74:77], v[156:159], v[204:207], v[74:77]
	v_mfma_f32_16x16x32_bf16 v[74:77], v[160:163], v[208:211], v[74:77]
	s_waitcnt lgkmcnt(0)
	v_mfma_f32_16x16x32_bf16 v[78:81], v[148:151], v[204:207], v[78:81]
	v_mfma_f32_16x16x32_bf16 v[78:81], v[152:155], v[208:211], v[78:81]
	s_setprio 0
	s_setprio 1
	v_mfma_f32_16x16x32_bf16 v[118:121], v[164:167], v[180:183], v[118:121]
	v_mfma_f32_16x16x32_bf16 v[118:121], v[168:171], v[184:187], v[118:121]
	v_mfma_f32_16x16x32_bf16 v[114:117], v[172:175], v[180:183], v[114:117]
	v_mfma_f32_16x16x32_bf16 v[114:117], v[176:179], v[184:187], v[114:117]
	v_mfma_f32_16x16x32_bf16 v[98:101], v[172:175], v[188:191], v[98:101]
	v_mfma_f32_16x16x32_bf16 v[98:101], v[176:179], v[192:195], v[98:101]
	v_mfma_f32_16x16x32_bf16 v[102:105], v[164:167], v[188:191], v[102:105]
	v_mfma_f32_16x16x32_bf16 v[102:105], v[168:171], v[192:195], v[102:105]
	v_mfma_f32_16x16x32_bf16 v[86:89], v[164:167], v[196:199], v[86:89]
	v_mfma_f32_16x16x32_bf16 v[86:89], v[168:171], v[200:203], v[86:89]
	v_mfma_f32_16x16x32_bf16 v[82:85], v[172:175], v[196:199], v[82:85]
	v_mfma_f32_16x16x32_bf16 v[82:85], v[176:179], v[200:203], v[82:85]
	v_mfma_f32_16x16x32_bf16 v[66:69], v[172:175], v[204:207], v[66:69]
	v_mfma_f32_16x16x32_bf16 v[66:69], v[176:179], v[208:211], v[66:69]
	s_setprio 2
	s_barrier
	v_mfma_f32_16x16x32_bf16 v[70:73], v[164:167], v[204:207], v[70:73]
	v_mfma_f32_16x16x32_bf16 v[70:73], v[168:171], v[208:211], v[70:73]
	s_setprio 0
	ds_read_b128 v[180:183], v145 offset:49152
	ds_read_b128 v[184:187], v145 offset:50176
	ds_read_b128 v[188:191], v145 offset:51200
	ds_read_b128 v[192:195], v145 offset:52224
	ds_read_b128 v[196:199], v145 offset:53248
	ds_read_b128 v[200:203], v145 offset:54272
	ds_read_b128 v[204:207], v145 offset:55296
	ds_read_b128 v[208:211], v145 offset:56320
	s_add_u32 s22, s20, 0x80
	s_addc_u32 s23, s21, 0
	s_mov_b32 s74, m0
	s_mov_b32 m0, s46
	s_nop 0
	global_load_lds_dwordx4 v139, s[22:23]
	s_mov_b32 m0, s74
	s_add_u32 s20, s20, 0x80080
	s_mov_b32 s74, m0
	s_mov_b32 m0, s47
	s_nop 0
	global_load_lds_dwordx4 v141, s[22:23]
	s_mov_b32 m0, s74
	s_addc_u32 s21, s21, 0
	s_mov_b32 s22, m0
	s_mov_b32 m0, s48
	s_nop 0
	global_load_lds_dwordx4 v139, s[20:21]
	s_mov_b32 m0, s22
	s_nop 0
	s_mov_b32 s22, m0
	s_mov_b32 m0, s49
	s_nop 0
	global_load_lds_dwordx4 v141, s[20:21]
	s_mov_b32 m0, s22
	s_waitcnt vmcnt(4)
	s_waitcnt lgkmcnt(0)
	s_waitcnt lgkmcnt(7)
	v_mfma_f32_16x16x32_bf16 v[62:65], v[148:151], v[180:183], v[62:65]
	v_mfma_f32_16x16x32_bf16 v[62:65], v[152:155], v[184:187], v[62:65]
	s_waitcnt lgkmcnt(5)
	v_mfma_f32_16x16x32_bf16 v[58:61], v[156:159], v[180:183], v[58:61]
	v_mfma_f32_16x16x32_bf16 v[58:61], v[160:163], v[184:187], v[58:61]
	s_barrier
	s_setprio 1
	s_waitcnt lgkmcnt(3)
	v_mfma_f32_16x16x32_bf16 v[42:45], v[156:159], v[188:191], v[42:45]
	v_mfma_f32_16x16x32_bf16 v[42:45], v[160:163], v[192:195], v[42:45]
	s_waitcnt lgkmcnt(1)
	v_mfma_f32_16x16x32_bf16 v[46:49], v[148:151], v[188:191], v[46:49]
	v_mfma_f32_16x16x32_bf16 v[46:49], v[152:155], v[192:195], v[46:49]
	v_mfma_f32_16x16x32_bf16 v[30:33], v[148:151], v[196:199], v[30:33]
	v_mfma_f32_16x16x32_bf16 v[30:33], v[152:155], v[200:203], v[30:33]
	v_mfma_f32_16x16x32_bf16 v[26:29], v[156:159], v[196:199], v[26:29]
	v_mfma_f32_16x16x32_bf16 v[26:29], v[160:163], v[200:203], v[26:29]
	v_mfma_f32_16x16x32_bf16 v[10:13], v[156:159], v[204:207], v[10:13]
	v_mfma_f32_16x16x32_bf16 v[10:13], v[160:163], v[208:211], v[10:13]
	s_waitcnt lgkmcnt(0)
	v_mfma_f32_16x16x32_bf16 v[14:17], v[148:151], v[204:207], v[14:17]
	v_mfma_f32_16x16x32_bf16 v[14:17], v[152:155], v[208:211], v[14:17]
	s_setprio 0
	s_setprio 1
	v_mfma_f32_16x16x32_bf16 v[54:57], v[164:167], v[180:183], v[54:57]
	v_mfma_f32_16x16x32_bf16 v[54:57], v[168:171], v[184:187], v[54:57]
	v_mfma_f32_16x16x32_bf16 v[50:53], v[172:175], v[180:183], v[50:53]
	v_mfma_f32_16x16x32_bf16 v[50:53], v[176:179], v[184:187], v[50:53]
	v_mfma_f32_16x16x32_bf16 v[34:37], v[172:175], v[188:191], v[34:37]
	v_mfma_f32_16x16x32_bf16 v[34:37], v[176:179], v[192:195], v[34:37]
	v_mfma_f32_16x16x32_bf16 v[38:41], v[164:167], v[188:191], v[38:41]
	v_mfma_f32_16x16x32_bf16 v[38:41], v[168:171], v[192:195], v[38:41]
	v_mfma_f32_16x16x32_bf16 v[22:25], v[164:167], v[196:199], v[22:25]
	v_mfma_f32_16x16x32_bf16 v[22:25], v[168:171], v[200:203], v[22:25]
	v_mfma_f32_16x16x32_bf16 v[18:21], v[172:175], v[196:199], v[18:21]
	v_mfma_f32_16x16x32_bf16 v[18:21], v[176:179], v[200:203], v[18:21]
	v_mfma_f32_16x16x32_bf16 v[2:5], v[172:175], v[204:207], v[2:5]
	v_mfma_f32_16x16x32_bf16 v[2:5], v[176:179], v[208:211], v[2:5]
	s_setprio 2
	s_barrier
	v_mfma_f32_16x16x32_bf16 v[6:9], v[164:167], v[204:207], v[6:9]
	v_mfma_f32_16x16x32_bf16 v[6:9], v[168:171], v[208:211], v[6:9]
	s_setprio 0
	s_add_i32 s73, s73, 2
	s_add_u32 s66, s66, 0x100
	s_addc_u32 s67, s67, 0
	s_add_u32 s18, s18, 0x100
	s_addc_u32 s19, s19, 0
	s_add_u32 s70, s70, 0x100
	s_addc_u32 s71, s71, 0
	s_cmp_gt_u32 s73, 29
	s_cbranch_scc0 .LBB0_1785
	s_and_b64 vcc, exec, s[6:7]
	s_cbranch_vccz .LBB0_1788
	s_barrier

.LBB0_1951:
	s_ashr_i32 s13, s12, 31
	s_lshl_b64 s[14:15], s[12:13], 15
	s_add_u32 s14, s28, s14
	s_addc_u32 s15, s29, s15
	s_and_b64 s[16:17], s[2:3], exec
	s_cselect_b32 s13, s15, s23
	s_cselect_b32 s65, s14, s22
	s_ashr_i32 s11, s10, 31
	s_lshl_b64 s[16:17], s[10:11], 15
	s_add_u32 s16, s30, s16
	s_addc_u32 s17, s31, s17
	s_and_b64 s[24:25], s[2:3], exec
	s_cselect_b32 s11, s17, s21
	s_cselect_b32 s66, s16, s20
	s_add_u32 s67, s20, 0x80000
	s_addc_u32 s70, s21, 0
	s_add_u32 s20, s22, 0x204000
	s_addc_u32 s21, s23, 0
	s_add_u32 s71, s22, 0x400000
	s_addc_u32 s73, s23, 0
	s_mov_b32 s74, -2
	s_waitcnt vmcnt(25)
	s_waitcnt vmcnt(24)
	s_waitcnt vmcnt(4)
	s_waitcnt vmcnt(2)
	s_waitcnt vmcnt(1)
	s_waitcnt vmcnt(0)
	ds_read_b128 v[130:133], v181
	ds_read_b128 v[134:137], v181 offset:1024
	ds_read_b128 v[138:141], v181 offset:2048
	ds_read_b128 v[142:145], v181 offset:3072
	ds_read_b128 v[150:153], v182
	ds_read_b128 v[154:157], v182 offset:1024
	ds_read_b128 v[158:161], v182 offset:2048
	ds_read_b128 v[162:165], v182 offset:3072
	s_cmpk_eq_i32 s74, 0x52
	s_cselect_b32 s23, s11, s70
	s_cselect_b32 s22, s66, s67
	s_cselect_b32 s25, s13, s73
	s_cselect_b32 s24, s65, s71
	ds_read_b128 v[166:169], v183
	ds_read_b128 v[170:173], v183 offset:1024
	ds_read_b128 v[186:189], v183 offset:2048
	ds_read_b128 v[190:193], v183 offset:3072
	ds_read_b128 v[194:197], v183 offset:4096
	ds_read_b128 v[198:201], v183 offset:5120
	ds_read_b128 v[202:205], v183 offset:6144
	ds_read_b128 v[206:209], v183 offset:7168
	s_add_u32 s76, s20, 0xffffc000
	s_addc_u32 s77, s21, -1
	s_mov_b32 s75, m0
	s_mov_b32 m0, s58
	s_nop 0
	global_load_lds_dwordx4 v1, s[76:77]
	s_mov_b32 m0, s75
	s_nop 0
	s_mov_b32 s75, m0
	s_mov_b32 m0, s62
	s_nop 0
	global_load_lds_dwordx4 v177, s[76:77]
	s_mov_b32 m0, s75
	s_nop 0
	s_mov_b32 s75, m0
	s_mov_b32 m0, s59
	s_nop 0
	global_load_lds_dwordx4 v1, s[20:21]
	s_mov_b32 m0, s75
	s_nop 0
	s_mov_b32 s75, m0
	s_mov_b32 m0, s63
	s_nop 0
	global_load_lds_dwordx4 v177, s[20:21]
	s_mov_b32 m0, s75
	s_waitcnt vmcnt(8)
	s_waitcnt lgkmcnt(0)
	s_waitcnt lgkmcnt(7)
	v_mfma_f32_16x16x32_bf16 v[126:129], v[130:133], v[166:169], 0
	v_mfma_f32_16x16x32_bf16 v[126:129], v[134:137], v[170:173], v[126:129]
	s_waitcnt lgkmcnt(5)
	v_mfma_f32_16x16x32_bf16 v[122:125], v[138:141], v[166:169], 0
	v_mfma_f32_16x16x32_bf16 v[122:125], v[142:145], v[170:173], v[122:125]
	s_barrier
	s_setprio 1
	s_waitcnt lgkmcnt(3)
	v_mfma_f32_16x16x32_bf16 v[110:113], v[138:141], v[186:189], 0
	v_mfma_f32_16x16x32_bf16 v[110:113], v[142:145], v[190:193], v[110:113]
	s_waitcnt lgkmcnt(1)
	v_mfma_f32_16x16x32_bf16 v[118:121], v[130:133], v[186:189], 0
	v_mfma_f32_16x16x32_bf16 v[118:121], v[134:137], v[190:193], v[118:121]
	v_mfma_f32_16x16x32_bf16 v[94:97], v[130:133], v[194:197], 0
	v_mfma_f32_16x16x32_bf16 v[94:97], v[134:137], v[198:201], v[94:97]
	v_mfma_f32_16x16x32_bf16 v[90:93], v[138:141], v[194:197], 0
	v_mfma_f32_16x16x32_bf16 v[90:93], v[142:145], v[198:201], v[90:93]
	v_mfma_f32_16x16x32_bf16 v[78:81], v[138:141], v[202:205], 0
	v_mfma_f32_16x16x32_bf16 v[78:81], v[142:145], v[206:209], v[78:81]
	s_waitcnt lgkmcnt(0)
	v_mfma_f32_16x16x32_bf16 v[86:89], v[130:133], v[202:205], 0
	v_mfma_f32_16x16x32_bf16 v[86:89], v[134:137], v[206:209], v[86:89]
	s_setprio 0
	s_setprio 1
	v_mfma_f32_16x16x32_bf16 v[114:117], v[150:153], v[166:169], 0
	v_mfma_f32_16x16x32_bf16 v[114:117], v[154:157], v[170:173], v[114:117]
	v_mfma_f32_16x16x32_bf16 v[106:109], v[158:161], v[166:169], 0
	v_mfma_f32_16x16x32_bf16 v[106:109], v[162:165], v[170:173], v[106:109]
	v_mfma_f32_16x16x32_bf16 v[98:101], v[158:161], v[186:189], 0
	v_mfma_f32_16x16x32_bf16 v[98:101], v[162:165], v[190:193], v[98:101]
	v_mfma_f32_16x16x32_bf16 v[102:105], v[150:153], v[186:189], 0
	v_mfma_f32_16x16x32_bf16 v[102:105], v[154:157], v[190:193], v[102:105]
	v_mfma_f32_16x16x32_bf16 v[82:85], v[150:153], v[194:197], 0
	v_mfma_f32_16x16x32_bf16 v[82:85], v[154:157], v[198:201], v[82:85]
	v_mfma_f32_16x16x32_bf16 v[74:77], v[158:161], v[194:197], 0
	v_mfma_f32_16x16x32_bf16 v[74:77], v[162:165], v[198:201], v[74:77]
	v_mfma_f32_16x16x32_bf16 v[66:69], v[158:161], v[202:205], 0
	v_mfma_f32_16x16x32_bf16 v[66:69], v[162:165], v[206:209], v[66:69]
	s_setprio 2
	s_barrier
	v_mfma_f32_16x16x32_bf16 v[70:73], v[150:153], v[202:205], 0
	v_mfma_f32_16x16x32_bf16 v[70:73], v[154:157], v[206:209], v[70:73]
	s_setprio 0
	ds_read_b128 v[166:169], v183 offset:16384
	ds_read_b128 v[170:173], v183 offset:17408
	ds_read_b128 v[186:189], v183 offset:18432
	ds_read_b128 v[190:193], v183 offset:19456
	ds_read_b128 v[194:197], v183 offset:20480
	ds_read_b128 v[198:201], v183 offset:21504
	ds_read_b128 v[202:205], v183 offset:22528
	ds_read_b128 v[206:209], v183 offset:23552
	s_mov_b32 s75, m0
	s_mov_b32 m0, s35
	s_nop 0
	global_load_lds_dwordx4 v176, s[22:23]
	s_mov_b32 m0, s75
	s_add_u32 s76, s22, 0x4000
	s_mov_b32 s75, m0
	s_mov_b32 m0, s36
	s_nop 0
	global_load_lds_dwordx4 v178, s[22:23]
	s_mov_b32 m0, s75
	s_addc_u32 s77, s23, 0
	s_mov_b32 s75, m0
	s_mov_b32 m0, s37
	s_nop 0
	global_load_lds_dwordx4 v176, s[76:77]
	s_mov_b32 m0, s75
	s_nop 0
	s_mov_b32 s75, m0
	s_mov_b32 m0, s40
	s_nop 0
	global_load_lds_dwordx4 v178, s[76:77]
	s_mov_b32 m0, s75
	s_waitcnt vmcnt(4)
	s_waitcnt lgkmcnt(0)
	s_waitcnt lgkmcnt(7)
	v_mfma_f32_16x16x32_bf16 v[62:65], v[130:133], v[166:169], 0
	v_mfma_f32_16x16x32_bf16 v[62:65], v[134:137], v[170:173], v[62:65]
	s_waitcnt lgkmcnt(5)
	v_mfma_f32_16x16x32_bf16 v[58:61], v[138:141], v[166:169], 0
	v_mfma_f32_16x16x32_bf16 v[58:61], v[142:145], v[170:173], v[58:61]
	s_barrier
	s_setprio 1
	s_waitcnt lgkmcnt(3)
	v_mfma_f32_16x16x32_bf16 v[42:45], v[138:141], v[186:189], 0
	v_mfma_f32_16x16x32_bf16 v[42:45], v[142:145], v[190:193], v[42:45]
	s_waitcnt lgkmcnt(1)
	v_mfma_f32_16x16x32_bf16 v[46:49], v[130:133], v[186:189], 0
	v_mfma_f32_16x16x32_bf16 v[46:49], v[134:137], v[190:193], v[46:49]
	v_mfma_f32_16x16x32_bf16 v[30:33], v[130:133], v[194:197], 0
	v_mfma_f32_16x16x32_bf16 v[30:33], v[134:137], v[198:201], v[30:33]
	v_mfma_f32_16x16x32_bf16 v[26:29], v[138:141], v[194:197], 0
	v_mfma_f32_16x16x32_bf16 v[26:29], v[142:145], v[198:201], v[26:29]
	v_mfma_f32_16x16x32_bf16 v[10:13], v[138:141], v[202:205], 0
	v_mfma_f32_16x16x32_bf16 v[10:13], v[142:145], v[206:209], v[10:13]
	s_waitcnt lgkmcnt(0)
	v_mfma_f32_16x16x32_bf16 v[14:17], v[130:133], v[202:205], 0
	v_mfma_f32_16x16x32_bf16 v[14:17], v[134:137], v[206:209], v[14:17]
	s_setprio 0
	s_setprio 1
	v_mfma_f32_16x16x32_bf16 v[54:57], v[150:153], v[166:169], 0
	v_mfma_f32_16x16x32_bf16 v[54:57], v[154:157], v[170:173], v[54:57]
	v_mfma_f32_16x16x32_bf16 v[50:53], v[158:161], v[166:169], 0
	v_mfma_f32_16x16x32_bf16 v[50:53], v[162:165], v[170:173], v[50:53]
	v_mfma_f32_16x16x32_bf16 v[34:37], v[158:161], v[186:189], 0
	v_mfma_f32_16x16x32_bf16 v[34:37], v[162:165], v[190:193], v[34:37]
	v_mfma_f32_16x16x32_bf16 v[38:41], v[150:153], v[186:189], 0
	v_mfma_f32_16x16x32_bf16 v[38:41], v[154:157], v[190:193], v[38:41]
	v_mfma_f32_16x16x32_bf16 v[22:25], v[150:153], v[194:197], 0
	v_mfma_f32_16x16x32_bf16 v[22:25], v[154:157], v[198:201], v[22:25]
	v_mfma_f32_16x16x32_bf16 v[18:21], v[158:161], v[194:197], 0
	v_mfma_f32_16x16x32_bf16 v[18:21], v[162:165], v[198:201], v[18:21]
	v_mfma_f32_16x16x32_bf16 v[2:5], v[158:161], v[202:205], 0
	v_mfma_f32_16x16x32_bf16 v[2:5], v[162:165], v[206:209], v[2:5]
	s_setprio 2
	s_barrier
	v_mfma_f32_16x16x32_bf16 v[6:9], v[150:153], v[202:205], 0
	v_mfma_f32_16x16x32_bf16 v[6:9], v[154:157], v[206:209], v[6:9]
	s_setprio 0
	ds_read_b128 v[130:133], v184
	ds_read_b128 v[134:137], v184 offset:1024
	ds_read_b128 v[138:141], v184 offset:2048
	ds_read_b128 v[142:145], v184 offset:3072
	ds_read_b128 v[150:153], v185
	ds_read_b128 v[154:157], v185 offset:1024
	ds_read_b128 v[158:161], v185 offset:2048
	ds_read_b128 v[162:165], v185 offset:3072
	ds_read_b128 v[166:169], v183 offset:32768
	ds_read_b128 v[170:173], v183 offset:33792
	ds_read_b128 v[186:189], v183 offset:34816
	ds_read_b128 v[190:193], v183 offset:35840
	ds_read_b128 v[194:197], v183 offset:36864
	ds_read_b128 v[198:201], v183 offset:37888
	ds_read_b128 v[202:205], v183 offset:38912
	ds_read_b128 v[206:209], v183 offset:39936
	s_mov_b32 s75, m0
	s_mov_b32 m0, s34
	s_nop 0
	global_load_lds_dwordx4 v1, s[24:25]
	s_mov_b32 m0, s75
	s_nop 0
	s_mov_b32 s75, m0
	s_mov_b32 m0, s41
	s_nop 0
	global_load_lds_dwordx4 v177, s[24:25]
	s_mov_b32 m0, s75
	s_add_u32 s24, s24, 0x4000
	s_addc_u32 s25, s25, 0
	s_mov_b32 s75, m0
	s_mov_b32 m0, s42
	s_nop 0
	global_load_lds_dwordx4 v1, s[24:25]
	s_mov_b32 m0, s75
	s_nop 0
	s_mov_b32 s75, m0
	s_mov_b32 m0, s43
	s_nop 0
	global_load_lds_dwordx4 v177, s[24:25]
	s_mov_b32 m0, s75
	s_waitcnt vmcnt(8)
	s_waitcnt lgkmcnt(0)
	s_waitcnt lgkmcnt(7)
	v_mfma_f32_16x16x32_bf16 v[126:129], v[130:133], v[166:169], v[126:129]
	v_mfma_f32_16x16x32_bf16 v[126:129], v[134:137], v[170:173], v[126:129]
	s_waitcnt lgkmcnt(5)
	v_mfma_f32_16x16x32_bf16 v[122:125], v[138:141], v[166:169], v[122:125]
	v_mfma_f32_16x16x32_bf16 v[122:125], v[142:145], v[170:173], v[122:125]
	s_barrier
	s_setprio 1
	s_waitcnt lgkmcnt(3)
	v_mfma_f32_16x16x32_bf16 v[110:113], v[138:141], v[186:189], v[110:113]
	v_mfma_f32_16x16x32_bf16 v[110:113], v[142:145], v[190:193], v[110:113]
	s_waitcnt lgkmcnt(1)
	v_mfma_f32_16x16x32_bf16 v[118:121], v[130:133], v[186:189], v[118:121]
	v_mfma_f32_16x16x32_bf16 v[118:121], v[134:137], v[190:193], v[118:121]
	v_mfma_f32_16x16x32_bf16 v[94:97], v[130:133], v[194:197], v[94:97]
	v_mfma_f32_16x16x32_bf16 v[94:97], v[134:137], v[198:201], v[94:97]
	v_mfma_f32_16x16x32_bf16 v[90:93], v[138:141], v[194:197], v[90:93]
	v_mfma_f32_16x16x32_bf16 v[90:93], v[142:145], v[198:201], v[90:93]
	v_mfma_f32_16x16x32_bf16 v[78:81], v[138:141], v[202:205], v[78:81]
	v_mfma_f32_16x16x32_bf16 v[78:81], v[142:145], v[206:209], v[78:81]
	s_waitcnt lgkmcnt(0)
	v_mfma_f32_16x16x32_bf16 v[86:89], v[130:133], v[202:205], v[86:89]
	v_mfma_f32_16x16x32_bf16 v[86:89], v[134:137], v[206:209], v[86:89]
	s_setprio 0
	s_setprio 1
	v_mfma_f32_16x16x32_bf16 v[114:117], v[150:153], v[166:169], v[114:117]
	v_mfma_f32_16x16x32_bf16 v[114:117], v[154:157], v[170:173], v[114:117]
	v_mfma_f32_16x16x32_bf16 v[106:109], v[158:161], v[166:169], v[106:109]
	v_mfma_f32_16x16x32_bf16 v[106:109], v[162:165], v[170:173], v[106:109]
	v_mfma_f32_16x16x32_bf16 v[98:101], v[158:161], v[186:189], v[98:101]
	v_mfma_f32_16x16x32_bf16 v[98:101], v[162:165], v[190:193], v[98:101]
	v_mfma_f32_16x16x32_bf16 v[102:105], v[150:153], v[186:189], v[102:105]
	v_mfma_f32_16x16x32_bf16 v[102:105], v[154:157], v[190:193], v[102:105]
	v_mfma_f32_16x16x32_bf16 v[82:85], v[150:153], v[194:197], v[82:85]
	v_mfma_f32_16x16x32_bf16 v[82:85], v[154:157], v[198:201], v[82:85]
	v_mfma_f32_16x16x32_bf16 v[74:77], v[158:161], v[194:197], v[74:77]
	v_mfma_f32_16x16x32_bf16 v[74:77], v[162:165], v[198:201], v[74:77]
	v_mfma_f32_16x16x32_bf16 v[66:69], v[158:161], v[202:205], v[66:69]
	v_mfma_f32_16x16x32_bf16 v[66:69], v[162:165], v[206:209], v[66:69]
	s_setprio 2
	s_barrier
	v_mfma_f32_16x16x32_bf16 v[70:73], v[150:153], v[202:205], v[70:73]
	v_mfma_f32_16x16x32_bf16 v[70:73], v[154:157], v[206:209], v[70:73]
	s_setprio 0
	ds_read_b128 v[166:169], v183 offset:49152
	ds_read_b128 v[170:173], v183 offset:50176
	ds_read_b128 v[186:189], v183 offset:51200
	ds_read_b128 v[190:193], v183 offset:52224
	ds_read_b128 v[194:197], v183 offset:53248
	ds_read_b128 v[198:201], v183 offset:54272
	ds_read_b128 v[202:205], v183 offset:55296
	ds_read_b128 v[206:209], v183 offset:56320
	s_add_u32 s24, s22, 0x40000
	s_addc_u32 s25, s23, 0
	s_mov_b32 s75, m0
	s_mov_b32 m0, s46
	s_nop 0
	global_load_lds_dwordx4 v176, s[24:25]
	s_mov_b32 m0, s75
	s_add_u32 s22, s22, 0x44000
	s_mov_b32 s75, m0
	s_mov_b32 m0, s47
	s_nop 0
	global_load_lds_dwordx4 v178, s[24:25]
	s_mov_b32 m0, s75
	s_addc_u32 s23, s23, 0
	s_mov_b32 s24, m0
	s_mov_b32 m0, s48
	s_nop 0
	global_load_lds_dwordx4 v176, s[22:23]
	s_mov_b32 m0, s24
	s_nop 0
	s_mov_b32 s24, m0
	s_mov_b32 m0, s49
	s_nop 0
	global_load_lds_dwordx4 v178, s[22:23]
	s_mov_b32 m0, s24
	s_waitcnt vmcnt(4)
	s_waitcnt lgkmcnt(0)
	s_waitcnt lgkmcnt(7)
	v_mfma_f32_16x16x32_bf16 v[62:65], v[130:133], v[166:169], v[62:65]
	v_mfma_f32_16x16x32_bf16 v[62:65], v[134:137], v[170:173], v[62:65]
	s_waitcnt lgkmcnt(5)
	v_mfma_f32_16x16x32_bf16 v[58:61], v[138:141], v[166:169], v[58:61]
	v_mfma_f32_16x16x32_bf16 v[58:61], v[142:145], v[170:173], v[58:61]
	s_barrier
	s_setprio 1
	s_waitcnt lgkmcnt(3)
	v_mfma_f32_16x16x32_bf16 v[42:45], v[138:141], v[186:189], v[42:45]
	v_mfma_f32_16x16x32_bf16 v[42:45], v[142:145], v[190:193], v[42:45]
	s_waitcnt lgkmcnt(1)
	v_mfma_f32_16x16x32_bf16 v[46:49], v[130:133], v[186:189], v[46:49]
	v_mfma_f32_16x16x32_bf16 v[46:49], v[134:137], v[190:193], v[46:49]
	v_mfma_f32_16x16x32_bf16 v[30:33], v[130:133], v[194:197], v[30:33]
	v_mfma_f32_16x16x32_bf16 v[30:33], v[134:137], v[198:201], v[30:33]
	v_mfma_f32_16x16x32_bf16 v[26:29], v[138:141], v[194:197], v[26:29]
	v_mfma_f32_16x16x32_bf16 v[26:29], v[142:145], v[198:201], v[26:29]
	v_mfma_f32_16x16x32_bf16 v[10:13], v[138:141], v[202:205], v[10:13]
	v_mfma_f32_16x16x32_bf16 v[10:13], v[142:145], v[206:209], v[10:13]
	s_waitcnt lgkmcnt(0)
	v_mfma_f32_16x16x32_bf16 v[14:17], v[130:133], v[202:205], v[14:17]
	v_mfma_f32_16x16x32_bf16 v[14:17], v[134:137], v[206:209], v[14:17]
	s_setprio 0
	s_setprio 1
	v_mfma_f32_16x16x32_bf16 v[54:57], v[150:153], v[166:169], v[54:57]
	v_mfma_f32_16x16x32_bf16 v[54:57], v[154:157], v[170:173], v[54:57]
	v_mfma_f32_16x16x32_bf16 v[50:53], v[158:161], v[166:169], v[50:53]
	v_mfma_f32_16x16x32_bf16 v[50:53], v[162:165], v[170:173], v[50:53]
	v_mfma_f32_16x16x32_bf16 v[34:37], v[158:161], v[186:189], v[34:37]
	v_mfma_f32_16x16x32_bf16 v[34:37], v[162:165], v[190:193], v[34:37]
	v_mfma_f32_16x16x32_bf16 v[38:41], v[150:153], v[186:189], v[38:41]
	v_mfma_f32_16x16x32_bf16 v[38:41], v[154:157], v[190:193], v[38:41]
	v_mfma_f32_16x16x32_bf16 v[22:25], v[150:153], v[194:197], v[22:25]
	v_mfma_f32_16x16x32_bf16 v[22:25], v[154:157], v[198:201], v[22:25]
	v_mfma_f32_16x16x32_bf16 v[18:21], v[158:161], v[194:197], v[18:21]
	v_mfma_f32_16x16x32_bf16 v[18:21], v[162:165], v[198:201], v[18:21]
	v_mfma_f32_16x16x32_bf16 v[2:5], v[158:161], v[202:205], v[2:5]
	v_mfma_f32_16x16x32_bf16 v[2:5], v[162:165], v[206:209], v[2:5]
	s_setprio 2
	s_barrier
	v_mfma_f32_16x16x32_bf16 v[6:9], v[150:153], v[202:205], v[6:9]
	v_mfma_f32_16x16x32_bf16 v[6:9], v[154:157], v[206:209], v[6:9]
	s_setprio 0
	s_add_i32 s74, s74, 2
	s_add_u32 s67, s67, 0x80000
	s_addc_u32 s70, s70, 0
	s_add_u32 s20, s20, 0x400000
	s_addc_u32 s21, s21, 0
	s_add_u32 s71, s71, 0x400000
	s_addc_u32 s73, s73, 0
	s_cmpk_gt_u32 s74, 0x53
	.p2align 6
.LBB0_1952:
	ds_read_b128 v[130:133], v181
	ds_read_b128 v[134:137], v181 offset:1024
	ds_read_b128 v[138:141], v181 offset:2048
	ds_read_b128 v[142:145], v181 offset:3072
	ds_read_b128 v[150:153], v182
	ds_read_b128 v[154:157], v182 offset:1024
	ds_read_b128 v[158:161], v182 offset:2048
	ds_read_b128 v[162:165], v182 offset:3072
	s_cmpk_eq_i32 s74, 0x52
	s_cselect_b32 s23, s11, s70
	s_cselect_b32 s22, s66, s67
	s_cselect_b32 s25, s13, s73
	s_cselect_b32 s24, s65, s71
	ds_read_b128 v[166:169], v183
	ds_read_b128 v[170:173], v183 offset:1024
	ds_read_b128 v[186:189], v183 offset:2048
	ds_read_b128 v[190:193], v183 offset:3072
	ds_read_b128 v[194:197], v183 offset:4096
	ds_read_b128 v[198:201], v183 offset:5120
	ds_read_b128 v[202:205], v183 offset:6144
	ds_read_b128 v[206:209], v183 offset:7168
	s_add_u32 s76, s20, 0xffffc000
	s_addc_u32 s77, s21, -1
	s_mov_b32 s75, m0
	s_mov_b32 m0, s58
	s_nop 0
	global_load_lds_dwordx4 v1, s[76:77]
	s_mov_b32 m0, s75
	s_nop 0
	s_mov_b32 s75, m0
	s_mov_b32 m0, s62
	s_nop 0
	global_load_lds_dwordx4 v177, s[76:77]
	s_mov_b32 m0, s75
	s_nop 0
	s_mov_b32 s75, m0
	s_mov_b32 m0, s59
	s_nop 0
	global_load_lds_dwordx4 v1, s[20:21]
	s_mov_b32 m0, s75
	s_nop 0
	s_mov_b32 s75, m0
	s_mov_b32 m0, s63
	s_nop 0
	global_load_lds_dwordx4 v177, s[20:21]
	s_mov_b32 m0, s75
	s_waitcnt vmcnt(8)
	s_waitcnt lgkmcnt(0)
	s_waitcnt lgkmcnt(7)
	v_mfma_f32_16x16x32_bf16 v[126:129], v[130:133], v[166:169], v[126:129]
	v_mfma_f32_16x16x32_bf16 v[126:129], v[134:137], v[170:173], v[126:129]
	s_waitcnt lgkmcnt(5)
	v_mfma_f32_16x16x32_bf16 v[122:125], v[138:141], v[166:169], v[122:125]
	v_mfma_f32_16x16x32_bf16 v[122:125], v[142:145], v[170:173], v[122:125]
	s_barrier
	s_setprio 1
	s_waitcnt lgkmcnt(3)
	v_mfma_f32_16x16x32_bf16 v[110:113], v[138:141], v[186:189], v[110:113]
	v_mfma_f32_16x16x32_bf16 v[110:113], v[142:145], v[190:193], v[110:113]
	s_waitcnt lgkmcnt(1)
	v_mfma_f32_16x16x32_bf16 v[118:121], v[130:133], v[186:189], v[118:121]
	v_mfma_f32_16x16x32_bf16 v[118:121], v[134:137], v[190:193], v[118:121]
	v_mfma_f32_16x16x32_bf16 v[94:97], v[130:133], v[194:197], v[94:97]
	v_mfma_f32_16x16x32_bf16 v[94:97], v[134:137], v[198:201], v[94:97]
	v_mfma_f32_16x16x32_bf16 v[90:93], v[138:141], v[194:197], v[90:93]
	v_mfma_f32_16x16x32_bf16 v[90:93], v[142:145], v[198:201], v[90:93]
	v_mfma_f32_16x16x32_bf16 v[78:81], v[138:141], v[202:205], v[78:81]
	v_mfma_f32_16x16x32_bf16 v[78:81], v[142:145], v[206:209], v[78:81]
	s_waitcnt lgkmcnt(0)
	v_mfma_f32_16x16x32_bf16 v[86:89], v[130:133], v[202:205], v[86:89]
	v_mfma_f32_16x16x32_bf16 v[86:89], v[134:137], v[206:209], v[86:89]
	s_setprio 0
	s_setprio 1
	v_mfma_f32_16x16x32_bf16 v[114:117], v[150:153], v[166:169], v[114:117]
	v_mfma_f32_16x16x32_bf16 v[114:117], v[154:157], v[170:173], v[114:117]
	v_mfma_f32_16x16x32_bf16 v[106:109], v[158:161], v[166:169], v[106:109]
	v_mfma_f32_16x16x32_bf16 v[106:109], v[162:165], v[170:173], v[106:109]
	v_mfma_f32_16x16x32_bf16 v[98:101], v[158:161], v[186:189], v[98:101]
	v_mfma_f32_16x16x32_bf16 v[98:101], v[162:165], v[190:193], v[98:101]
	v_mfma_f32_16x16x32_bf16 v[102:105], v[150:153], v[186:189], v[102:105]
	v_mfma_f32_16x16x32_bf16 v[102:105], v[154:157], v[190:193], v[102:105]
	v_mfma_f32_16x16x32_bf16 v[82:85], v[150:153], v[194:197], v[82:85]
	v_mfma_f32_16x16x32_bf16 v[82:85], v[154:157], v[198:201], v[82:85]
	v_mfma_f32_16x16x32_bf16 v[74:77], v[158:161], v[194:197], v[74:77]
	v_mfma_f32_16x16x32_bf16 v[74:77], v[162:165], v[198:201], v[74:77]
	v_mfma_f32_16x16x32_bf16 v[66:69], v[158:161], v[202:205], v[66:69]
	v_mfma_f32_16x16x32_bf16 v[66:69], v[162:165], v[206:209], v[66:69]
	s_setprio 2
	s_barrier
	v_mfma_f32_16x16x32_bf16 v[70:73], v[150:153], v[202:205], v[70:73]
	v_mfma_f32_16x16x32_bf16 v[70:73], v[154:157], v[206:209], v[70:73]
	s_setprio 0
	ds_read_b128 v[166:169], v183 offset:16384
	ds_read_b128 v[170:173], v183 offset:17408
	ds_read_b128 v[186:189], v183 offset:18432
	ds_read_b128 v[190:193], v183 offset:19456
	ds_read_b128 v[194:197], v183 offset:20480
	ds_read_b128 v[198:201], v183 offset:21504
	ds_read_b128 v[202:205], v183 offset:22528
	ds_read_b128 v[206:209], v183 offset:23552
	s_mov_b32 s75, m0
	s_mov_b32 m0, s35
	s_nop 0
	global_load_lds_dwordx4 v176, s[22:23]
	s_mov_b32 m0, s75
	s_add_u32 s76, s22, 0x4000
	s_mov_b32 s75, m0
	s_mov_b32 m0, s36
	s_nop 0
	global_load_lds_dwordx4 v178, s[22:23]
	s_mov_b32 m0, s75
	s_addc_u32 s77, s23, 0
	s_mov_b32 s75, m0
	s_mov_b32 m0, s37
	s_nop 0
	global_load_lds_dwordx4 v176, s[76:77]
	s_mov_b32 m0, s75
	s_nop 0
	s_mov_b32 s75, m0
	s_mov_b32 m0, s40
	s_nop 0
	global_load_lds_dwordx4 v178, s[76:77]
	s_mov_b32 m0, s75
	s_waitcnt vmcnt(4)
	s_waitcnt lgkmcnt(0)
	s_waitcnt lgkmcnt(7)
	v_mfma_f32_16x16x32_bf16 v[62:65], v[130:133], v[166:169], v[62:65]
	v_mfma_f32_16x16x32_bf16 v[62:65], v[134:137], v[170:173], v[62:65]
	s_waitcnt lgkmcnt(5)
	v_mfma_f32_16x16x32_bf16 v[58:61], v[138:141], v[166:169], v[58:61]
	v_mfma_f32_16x16x32_bf16 v[58:61], v[142:145], v[170:173], v[58:61]
	s_barrier
	s_setprio 1
	s_waitcnt lgkmcnt(3)
	v_mfma_f32_16x16x32_bf16 v[42:45], v[138:141], v[186:189], v[42:45]
	v_mfma_f32_16x16x32_bf16 v[42:45], v[142:145], v[190:193], v[42:45]
	s_waitcnt lgkmcnt(1)
	v_mfma_f32_16x16x32_bf16 v[46:49], v[130:133], v[186:189], v[46:49]
	v_mfma_f32_16x16x32_bf16 v[46:49], v[134:137], v[190:193], v[46:49]
	v_mfma_f32_16x16x32_bf16 v[30:33], v[130:133], v[194:197], v[30:33]
	v_mfma_f32_16x16x32_bf16 v[30:33], v[134:137], v[198:201], v[30:33]
	v_mfma_f32_16x16x32_bf16 v[26:29], v[138:141], v[194:197], v[26:29]
	v_mfma_f32_16x16x32_bf16 v[26:29], v[142:145], v[198:201], v[26:29]
	v_mfma_f32_16x16x32_bf16 v[10:13], v[138:141], v[202:205], v[10:13]
	v_mfma_f32_16x16x32_bf16 v[10:13], v[142:145], v[206:209], v[10:13]
	s_waitcnt lgkmcnt(0)
	v_mfma_f32_16x16x32_bf16 v[14:17], v[130:133], v[202:205], v[14:17]
	v_mfma_f32_16x16x32_bf16 v[14:17], v[134:137], v[206:209], v[14:17]
	s_setprio 0
	s_setprio 1
	v_mfma_f32_16x16x32_bf16 v[54:57], v[150:153], v[166:169], v[54:57]
	v_mfma_f32_16x16x32_bf16 v[54:57], v[154:157], v[170:173], v[54:57]
	v_mfma_f32_16x16x32_bf16 v[50:53], v[158:161], v[166:169], v[50:53]
	v_mfma_f32_16x16x32_bf16 v[50:53], v[162:165], v[170:173], v[50:53]
	v_mfma_f32_16x16x32_bf16 v[34:37], v[158:161], v[186:189], v[34:37]
	v_mfma_f32_16x16x32_bf16 v[34:37], v[162:165], v[190:193], v[34:37]
	v_mfma_f32_16x16x32_bf16 v[38:41], v[150:153], v[186:189], v[38:41]
	v_mfma_f32_16x16x32_bf16 v[38:41], v[154:157], v[190:193], v[38:41]
	v_mfma_f32_16x16x32_bf16 v[22:25], v[150:153], v[194:197], v[22:25]
	v_mfma_f32_16x16x32_bf16 v[22:25], v[154:157], v[198:201], v[22:25]
	v_mfma_f32_16x16x32_bf16 v[18:21], v[158:161], v[194:197], v[18:21]
	v_mfma_f32_16x16x32_bf16 v[18:21], v[162:165], v[198:201], v[18:21]
	v_mfma_f32_16x16x32_bf16 v[2:5], v[158:161], v[202:205], v[2:5]
	v_mfma_f32_16x16x32_bf16 v[2:5], v[162:165], v[206:209], v[2:5]
	s_setprio 2
	s_barrier
	v_mfma_f32_16x16x32_bf16 v[6:9], v[150:153], v[202:205], v[6:9]
	v_mfma_f32_16x16x32_bf16 v[6:9], v[154:157], v[206:209], v[6:9]
	s_setprio 0
	ds_read_b128 v[130:133], v184
	ds_read_b128 v[134:137], v184 offset:1024
	ds_read_b128 v[138:141], v184 offset:2048
	ds_read_b128 v[142:145], v184 offset:3072
	ds_read_b128 v[150:153], v185
	ds_read_b128 v[154:157], v185 offset:1024
	ds_read_b128 v[158:161], v185 offset:2048
	ds_read_b128 v[162:165], v185 offset:3072
	ds_read_b128 v[166:169], v183 offset:32768
	ds_read_b128 v[170:173], v183 offset:33792
	ds_read_b128 v[186:189], v183 offset:34816
	ds_read_b128 v[190:193], v183 offset:35840
	ds_read_b128 v[194:197], v183 offset:36864
	ds_read_b128 v[198:201], v183 offset:37888
	ds_read_b128 v[202:205], v183 offset:38912
	ds_read_b128 v[206:209], v183 offset:39936
	s_mov_b32 s75, m0
	s_mov_b32 m0, s34
	s_nop 0
	global_load_lds_dwordx4 v1, s[24:25]
	s_mov_b32 m0, s75
	s_nop 0
	s_mov_b32 s75, m0
	s_mov_b32 m0, s41
	s_nop 0
	global_load_lds_dwordx4 v177, s[24:25]
	s_mov_b32 m0, s75
	s_add_u32 s24, s24, 0x4000
	s_addc_u32 s25, s25, 0
	s_mov_b32 s75, m0
	s_mov_b32 m0, s42
	s_nop 0
	global_load_lds_dwordx4 v1, s[24:25]
	s_mov_b32 m0, s75
	s_nop 0
	s_mov_b32 s75, m0
	s_mov_b32 m0, s43
	s_nop 0
	global_load_lds_dwordx4 v177, s[24:25]
	s_mov_b32 m0, s75
	s_waitcnt vmcnt(8)
	s_waitcnt lgkmcnt(0)
	s_waitcnt lgkmcnt(7)
	v_mfma_f32_16x16x32_bf16 v[126:129], v[130:133], v[166:169], v[126:129]
	v_mfma_f32_16x16x32_bf16 v[126:129], v[134:137], v[170:173], v[126:129]
	s_waitcnt lgkmcnt(5)
	v_mfma_f32_16x16x32_bf16 v[122:125], v[138:141], v[166:169], v[122:125]
	v_mfma_f32_16x16x32_bf16 v[122:125], v[142:145], v[170:173], v[122:125]
	s_barrier
	s_setprio 1
	s_waitcnt lgkmcnt(3)
	v_mfma_f32_16x16x32_bf16 v[110:113], v[138:141], v[186:189], v[110:113]
	v_mfma_f32_16x16x32_bf16 v[110:113], v[142:145], v[190:193], v[110:113]
	s_waitcnt lgkmcnt(1)
	v_mfma_f32_16x16x32_bf16 v[118:121], v[130:133], v[186:189], v[118:121]
	v_mfma_f32_16x16x32_bf16 v[118:121], v[134:137], v[190:193], v[118:121]
	v_mfma_f32_16x16x32_bf16 v[94:97], v[130:133], v[194:197], v[94:97]
	v_mfma_f32_16x16x32_bf16 v[94:97], v[134:137], v[198:201], v[94:97]
	v_mfma_f32_16x16x32_bf16 v[90:93], v[138:141], v[194:197], v[90:93]
	v_mfma_f32_16x16x32_bf16 v[90:93], v[142:145], v[198:201], v[90:93]
	v_mfma_f32_16x16x32_bf16 v[78:81], v[138:141], v[202:205], v[78:81]
	v_mfma_f32_16x16x32_bf16 v[78:81], v[142:145], v[206:209], v[78:81]
	s_waitcnt lgkmcnt(0)
	v_mfma_f32_16x16x32_bf16 v[86:89], v[130:133], v[202:205], v[86:89]
	v_mfma_f32_16x16x32_bf16 v[86:89], v[134:137], v[206:209], v[86:89]
	s_setprio 0
	s_setprio 1
	v_mfma_f32_16x16x32_bf16 v[114:117], v[150:153], v[166:169], v[114:117]
	v_mfma_f32_16x16x32_bf16 v[114:117], v[154:157], v[170:173], v[114:117]
	v_mfma_f32_16x16x32_bf16 v[106:109], v[158:161], v[166:169], v[106:109]
	v_mfma_f32_16x16x32_bf16 v[106:109], v[162:165], v[170:173], v[106:109]
	v_mfma_f32_16x16x32_bf16 v[98:101], v[158:161], v[186:189], v[98:101]
	v_mfma_f32_16x16x32_bf16 v[98:101], v[162:165], v[190:193], v[98:101]
	v_mfma_f32_16x16x32_bf16 v[102:105], v[150:153], v[186:189], v[102:105]
	v_mfma_f32_16x16x32_bf16 v[102:105], v[154:157], v[190:193], v[102:105]
	v_mfma_f32_16x16x32_bf16 v[82:85], v[150:153], v[194:197], v[82:85]
	v_mfma_f32_16x16x32_bf16 v[82:85], v[154:157], v[198:201], v[82:85]
	v_mfma_f32_16x16x32_bf16 v[74:77], v[158:161], v[194:197], v[74:77]
	v_mfma_f32_16x16x32_bf16 v[74:77], v[162:165], v[198:201], v[74:77]
	v_mfma_f32_16x16x32_bf16 v[66:69], v[158:161], v[202:205], v[66:69]
	v_mfma_f32_16x16x32_bf16 v[66:69], v[162:165], v[206:209], v[66:69]
	s_setprio 2
	s_barrier
	v_mfma_f32_16x16x32_bf16 v[70:73], v[150:153], v[202:205], v[70:73]
	v_mfma_f32_16x16x32_bf16 v[70:73], v[154:157], v[206:209], v[70:73]
	s_setprio 0
	ds_read_b128 v[166:169], v183 offset:49152
	ds_read_b128 v[170:173], v183 offset:50176
	ds_read_b128 v[186:189], v183 offset:51200
	ds_read_b128 v[190:193], v183 offset:52224
	ds_read_b128 v[194:197], v183 offset:53248
	ds_read_b128 v[198:201], v183 offset:54272
	ds_read_b128 v[202:205], v183 offset:55296
	ds_read_b128 v[206:209], v183 offset:56320
	s_add_u32 s24, s22, 0x40000
	s_addc_u32 s25, s23, 0
	s_mov_b32 s75, m0
	s_mov_b32 m0, s46
	s_nop 0
	global_load_lds_dwordx4 v176, s[24:25]
	s_mov_b32 m0, s75
	s_add_u32 s22, s22, 0x44000
	s_mov_b32 s75, m0
	s_mov_b32 m0, s47
	s_nop 0
	global_load_lds_dwordx4 v178, s[24:25]
	s_mov_b32 m0, s75
	s_addc_u32 s23, s23, 0
	s_mov_b32 s24, m0
	s_mov_b32 m0, s48
	s_nop 0
	global_load_lds_dwordx4 v176, s[22:23]
	s_mov_b32 m0, s24
	s_nop 0
	s_mov_b32 s24, m0
	s_mov_b32 m0, s49
	s_nop 0
	global_load_lds_dwordx4 v178, s[22:23]
	s_mov_b32 m0, s24
	s_waitcnt vmcnt(4)
	s_waitcnt lgkmcnt(0)
	s_waitcnt lgkmcnt(7)
	v_mfma_f32_16x16x32_bf16 v[62:65], v[130:133], v[166:169], v[62:65]
	v_mfma_f32_16x16x32_bf16 v[62:65], v[134:137], v[170:173], v[62:65]
	s_waitcnt lgkmcnt(5)
	v_mfma_f32_16x16x32_bf16 v[58:61], v[138:141], v[166:169], v[58:61]
	v_mfma_f32_16x16x32_bf16 v[58:61], v[142:145], v[170:173], v[58:61]
	s_barrier
	s_setprio 1
	s_waitcnt lgkmcnt(3)
	v_mfma_f32_16x16x32_bf16 v[42:45], v[138:141], v[186:189], v[42:45]
	v_mfma_f32_16x16x32_bf16 v[42:45], v[142:145], v[190:193], v[42:45]
	s_waitcnt lgkmcnt(1)
	v_mfma_f32_16x16x32_bf16 v[46:49], v[130:133], v[186:189], v[46:49]
	v_mfma_f32_16x16x32_bf16 v[46:49], v[134:137], v[190:193], v[46:49]
	v_mfma_f32_16x16x32_bf16 v[30:33], v[130:133], v[194:197], v[30:33]
	v_mfma_f32_16x16x32_bf16 v[30:33], v[134:137], v[198:201], v[30:33]
	v_mfma_f32_16x16x32_bf16 v[26:29], v[138:141], v[194:197], v[26:29]
	v_mfma_f32_16x16x32_bf16 v[26:29], v[142:145], v[198:201], v[26:29]
	v_mfma_f32_16x16x32_bf16 v[10:13], v[138:141], v[202:205], v[10:13]
	v_mfma_f32_16x16x32_bf16 v[10:13], v[142:145], v[206:209], v[10:13]
	s_waitcnt lgkmcnt(0)
	v_mfma_f32_16x16x32_bf16 v[14:17], v[130:133], v[202:205], v[14:17]
	v_mfma_f32_16x16x32_bf16 v[14:17], v[134:137], v[206:209], v[14:17]
	s_setprio 0
	s_setprio 1
	v_mfma_f32_16x16x32_bf16 v[54:57], v[150:153], v[166:169], v[54:57]
	v_mfma_f32_16x16x32_bf16 v[54:57], v[154:157], v[170:173], v[54:57]
	v_mfma_f32_16x16x32_bf16 v[50:53], v[158:161], v[166:169], v[50:53]
	v_mfma_f32_16x16x32_bf16 v[50:53], v[162:165], v[170:173], v[50:53]
	v_mfma_f32_16x16x32_bf16 v[34:37], v[158:161], v[186:189], v[34:37]
	v_mfma_f32_16x16x32_bf16 v[34:37], v[162:165], v[190:193], v[34:37]
	v_mfma_f32_16x16x32_bf16 v[38:41], v[150:153], v[186:189], v[38:41]
	v_mfma_f32_16x16x32_bf16 v[38:41], v[154:157], v[190:193], v[38:41]
	v_mfma_f32_16x16x32_bf16 v[22:25], v[150:153], v[194:197], v[22:25]
	v_mfma_f32_16x16x32_bf16 v[22:25], v[154:157], v[198:201], v[22:25]
	v_mfma_f32_16x16x32_bf16 v[18:21], v[158:161], v[194:197], v[18:21]
	v_mfma_f32_16x16x32_bf16 v[18:21], v[162:165], v[198:201], v[18:21]
	v_mfma_f32_16x16x32_bf16 v[2:5], v[158:161], v[202:205], v[2:5]
	v_mfma_f32_16x16x32_bf16 v[2:5], v[162:165], v[206:209], v[2:5]
	s_setprio 2
	s_barrier
	v_mfma_f32_16x16x32_bf16 v[6:9], v[150:153], v[202:205], v[6:9]
	v_mfma_f32_16x16x32_bf16 v[6:9], v[154:157], v[206:209], v[6:9]
	s_setprio 0
	s_add_i32 s74, s74, 2
	s_add_u32 s67, s67, 0x80000
	s_addc_u32 s70, s70, 0
	s_add_u32 s20, s20, 0x400000
	s_addc_u32 s21, s21, 0
	s_add_u32 s71, s71, 0x400000
	s_addc_u32 s73, s73, 0
	s_cmpk_gt_u32 s74, 0x53
	s_cbranch_scc0 .LBB0_1952
	s_and_b64 vcc, exec, s[8:9]
	s_cbranch_vccz .LBB0_1955
	s_barrier

.LBB0_2145:
	s_ashr_i32 s25, s24, 31
	s_lshl_b64 s[26:27], s[24:25], 20
	s_add_u32 s26, s33, s26
	s_addc_u32 s27, s42, s27
	s_and_b64 s[28:29], s[2:3], exec
	s_cselect_b32 s5, s27, s37
	s_cselect_b32 s25, s26, s36
	s_ashr_i32 s23, s22, 31
	s_lshl_b64 s[28:29], s[22:23], 20
	s_add_u32 s28, s43, s28
	s_addc_u32 s29, s46, s29
	s_and_b64 s[40:41], s[2:3], exec
	s_cselect_b32 s23, s29, s35
	s_cselect_b32 s31, s28, s34
	s_add_u32 s77, s34, 0x100
	s_addc_u32 s78, s35, 0
	s_add_u32 s34, s36, 0x80080
	s_addc_u32 s35, s37, 0
	s_add_u32 s79, s36, 0x100
	s_addc_u32 s80, s37, 0
	s_mov_b32 s81, -2
	s_waitcnt vmcnt(25)
	s_waitcnt vmcnt(24)
	s_waitcnt vmcnt(4)
	s_waitcnt vmcnt(2)
	s_waitcnt vmcnt(1)
	s_waitcnt vmcnt(0)
	ds_read_b128 v[42:45], v181
	ds_read_b128 v[46:49], v181 offset:1024
	ds_read_b128 v[58:61], v181 offset:2048
	ds_read_b128 v[62:65], v181 offset:3072
	ds_read_b128 v[146:149], v182
	ds_read_b128 v[150:153], v182 offset:1024
	ds_read_b128 v[154:157], v182 offset:2048
	ds_read_b128 v[158:161], v182 offset:3072
	s_cmp_eq_u32 s81, 28
	s_cselect_b32 s37, s23, s78
	s_cselect_b32 s36, s31, s77
	s_cselect_b32 s41, s5, s80
	s_cselect_b32 s40, s25, s79
	ds_read_b128 v[170:173], v183
	ds_read_b128 v[188:191], v183 offset:1024
	ds_read_b128 v[192:195], v183 offset:2048
	ds_read_b128 v[196:199], v183 offset:3072
	ds_read_b128 v[200:203], v183 offset:4096
	ds_read_b128 v[204:207], v183 offset:5120
	ds_read_b128 v[208:211], v183 offset:6144
	ds_read_b128 v[212:215], v183 offset:7168
	s_add_u32 s82, s34, 0xfff80000
	s_addc_u32 s83, s35, -1
	s_mov_b32 s86, m0
	s_mov_b32 m0, s70
	s_nop 0
	global_load_lds_dwordx4 v1, s[82:83]
	s_mov_b32 m0, s86
	s_nop 0
	s_mov_b32 s86, m0
	s_mov_b32 m0, s73
	s_nop 0
	global_load_lds_dwordx4 v177, s[82:83]
	s_mov_b32 m0, s86
	s_mov_b32 s82, m0
	s_mov_b32 m0, s71
	s_nop 0
	global_load_lds_dwordx4 v1, s[34:35]
	s_mov_b32 m0, s82
	s_nop 0
	s_mov_b32 s82, m0
	s_mov_b32 m0, s74
	s_nop 0
	global_load_lds_dwordx4 v177, s[34:35]
	s_mov_b32 m0, s82
	s_waitcnt vmcnt(8)
	s_waitcnt lgkmcnt(0)
	s_waitcnt lgkmcnt(7)
	v_mfma_f32_16x16x32_bf16 v[142:145], v[42:45], v[170:173], 0
	v_mfma_f32_16x16x32_bf16 v[142:145], v[46:49], v[188:191], v[142:145]
	s_waitcnt lgkmcnt(5)
	v_mfma_f32_16x16x32_bf16 v[138:141], v[58:61], v[170:173], 0
	v_mfma_f32_16x16x32_bf16 v[138:141], v[62:65], v[188:191], v[138:141]
	s_barrier
	s_setprio 1
	s_waitcnt lgkmcnt(3)
	v_mfma_f32_16x16x32_bf16 v[126:129], v[42:45], v[192:195], 0
	v_mfma_f32_16x16x32_bf16 v[126:129], v[46:49], v[196:199], v[126:129]
	s_waitcnt lgkmcnt(1)
	v_mfma_f32_16x16x32_bf16 v[122:125], v[58:61], v[192:195], 0
	v_mfma_f32_16x16x32_bf16 v[122:125], v[62:65], v[196:199], v[122:125]
	v_mfma_f32_16x16x32_bf16 v[110:113], v[42:45], v[200:203], 0
	v_mfma_f32_16x16x32_bf16 v[110:113], v[46:49], v[204:207], v[110:113]
	v_mfma_f32_16x16x32_bf16 v[106:109], v[58:61], v[200:203], 0
	v_mfma_f32_16x16x32_bf16 v[106:109], v[62:65], v[204:207], v[106:109]
	v_mfma_f32_16x16x32_bf16 v[94:97], v[42:45], v[208:211], 0
	v_mfma_f32_16x16x32_bf16 v[94:97], v[46:49], v[212:215], v[94:97]
	s_waitcnt lgkmcnt(0)
	v_mfma_f32_16x16x32_bf16 v[90:93], v[58:61], v[208:211], 0
	v_mfma_f32_16x16x32_bf16 v[90:93], v[62:65], v[212:215], v[90:93]
	s_setprio 0
	s_setprio 1
	v_mfma_f32_16x16x32_bf16 v[134:137], v[146:149], v[170:173], 0
	v_mfma_f32_16x16x32_bf16 v[134:137], v[150:153], v[188:191], v[134:137]
	v_mfma_f32_16x16x32_bf16 v[130:133], v[154:157], v[170:173], 0
	v_mfma_f32_16x16x32_bf16 v[130:133], v[158:161], v[188:191], v[130:133]
	v_mfma_f32_16x16x32_bf16 v[118:121], v[146:149], v[192:195], 0
	v_mfma_f32_16x16x32_bf16 v[118:121], v[150:153], v[196:199], v[118:121]
	v_mfma_f32_16x16x32_bf16 v[114:117], v[154:157], v[192:195], 0
	v_mfma_f32_16x16x32_bf16 v[114:117], v[158:161], v[196:199], v[114:117]
	v_mfma_f32_16x16x32_bf16 v[102:105], v[146:149], v[200:203], 0
	v_mfma_f32_16x16x32_bf16 v[102:105], v[150:153], v[204:207], v[102:105]
	v_mfma_f32_16x16x32_bf16 v[98:101], v[154:157], v[200:203], 0
	v_mfma_f32_16x16x32_bf16 v[98:101], v[158:161], v[204:207], v[98:101]
	v_mfma_f32_16x16x32_bf16 v[86:89], v[146:149], v[208:211], 0
	v_mfma_f32_16x16x32_bf16 v[86:89], v[150:153], v[212:215], v[86:89]
	s_setprio 2
	s_barrier
	v_mfma_f32_16x16x32_bf16 v[82:85], v[154:157], v[208:211], 0
	v_mfma_f32_16x16x32_bf16 v[82:85], v[158:161], v[212:215], v[82:85]
	s_setprio 0
	ds_read_b128 v[170:173], v183 offset:16384
	ds_read_b128 v[188:191], v183 offset:17408
	ds_read_b128 v[192:195], v183 offset:18432
	ds_read_b128 v[196:199], v183 offset:19456
	ds_read_b128 v[200:203], v183 offset:20480
	ds_read_b128 v[204:207], v183 offset:21504
	ds_read_b128 v[208:211], v183 offset:22528
	ds_read_b128 v[212:215], v183 offset:23552
	s_mov_b32 s82, m0
	s_mov_b32 m0, s49
	s_nop 0
	global_load_lds_dwordx4 v176, s[36:37]
	s_mov_b32 m0, s82
	s_nop 0
	s_mov_b32 s82, m0
	s_mov_b32 m0, s56
	s_nop 0
	global_load_lds_dwordx4 v178, s[36:37]
	s_mov_b32 m0, s82
	s_add_u32 s82, s36, 0x80000
	s_addc_u32 s83, s37, 0
	s_mov_b32 s86, m0
	s_mov_b32 m0, s57
	s_nop 0
	global_load_lds_dwordx4 v176, s[82:83]
	s_mov_b32 m0, s86
	s_nop 0
	s_mov_b32 s86, m0
	s_mov_b32 m0, s58
	s_nop 0
	global_load_lds_dwordx4 v178, s[82:83]
	s_mov_b32 m0, s86
	s_waitcnt vmcnt(4)
	s_waitcnt lgkmcnt(0)
	s_waitcnt lgkmcnt(7)
	v_mfma_f32_16x16x32_bf16 v[78:81], v[42:45], v[170:173], 0
	v_mfma_f32_16x16x32_bf16 v[78:81], v[46:49], v[188:191], v[78:81]
	s_waitcnt lgkmcnt(5)
	v_mfma_f32_16x16x32_bf16 v[74:77], v[58:61], v[170:173], 0
	v_mfma_f32_16x16x32_bf16 v[74:77], v[62:65], v[188:191], v[74:77]
	s_barrier
	s_setprio 1
	s_waitcnt lgkmcnt(3)
	v_mfma_f32_16x16x32_bf16 v[54:57], v[42:45], v[192:195], 0
	v_mfma_f32_16x16x32_bf16 v[54:57], v[46:49], v[196:199], v[54:57]
	s_waitcnt lgkmcnt(1)
	v_mfma_f32_16x16x32_bf16 v[50:53], v[58:61], v[192:195], 0
	v_mfma_f32_16x16x32_bf16 v[50:53], v[62:65], v[196:199], v[50:53]
	v_mfma_f32_16x16x32_bf16 v[30:33], v[42:45], v[200:203], 0
	v_mfma_f32_16x16x32_bf16 v[30:33], v[46:49], v[204:207], v[30:33]
	v_mfma_f32_16x16x32_bf16 v[26:29], v[58:61], v[200:203], 0
	v_mfma_f32_16x16x32_bf16 v[26:29], v[62:65], v[204:207], v[26:29]
	v_mfma_f32_16x16x32_bf16 v[14:17], v[42:45], v[208:211], 0
	v_mfma_f32_16x16x32_bf16 v[14:17], v[46:49], v[212:215], v[14:17]
	s_waitcnt lgkmcnt(0)
	v_mfma_f32_16x16x32_bf16 v[10:13], v[58:61], v[208:211], 0
	v_mfma_f32_16x16x32_bf16 v[10:13], v[62:65], v[212:215], v[10:13]
	s_setprio 0
	s_setprio 1
	v_mfma_f32_16x16x32_bf16 v[38:41], v[146:149], v[192:195], 0
	v_mfma_f32_16x16x32_bf16 v[38:41], v[150:153], v[196:199], v[38:41]
	v_mfma_f32_16x16x32_bf16 v[34:37], v[154:157], v[192:195], 0
	v_mfma_f32_16x16x32_bf16 v[34:37], v[158:161], v[196:199], v[34:37]
	v_mfma_f32_16x16x32_bf16 v[22:25], v[146:149], v[200:203], 0
	v_mfma_f32_16x16x32_bf16 v[22:25], v[150:153], v[204:207], v[22:25]
	v_mfma_f32_16x16x32_bf16 v[18:21], v[154:157], v[200:203], 0
	v_mfma_f32_16x16x32_bf16 v[18:21], v[158:161], v[204:207], v[18:21]
	v_mfma_f32_16x16x32_bf16 v[6:9], v[146:149], v[208:211], 0
	v_mfma_f32_16x16x32_bf16 v[6:9], v[150:153], v[212:215], v[6:9]
	v_mfma_f32_16x16x32_bf16 v[2:5], v[154:157], v[208:211], 0
	v_mfma_f32_16x16x32_bf16 v[2:5], v[158:161], v[212:215], v[2:5]
	v_mfma_f32_16x16x32_bf16 v[42:45], v[146:149], v[170:173], 0
	v_mfma_f32_16x16x32_bf16 v[42:45], v[150:153], v[188:191], v[42:45]
	s_setprio 2
	s_barrier
	v_mfma_f32_16x16x32_bf16 v[46:49], v[154:157], v[170:173], 0
	v_mfma_f32_16x16x32_bf16 v[46:49], v[158:161], v[188:191], v[46:49]
	s_setprio 0
	ds_read_b128 v[58:61], v184
	ds_read_b128 v[62:65], v184 offset:1024
	ds_read_b128 v[66:69], v184 offset:2048
	ds_read_b128 v[70:73], v184 offset:3072
	ds_read_b128 v[146:149], v185
	ds_read_b128 v[150:153], v185 offset:1024
	ds_read_b128 v[154:157], v185 offset:2048
	ds_read_b128 v[158:161], v185 offset:3072
	ds_read_b128 v[170:173], v183 offset:32768
	ds_read_b128 v[188:191], v183 offset:33792
	ds_read_b128 v[192:195], v183 offset:34816
	ds_read_b128 v[196:199], v183 offset:35840
	ds_read_b128 v[200:203], v183 offset:36864
	ds_read_b128 v[204:207], v183 offset:37888
	ds_read_b128 v[208:211], v183 offset:38912
	ds_read_b128 v[212:215], v183 offset:39936
	s_mov_b32 s82, m0
	s_mov_b32 m0, s48
	s_nop 0
	global_load_lds_dwordx4 v1, s[40:41]
	s_mov_b32 m0, s82
	s_nop 0
	s_mov_b32 s82, m0
	s_mov_b32 m0, s59
	s_nop 0
	global_load_lds_dwordx4 v177, s[40:41]
	s_mov_b32 m0, s82
	s_add_u32 s40, s40, 0x80000
	s_addc_u32 s41, s41, 0
	s_mov_b32 s82, m0
	s_mov_b32 m0, s62
	s_nop 0
	global_load_lds_dwordx4 v1, s[40:41]
	s_mov_b32 m0, s82
	s_nop 0
	s_mov_b32 s82, m0
	s_mov_b32 m0, s63
	s_nop 0
	global_load_lds_dwordx4 v177, s[40:41]
	s_mov_b32 m0, s82
	s_waitcnt vmcnt(8)
	s_waitcnt lgkmcnt(0)
	s_waitcnt lgkmcnt(7)
	v_mfma_f32_16x16x32_bf16 v[142:145], v[58:61], v[170:173], v[142:145]
	v_mfma_f32_16x16x32_bf16 v[142:145], v[62:65], v[188:191], v[142:145]
	s_waitcnt lgkmcnt(5)
	v_mfma_f32_16x16x32_bf16 v[138:141], v[66:69], v[170:173], v[138:141]
	v_mfma_f32_16x16x32_bf16 v[138:141], v[70:73], v[188:191], v[138:141]
	s_barrier
	s_setprio 1
	s_waitcnt lgkmcnt(3)
	v_mfma_f32_16x16x32_bf16 v[126:129], v[58:61], v[192:195], v[126:129]
	v_mfma_f32_16x16x32_bf16 v[126:129], v[62:65], v[196:199], v[126:129]
	s_waitcnt lgkmcnt(1)
	v_mfma_f32_16x16x32_bf16 v[122:125], v[66:69], v[192:195], v[122:125]
	v_mfma_f32_16x16x32_bf16 v[122:125], v[70:73], v[196:199], v[122:125]
	v_mfma_f32_16x16x32_bf16 v[110:113], v[58:61], v[200:203], v[110:113]
	v_mfma_f32_16x16x32_bf16 v[110:113], v[62:65], v[204:207], v[110:113]
	v_mfma_f32_16x16x32_bf16 v[106:109], v[66:69], v[200:203], v[106:109]
	v_mfma_f32_16x16x32_bf16 v[106:109], v[70:73], v[204:207], v[106:109]
	v_mfma_f32_16x16x32_bf16 v[94:97], v[58:61], v[208:211], v[94:97]
	v_mfma_f32_16x16x32_bf16 v[94:97], v[62:65], v[212:215], v[94:97]
	s_waitcnt lgkmcnt(0)
	v_mfma_f32_16x16x32_bf16 v[90:93], v[66:69], v[208:211], v[90:93]
	v_mfma_f32_16x16x32_bf16 v[90:93], v[70:73], v[212:215], v[90:93]
	s_setprio 0
	s_setprio 1
	v_mfma_f32_16x16x32_bf16 v[134:137], v[146:149], v[170:173], v[134:137]
	v_mfma_f32_16x16x32_bf16 v[134:137], v[150:153], v[188:191], v[134:137]
	v_mfma_f32_16x16x32_bf16 v[130:133], v[154:157], v[170:173], v[130:133]
	v_mfma_f32_16x16x32_bf16 v[130:133], v[158:161], v[188:191], v[130:133]
	v_mfma_f32_16x16x32_bf16 v[118:121], v[146:149], v[192:195], v[118:121]
	v_mfma_f32_16x16x32_bf16 v[118:121], v[150:153], v[196:199], v[118:121]
	v_mfma_f32_16x16x32_bf16 v[114:117], v[154:157], v[192:195], v[114:117]
	v_mfma_f32_16x16x32_bf16 v[114:117], v[158:161], v[196:199], v[114:117]
	v_mfma_f32_16x16x32_bf16 v[102:105], v[146:149], v[200:203], v[102:105]
	v_mfma_f32_16x16x32_bf16 v[102:105], v[150:153], v[204:207], v[102:105]
	v_mfma_f32_16x16x32_bf16 v[98:101], v[154:157], v[200:203], v[98:101]
	v_mfma_f32_16x16x32_bf16 v[98:101], v[158:161], v[204:207], v[98:101]
	v_mfma_f32_16x16x32_bf16 v[86:89], v[146:149], v[208:211], v[86:89]
	v_mfma_f32_16x16x32_bf16 v[86:89], v[150:153], v[212:215], v[86:89]
	s_setprio 2
	s_barrier
	v_mfma_f32_16x16x32_bf16 v[82:85], v[154:157], v[208:211], v[82:85]
	v_mfma_f32_16x16x32_bf16 v[82:85], v[158:161], v[212:215], v[82:85]
	s_setprio 0
	ds_read_b128 v[170:173], v183 offset:49152
	ds_read_b128 v[188:191], v183 offset:50176
	ds_read_b128 v[192:195], v183 offset:51200
	ds_read_b128 v[196:199], v183 offset:52224
	ds_read_b128 v[200:203], v183 offset:53248
	ds_read_b128 v[204:207], v183 offset:54272
	ds_read_b128 v[208:211], v183 offset:55296
	ds_read_b128 v[212:215], v183 offset:56320
	s_add_u32 s40, s36, 0x80
	s_addc_u32 s41, s37, 0
	s_mov_b32 s82, m0
	s_mov_b32 m0, s64
	s_nop 0
	global_load_lds_dwordx4 v176, s[40:41]
	s_mov_b32 m0, s82
	s_add_u32 s36, s36, 0x80080
	s_mov_b32 s82, m0
	s_mov_b32 m0, s65
	s_nop 0
	global_load_lds_dwordx4 v178, s[40:41]
	s_mov_b32 m0, s82
	s_addc_u32 s37, s37, 0
	s_mov_b32 s40, m0
	s_mov_b32 m0, s66
	s_nop 0
	global_load_lds_dwordx4 v176, s[36:37]
	s_mov_b32 m0, s40
	s_nop 0
	s_mov_b32 s40, m0
	s_mov_b32 m0, s67
	s_nop 0
	global_load_lds_dwordx4 v178, s[36:37]
	s_mov_b32 m0, s40
	s_waitcnt vmcnt(4)
	s_waitcnt lgkmcnt(0)
	s_waitcnt lgkmcnt(7)
	v_mfma_f32_16x16x32_bf16 v[78:81], v[58:61], v[170:173], v[78:81]
	v_mfma_f32_16x16x32_bf16 v[78:81], v[62:65], v[188:191], v[78:81]
	s_waitcnt lgkmcnt(5)
	v_mfma_f32_16x16x32_bf16 v[74:77], v[66:69], v[170:173], v[74:77]
	v_mfma_f32_16x16x32_bf16 v[74:77], v[70:73], v[188:191], v[74:77]
	s_barrier
	s_setprio 1
	s_waitcnt lgkmcnt(3)
	v_mfma_f32_16x16x32_bf16 v[54:57], v[58:61], v[192:195], v[54:57]
	v_mfma_f32_16x16x32_bf16 v[54:57], v[62:65], v[196:199], v[54:57]
	s_waitcnt lgkmcnt(1)
	v_mfma_f32_16x16x32_bf16 v[50:53], v[66:69], v[192:195], v[50:53]
	v_mfma_f32_16x16x32_bf16 v[50:53], v[70:73], v[196:199], v[50:53]
	v_mfma_f32_16x16x32_bf16 v[30:33], v[58:61], v[200:203], v[30:33]
	v_mfma_f32_16x16x32_bf16 v[30:33], v[62:65], v[204:207], v[30:33]
	v_mfma_f32_16x16x32_bf16 v[26:29], v[66:69], v[200:203], v[26:29]
	v_mfma_f32_16x16x32_bf16 v[26:29], v[70:73], v[204:207], v[26:29]
	v_mfma_f32_16x16x32_bf16 v[14:17], v[58:61], v[208:211], v[14:17]
	v_mfma_f32_16x16x32_bf16 v[14:17], v[62:65], v[212:215], v[14:17]
	s_waitcnt lgkmcnt(0)
	v_mfma_f32_16x16x32_bf16 v[10:13], v[66:69], v[208:211], v[10:13]
	v_mfma_f32_16x16x32_bf16 v[10:13], v[70:73], v[212:215], v[10:13]
	s_setprio 0
	s_setprio 1
	v_mfma_f32_16x16x32_bf16 v[42:45], v[146:149], v[170:173], v[42:45]
	v_mfma_f32_16x16x32_bf16 v[70:73], v[150:153], v[188:191], v[42:45]
	v_mfma_f32_16x16x32_bf16 v[42:45], v[154:157], v[170:173], v[46:49]
	v_mfma_f32_16x16x32_bf16 v[66:69], v[158:161], v[188:191], v[42:45]
	v_mfma_f32_16x16x32_bf16 v[38:41], v[146:149], v[192:195], v[38:41]
	v_mfma_f32_16x16x32_bf16 v[38:41], v[150:153], v[196:199], v[38:41]
	v_mfma_f32_16x16x32_bf16 v[34:37], v[154:157], v[192:195], v[34:37]
	v_mfma_f32_16x16x32_bf16 v[34:37], v[158:161], v[196:199], v[34:37]
	v_mfma_f32_16x16x32_bf16 v[22:25], v[146:149], v[200:203], v[22:25]
	v_mfma_f32_16x16x32_bf16 v[22:25], v[150:153], v[204:207], v[22:25]
	v_mfma_f32_16x16x32_bf16 v[18:21], v[154:157], v[200:203], v[18:21]
	v_mfma_f32_16x16x32_bf16 v[18:21], v[158:161], v[204:207], v[18:21]
	v_mfma_f32_16x16x32_bf16 v[6:9], v[146:149], v[208:211], v[6:9]
	v_mfma_f32_16x16x32_bf16 v[6:9], v[150:153], v[212:215], v[6:9]
	s_setprio 2
	s_barrier
	v_mfma_f32_16x16x32_bf16 v[2:5], v[154:157], v[208:211], v[2:5]
	v_mfma_f32_16x16x32_bf16 v[2:5], v[158:161], v[212:215], v[2:5]
	s_setprio 0
	s_add_i32 s81, s81, 2
	s_add_u32 s77, s77, 0x100
	s_addc_u32 s78, s78, 0
	s_add_u32 s34, s34, 0x100
	s_addc_u32 s35, s35, 0
	s_add_u32 s79, s79, 0x100
	s_addc_u32 s80, s80, 0
	s_cmp_gt_u32 s81, 29
	.p2align 6
.LBB0_2146:
	ds_read_b128 v[42:45], v181
	ds_read_b128 v[46:49], v181 offset:1024
	ds_read_b128 v[58:61], v181 offset:2048
	ds_read_b128 v[62:65], v181 offset:3072
	ds_read_b128 v[146:149], v182
	ds_read_b128 v[150:153], v182 offset:1024
	ds_read_b128 v[154:157], v182 offset:2048
	ds_read_b128 v[158:161], v182 offset:3072
	s_cmp_eq_u32 s81, 28
	s_cselect_b32 s37, s23, s78
	s_cselect_b32 s36, s31, s77
	s_cselect_b32 s41, s5, s80
	s_cselect_b32 s40, s25, s79
	ds_read_b128 v[170:173], v183
	ds_read_b128 v[188:191], v183 offset:1024
	ds_read_b128 v[192:195], v183 offset:2048
	ds_read_b128 v[196:199], v183 offset:3072
	ds_read_b128 v[200:203], v183 offset:4096
	ds_read_b128 v[204:207], v183 offset:5120
	ds_read_b128 v[208:211], v183 offset:6144
	ds_read_b128 v[212:215], v183 offset:7168
	s_add_u32 s82, s34, 0xfff80000
	s_addc_u32 s83, s35, -1
	s_mov_b32 s86, m0
	s_mov_b32 m0, s70
	s_nop 0
	global_load_lds_dwordx4 v1, s[82:83]
	s_mov_b32 m0, s86
	s_nop 0
	s_mov_b32 s86, m0
	s_mov_b32 m0, s73
	s_nop 0
	global_load_lds_dwordx4 v177, s[82:83]
	s_mov_b32 m0, s86
	s_mov_b32 s82, m0
	s_mov_b32 m0, s71
	s_nop 0
	global_load_lds_dwordx4 v1, s[34:35]
	s_mov_b32 m0, s82
	s_nop 0
	s_mov_b32 s82, m0
	s_mov_b32 m0, s74
	s_nop 0
	global_load_lds_dwordx4 v177, s[34:35]
	s_mov_b32 m0, s82
	s_waitcnt vmcnt(8)
	s_waitcnt lgkmcnt(0)
	s_waitcnt lgkmcnt(7)
	v_mfma_f32_16x16x32_bf16 v[142:145], v[42:45], v[170:173], v[142:145]
	v_mfma_f32_16x16x32_bf16 v[142:145], v[46:49], v[188:191], v[142:145]
	s_waitcnt lgkmcnt(5)
	v_mfma_f32_16x16x32_bf16 v[138:141], v[58:61], v[170:173], v[138:141]
	v_mfma_f32_16x16x32_bf16 v[138:141], v[62:65], v[188:191], v[138:141]
	s_barrier
	s_setprio 1
	s_waitcnt lgkmcnt(3)
	v_mfma_f32_16x16x32_bf16 v[126:129], v[42:45], v[192:195], v[126:129]
	v_mfma_f32_16x16x32_bf16 v[126:129], v[46:49], v[196:199], v[126:129]
	s_waitcnt lgkmcnt(1)
	v_mfma_f32_16x16x32_bf16 v[122:125], v[58:61], v[192:195], v[122:125]
	v_mfma_f32_16x16x32_bf16 v[122:125], v[62:65], v[196:199], v[122:125]
	v_mfma_f32_16x16x32_bf16 v[110:113], v[42:45], v[200:203], v[110:113]
	v_mfma_f32_16x16x32_bf16 v[110:113], v[46:49], v[204:207], v[110:113]
	v_mfma_f32_16x16x32_bf16 v[106:109], v[58:61], v[200:203], v[106:109]
	v_mfma_f32_16x16x32_bf16 v[106:109], v[62:65], v[204:207], v[106:109]
	v_mfma_f32_16x16x32_bf16 v[94:97], v[42:45], v[208:211], v[94:97]
	v_mfma_f32_16x16x32_bf16 v[94:97], v[46:49], v[212:215], v[94:97]
	s_waitcnt lgkmcnt(0)
	v_mfma_f32_16x16x32_bf16 v[90:93], v[58:61], v[208:211], v[90:93]
	v_mfma_f32_16x16x32_bf16 v[90:93], v[62:65], v[212:215], v[90:93]
	s_setprio 0
	s_setprio 1
	v_mfma_f32_16x16x32_bf16 v[134:137], v[146:149], v[170:173], v[134:137]
	v_mfma_f32_16x16x32_bf16 v[134:137], v[150:153], v[188:191], v[134:137]
	v_mfma_f32_16x16x32_bf16 v[130:133], v[154:157], v[170:173], v[130:133]
	v_mfma_f32_16x16x32_bf16 v[130:133], v[158:161], v[188:191], v[130:133]
	v_mfma_f32_16x16x32_bf16 v[118:121], v[146:149], v[192:195], v[118:121]
	v_mfma_f32_16x16x32_bf16 v[118:121], v[150:153], v[196:199], v[118:121]
	v_mfma_f32_16x16x32_bf16 v[114:117], v[154:157], v[192:195], v[114:117]
	v_mfma_f32_16x16x32_bf16 v[114:117], v[158:161], v[196:199], v[114:117]
	v_mfma_f32_16x16x32_bf16 v[102:105], v[146:149], v[200:203], v[102:105]
	v_mfma_f32_16x16x32_bf16 v[102:105], v[150:153], v[204:207], v[102:105]
	v_mfma_f32_16x16x32_bf16 v[98:101], v[154:157], v[200:203], v[98:101]
	v_mfma_f32_16x16x32_bf16 v[98:101], v[158:161], v[204:207], v[98:101]
	v_mfma_f32_16x16x32_bf16 v[86:89], v[146:149], v[208:211], v[86:89]
	v_mfma_f32_16x16x32_bf16 v[86:89], v[150:153], v[212:215], v[86:89]
	s_setprio 2
	s_barrier
	v_mfma_f32_16x16x32_bf16 v[82:85], v[154:157], v[208:211], v[82:85]
	v_mfma_f32_16x16x32_bf16 v[82:85], v[158:161], v[212:215], v[82:85]
	s_setprio 0
	ds_read_b128 v[170:173], v183 offset:16384
	ds_read_b128 v[188:191], v183 offset:17408
	ds_read_b128 v[192:195], v183 offset:18432
	ds_read_b128 v[196:199], v183 offset:19456
	ds_read_b128 v[200:203], v183 offset:20480
	ds_read_b128 v[204:207], v183 offset:21504
	ds_read_b128 v[208:211], v183 offset:22528
	ds_read_b128 v[212:215], v183 offset:23552
	s_mov_b32 s82, m0
	s_mov_b32 m0, s49
	s_nop 0
	global_load_lds_dwordx4 v176, s[36:37]
	s_mov_b32 m0, s82
	s_nop 0
	s_mov_b32 s82, m0
	s_mov_b32 m0, s56
	s_nop 0
	global_load_lds_dwordx4 v178, s[36:37]
	s_mov_b32 m0, s82
	s_add_u32 s82, s36, 0x80000
	s_addc_u32 s83, s37, 0
	s_mov_b32 s86, m0
	s_mov_b32 m0, s57
	s_nop 0
	global_load_lds_dwordx4 v176, s[82:83]
	s_mov_b32 m0, s86
	s_nop 0
	s_mov_b32 s86, m0
	s_mov_b32 m0, s58
	s_nop 0
	global_load_lds_dwordx4 v178, s[82:83]
	s_mov_b32 m0, s86
	s_waitcnt vmcnt(4)
	s_waitcnt lgkmcnt(0)
	s_waitcnt lgkmcnt(7)
	v_mfma_f32_16x16x32_bf16 v[78:81], v[42:45], v[170:173], v[78:81]
	v_mfma_f32_16x16x32_bf16 v[78:81], v[46:49], v[188:191], v[78:81]
	s_waitcnt lgkmcnt(5)
	v_mfma_f32_16x16x32_bf16 v[74:77], v[58:61], v[170:173], v[74:77]
	v_mfma_f32_16x16x32_bf16 v[74:77], v[62:65], v[188:191], v[74:77]
	s_barrier
	s_setprio 1
	s_waitcnt lgkmcnt(3)
	v_mfma_f32_16x16x32_bf16 v[54:57], v[42:45], v[192:195], v[54:57]
	v_mfma_f32_16x16x32_bf16 v[54:57], v[46:49], v[196:199], v[54:57]
	s_waitcnt lgkmcnt(1)
	v_mfma_f32_16x16x32_bf16 v[50:53], v[58:61], v[192:195], v[50:53]
	v_mfma_f32_16x16x32_bf16 v[50:53], v[62:65], v[196:199], v[50:53]
	v_mfma_f32_16x16x32_bf16 v[30:33], v[42:45], v[200:203], v[30:33]
	v_mfma_f32_16x16x32_bf16 v[30:33], v[46:49], v[204:207], v[30:33]
	v_mfma_f32_16x16x32_bf16 v[26:29], v[58:61], v[200:203], v[26:29]
	v_mfma_f32_16x16x32_bf16 v[26:29], v[62:65], v[204:207], v[26:29]
	v_mfma_f32_16x16x32_bf16 v[14:17], v[42:45], v[208:211], v[14:17]
	v_mfma_f32_16x16x32_bf16 v[14:17], v[46:49], v[212:215], v[14:17]
	s_waitcnt lgkmcnt(0)
	v_mfma_f32_16x16x32_bf16 v[10:13], v[58:61], v[208:211], v[10:13]
	v_mfma_f32_16x16x32_bf16 v[10:13], v[62:65], v[212:215], v[10:13]
	s_setprio 0
	s_setprio 1
	v_mfma_f32_16x16x32_bf16 v[38:41], v[146:149], v[192:195], v[38:41]
	v_mfma_f32_16x16x32_bf16 v[38:41], v[150:153], v[196:199], v[38:41]
	v_mfma_f32_16x16x32_bf16 v[34:37], v[154:157], v[192:195], v[34:37]
	v_mfma_f32_16x16x32_bf16 v[34:37], v[158:161], v[196:199], v[34:37]
	v_mfma_f32_16x16x32_bf16 v[22:25], v[146:149], v[200:203], v[22:25]
	v_mfma_f32_16x16x32_bf16 v[22:25], v[150:153], v[204:207], v[22:25]
	v_mfma_f32_16x16x32_bf16 v[18:21], v[154:157], v[200:203], v[18:21]
	v_mfma_f32_16x16x32_bf16 v[18:21], v[158:161], v[204:207], v[18:21]
	v_mfma_f32_16x16x32_bf16 v[6:9], v[146:149], v[208:211], v[6:9]
	v_mfma_f32_16x16x32_bf16 v[6:9], v[150:153], v[212:215], v[6:9]
	v_mfma_f32_16x16x32_bf16 v[2:5], v[154:157], v[208:211], v[2:5]
	v_mfma_f32_16x16x32_bf16 v[2:5], v[158:161], v[212:215], v[2:5]
	v_mfma_f32_16x16x32_bf16 v[42:45], v[146:149], v[170:173], v[70:73]
	v_mfma_f32_16x16x32_bf16 v[42:45], v[150:153], v[188:191], v[42:45]
	s_setprio 2
	s_barrier
	v_mfma_f32_16x16x32_bf16 v[46:49], v[154:157], v[170:173], v[66:69]
	v_mfma_f32_16x16x32_bf16 v[46:49], v[158:161], v[188:191], v[46:49]
	s_setprio 0
	ds_read_b128 v[58:61], v184
	ds_read_b128 v[62:65], v184 offset:1024
	ds_read_b128 v[66:69], v184 offset:2048
	ds_read_b128 v[70:73], v184 offset:3072
	ds_read_b128 v[146:149], v185
	ds_read_b128 v[150:153], v185 offset:1024
	ds_read_b128 v[154:157], v185 offset:2048
	ds_read_b128 v[158:161], v185 offset:3072
	ds_read_b128 v[170:173], v183 offset:32768
	ds_read_b128 v[188:191], v183 offset:33792
	ds_read_b128 v[192:195], v183 offset:34816
	ds_read_b128 v[196:199], v183 offset:35840
	ds_read_b128 v[200:203], v183 offset:36864
	ds_read_b128 v[204:207], v183 offset:37888
	ds_read_b128 v[208:211], v183 offset:38912
	ds_read_b128 v[212:215], v183 offset:39936
	s_mov_b32 s82, m0
	s_mov_b32 m0, s48
	s_nop 0
	global_load_lds_dwordx4 v1, s[40:41]
	s_mov_b32 m0, s82
	s_nop 0
	s_mov_b32 s82, m0
	s_mov_b32 m0, s59
	s_nop 0
	global_load_lds_dwordx4 v177, s[40:41]
	s_mov_b32 m0, s82
	s_add_u32 s40, s40, 0x80000
	s_addc_u32 s41, s41, 0
	s_mov_b32 s82, m0
	s_mov_b32 m0, s62
	s_nop 0
	global_load_lds_dwordx4 v1, s[40:41]
	s_mov_b32 m0, s82
	s_nop 0
	s_mov_b32 s82, m0
	s_mov_b32 m0, s63
	s_nop 0
	global_load_lds_dwordx4 v177, s[40:41]
	s_mov_b32 m0, s82
	s_waitcnt vmcnt(8)
	s_waitcnt lgkmcnt(0)
	s_waitcnt lgkmcnt(7)
	v_mfma_f32_16x16x32_bf16 v[142:145], v[58:61], v[170:173], v[142:145]
	v_mfma_f32_16x16x32_bf16 v[142:145], v[62:65], v[188:191], v[142:145]
	s_waitcnt lgkmcnt(5)
	v_mfma_f32_16x16x32_bf16 v[138:141], v[66:69], v[170:173], v[138:141]
	v_mfma_f32_16x16x32_bf16 v[138:141], v[70:73], v[188:191], v[138:141]
	s_barrier
	s_setprio 1
	s_waitcnt lgkmcnt(3)
	v_mfma_f32_16x16x32_bf16 v[126:129], v[58:61], v[192:195], v[126:129]
	v_mfma_f32_16x16x32_bf16 v[126:129], v[62:65], v[196:199], v[126:129]
	s_waitcnt lgkmcnt(1)
	v_mfma_f32_16x16x32_bf16 v[122:125], v[66:69], v[192:195], v[122:125]
	v_mfma_f32_16x16x32_bf16 v[122:125], v[70:73], v[196:199], v[122:125]
	v_mfma_f32_16x16x32_bf16 v[110:113], v[58:61], v[200:203], v[110:113]
	v_mfma_f32_16x16x32_bf16 v[110:113], v[62:65], v[204:207], v[110:113]
	v_mfma_f32_16x16x32_bf16 v[106:109], v[66:69], v[200:203], v[106:109]
	v_mfma_f32_16x16x32_bf16 v[106:109], v[70:73], v[204:207], v[106:109]
	v_mfma_f32_16x16x32_bf16 v[94:97], v[58:61], v[208:211], v[94:97]
	v_mfma_f32_16x16x32_bf16 v[94:97], v[62:65], v[212:215], v[94:97]
	s_waitcnt lgkmcnt(0)
	v_mfma_f32_16x16x32_bf16 v[90:93], v[66:69], v[208:211], v[90:93]
	v_mfma_f32_16x16x32_bf16 v[90:93], v[70:73], v[212:215], v[90:93]
	s_setprio 0
	s_setprio 1
	v_mfma_f32_16x16x32_bf16 v[134:137], v[146:149], v[170:173], v[134:137]
	v_mfma_f32_16x16x32_bf16 v[134:137], v[150:153], v[188:191], v[134:137]
	v_mfma_f32_16x16x32_bf16 v[130:133], v[154:157], v[170:173], v[130:133]
	v_mfma_f32_16x16x32_bf16 v[130:133], v[158:161], v[188:191], v[130:133]
	v_mfma_f32_16x16x32_bf16 v[118:121], v[146:149], v[192:195], v[118:121]
	v_mfma_f32_16x16x32_bf16 v[118:121], v[150:153], v[196:199], v[118:121]
	v_mfma_f32_16x16x32_bf16 v[114:117], v[154:157], v[192:195], v[114:117]
	v_mfma_f32_16x16x32_bf16 v[114:117], v[158:161], v[196:199], v[114:117]
	v_mfma_f32_16x16x32_bf16 v[102:105], v[146:149], v[200:203], v[102:105]
	v_mfma_f32_16x16x32_bf16 v[102:105], v[150:153], v[204:207], v[102:105]
	v_mfma_f32_16x16x32_bf16 v[98:101], v[154:157], v[200:203], v[98:101]
	v_mfma_f32_16x16x32_bf16 v[98:101], v[158:161], v[204:207], v[98:101]
	v_mfma_f32_16x16x32_bf16 v[86:89], v[146:149], v[208:211], v[86:89]
	v_mfma_f32_16x16x32_bf16 v[86:89], v[150:153], v[212:215], v[86:89]
	s_setprio 2
	s_barrier
	v_mfma_f32_16x16x32_bf16 v[82:85], v[154:157], v[208:211], v[82:85]
	v_mfma_f32_16x16x32_bf16 v[82:85], v[158:161], v[212:215], v[82:85]
	s_setprio 0
	ds_read_b128 v[170:173], v183 offset:49152
	ds_read_b128 v[188:191], v183 offset:50176
	ds_read_b128 v[192:195], v183 offset:51200
	ds_read_b128 v[196:199], v183 offset:52224
	ds_read_b128 v[200:203], v183 offset:53248
	ds_read_b128 v[204:207], v183 offset:54272
	ds_read_b128 v[208:211], v183 offset:55296
	ds_read_b128 v[212:215], v183 offset:56320
	s_add_u32 s40, s36, 0x80
	s_addc_u32 s41, s37, 0
	s_mov_b32 s82, m0
	s_mov_b32 m0, s64
	s_nop 0
	global_load_lds_dwordx4 v176, s[40:41]
	s_mov_b32 m0, s82
	s_add_u32 s36, s36, 0x80080
	s_mov_b32 s82, m0
	s_mov_b32 m0, s65
	s_nop 0
	global_load_lds_dwordx4 v178, s[40:41]
	s_mov_b32 m0, s82
	s_addc_u32 s37, s37, 0
	s_mov_b32 s40, m0
	s_mov_b32 m0, s66
	s_nop 0
	global_load_lds_dwordx4 v176, s[36:37]
	s_mov_b32 m0, s40
	s_nop 0
	s_mov_b32 s40, m0
	s_mov_b32 m0, s67
	s_nop 0
	global_load_lds_dwordx4 v178, s[36:37]
	s_mov_b32 m0, s40
	s_waitcnt vmcnt(4)
	s_waitcnt lgkmcnt(0)
	s_waitcnt lgkmcnt(7)
	v_mfma_f32_16x16x32_bf16 v[78:81], v[58:61], v[170:173], v[78:81]
	v_mfma_f32_16x16x32_bf16 v[78:81], v[62:65], v[188:191], v[78:81]
	s_waitcnt lgkmcnt(5)
	v_mfma_f32_16x16x32_bf16 v[74:77], v[66:69], v[170:173], v[74:77]
	v_mfma_f32_16x16x32_bf16 v[74:77], v[70:73], v[188:191], v[74:77]
	s_barrier
	s_setprio 1
	s_waitcnt lgkmcnt(3)
	v_mfma_f32_16x16x32_bf16 v[54:57], v[58:61], v[192:195], v[54:57]
	v_mfma_f32_16x16x32_bf16 v[54:57], v[62:65], v[196:199], v[54:57]
	s_waitcnt lgkmcnt(1)
	v_mfma_f32_16x16x32_bf16 v[50:53], v[66:69], v[192:195], v[50:53]
	v_mfma_f32_16x16x32_bf16 v[50:53], v[70:73], v[196:199], v[50:53]
	v_mfma_f32_16x16x32_bf16 v[30:33], v[58:61], v[200:203], v[30:33]
	v_mfma_f32_16x16x32_bf16 v[30:33], v[62:65], v[204:207], v[30:33]
	v_mfma_f32_16x16x32_bf16 v[26:29], v[66:69], v[200:203], v[26:29]
	v_mfma_f32_16x16x32_bf16 v[26:29], v[70:73], v[204:207], v[26:29]
	v_mfma_f32_16x16x32_bf16 v[14:17], v[58:61], v[208:211], v[14:17]
	v_mfma_f32_16x16x32_bf16 v[14:17], v[62:65], v[212:215], v[14:17]
	s_waitcnt lgkmcnt(0)
	v_mfma_f32_16x16x32_bf16 v[10:13], v[66:69], v[208:211], v[10:13]
	v_mfma_f32_16x16x32_bf16 v[10:13], v[70:73], v[212:215], v[10:13]
	s_setprio 0
	s_setprio 1
	v_mfma_f32_16x16x32_bf16 v[42:45], v[146:149], v[170:173], v[42:45]
	v_mfma_f32_16x16x32_bf16 v[70:73], v[150:153], v[188:191], v[42:45]
	v_mfma_f32_16x16x32_bf16 v[42:45], v[154:157], v[170:173], v[46:49]
	v_mfma_f32_16x16x32_bf16 v[66:69], v[158:161], v[188:191], v[42:45]
	v_mfma_f32_16x16x32_bf16 v[38:41], v[146:149], v[192:195], v[38:41]
	v_mfma_f32_16x16x32_bf16 v[38:41], v[150:153], v[196:199], v[38:41]
	v_mfma_f32_16x16x32_bf16 v[34:37], v[154:157], v[192:195], v[34:37]
	v_mfma_f32_16x16x32_bf16 v[34:37], v[158:161], v[196:199], v[34:37]
	v_mfma_f32_16x16x32_bf16 v[22:25], v[146:149], v[200:203], v[22:25]
	v_mfma_f32_16x16x32_bf16 v[22:25], v[150:153], v[204:207], v[22:25]
	v_mfma_f32_16x16x32_bf16 v[18:21], v[154:157], v[200:203], v[18:21]
	v_mfma_f32_16x16x32_bf16 v[18:21], v[158:161], v[204:207], v[18:21]
	v_mfma_f32_16x16x32_bf16 v[6:9], v[146:149], v[208:211], v[6:9]
	v_mfma_f32_16x16x32_bf16 v[6:9], v[150:153], v[212:215], v[6:9]
	s_setprio 2
	s_barrier
	v_mfma_f32_16x16x32_bf16 v[2:5], v[154:157], v[208:211], v[2:5]
	v_mfma_f32_16x16x32_bf16 v[2:5], v[158:161], v[212:215], v[2:5]
	s_setprio 0
	s_add_i32 s81, s81, 2
	s_add_u32 s77, s77, 0x100
	s_addc_u32 s78, s78, 0
	s_add_u32 s34, s34, 0x100
	s_addc_u32 s35, s35, 0
	s_add_u32 s79, s79, 0x100
	s_addc_u32 s80, s80, 0
	s_cmp_gt_u32 s81, 29
	s_cbranch_scc0 .LBB0_2146
	s_and_b64 vcc, exec, s[14:15]
	s_cbranch_vccz .LBB0_2149
	s_barrier

.LBB0_2409:
	s_ashr_i32 s17, s16, 31
	s_lshl_b64 s[18:19], s[16:17], 20
	s_add_u32 s18, s33, s18
	s_addc_u32 s19, s34, s19
	s_and_b64 s[20:21], s[2:3], exec
	s_cselect_b32 s17, s19, s27
	s_cselect_b32 s71, s18, s26
	s_ashr_i32 s15, s14, 31
	s_lshl_b64 s[20:21], s[14:15], 20
	s_add_u32 s20, s35, s20
	s_addc_u32 s21, s36, s21
	s_and_b64 s[28:29], s[2:3], exec
	s_cselect_b32 s15, s21, s25
	s_cselect_b32 s73, s20, s24
	s_add_u32 s74, s24, 0x100
	s_addc_u32 s75, s25, 0
	s_add_u32 s24, s26, 0x80080
	s_addc_u32 s25, s27, 0
	s_add_u32 s76, s26, 0x100
	s_addc_u32 s77, s27, 0
	s_mov_b32 s78, -2
	s_waitcnt vmcnt(25)
	s_waitcnt vmcnt(24)
	s_waitcnt vmcnt(4)
	s_waitcnt vmcnt(2)
	s_waitcnt vmcnt(1)
	s_waitcnt vmcnt(0)
	ds_read_b128 v[130:133], v181
	ds_read_b128 v[134:137], v181 offset:1024
	ds_read_b128 v[138:141], v181 offset:2048
	ds_read_b128 v[142:145], v181 offset:3072
	ds_read_b128 v[146:149], v182
	ds_read_b128 v[150:153], v182 offset:1024
	ds_read_b128 v[154:157], v182 offset:2048
	ds_read_b128 v[158:161], v182 offset:3072
	s_cmp_eq_u32 s78, 28
	s_cselect_b32 s27, s15, s75
	s_cselect_b32 s26, s73, s74
	s_cselect_b32 s29, s17, s77
	s_cselect_b32 s28, s71, s76
	ds_read_b128 v[166:169], v183
	ds_read_b128 v[170:173], v183 offset:1024
	ds_read_b128 v[186:189], v183 offset:2048
	ds_read_b128 v[190:193], v183 offset:3072
	ds_read_b128 v[194:197], v183 offset:4096
	ds_read_b128 v[198:201], v183 offset:5120
	ds_read_b128 v[202:205], v183 offset:6144
	ds_read_b128 v[206:209], v183 offset:7168
	s_add_u32 s80, s24, 0xfff80000
	s_addc_u32 s81, s25, -1
	s_mov_b32 s79, m0
	s_mov_b32 m0, s64
	s_nop 0
	global_load_lds_dwordx4 v1, s[80:81]
	s_mov_b32 m0, s79
	s_nop 0
	s_mov_b32 s79, m0
	s_mov_b32 m0, s66
	s_nop 0
	global_load_lds_dwordx4 v177, s[80:81]
	s_mov_b32 m0, s79
	s_nop 0
	s_mov_b32 s79, m0
	s_mov_b32 m0, s65
	s_nop 0
	global_load_lds_dwordx4 v1, s[24:25]
	s_mov_b32 m0, s79
	s_nop 0
	s_mov_b32 s79, m0
	s_mov_b32 m0, s67
	s_nop 0
	global_load_lds_dwordx4 v177, s[24:25]
	s_mov_b32 m0, s79
	s_waitcnt vmcnt(8)
	s_waitcnt lgkmcnt(0)
	s_waitcnt lgkmcnt(7)
	v_mfma_f32_16x16x32_bf16 v[126:129], v[130:133], v[166:169], 0
	v_mfma_f32_16x16x32_bf16 v[126:129], v[134:137], v[170:173], v[126:129]
	s_waitcnt lgkmcnt(5)
	v_mfma_f32_16x16x32_bf16 v[122:125], v[138:141], v[166:169], 0
	v_mfma_f32_16x16x32_bf16 v[122:125], v[142:145], v[170:173], v[122:125]
	s_barrier
	s_setprio 1
	s_waitcnt lgkmcnt(3)
	v_mfma_f32_16x16x32_bf16 v[114:117], v[138:141], v[186:189], 0
	v_mfma_f32_16x16x32_bf16 v[114:117], v[142:145], v[190:193], v[114:117]
	s_waitcnt lgkmcnt(1)
	v_mfma_f32_16x16x32_bf16 v[118:121], v[130:133], v[186:189], 0
	v_mfma_f32_16x16x32_bf16 v[118:121], v[134:137], v[190:193], v[118:121]
	v_mfma_f32_16x16x32_bf16 v[94:97], v[130:133], v[194:197], 0
	v_mfma_f32_16x16x32_bf16 v[94:97], v[134:137], v[198:201], v[94:97]
	v_mfma_f32_16x16x32_bf16 v[90:93], v[138:141], v[194:197], 0
	v_mfma_f32_16x16x32_bf16 v[90:93], v[142:145], v[198:201], v[90:93]
	v_mfma_f32_16x16x32_bf16 v[78:81], v[138:141], v[202:205], 0
	v_mfma_f32_16x16x32_bf16 v[78:81], v[142:145], v[206:209], v[78:81]
	s_waitcnt lgkmcnt(0)
	v_mfma_f32_16x16x32_bf16 v[86:89], v[130:133], v[202:205], 0
	v_mfma_f32_16x16x32_bf16 v[86:89], v[134:137], v[206:209], v[86:89]
	s_setprio 0
	s_setprio 1
	v_mfma_f32_16x16x32_bf16 v[110:113], v[146:149], v[166:169], 0
	v_mfma_f32_16x16x32_bf16 v[110:113], v[150:153], v[170:173], v[110:113]
	v_mfma_f32_16x16x32_bf16 v[106:109], v[154:157], v[166:169], 0
	v_mfma_f32_16x16x32_bf16 v[106:109], v[158:161], v[170:173], v[106:109]
	v_mfma_f32_16x16x32_bf16 v[98:101], v[154:157], v[186:189], 0
	v_mfma_f32_16x16x32_bf16 v[98:101], v[158:161], v[190:193], v[98:101]
	v_mfma_f32_16x16x32_bf16 v[102:105], v[146:149], v[186:189], 0
	v_mfma_f32_16x16x32_bf16 v[102:105], v[150:153], v[190:193], v[102:105]
	v_mfma_f32_16x16x32_bf16 v[82:85], v[146:149], v[194:197], 0
	v_mfma_f32_16x16x32_bf16 v[82:85], v[150:153], v[198:201], v[82:85]
	v_mfma_f32_16x16x32_bf16 v[74:77], v[154:157], v[194:197], 0
	v_mfma_f32_16x16x32_bf16 v[74:77], v[158:161], v[198:201], v[74:77]
	v_mfma_f32_16x16x32_bf16 v[66:69], v[154:157], v[202:205], 0
	v_mfma_f32_16x16x32_bf16 v[66:69], v[158:161], v[206:209], v[66:69]
	s_setprio 2
	s_barrier
	v_mfma_f32_16x16x32_bf16 v[70:73], v[146:149], v[202:205], 0
	v_mfma_f32_16x16x32_bf16 v[70:73], v[150:153], v[206:209], v[70:73]
	s_setprio 0
	ds_read_b128 v[166:169], v183 offset:16384
	ds_read_b128 v[170:173], v183 offset:17408
	ds_read_b128 v[186:189], v183 offset:18432
	ds_read_b128 v[190:193], v183 offset:19456
	ds_read_b128 v[194:197], v183 offset:20480
	ds_read_b128 v[198:201], v183 offset:21504
	ds_read_b128 v[202:205], v183 offset:22528
	ds_read_b128 v[206:209], v183 offset:23552
	s_mov_b32 s79, m0
	s_mov_b32 m0, s41
	s_nop 0
	global_load_lds_dwordx4 v176, s[26:27]
	s_mov_b32 m0, s79
	s_add_u32 s80, s26, 0x80000
	s_mov_b32 s79, m0
	s_mov_b32 m0, s42
	s_nop 0
	global_load_lds_dwordx4 v178, s[26:27]
	s_mov_b32 m0, s79
	s_addc_u32 s81, s27, 0
	s_mov_b32 s79, m0
	s_mov_b32 m0, s43
	s_nop 0
	global_load_lds_dwordx4 v176, s[80:81]
	s_mov_b32 m0, s79
	s_nop 0
	s_mov_b32 s79, m0
	s_mov_b32 m0, s46
	s_nop 0
	global_load_lds_dwordx4 v178, s[80:81]
	s_mov_b32 m0, s79
	s_waitcnt vmcnt(4)
	s_waitcnt lgkmcnt(0)
	s_waitcnt lgkmcnt(7)
	v_mfma_f32_16x16x32_bf16 v[62:65], v[130:133], v[166:169], 0
	v_mfma_f32_16x16x32_bf16 v[62:65], v[134:137], v[170:173], v[62:65]
	s_waitcnt lgkmcnt(5)
	v_mfma_f32_16x16x32_bf16 v[58:61], v[138:141], v[166:169], 0
	v_mfma_f32_16x16x32_bf16 v[58:61], v[142:145], v[170:173], v[58:61]
	s_barrier
	s_setprio 1
	s_waitcnt lgkmcnt(3)
	v_mfma_f32_16x16x32_bf16 v[42:45], v[138:141], v[186:189], 0
	v_mfma_f32_16x16x32_bf16 v[42:45], v[142:145], v[190:193], v[42:45]
	s_waitcnt lgkmcnt(1)
	v_mfma_f32_16x16x32_bf16 v[46:49], v[130:133], v[186:189], 0
	v_mfma_f32_16x16x32_bf16 v[46:49], v[134:137], v[190:193], v[46:49]
	v_mfma_f32_16x16x32_bf16 v[30:33], v[130:133], v[194:197], 0
	v_mfma_f32_16x16x32_bf16 v[30:33], v[134:137], v[198:201], v[30:33]
	v_mfma_f32_16x16x32_bf16 v[26:29], v[138:141], v[194:197], 0
	v_mfma_f32_16x16x32_bf16 v[26:29], v[142:145], v[198:201], v[26:29]
	v_mfma_f32_16x16x32_bf16 v[10:13], v[138:141], v[202:205], 0
	v_mfma_f32_16x16x32_bf16 v[10:13], v[142:145], v[206:209], v[10:13]
	s_waitcnt lgkmcnt(0)
	v_mfma_f32_16x16x32_bf16 v[14:17], v[130:133], v[202:205], 0
	v_mfma_f32_16x16x32_bf16 v[14:17], v[134:137], v[206:209], v[14:17]
	s_setprio 0
	s_setprio 1
	v_mfma_f32_16x16x32_bf16 v[54:57], v[146:149], v[166:169], 0
	v_mfma_f32_16x16x32_bf16 v[54:57], v[150:153], v[170:173], v[54:57]
	v_mfma_f32_16x16x32_bf16 v[50:53], v[154:157], v[166:169], 0
	v_mfma_f32_16x16x32_bf16 v[50:53], v[158:161], v[170:173], v[50:53]
	v_mfma_f32_16x16x32_bf16 v[34:37], v[154:157], v[186:189], 0
	v_mfma_f32_16x16x32_bf16 v[34:37], v[158:161], v[190:193], v[34:37]
	v_mfma_f32_16x16x32_bf16 v[38:41], v[146:149], v[186:189], 0
	v_mfma_f32_16x16x32_bf16 v[38:41], v[150:153], v[190:193], v[38:41]
	v_mfma_f32_16x16x32_bf16 v[22:25], v[146:149], v[194:197], 0
	v_mfma_f32_16x16x32_bf16 v[22:25], v[150:153], v[198:201], v[22:25]
	v_mfma_f32_16x16x32_bf16 v[18:21], v[154:157], v[194:197], 0
	v_mfma_f32_16x16x32_bf16 v[18:21], v[158:161], v[198:201], v[18:21]
	v_mfma_f32_16x16x32_bf16 v[2:5], v[154:157], v[202:205], 0
	v_mfma_f32_16x16x32_bf16 v[2:5], v[158:161], v[206:209], v[2:5]
	s_setprio 2
	s_barrier
	v_mfma_f32_16x16x32_bf16 v[6:9], v[146:149], v[202:205], 0
	v_mfma_f32_16x16x32_bf16 v[6:9], v[150:153], v[206:209], v[6:9]
	s_setprio 0
	ds_read_b128 v[130:133], v184
	ds_read_b128 v[134:137], v184 offset:1024
	ds_read_b128 v[138:141], v184 offset:2048
	ds_read_b128 v[142:145], v184 offset:3072
	ds_read_b128 v[146:149], v185
	ds_read_b128 v[150:153], v185 offset:1024
	ds_read_b128 v[154:157], v185 offset:2048
	ds_read_b128 v[158:161], v185 offset:3072
	ds_read_b128 v[166:169], v183 offset:32768
	ds_read_b128 v[170:173], v183 offset:33792
	ds_read_b128 v[186:189], v183 offset:34816
	ds_read_b128 v[190:193], v183 offset:35840
	ds_read_b128 v[194:197], v183 offset:36864
	ds_read_b128 v[198:201], v183 offset:37888
	ds_read_b128 v[202:205], v183 offset:38912
	ds_read_b128 v[206:209], v183 offset:39936
	s_mov_b32 s79, m0
	s_mov_b32 m0, s40
	s_nop 0
	global_load_lds_dwordx4 v1, s[28:29]
	s_mov_b32 m0, s79
	s_nop 0
	s_mov_b32 s79, m0
	s_mov_b32 m0, s47
	s_nop 0
	global_load_lds_dwordx4 v177, s[28:29]
	s_mov_b32 m0, s79
	s_add_u32 s28, s28, 0x80000
	s_addc_u32 s29, s29, 0
	s_mov_b32 s79, m0
	s_mov_b32 m0, s48
	s_nop 0
	global_load_lds_dwordx4 v1, s[28:29]
	s_mov_b32 m0, s79
	s_nop 0
	s_mov_b32 s79, m0
	s_mov_b32 m0, s49
	s_nop 0
	global_load_lds_dwordx4 v177, s[28:29]
	s_mov_b32 m0, s79
	s_waitcnt vmcnt(8)
	s_waitcnt lgkmcnt(0)
	s_waitcnt lgkmcnt(7)
	v_mfma_f32_16x16x32_bf16 v[126:129], v[130:133], v[166:169], v[126:129]
	v_mfma_f32_16x16x32_bf16 v[126:129], v[134:137], v[170:173], v[126:129]
	s_waitcnt lgkmcnt(5)
	v_mfma_f32_16x16x32_bf16 v[122:125], v[138:141], v[166:169], v[122:125]
	v_mfma_f32_16x16x32_bf16 v[122:125], v[142:145], v[170:173], v[122:125]
	s_barrier
	s_setprio 1
	s_waitcnt lgkmcnt(3)
	v_mfma_f32_16x16x32_bf16 v[114:117], v[138:141], v[186:189], v[114:117]
	v_mfma_f32_16x16x32_bf16 v[114:117], v[142:145], v[190:193], v[114:117]
	s_waitcnt lgkmcnt(1)
	v_mfma_f32_16x16x32_bf16 v[118:121], v[130:133], v[186:189], v[118:121]
	v_mfma_f32_16x16x32_bf16 v[118:121], v[134:137], v[190:193], v[118:121]
	v_mfma_f32_16x16x32_bf16 v[94:97], v[130:133], v[194:197], v[94:97]
	v_mfma_f32_16x16x32_bf16 v[94:97], v[134:137], v[198:201], v[94:97]
	v_mfma_f32_16x16x32_bf16 v[90:93], v[138:141], v[194:197], v[90:93]
	v_mfma_f32_16x16x32_bf16 v[90:93], v[142:145], v[198:201], v[90:93]
	v_mfma_f32_16x16x32_bf16 v[78:81], v[138:141], v[202:205], v[78:81]
	v_mfma_f32_16x16x32_bf16 v[78:81], v[142:145], v[206:209], v[78:81]
	s_waitcnt lgkmcnt(0)
	v_mfma_f32_16x16x32_bf16 v[86:89], v[130:133], v[202:205], v[86:89]
	v_mfma_f32_16x16x32_bf16 v[86:89], v[134:137], v[206:209], v[86:89]
	s_setprio 0
	s_setprio 1
	v_mfma_f32_16x16x32_bf16 v[110:113], v[146:149], v[166:169], v[110:113]
	v_mfma_f32_16x16x32_bf16 v[110:113], v[150:153], v[170:173], v[110:113]
	v_mfma_f32_16x16x32_bf16 v[106:109], v[154:157], v[166:169], v[106:109]
	v_mfma_f32_16x16x32_bf16 v[106:109], v[158:161], v[170:173], v[106:109]
	v_mfma_f32_16x16x32_bf16 v[98:101], v[154:157], v[186:189], v[98:101]
	v_mfma_f32_16x16x32_bf16 v[98:101], v[158:161], v[190:193], v[98:101]
	v_mfma_f32_16x16x32_bf16 v[102:105], v[146:149], v[186:189], v[102:105]
	v_mfma_f32_16x16x32_bf16 v[102:105], v[150:153], v[190:193], v[102:105]
	v_mfma_f32_16x16x32_bf16 v[82:85], v[146:149], v[194:197], v[82:85]
	v_mfma_f32_16x16x32_bf16 v[82:85], v[150:153], v[198:201], v[82:85]
	v_mfma_f32_16x16x32_bf16 v[74:77], v[154:157], v[194:197], v[74:77]
	v_mfma_f32_16x16x32_bf16 v[74:77], v[158:161], v[198:201], v[74:77]
	v_mfma_f32_16x16x32_bf16 v[66:69], v[154:157], v[202:205], v[66:69]
	v_mfma_f32_16x16x32_bf16 v[66:69], v[158:161], v[206:209], v[66:69]
	s_setprio 2
	s_barrier
	v_mfma_f32_16x16x32_bf16 v[70:73], v[146:149], v[202:205], v[70:73]
	v_mfma_f32_16x16x32_bf16 v[70:73], v[150:153], v[206:209], v[70:73]
	s_setprio 0
	ds_read_b128 v[166:169], v183 offset:49152
	ds_read_b128 v[170:173], v183 offset:50176
	ds_read_b128 v[186:189], v183 offset:51200
	ds_read_b128 v[190:193], v183 offset:52224
	ds_read_b128 v[194:197], v183 offset:53248
	ds_read_b128 v[198:201], v183 offset:54272
	ds_read_b128 v[202:205], v183 offset:55296
	ds_read_b128 v[206:209], v183 offset:56320
	s_add_u32 s28, s26, 0x80
	s_addc_u32 s29, s27, 0
	s_mov_b32 s79, m0
	s_mov_b32 m0, s56
	s_nop 0
	global_load_lds_dwordx4 v176, s[28:29]
	s_mov_b32 m0, s79
	s_add_u32 s26, s26, 0x80080
	s_mov_b32 s79, m0
	s_mov_b32 m0, s57
	s_nop 0
	global_load_lds_dwordx4 v178, s[28:29]
	s_mov_b32 m0, s79
	s_addc_u32 s27, s27, 0
	s_mov_b32 s28, m0
	s_mov_b32 m0, s58
	s_nop 0
	global_load_lds_dwordx4 v176, s[26:27]
	s_mov_b32 m0, s28
	s_nop 0
	s_mov_b32 s28, m0
	s_mov_b32 m0, s59
	s_nop 0
	global_load_lds_dwordx4 v178, s[26:27]
	s_mov_b32 m0, s28
	s_waitcnt vmcnt(4)
	s_waitcnt lgkmcnt(0)
	s_waitcnt lgkmcnt(7)
	v_mfma_f32_16x16x32_bf16 v[62:65], v[130:133], v[166:169], v[62:65]
	v_mfma_f32_16x16x32_bf16 v[62:65], v[134:137], v[170:173], v[62:65]
	s_waitcnt lgkmcnt(5)
	v_mfma_f32_16x16x32_bf16 v[58:61], v[138:141], v[166:169], v[58:61]
	v_mfma_f32_16x16x32_bf16 v[58:61], v[142:145], v[170:173], v[58:61]
	s_barrier
	s_setprio 1
	s_waitcnt lgkmcnt(3)
	v_mfma_f32_16x16x32_bf16 v[42:45], v[138:141], v[186:189], v[42:45]
	v_mfma_f32_16x16x32_bf16 v[42:45], v[142:145], v[190:193], v[42:45]
	s_waitcnt lgkmcnt(1)
	v_mfma_f32_16x16x32_bf16 v[46:49], v[130:133], v[186:189], v[46:49]
	v_mfma_f32_16x16x32_bf16 v[46:49], v[134:137], v[190:193], v[46:49]
	v_mfma_f32_16x16x32_bf16 v[30:33], v[130:133], v[194:197], v[30:33]
	v_mfma_f32_16x16x32_bf16 v[30:33], v[134:137], v[198:201], v[30:33]
	v_mfma_f32_16x16x32_bf16 v[26:29], v[138:141], v[194:197], v[26:29]
	v_mfma_f32_16x16x32_bf16 v[26:29], v[142:145], v[198:201], v[26:29]
	v_mfma_f32_16x16x32_bf16 v[10:13], v[138:141], v[202:205], v[10:13]
	v_mfma_f32_16x16x32_bf16 v[10:13], v[142:145], v[206:209], v[10:13]
	s_waitcnt lgkmcnt(0)
	v_mfma_f32_16x16x32_bf16 v[14:17], v[130:133], v[202:205], v[14:17]
	v_mfma_f32_16x16x32_bf16 v[14:17], v[134:137], v[206:209], v[14:17]
	s_setprio 0
	s_setprio 1
	v_mfma_f32_16x16x32_bf16 v[54:57], v[146:149], v[166:169], v[54:57]
	v_mfma_f32_16x16x32_bf16 v[54:57], v[150:153], v[170:173], v[54:57]
	v_mfma_f32_16x16x32_bf16 v[50:53], v[154:157], v[166:169], v[50:53]
	v_mfma_f32_16x16x32_bf16 v[50:53], v[158:161], v[170:173], v[50:53]
	v_mfma_f32_16x16x32_bf16 v[34:37], v[154:157], v[186:189], v[34:37]
	v_mfma_f32_16x16x32_bf16 v[34:37], v[158:161], v[190:193], v[34:37]
	v_mfma_f32_16x16x32_bf16 v[38:41], v[146:149], v[186:189], v[38:41]
	v_mfma_f32_16x16x32_bf16 v[38:41], v[150:153], v[190:193], v[38:41]
	v_mfma_f32_16x16x32_bf16 v[22:25], v[146:149], v[194:197], v[22:25]
	v_mfma_f32_16x16x32_bf16 v[22:25], v[150:153], v[198:201], v[22:25]
	v_mfma_f32_16x16x32_bf16 v[18:21], v[154:157], v[194:197], v[18:21]
	v_mfma_f32_16x16x32_bf16 v[18:21], v[158:161], v[198:201], v[18:21]
	v_mfma_f32_16x16x32_bf16 v[2:5], v[154:157], v[202:205], v[2:5]
	v_mfma_f32_16x16x32_bf16 v[2:5], v[158:161], v[206:209], v[2:5]
	s_setprio 2
	s_barrier
	v_mfma_f32_16x16x32_bf16 v[6:9], v[146:149], v[202:205], v[6:9]
	v_mfma_f32_16x16x32_bf16 v[6:9], v[150:153], v[206:209], v[6:9]
	s_setprio 0
	s_add_i32 s78, s78, 2
	s_add_u32 s74, s74, 0x100
	s_addc_u32 s75, s75, 0
	s_add_u32 s24, s24, 0x100
	s_addc_u32 s25, s25, 0
	s_add_u32 s76, s76, 0x100
	s_addc_u32 s77, s77, 0
	s_cmp_gt_u32 s78, 29
	.p2align 6
.LBB0_2410:
	ds_read_b128 v[130:133], v181
	ds_read_b128 v[134:137], v181 offset:1024
	ds_read_b128 v[138:141], v181 offset:2048
	ds_read_b128 v[142:145], v181 offset:3072
	ds_read_b128 v[146:149], v182
	ds_read_b128 v[150:153], v182 offset:1024
	ds_read_b128 v[154:157], v182 offset:2048
	ds_read_b128 v[158:161], v182 offset:3072
	s_cmp_eq_u32 s78, 28
	s_cselect_b32 s27, s15, s75
	s_cselect_b32 s26, s73, s74
	s_cselect_b32 s29, s17, s77
	s_cselect_b32 s28, s71, s76
	ds_read_b128 v[166:169], v183
	ds_read_b128 v[170:173], v183 offset:1024
	ds_read_b128 v[186:189], v183 offset:2048
	ds_read_b128 v[190:193], v183 offset:3072
	ds_read_b128 v[194:197], v183 offset:4096
	ds_read_b128 v[198:201], v183 offset:5120
	ds_read_b128 v[202:205], v183 offset:6144
	ds_read_b128 v[206:209], v183 offset:7168
	s_add_u32 s80, s24, 0xfff80000
	s_addc_u32 s81, s25, -1
	s_mov_b32 s79, m0
	s_mov_b32 m0, s64
	s_nop 0
	global_load_lds_dwordx4 v1, s[80:81]
	s_mov_b32 m0, s79
	s_nop 0
	s_mov_b32 s79, m0
	s_mov_b32 m0, s66
	s_nop 0
	global_load_lds_dwordx4 v177, s[80:81]
	s_mov_b32 m0, s79
	s_nop 0
	s_mov_b32 s79, m0
	s_mov_b32 m0, s65
	s_nop 0
	global_load_lds_dwordx4 v1, s[24:25]
	s_mov_b32 m0, s79
	s_nop 0
	s_mov_b32 s79, m0
	s_mov_b32 m0, s67
	s_nop 0
	global_load_lds_dwordx4 v177, s[24:25]
	s_mov_b32 m0, s79
	s_waitcnt vmcnt(8)
	s_waitcnt lgkmcnt(0)
	s_waitcnt lgkmcnt(7)
	v_mfma_f32_16x16x32_bf16 v[126:129], v[130:133], v[166:169], v[126:129]
	v_mfma_f32_16x16x32_bf16 v[126:129], v[134:137], v[170:173], v[126:129]
	s_waitcnt lgkmcnt(5)
	v_mfma_f32_16x16x32_bf16 v[122:125], v[138:141], v[166:169], v[122:125]
	v_mfma_f32_16x16x32_bf16 v[122:125], v[142:145], v[170:173], v[122:125]
	s_barrier
	s_setprio 1
	s_waitcnt lgkmcnt(3)
	v_mfma_f32_16x16x32_bf16 v[114:117], v[138:141], v[186:189], v[114:117]
	v_mfma_f32_16x16x32_bf16 v[114:117], v[142:145], v[190:193], v[114:117]
	s_waitcnt lgkmcnt(1)
	v_mfma_f32_16x16x32_bf16 v[118:121], v[130:133], v[186:189], v[118:121]
	v_mfma_f32_16x16x32_bf16 v[118:121], v[134:137], v[190:193], v[118:121]
	v_mfma_f32_16x16x32_bf16 v[94:97], v[130:133], v[194:197], v[94:97]
	v_mfma_f32_16x16x32_bf16 v[94:97], v[134:137], v[198:201], v[94:97]
	v_mfma_f32_16x16x32_bf16 v[90:93], v[138:141], v[194:197], v[90:93]
	v_mfma_f32_16x16x32_bf16 v[90:93], v[142:145], v[198:201], v[90:93]
	v_mfma_f32_16x16x32_bf16 v[78:81], v[138:141], v[202:205], v[78:81]
	v_mfma_f32_16x16x32_bf16 v[78:81], v[142:145], v[206:209], v[78:81]
	s_waitcnt lgkmcnt(0)
	v_mfma_f32_16x16x32_bf16 v[86:89], v[130:133], v[202:205], v[86:89]
	v_mfma_f32_16x16x32_bf16 v[86:89], v[134:137], v[206:209], v[86:89]
	s_setprio 0
	s_setprio 1
	v_mfma_f32_16x16x32_bf16 v[110:113], v[146:149], v[166:169], v[110:113]
	v_mfma_f32_16x16x32_bf16 v[110:113], v[150:153], v[170:173], v[110:113]
	v_mfma_f32_16x16x32_bf16 v[106:109], v[154:157], v[166:169], v[106:109]
	v_mfma_f32_16x16x32_bf16 v[106:109], v[158:161], v[170:173], v[106:109]
	v_mfma_f32_16x16x32_bf16 v[98:101], v[154:157], v[186:189], v[98:101]
	v_mfma_f32_16x16x32_bf16 v[98:101], v[158:161], v[190:193], v[98:101]
	v_mfma_f32_16x16x32_bf16 v[102:105], v[146:149], v[186:189], v[102:105]
	v_mfma_f32_16x16x32_bf16 v[102:105], v[150:153], v[190:193], v[102:105]
	v_mfma_f32_16x16x32_bf16 v[82:85], v[146:149], v[194:197], v[82:85]
	v_mfma_f32_16x16x32_bf16 v[82:85], v[150:153], v[198:201], v[82:85]
	v_mfma_f32_16x16x32_bf16 v[74:77], v[154:157], v[194:197], v[74:77]
	v_mfma_f32_16x16x32_bf16 v[74:77], v[158:161], v[198:201], v[74:77]
	v_mfma_f32_16x16x32_bf16 v[66:69], v[154:157], v[202:205], v[66:69]
	v_mfma_f32_16x16x32_bf16 v[66:69], v[158:161], v[206:209], v[66:69]
	s_setprio 2
	s_barrier
	v_mfma_f32_16x16x32_bf16 v[70:73], v[146:149], v[202:205], v[70:73]
	v_mfma_f32_16x16x32_bf16 v[70:73], v[150:153], v[206:209], v[70:73]
	s_setprio 0
	ds_read_b128 v[166:169], v183 offset:16384
	ds_read_b128 v[170:173], v183 offset:17408
	ds_read_b128 v[186:189], v183 offset:18432
	ds_read_b128 v[190:193], v183 offset:19456
	ds_read_b128 v[194:197], v183 offset:20480
	ds_read_b128 v[198:201], v183 offset:21504
	ds_read_b128 v[202:205], v183 offset:22528
	ds_read_b128 v[206:209], v183 offset:23552
	s_mov_b32 s79, m0
	s_mov_b32 m0, s41
	s_nop 0
	global_load_lds_dwordx4 v176, s[26:27]
	s_mov_b32 m0, s79
	s_add_u32 s80, s26, 0x80000
	s_mov_b32 s79, m0
	s_mov_b32 m0, s42
	s_nop 0
	global_load_lds_dwordx4 v178, s[26:27]
	s_mov_b32 m0, s79
	s_addc_u32 s81, s27, 0
	s_mov_b32 s79, m0
	s_mov_b32 m0, s43
	s_nop 0
	global_load_lds_dwordx4 v176, s[80:81]
	s_mov_b32 m0, s79
	s_nop 0
	s_mov_b32 s79, m0
	s_mov_b32 m0, s46
	s_nop 0
	global_load_lds_dwordx4 v178, s[80:81]
	s_mov_b32 m0, s79
	s_waitcnt vmcnt(4)
	s_waitcnt lgkmcnt(0)
	s_waitcnt lgkmcnt(7)
	v_mfma_f32_16x16x32_bf16 v[62:65], v[130:133], v[166:169], v[62:65]
	v_mfma_f32_16x16x32_bf16 v[62:65], v[134:137], v[170:173], v[62:65]
	s_waitcnt lgkmcnt(5)
	v_mfma_f32_16x16x32_bf16 v[58:61], v[138:141], v[166:169], v[58:61]
	v_mfma_f32_16x16x32_bf16 v[58:61], v[142:145], v[170:173], v[58:61]
	s_barrier
	s_setprio 1
	s_waitcnt lgkmcnt(3)
	v_mfma_f32_16x16x32_bf16 v[42:45], v[138:141], v[186:189], v[42:45]
	v_mfma_f32_16x16x32_bf16 v[42:45], v[142:145], v[190:193], v[42:45]
	s_waitcnt lgkmcnt(1)
	v_mfma_f32_16x16x32_bf16 v[46:49], v[130:133], v[186:189], v[46:49]
	v_mfma_f32_16x16x32_bf16 v[46:49], v[134:137], v[190:193], v[46:49]
	v_mfma_f32_16x16x32_bf16 v[30:33], v[130:133], v[194:197], v[30:33]
	v_mfma_f32_16x16x32_bf16 v[30:33], v[134:137], v[198:201], v[30:33]
	v_mfma_f32_16x16x32_bf16 v[26:29], v[138:141], v[194:197], v[26:29]
	v_mfma_f32_16x16x32_bf16 v[26:29], v[142:145], v[198:201], v[26:29]
	v_mfma_f32_16x16x32_bf16 v[10:13], v[138:141], v[202:205], v[10:13]
	v_mfma_f32_16x16x32_bf16 v[10:13], v[142:145], v[206:209], v[10:13]
	s_waitcnt lgkmcnt(0)
	v_mfma_f32_16x16x32_bf16 v[14:17], v[130:133], v[202:205], v[14:17]
	v_mfma_f32_16x16x32_bf16 v[14:17], v[134:137], v[206:209], v[14:17]
	s_setprio 0
	s_setprio 1
	v_mfma_f32_16x16x32_bf16 v[54:57], v[146:149], v[166:169], v[54:57]
	v_mfma_f32_16x16x32_bf16 v[54:57], v[150:153], v[170:173], v[54:57]
	v_mfma_f32_16x16x32_bf16 v[50:53], v[154:157], v[166:169], v[50:53]
	v_mfma_f32_16x16x32_bf16 v[50:53], v[158:161], v[170:173], v[50:53]
	v_mfma_f32_16x16x32_bf16 v[34:37], v[154:157], v[186:189], v[34:37]
	v_mfma_f32_16x16x32_bf16 v[34:37], v[158:161], v[190:193], v[34:37]
	v_mfma_f32_16x16x32_bf16 v[38:41], v[146:149], v[186:189], v[38:41]
	v_mfma_f32_16x16x32_bf16 v[38:41], v[150:153], v[190:193], v[38:41]
	v_mfma_f32_16x16x32_bf16 v[22:25], v[146:149], v[194:197], v[22:25]
	v_mfma_f32_16x16x32_bf16 v[22:25], v[150:153], v[198:201], v[22:25]
	v_mfma_f32_16x16x32_bf16 v[18:21], v[154:157], v[194:197], v[18:21]
	v_mfma_f32_16x16x32_bf16 v[18:21], v[158:161], v[198:201], v[18:21]
	v_mfma_f32_16x16x32_bf16 v[2:5], v[154:157], v[202:205], v[2:5]
	v_mfma_f32_16x16x32_bf16 v[2:5], v[158:161], v[206:209], v[2:5]
	s_setprio 2
	s_barrier
	v_mfma_f32_16x16x32_bf16 v[6:9], v[146:149], v[202:205], v[6:9]
	v_mfma_f32_16x16x32_bf16 v[6:9], v[150:153], v[206:209], v[6:9]
	s_setprio 0
	ds_read_b128 v[130:133], v184
	ds_read_b128 v[134:137], v184 offset:1024
	ds_read_b128 v[138:141], v184 offset:2048
	ds_read_b128 v[142:145], v184 offset:3072
	ds_read_b128 v[146:149], v185
	ds_read_b128 v[150:153], v185 offset:1024
	ds_read_b128 v[154:157], v185 offset:2048
	ds_read_b128 v[158:161], v185 offset:3072
	ds_read_b128 v[166:169], v183 offset:32768
	ds_read_b128 v[170:173], v183 offset:33792
	ds_read_b128 v[186:189], v183 offset:34816
	ds_read_b128 v[190:193], v183 offset:35840
	ds_read_b128 v[194:197], v183 offset:36864
	ds_read_b128 v[198:201], v183 offset:37888
	ds_read_b128 v[202:205], v183 offset:38912
	ds_read_b128 v[206:209], v183 offset:39936
	s_mov_b32 s79, m0
	s_mov_b32 m0, s40
	s_nop 0
	global_load_lds_dwordx4 v1, s[28:29]
	s_mov_b32 m0, s79
	s_nop 0
	s_mov_b32 s79, m0
	s_mov_b32 m0, s47
	s_nop 0
	global_load_lds_dwordx4 v177, s[28:29]
	s_mov_b32 m0, s79
	s_add_u32 s28, s28, 0x80000
	s_addc_u32 s29, s29, 0
	s_mov_b32 s79, m0
	s_mov_b32 m0, s48
	s_nop 0
	global_load_lds_dwordx4 v1, s[28:29]
	s_mov_b32 m0, s79
	s_nop 0
	s_mov_b32 s79, m0
	s_mov_b32 m0, s49
	s_nop 0
	global_load_lds_dwordx4 v177, s[28:29]
	s_mov_b32 m0, s79
	s_waitcnt vmcnt(8)
	s_waitcnt lgkmcnt(0)
	s_waitcnt lgkmcnt(7)
	v_mfma_f32_16x16x32_bf16 v[126:129], v[130:133], v[166:169], v[126:129]
	v_mfma_f32_16x16x32_bf16 v[126:129], v[134:137], v[170:173], v[126:129]
	s_waitcnt lgkmcnt(5)
	v_mfma_f32_16x16x32_bf16 v[122:125], v[138:141], v[166:169], v[122:125]
	v_mfma_f32_16x16x32_bf16 v[122:125], v[142:145], v[170:173], v[122:125]
	s_barrier
	s_setprio 1
	s_waitcnt lgkmcnt(3)
	v_mfma_f32_16x16x32_bf16 v[114:117], v[138:141], v[186:189], v[114:117]
	v_mfma_f32_16x16x32_bf16 v[114:117], v[142:145], v[190:193], v[114:117]
	s_waitcnt lgkmcnt(1)
	v_mfma_f32_16x16x32_bf16 v[118:121], v[130:133], v[186:189], v[118:121]
	v_mfma_f32_16x16x32_bf16 v[118:121], v[134:137], v[190:193], v[118:121]
	v_mfma_f32_16x16x32_bf16 v[94:97], v[130:133], v[194:197], v[94:97]
	v_mfma_f32_16x16x32_bf16 v[94:97], v[134:137], v[198:201], v[94:97]
	v_mfma_f32_16x16x32_bf16 v[90:93], v[138:141], v[194:197], v[90:93]
	v_mfma_f32_16x16x32_bf16 v[90:93], v[142:145], v[198:201], v[90:93]
	v_mfma_f32_16x16x32_bf16 v[78:81], v[138:141], v[202:205], v[78:81]
	v_mfma_f32_16x16x32_bf16 v[78:81], v[142:145], v[206:209], v[78:81]
	s_waitcnt lgkmcnt(0)
	v_mfma_f32_16x16x32_bf16 v[86:89], v[130:133], v[202:205], v[86:89]
	v_mfma_f32_16x16x32_bf16 v[86:89], v[134:137], v[206:209], v[86:89]
	s_setprio 0
	s_setprio 1
	v_mfma_f32_16x16x32_bf16 v[110:113], v[146:149], v[166:169], v[110:113]
	v_mfma_f32_16x16x32_bf16 v[110:113], v[150:153], v[170:173], v[110:113]
	v_mfma_f32_16x16x32_bf16 v[106:109], v[154:157], v[166:169], v[106:109]
	v_mfma_f32_16x16x32_bf16 v[106:109], v[158:161], v[170:173], v[106:109]
	v_mfma_f32_16x16x32_bf16 v[98:101], v[154:157], v[186:189], v[98:101]
	v_mfma_f32_16x16x32_bf16 v[98:101], v[158:161], v[190:193], v[98:101]
	v_mfma_f32_16x16x32_bf16 v[102:105], v[146:149], v[186:189], v[102:105]
	v_mfma_f32_16x16x32_bf16 v[102:105], v[150:153], v[190:193], v[102:105]
	v_mfma_f32_16x16x32_bf16 v[82:85], v[146:149], v[194:197], v[82:85]
	v_mfma_f32_16x16x32_bf16 v[82:85], v[150:153], v[198:201], v[82:85]
	v_mfma_f32_16x16x32_bf16 v[74:77], v[154:157], v[194:197], v[74:77]
	v_mfma_f32_16x16x32_bf16 v[74:77], v[158:161], v[198:201], v[74:77]
	v_mfma_f32_16x16x32_bf16 v[66:69], v[154:157], v[202:205], v[66:69]
	v_mfma_f32_16x16x32_bf16 v[66:69], v[158:161], v[206:209], v[66:69]
	s_setprio 2
	s_barrier
	v_mfma_f32_16x16x32_bf16 v[70:73], v[146:149], v[202:205], v[70:73]
	v_mfma_f32_16x16x32_bf16 v[70:73], v[150:153], v[206:209], v[70:73]
	s_setprio 0
	ds_read_b128 v[166:169], v183 offset:49152
	ds_read_b128 v[170:173], v183 offset:50176
	ds_read_b128 v[186:189], v183 offset:51200
	ds_read_b128 v[190:193], v183 offset:52224
	ds_read_b128 v[194:197], v183 offset:53248
	ds_read_b128 v[198:201], v183 offset:54272
	ds_read_b128 v[202:205], v183 offset:55296
	ds_read_b128 v[206:209], v183 offset:56320
	s_add_u32 s28, s26, 0x80
	s_addc_u32 s29, s27, 0
	s_mov_b32 s79, m0
	s_mov_b32 m0, s56
	s_nop 0
	global_load_lds_dwordx4 v176, s[28:29]
	s_mov_b32 m0, s79
	s_add_u32 s26, s26, 0x80080
	s_mov_b32 s79, m0
	s_mov_b32 m0, s57
	s_nop 0
	global_load_lds_dwordx4 v178, s[28:29]
	s_mov_b32 m0, s79
	s_addc_u32 s27, s27, 0
	s_mov_b32 s28, m0
	s_mov_b32 m0, s58
	s_nop 0
	global_load_lds_dwordx4 v176, s[26:27]
	s_mov_b32 m0, s28
	s_nop 0
	s_mov_b32 s28, m0
	s_mov_b32 m0, s59
	s_nop 0
	global_load_lds_dwordx4 v178, s[26:27]
	s_mov_b32 m0, s28
	s_waitcnt vmcnt(4)
	s_waitcnt lgkmcnt(0)
	s_waitcnt lgkmcnt(7)
	v_mfma_f32_16x16x32_bf16 v[62:65], v[130:133], v[166:169], v[62:65]
	v_mfma_f32_16x16x32_bf16 v[62:65], v[134:137], v[170:173], v[62:65]
	s_waitcnt lgkmcnt(5)
	v_mfma_f32_16x16x32_bf16 v[58:61], v[138:141], v[166:169], v[58:61]
	v_mfma_f32_16x16x32_bf16 v[58:61], v[142:145], v[170:173], v[58:61]
	s_barrier
	s_setprio 1
	s_waitcnt lgkmcnt(3)
	v_mfma_f32_16x16x32_bf16 v[42:45], v[138:141], v[186:189], v[42:45]
	v_mfma_f32_16x16x32_bf16 v[42:45], v[142:145], v[190:193], v[42:45]
	s_waitcnt lgkmcnt(1)
	v_mfma_f32_16x16x32_bf16 v[46:49], v[130:133], v[186:189], v[46:49]
	v_mfma_f32_16x16x32_bf16 v[46:49], v[134:137], v[190:193], v[46:49]
	v_mfma_f32_16x16x32_bf16 v[30:33], v[130:133], v[194:197], v[30:33]
	v_mfma_f32_16x16x32_bf16 v[30:33], v[134:137], v[198:201], v[30:33]
	v_mfma_f32_16x16x32_bf16 v[26:29], v[138:141], v[194:197], v[26:29]
	v_mfma_f32_16x16x32_bf16 v[26:29], v[142:145], v[198:201], v[26:29]
	v_mfma_f32_16x16x32_bf16 v[10:13], v[138:141], v[202:205], v[10:13]
	v_mfma_f32_16x16x32_bf16 v[10:13], v[142:145], v[206:209], v[10:13]
	s_waitcnt lgkmcnt(0)
	v_mfma_f32_16x16x32_bf16 v[14:17], v[130:133], v[202:205], v[14:17]
	v_mfma_f32_16x16x32_bf16 v[14:17], v[134:137], v[206:209], v[14:17]
	s_setprio 0
	s_setprio 1
	v_mfma_f32_16x16x32_bf16 v[54:57], v[146:149], v[166:169], v[54:57]
	v_mfma_f32_16x16x32_bf16 v[54:57], v[150:153], v[170:173], v[54:57]
	v_mfma_f32_16x16x32_bf16 v[50:53], v[154:157], v[166:169], v[50:53]
	v_mfma_f32_16x16x32_bf16 v[50:53], v[158:161], v[170:173], v[50:53]
	v_mfma_f32_16x16x32_bf16 v[34:37], v[154:157], v[186:189], v[34:37]
	v_mfma_f32_16x16x32_bf16 v[34:37], v[158:161], v[190:193], v[34:37]
	v_mfma_f32_16x16x32_bf16 v[38:41], v[146:149], v[186:189], v[38:41]
	v_mfma_f32_16x16x32_bf16 v[38:41], v[150:153], v[190:193], v[38:41]
	v_mfma_f32_16x16x32_bf16 v[22:25], v[146:149], v[194:197], v[22:25]
	v_mfma_f32_16x16x32_bf16 v[22:25], v[150:153], v[198:201], v[22:25]
	v_mfma_f32_16x16x32_bf16 v[18:21], v[154:157], v[194:197], v[18:21]
	v_mfma_f32_16x16x32_bf16 v[18:21], v[158:161], v[198:201], v[18:21]
	v_mfma_f32_16x16x32_bf16 v[2:5], v[154:157], v[202:205], v[2:5]
	v_mfma_f32_16x16x32_bf16 v[2:5], v[158:161], v[206:209], v[2:5]
	s_setprio 2
	s_barrier
	v_mfma_f32_16x16x32_bf16 v[6:9], v[146:149], v[202:205], v[6:9]
	v_mfma_f32_16x16x32_bf16 v[6:9], v[150:153], v[206:209], v[6:9]
	s_setprio 0
	s_add_i32 s78, s78, 2
	s_add_u32 s74, s74, 0x100
	s_addc_u32 s75, s75, 0
	s_add_u32 s24, s24, 0x100
	s_addc_u32 s25, s25, 0
	s_add_u32 s76, s76, 0x100
	s_addc_u32 s77, s77, 0
	s_cmp_gt_u32 s78, 29
	s_cbranch_scc0 .LBB0_2410
	s_and_b64 vcc, exec, s[8:9]
	s_cbranch_vccz .LBB0_2413
	s_barrier

.LBB0_2593:
	s_ashr_i32 s11, s10, 31
	s_lshl_b64 s[12:13], s[10:11], 20
	s_add_u32 s12, s26, s12
	s_addc_u32 s13, s27, s13
	s_and_b64 s[14:15], s[2:3], exec
	s_cselect_b32 s11, s13, s21
	s_cselect_b32 s62, s12, s20
	s_ashr_i32 s9, s8, 31
	s_lshl_b64 s[14:15], s[8:9], 20
	s_add_u32 s14, s28, s14
	s_addc_u32 s15, s29, s15
	s_and_b64 s[22:23], s[2:3], exec
	s_cselect_b32 s9, s15, s19
	s_cselect_b32 s63, s14, s18
	s_add_u32 s64, s18, 0x100
	s_addc_u32 s65, s19, 0
	s_add_u32 s18, s20, 0x80080
	s_addc_u32 s19, s21, 0
	s_add_u32 s66, s20, 0x100
	s_addc_u32 s67, s21, 0
	s_mov_b32 s70, -2
	ds_read_b128 v[148:151], v143
	ds_read_b128 v[152:155], v143 offset:1024
	ds_read_b128 v[156:159], v143 offset:2048
	ds_read_b128 v[160:163], v143 offset:3072
	ds_read_b128 v[164:167], v144
	ds_read_b128 v[168:171], v144 offset:1024
	ds_read_b128 v[172:175], v144 offset:2048
	ds_read_b128 v[176:179], v144 offset:3072
	s_cmp_eq_u32 s70, 28
	s_cselect_b32 s21, s9, s65
	s_cselect_b32 s20, s63, s64
	s_cselect_b32 s23, s11, s67
	s_cselect_b32 s22, s62, s66
	ds_read_b128 v[180:183], v145
	ds_read_b128 v[184:187], v145 offset:1024
	ds_read_b128 v[188:191], v145 offset:2048
	ds_read_b128 v[192:195], v145 offset:3072
	ds_read_b128 v[196:199], v145 offset:4096
	ds_read_b128 v[200:203], v145 offset:5120
	ds_read_b128 v[204:207], v145 offset:6144
	ds_read_b128 v[208:211], v145 offset:7168
	s_add_u32 s74, s18, 0xfff80000
	s_addc_u32 s75, s19, -1
	s_mov_b32 s71, m0
	s_mov_b32 m0, s48
	s_nop 0
	global_load_lds_dwordx4 v138, s[74:75]
	s_mov_b32 m0, s71
	s_nop 0
	s_mov_b32 s71, m0
	s_mov_b32 m0, s57
	s_nop 0
	global_load_lds_dwordx4 v140, s[74:75]
	s_mov_b32 m0, s71
	s_nop 0
	s_mov_b32 s71, m0
	s_mov_b32 m0, s49
	s_nop 0
	global_load_lds_dwordx4 v138, s[18:19]
	s_mov_b32 m0, s71
	s_nop 0
	s_mov_b32 s71, m0
	s_mov_b32 m0, s58
	s_nop 0
	global_load_lds_dwordx4 v140, s[18:19]
	s_mov_b32 m0, s71
	s_waitcnt vmcnt(8)
	s_waitcnt lgkmcnt(0)
	s_waitcnt lgkmcnt(7)
	v_mfma_f32_16x16x32_bf16 v[126:129], v[148:151], v[180:183], 0
	v_mfma_f32_16x16x32_bf16 v[126:129], v[152:155], v[184:187], v[126:129]
	s_waitcnt lgkmcnt(5)
	v_mfma_f32_16x16x32_bf16 v[122:125], v[156:159], v[180:183], 0
	v_mfma_f32_16x16x32_bf16 v[122:125], v[160:163], v[184:187], v[122:125]
	s_barrier
	s_setprio 1
	s_waitcnt lgkmcnt(3)
	v_mfma_f32_16x16x32_bf16 v[106:109], v[156:159], v[188:191], 0
	v_mfma_f32_16x16x32_bf16 v[106:109], v[160:163], v[192:195], v[106:109]
	s_waitcnt lgkmcnt(1)
	v_mfma_f32_16x16x32_bf16 v[110:113], v[148:151], v[188:191], 0
	v_mfma_f32_16x16x32_bf16 v[110:113], v[152:155], v[192:195], v[110:113]
	v_mfma_f32_16x16x32_bf16 v[94:97], v[148:151], v[196:199], 0
	v_mfma_f32_16x16x32_bf16 v[94:97], v[152:155], v[200:203], v[94:97]
	v_mfma_f32_16x16x32_bf16 v[90:93], v[156:159], v[196:199], 0
	v_mfma_f32_16x16x32_bf16 v[90:93], v[160:163], v[200:203], v[90:93]
	v_mfma_f32_16x16x32_bf16 v[74:77], v[156:159], v[204:207], 0
	v_mfma_f32_16x16x32_bf16 v[74:77], v[160:163], v[208:211], v[74:77]
	s_waitcnt lgkmcnt(0)
	v_mfma_f32_16x16x32_bf16 v[78:81], v[148:151], v[204:207], 0
	v_mfma_f32_16x16x32_bf16 v[78:81], v[152:155], v[208:211], v[78:81]
	s_setprio 0
	s_setprio 1
	v_mfma_f32_16x16x32_bf16 v[118:121], v[164:167], v[180:183], 0
	v_mfma_f32_16x16x32_bf16 v[118:121], v[168:171], v[184:187], v[118:121]
	v_mfma_f32_16x16x32_bf16 v[114:117], v[172:175], v[180:183], 0
	v_mfma_f32_16x16x32_bf16 v[114:117], v[176:179], v[184:187], v[114:117]
	v_mfma_f32_16x16x32_bf16 v[98:101], v[172:175], v[188:191], 0
	v_mfma_f32_16x16x32_bf16 v[98:101], v[176:179], v[192:195], v[98:101]
	v_mfma_f32_16x16x32_bf16 v[102:105], v[164:167], v[188:191], 0
	v_mfma_f32_16x16x32_bf16 v[102:105], v[168:171], v[192:195], v[102:105]
	v_mfma_f32_16x16x32_bf16 v[86:89], v[164:167], v[196:199], 0
	v_mfma_f32_16x16x32_bf16 v[86:89], v[168:171], v[200:203], v[86:89]
	v_mfma_f32_16x16x32_bf16 v[82:85], v[172:175], v[196:199], 0
	v_mfma_f32_16x16x32_bf16 v[82:85], v[176:179], v[200:203], v[82:85]
	v_mfma_f32_16x16x32_bf16 v[66:69], v[172:175], v[204:207], 0
	v_mfma_f32_16x16x32_bf16 v[66:69], v[176:179], v[208:211], v[66:69]
	s_setprio 2
	s_barrier
	v_mfma_f32_16x16x32_bf16 v[70:73], v[164:167], v[204:207], 0
	v_mfma_f32_16x16x32_bf16 v[70:73], v[168:171], v[208:211], v[70:73]
	s_setprio 0
	ds_read_b128 v[180:183], v145 offset:16384
	ds_read_b128 v[184:187], v145 offset:17408
	ds_read_b128 v[188:191], v145 offset:18432
	ds_read_b128 v[192:195], v145 offset:19456
	ds_read_b128 v[196:199], v145 offset:20480
	ds_read_b128 v[200:203], v145 offset:21504
	ds_read_b128 v[204:207], v145 offset:22528
	ds_read_b128 v[208:211], v145 offset:23552
	s_mov_b32 s71, m0
	s_mov_b32 m0, s35
	s_nop 0
	global_load_lds_dwordx4 v139, s[20:21]
	s_mov_b32 m0, s71
	s_add_u32 s74, s20, 0x80000
	s_mov_b32 s71, m0
	s_mov_b32 m0, s36
	s_nop 0
	global_load_lds_dwordx4 v141, s[20:21]
	s_mov_b32 m0, s71
	s_addc_u32 s75, s21, 0
	s_mov_b32 s71, m0
	s_mov_b32 m0, s37
	s_nop 0
	global_load_lds_dwordx4 v139, s[74:75]
	s_mov_b32 m0, s71
	s_nop 0
	s_mov_b32 s71, m0
	s_mov_b32 m0, s40
	s_nop 0
	global_load_lds_dwordx4 v141, s[74:75]
	s_mov_b32 m0, s71
	s_waitcnt vmcnt(4)
	s_waitcnt lgkmcnt(0)
	s_waitcnt lgkmcnt(7)
	v_mfma_f32_16x16x32_bf16 v[62:65], v[148:151], v[180:183], 0
	v_mfma_f32_16x16x32_bf16 v[62:65], v[152:155], v[184:187], v[62:65]
	s_waitcnt lgkmcnt(5)
	v_mfma_f32_16x16x32_bf16 v[58:61], v[156:159], v[180:183], 0
	v_mfma_f32_16x16x32_bf16 v[58:61], v[160:163], v[184:187], v[58:61]
	s_barrier
	s_setprio 1
	s_waitcnt lgkmcnt(3)
	v_mfma_f32_16x16x32_bf16 v[42:45], v[156:159], v[188:191], 0
	v_mfma_f32_16x16x32_bf16 v[42:45], v[160:163], v[192:195], v[42:45]
	s_waitcnt lgkmcnt(1)
	v_mfma_f32_16x16x32_bf16 v[46:49], v[148:151], v[188:191], 0
	v_mfma_f32_16x16x32_bf16 v[46:49], v[152:155], v[192:195], v[46:49]
	v_mfma_f32_16x16x32_bf16 v[30:33], v[148:151], v[196:199], 0
	v_mfma_f32_16x16x32_bf16 v[30:33], v[152:155], v[200:203], v[30:33]
	v_mfma_f32_16x16x32_bf16 v[26:29], v[156:159], v[196:199], 0
	v_mfma_f32_16x16x32_bf16 v[26:29], v[160:163], v[200:203], v[26:29]
	v_mfma_f32_16x16x32_bf16 v[10:13], v[156:159], v[204:207], 0
	v_mfma_f32_16x16x32_bf16 v[10:13], v[160:163], v[208:211], v[10:13]
	s_waitcnt lgkmcnt(0)
	v_mfma_f32_16x16x32_bf16 v[14:17], v[148:151], v[204:207], 0
	v_mfma_f32_16x16x32_bf16 v[14:17], v[152:155], v[208:211], v[14:17]
	s_setprio 0
	s_setprio 1
	v_mfma_f32_16x16x32_bf16 v[54:57], v[164:167], v[180:183], 0
	v_mfma_f32_16x16x32_bf16 v[54:57], v[168:171], v[184:187], v[54:57]
	v_mfma_f32_16x16x32_bf16 v[50:53], v[172:175], v[180:183], 0
	v_mfma_f32_16x16x32_bf16 v[50:53], v[176:179], v[184:187], v[50:53]
	v_mfma_f32_16x16x32_bf16 v[34:37], v[172:175], v[188:191], 0
	v_mfma_f32_16x16x32_bf16 v[34:37], v[176:179], v[192:195], v[34:37]
	v_mfma_f32_16x16x32_bf16 v[38:41], v[164:167], v[188:191], 0
	v_mfma_f32_16x16x32_bf16 v[38:41], v[168:171], v[192:195], v[38:41]
	v_mfma_f32_16x16x32_bf16 v[22:25], v[164:167], v[196:199], 0
	v_mfma_f32_16x16x32_bf16 v[22:25], v[168:171], v[200:203], v[22:25]
	v_mfma_f32_16x16x32_bf16 v[18:21], v[172:175], v[196:199], 0
	v_mfma_f32_16x16x32_bf16 v[18:21], v[176:179], v[200:203], v[18:21]
	v_mfma_f32_16x16x32_bf16 v[2:5], v[172:175], v[204:207], 0
	v_mfma_f32_16x16x32_bf16 v[2:5], v[176:179], v[208:211], v[2:5]
	s_setprio 2
	s_barrier
	v_mfma_f32_16x16x32_bf16 v[6:9], v[164:167], v[204:207], 0
	v_mfma_f32_16x16x32_bf16 v[6:9], v[168:171], v[208:211], v[6:9]
	s_setprio 0
	ds_read_b128 v[148:151], v146
	ds_read_b128 v[152:155], v146 offset:1024
	ds_read_b128 v[156:159], v146 offset:2048
	ds_read_b128 v[160:163], v146 offset:3072
	ds_read_b128 v[164:167], v147
	ds_read_b128 v[168:171], v147 offset:1024
	ds_read_b128 v[172:175], v147 offset:2048
	ds_read_b128 v[176:179], v147 offset:3072
	ds_read_b128 v[180:183], v145 offset:32768
	ds_read_b128 v[184:187], v145 offset:33792
	ds_read_b128 v[188:191], v145 offset:34816
	ds_read_b128 v[192:195], v145 offset:35840
	ds_read_b128 v[196:199], v145 offset:36864
	ds_read_b128 v[200:203], v145 offset:37888
	ds_read_b128 v[204:207], v145 offset:38912
	ds_read_b128 v[208:211], v145 offset:39936
	s_mov_b32 s71, m0
	s_mov_b32 m0, s31
	s_nop 0
	global_load_lds_dwordx4 v138, s[22:23]
	s_mov_b32 m0, s71
	s_nop 0
	s_mov_b32 s71, m0
	s_mov_b32 m0, s41
	s_nop 0
	global_load_lds_dwordx4 v140, s[22:23]
	s_mov_b32 m0, s71
	s_add_u32 s22, s22, 0x80000
	s_addc_u32 s23, s23, 0
	s_mov_b32 s71, m0
	s_mov_b32 m0, s42
	s_nop 0
	global_load_lds_dwordx4 v138, s[22:23]
	s_mov_b32 m0, s71
	s_nop 0
	s_mov_b32 s71, m0
	s_mov_b32 m0, s43
	s_nop 0
	global_load_lds_dwordx4 v140, s[22:23]
	s_mov_b32 m0, s71
	s_waitcnt vmcnt(8)
	s_waitcnt lgkmcnt(0)
	s_waitcnt lgkmcnt(7)
	v_mfma_f32_16x16x32_bf16 v[126:129], v[148:151], v[180:183], v[126:129]
	v_mfma_f32_16x16x32_bf16 v[126:129], v[152:155], v[184:187], v[126:129]
	s_waitcnt lgkmcnt(5)
	v_mfma_f32_16x16x32_bf16 v[122:125], v[156:159], v[180:183], v[122:125]
	v_mfma_f32_16x16x32_bf16 v[122:125], v[160:163], v[184:187], v[122:125]
	s_barrier
	s_setprio 1
	s_waitcnt lgkmcnt(3)
	v_mfma_f32_16x16x32_bf16 v[106:109], v[156:159], v[188:191], v[106:109]
	v_mfma_f32_16x16x32_bf16 v[106:109], v[160:163], v[192:195], v[106:109]
	s_waitcnt lgkmcnt(1)
	v_mfma_f32_16x16x32_bf16 v[110:113], v[148:151], v[188:191], v[110:113]
	v_mfma_f32_16x16x32_bf16 v[110:113], v[152:155], v[192:195], v[110:113]
	v_mfma_f32_16x16x32_bf16 v[94:97], v[148:151], v[196:199], v[94:97]
	v_mfma_f32_16x16x32_bf16 v[94:97], v[152:155], v[200:203], v[94:97]
	v_mfma_f32_16x16x32_bf16 v[90:93], v[156:159], v[196:199], v[90:93]
	v_mfma_f32_16x16x32_bf16 v[90:93], v[160:163], v[200:203], v[90:93]
	v_mfma_f32_16x16x32_bf16 v[74:77], v[156:159], v[204:207], v[74:77]
	v_mfma_f32_16x16x32_bf16 v[74:77], v[160:163], v[208:211], v[74:77]
	s_waitcnt lgkmcnt(0)
	v_mfma_f32_16x16x32_bf16 v[78:81], v[148:151], v[204:207], v[78:81]
	v_mfma_f32_16x16x32_bf16 v[78:81], v[152:155], v[208:211], v[78:81]
	s_setprio 0
	s_setprio 1
	v_mfma_f32_16x16x32_bf16 v[118:121], v[164:167], v[180:183], v[118:121]
	v_mfma_f32_16x16x32_bf16 v[118:121], v[168:171], v[184:187], v[118:121]
	v_mfma_f32_16x16x32_bf16 v[114:117], v[172:175], v[180:183], v[114:117]
	v_mfma_f32_16x16x32_bf16 v[114:117], v[176:179], v[184:187], v[114:117]
	v_mfma_f32_16x16x32_bf16 v[98:101], v[172:175], v[188:191], v[98:101]
	v_mfma_f32_16x16x32_bf16 v[98:101], v[176:179], v[192:195], v[98:101]
	v_mfma_f32_16x16x32_bf16 v[102:105], v[164:167], v[188:191], v[102:105]
	v_mfma_f32_16x16x32_bf16 v[102:105], v[168:171], v[192:195], v[102:105]
	v_mfma_f32_16x16x32_bf16 v[86:89], v[164:167], v[196:199], v[86:89]
	v_mfma_f32_16x16x32_bf16 v[86:89], v[168:171], v[200:203], v[86:89]
	v_mfma_f32_16x16x32_bf16 v[82:85], v[172:175], v[196:199], v[82:85]
	v_mfma_f32_16x16x32_bf16 v[82:85], v[176:179], v[200:203], v[82:85]
	v_mfma_f32_16x16x32_bf16 v[66:69], v[172:175], v[204:207], v[66:69]
	v_mfma_f32_16x16x32_bf16 v[66:69], v[176:179], v[208:211], v[66:69]
	s_setprio 2
	s_barrier
	v_mfma_f32_16x16x32_bf16 v[70:73], v[164:167], v[204:207], v[70:73]
	v_mfma_f32_16x16x32_bf16 v[70:73], v[168:171], v[208:211], v[70:73]
	s_setprio 0
	ds_read_b128 v[180:183], v145 offset:49152
	ds_read_b128 v[184:187], v145 offset:50176
	ds_read_b128 v[188:191], v145 offset:51200
	ds_read_b128 v[192:195], v145 offset:52224
	ds_read_b128 v[196:199], v145 offset:53248
	ds_read_b128 v[200:203], v145 offset:54272
	ds_read_b128 v[204:207], v145 offset:55296
	ds_read_b128 v[208:211], v145 offset:56320
	s_add_u32 s22, s20, 0x80
	s_addc_u32 s23, s21, 0
	s_mov_b32 s71, m0
	s_mov_b32 m0, s44
	s_nop 0
	global_load_lds_dwordx4 v139, s[22:23]
	s_mov_b32 m0, s71
	s_add_u32 s20, s20, 0x80080
	s_mov_b32 s71, m0
	s_mov_b32 m0, s45
	s_nop 0
	global_load_lds_dwordx4 v141, s[22:23]
	s_mov_b32 m0, s71
	s_addc_u32 s21, s21, 0
	s_mov_b32 s22, m0
	s_mov_b32 m0, s46
	s_nop 0
	global_load_lds_dwordx4 v139, s[20:21]
	s_mov_b32 m0, s22
	s_nop 0
	s_mov_b32 s22, m0
	s_mov_b32 m0, s47
	s_nop 0
	global_load_lds_dwordx4 v141, s[20:21]
	s_mov_b32 m0, s22
	s_waitcnt vmcnt(4)
	s_waitcnt lgkmcnt(0)
	s_waitcnt lgkmcnt(7)
	v_mfma_f32_16x16x32_bf16 v[62:65], v[148:151], v[180:183], v[62:65]
	v_mfma_f32_16x16x32_bf16 v[62:65], v[152:155], v[184:187], v[62:65]
	s_waitcnt lgkmcnt(5)
	v_mfma_f32_16x16x32_bf16 v[58:61], v[156:159], v[180:183], v[58:61]
	v_mfma_f32_16x16x32_bf16 v[58:61], v[160:163], v[184:187], v[58:61]
	s_barrier
	s_setprio 1
	s_waitcnt lgkmcnt(3)
	v_mfma_f32_16x16x32_bf16 v[42:45], v[156:159], v[188:191], v[42:45]
	v_mfma_f32_16x16x32_bf16 v[42:45], v[160:163], v[192:195], v[42:45]
	s_waitcnt lgkmcnt(1)
	v_mfma_f32_16x16x32_bf16 v[46:49], v[148:151], v[188:191], v[46:49]
	v_mfma_f32_16x16x32_bf16 v[46:49], v[152:155], v[192:195], v[46:49]
	v_mfma_f32_16x16x32_bf16 v[30:33], v[148:151], v[196:199], v[30:33]
	v_mfma_f32_16x16x32_bf16 v[30:33], v[152:155], v[200:203], v[30:33]
	v_mfma_f32_16x16x32_bf16 v[26:29], v[156:159], v[196:199], v[26:29]
	v_mfma_f32_16x16x32_bf16 v[26:29], v[160:163], v[200:203], v[26:29]
	v_mfma_f32_16x16x32_bf16 v[10:13], v[156:159], v[204:207], v[10:13]
	v_mfma_f32_16x16x32_bf16 v[10:13], v[160:163], v[208:211], v[10:13]
	s_waitcnt lgkmcnt(0)
	v_mfma_f32_16x16x32_bf16 v[14:17], v[148:151], v[204:207], v[14:17]
	v_mfma_f32_16x16x32_bf16 v[14:17], v[152:155], v[208:211], v[14:17]
	s_setprio 0
	s_setprio 1
	v_mfma_f32_16x16x32_bf16 v[54:57], v[164:167], v[180:183], v[54:57]
	v_mfma_f32_16x16x32_bf16 v[54:57], v[168:171], v[184:187], v[54:57]
	v_mfma_f32_16x16x32_bf16 v[50:53], v[172:175], v[180:183], v[50:53]
	v_mfma_f32_16x16x32_bf16 v[50:53], v[176:179], v[184:187], v[50:53]
	v_mfma_f32_16x16x32_bf16 v[34:37], v[172:175], v[188:191], v[34:37]
	v_mfma_f32_16x16x32_bf16 v[34:37], v[176:179], v[192:195], v[34:37]
	v_mfma_f32_16x16x32_bf16 v[38:41], v[164:167], v[188:191], v[38:41]
	v_mfma_f32_16x16x32_bf16 v[38:41], v[168:171], v[192:195], v[38:41]
	v_mfma_f32_16x16x32_bf16 v[22:25], v[164:167], v[196:199], v[22:25]
	v_mfma_f32_16x16x32_bf16 v[22:25], v[168:171], v[200:203], v[22:25]
	v_mfma_f32_16x16x32_bf16 v[18:21], v[172:175], v[196:199], v[18:21]
	v_mfma_f32_16x16x32_bf16 v[18:21], v[176:179], v[200:203], v[18:21]
	v_mfma_f32_16x16x32_bf16 v[2:5], v[172:175], v[204:207], v[2:5]
	v_mfma_f32_16x16x32_bf16 v[2:5], v[176:179], v[208:211], v[2:5]
	s_setprio 2
	s_barrier
	v_mfma_f32_16x16x32_bf16 v[6:9], v[164:167], v[204:207], v[6:9]
	v_mfma_f32_16x16x32_bf16 v[6:9], v[168:171], v[208:211], v[6:9]
	s_setprio 0
	s_add_i32 s70, s70, 2
	s_add_u32 s64, s64, 0x100
	s_addc_u32 s65, s65, 0
	s_add_u32 s18, s18, 0x100
	s_addc_u32 s19, s19, 0
	s_add_u32 s66, s66, 0x100
	s_addc_u32 s67, s67, 0
	s_cmp_gt_u32 s70, 29
	.p2align 6
.LBB0_2594:
	ds_read_b128 v[148:151], v143
	ds_read_b128 v[152:155], v143 offset:1024
	ds_read_b128 v[156:159], v143 offset:2048
	ds_read_b128 v[160:163], v143 offset:3072
	ds_read_b128 v[164:167], v144
	ds_read_b128 v[168:171], v144 offset:1024
	ds_read_b128 v[172:175], v144 offset:2048
	ds_read_b128 v[176:179], v144 offset:3072
	s_cmp_eq_u32 s70, 28
	s_cselect_b32 s21, s9, s65
	s_cselect_b32 s20, s63, s64
	s_cselect_b32 s23, s11, s67
	s_cselect_b32 s22, s62, s66
	ds_read_b128 v[180:183], v145
	ds_read_b128 v[184:187], v145 offset:1024
	ds_read_b128 v[188:191], v145 offset:2048
	ds_read_b128 v[192:195], v145 offset:3072
	ds_read_b128 v[196:199], v145 offset:4096
	ds_read_b128 v[200:203], v145 offset:5120
	ds_read_b128 v[204:207], v145 offset:6144
	ds_read_b128 v[208:211], v145 offset:7168
	s_add_u32 s74, s18, 0xfff80000
	s_addc_u32 s75, s19, -1
	s_mov_b32 s71, m0
	s_mov_b32 m0, s48
	s_nop 0
	global_load_lds_dwordx4 v138, s[74:75]
	s_mov_b32 m0, s71
	s_nop 0
	s_mov_b32 s71, m0
	s_mov_b32 m0, s57
	s_nop 0
	global_load_lds_dwordx4 v140, s[74:75]
	s_mov_b32 m0, s71
	s_nop 0
	s_mov_b32 s71, m0
	s_mov_b32 m0, s49
	s_nop 0
	global_load_lds_dwordx4 v138, s[18:19]
	s_mov_b32 m0, s71
	s_nop 0
	s_mov_b32 s71, m0
	s_mov_b32 m0, s58
	s_nop 0
	global_load_lds_dwordx4 v140, s[18:19]
	s_mov_b32 m0, s71
	s_waitcnt vmcnt(8)
	s_waitcnt lgkmcnt(0)
	s_waitcnt lgkmcnt(7)
	v_mfma_f32_16x16x32_bf16 v[126:129], v[148:151], v[180:183], v[126:129]
	v_mfma_f32_16x16x32_bf16 v[126:129], v[152:155], v[184:187], v[126:129]
	s_waitcnt lgkmcnt(5)
	v_mfma_f32_16x16x32_bf16 v[122:125], v[156:159], v[180:183], v[122:125]
	v_mfma_f32_16x16x32_bf16 v[122:125], v[160:163], v[184:187], v[122:125]
	s_barrier
	s_setprio 1
	s_waitcnt lgkmcnt(3)
	v_mfma_f32_16x16x32_bf16 v[106:109], v[156:159], v[188:191], v[106:109]
	v_mfma_f32_16x16x32_bf16 v[106:109], v[160:163], v[192:195], v[106:109]
	s_waitcnt lgkmcnt(1)
	v_mfma_f32_16x16x32_bf16 v[110:113], v[148:151], v[188:191], v[110:113]
	v_mfma_f32_16x16x32_bf16 v[110:113], v[152:155], v[192:195], v[110:113]
	v_mfma_f32_16x16x32_bf16 v[94:97], v[148:151], v[196:199], v[94:97]
	v_mfma_f32_16x16x32_bf16 v[94:97], v[152:155], v[200:203], v[94:97]
	v_mfma_f32_16x16x32_bf16 v[90:93], v[156:159], v[196:199], v[90:93]
	v_mfma_f32_16x16x32_bf16 v[90:93], v[160:163], v[200:203], v[90:93]
	v_mfma_f32_16x16x32_bf16 v[74:77], v[156:159], v[204:207], v[74:77]
	v_mfma_f32_16x16x32_bf16 v[74:77], v[160:163], v[208:211], v[74:77]
	s_waitcnt lgkmcnt(0)
	v_mfma_f32_16x16x32_bf16 v[78:81], v[148:151], v[204:207], v[78:81]
	v_mfma_f32_16x16x32_bf16 v[78:81], v[152:155], v[208:211], v[78:81]
	s_setprio 0
	s_setprio 1
	v_mfma_f32_16x16x32_bf16 v[118:121], v[164:167], v[180:183], v[118:121]
	v_mfma_f32_16x16x32_bf16 v[118:121], v[168:171], v[184:187], v[118:121]
	v_mfma_f32_16x16x32_bf16 v[114:117], v[172:175], v[180:183], v[114:117]
	v_mfma_f32_16x16x32_bf16 v[114:117], v[176:179], v[184:187], v[114:117]
	v_mfma_f32_16x16x32_bf16 v[98:101], v[172:175], v[188:191], v[98:101]
	v_mfma_f32_16x16x32_bf16 v[98:101], v[176:179], v[192:195], v[98:101]
	v_mfma_f32_16x16x32_bf16 v[102:105], v[164:167], v[188:191], v[102:105]
	v_mfma_f32_16x16x32_bf16 v[102:105], v[168:171], v[192:195], v[102:105]
	v_mfma_f32_16x16x32_bf16 v[86:89], v[164:167], v[196:199], v[86:89]
	v_mfma_f32_16x16x32_bf16 v[86:89], v[168:171], v[200:203], v[86:89]
	v_mfma_f32_16x16x32_bf16 v[82:85], v[172:175], v[196:199], v[82:85]
	v_mfma_f32_16x16x32_bf16 v[82:85], v[176:179], v[200:203], v[82:85]
	v_mfma_f32_16x16x32_bf16 v[66:69], v[172:175], v[204:207], v[66:69]
	v_mfma_f32_16x16x32_bf16 v[66:69], v[176:179], v[208:211], v[66:69]
	s_setprio 2
	s_barrier
	v_mfma_f32_16x16x32_bf16 v[70:73], v[164:167], v[204:207], v[70:73]
	v_mfma_f32_16x16x32_bf16 v[70:73], v[168:171], v[208:211], v[70:73]
	s_setprio 0
	ds_read_b128 v[180:183], v145 offset:16384
	ds_read_b128 v[184:187], v145 offset:17408
	ds_read_b128 v[188:191], v145 offset:18432
	ds_read_b128 v[192:195], v145 offset:19456
	ds_read_b128 v[196:199], v145 offset:20480
	ds_read_b128 v[200:203], v145 offset:21504
	ds_read_b128 v[204:207], v145 offset:22528
	ds_read_b128 v[208:211], v145 offset:23552
	s_mov_b32 s71, m0
	s_mov_b32 m0, s35
	s_nop 0
	global_load_lds_dwordx4 v139, s[20:21]
	s_mov_b32 m0, s71
	s_add_u32 s74, s20, 0x80000
	s_mov_b32 s71, m0
	s_mov_b32 m0, s36
	s_nop 0
	global_load_lds_dwordx4 v141, s[20:21]
	s_mov_b32 m0, s71
	s_addc_u32 s75, s21, 0
	s_mov_b32 s71, m0
	s_mov_b32 m0, s37
	s_nop 0
	global_load_lds_dwordx4 v139, s[74:75]
	s_mov_b32 m0, s71
	s_nop 0
	s_mov_b32 s71, m0
	s_mov_b32 m0, s40
	s_nop 0
	global_load_lds_dwordx4 v141, s[74:75]
	s_mov_b32 m0, s71
	s_waitcnt vmcnt(4)
	s_waitcnt lgkmcnt(0)
	s_waitcnt lgkmcnt(7)
	v_mfma_f32_16x16x32_bf16 v[62:65], v[148:151], v[180:183], v[62:65]
	v_mfma_f32_16x16x32_bf16 v[62:65], v[152:155], v[184:187], v[62:65]
	s_waitcnt lgkmcnt(5)
	v_mfma_f32_16x16x32_bf16 v[58:61], v[156:159], v[180:183], v[58:61]
	v_mfma_f32_16x16x32_bf16 v[58:61], v[160:163], v[184:187], v[58:61]
	s_barrier
	s_setprio 1
	s_waitcnt lgkmcnt(3)
	v_mfma_f32_16x16x32_bf16 v[42:45], v[156:159], v[188:191], v[42:45]
	v_mfma_f32_16x16x32_bf16 v[42:45], v[160:163], v[192:195], v[42:45]
	s_waitcnt lgkmcnt(1)
	v_mfma_f32_16x16x32_bf16 v[46:49], v[148:151], v[188:191], v[46:49]
	v_mfma_f32_16x16x32_bf16 v[46:49], v[152:155], v[192:195], v[46:49]
	v_mfma_f32_16x16x32_bf16 v[30:33], v[148:151], v[196:199], v[30:33]
	v_mfma_f32_16x16x32_bf16 v[30:33], v[152:155], v[200:203], v[30:33]
	v_mfma_f32_16x16x32_bf16 v[26:29], v[156:159], v[196:199], v[26:29]
	v_mfma_f32_16x16x32_bf16 v[26:29], v[160:163], v[200:203], v[26:29]
	v_mfma_f32_16x16x32_bf16 v[10:13], v[156:159], v[204:207], v[10:13]
	v_mfma_f32_16x16x32_bf16 v[10:13], v[160:163], v[208:211], v[10:13]
	s_waitcnt lgkmcnt(0)
	v_mfma_f32_16x16x32_bf16 v[14:17], v[148:151], v[204:207], v[14:17]
	v_mfma_f32_16x16x32_bf16 v[14:17], v[152:155], v[208:211], v[14:17]
	s_setprio 0
	s_setprio 1
	v_mfma_f32_16x16x32_bf16 v[54:57], v[164:167], v[180:183], v[54:57]
	v_mfma_f32_16x16x32_bf16 v[54:57], v[168:171], v[184:187], v[54:57]
	v_mfma_f32_16x16x32_bf16 v[50:53], v[172:175], v[180:183], v[50:53]
	v_mfma_f32_16x16x32_bf16 v[50:53], v[176:179], v[184:187], v[50:53]
	v_mfma_f32_16x16x32_bf16 v[34:37], v[172:175], v[188:191], v[34:37]
	v_mfma_f32_16x16x32_bf16 v[34:37], v[176:179], v[192:195], v[34:37]
	v_mfma_f32_16x16x32_bf16 v[38:41], v[164:167], v[188:191], v[38:41]
	v_mfma_f32_16x16x32_bf16 v[38:41], v[168:171], v[192:195], v[38:41]
	v_mfma_f32_16x16x32_bf16 v[22:25], v[164:167], v[196:199], v[22:25]
	v_mfma_f32_16x16x32_bf16 v[22:25], v[168:171], v[200:203], v[22:25]
	v_mfma_f32_16x16x32_bf16 v[18:21], v[172:175], v[196:199], v[18:21]
	v_mfma_f32_16x16x32_bf16 v[18:21], v[176:179], v[200:203], v[18:21]
	v_mfma_f32_16x16x32_bf16 v[2:5], v[172:175], v[204:207], v[2:5]
	v_mfma_f32_16x16x32_bf16 v[2:5], v[176:179], v[208:211], v[2:5]
	s_setprio 2
	s_barrier
	v_mfma_f32_16x16x32_bf16 v[6:9], v[164:167], v[204:207], v[6:9]
	v_mfma_f32_16x16x32_bf16 v[6:9], v[168:171], v[208:211], v[6:9]
	s_setprio 0
	ds_read_b128 v[148:151], v146
	ds_read_b128 v[152:155], v146 offset:1024
	ds_read_b128 v[156:159], v146 offset:2048
	ds_read_b128 v[160:163], v146 offset:3072
	ds_read_b128 v[164:167], v147
	ds_read_b128 v[168:171], v147 offset:1024
	ds_read_b128 v[172:175], v147 offset:2048
	ds_read_b128 v[176:179], v147 offset:3072
	ds_read_b128 v[180:183], v145 offset:32768
	ds_read_b128 v[184:187], v145 offset:33792
	ds_read_b128 v[188:191], v145 offset:34816
	ds_read_b128 v[192:195], v145 offset:35840
	ds_read_b128 v[196:199], v145 offset:36864
	ds_read_b128 v[200:203], v145 offset:37888
	ds_read_b128 v[204:207], v145 offset:38912
	ds_read_b128 v[208:211], v145 offset:39936
	s_mov_b32 s71, m0
	s_mov_b32 m0, s31
	s_nop 0
	global_load_lds_dwordx4 v138, s[22:23]
	s_mov_b32 m0, s71
	s_nop 0
	s_mov_b32 s71, m0
	s_mov_b32 m0, s41
	s_nop 0
	global_load_lds_dwordx4 v140, s[22:23]
	s_mov_b32 m0, s71
	s_add_u32 s22, s22, 0x80000
	s_addc_u32 s23, s23, 0
	s_mov_b32 s71, m0
	s_mov_b32 m0, s42
	s_nop 0
	global_load_lds_dwordx4 v138, s[22:23]
	s_mov_b32 m0, s71
	s_nop 0
	s_mov_b32 s71, m0
	s_mov_b32 m0, s43
	s_nop 0
	global_load_lds_dwordx4 v140, s[22:23]
	s_mov_b32 m0, s71
	s_waitcnt vmcnt(8)
	s_waitcnt lgkmcnt(0)
	s_waitcnt lgkmcnt(7)
	v_mfma_f32_16x16x32_bf16 v[126:129], v[148:151], v[180:183], v[126:129]
	v_mfma_f32_16x16x32_bf16 v[126:129], v[152:155], v[184:187], v[126:129]
	s_waitcnt lgkmcnt(5)
	v_mfma_f32_16x16x32_bf16 v[122:125], v[156:159], v[180:183], v[122:125]
	v_mfma_f32_16x16x32_bf16 v[122:125], v[160:163], v[184:187], v[122:125]
	s_barrier
	s_setprio 1
	s_waitcnt lgkmcnt(3)
	v_mfma_f32_16x16x32_bf16 v[106:109], v[156:159], v[188:191], v[106:109]
	v_mfma_f32_16x16x32_bf16 v[106:109], v[160:163], v[192:195], v[106:109]
	s_waitcnt lgkmcnt(1)
	v_mfma_f32_16x16x32_bf16 v[110:113], v[148:151], v[188:191], v[110:113]
	v_mfma_f32_16x16x32_bf16 v[110:113], v[152:155], v[192:195], v[110:113]
	v_mfma_f32_16x16x32_bf16 v[94:97], v[148:151], v[196:199], v[94:97]
	v_mfma_f32_16x16x32_bf16 v[94:97], v[152:155], v[200:203], v[94:97]
	v_mfma_f32_16x16x32_bf16 v[90:93], v[156:159], v[196:199], v[90:93]
	v_mfma_f32_16x16x32_bf16 v[90:93], v[160:163], v[200:203], v[90:93]
	v_mfma_f32_16x16x32_bf16 v[74:77], v[156:159], v[204:207], v[74:77]
	v_mfma_f32_16x16x32_bf16 v[74:77], v[160:163], v[208:211], v[74:77]
	s_waitcnt lgkmcnt(0)
	v_mfma_f32_16x16x32_bf16 v[78:81], v[148:151], v[204:207], v[78:81]
	v_mfma_f32_16x16x32_bf16 v[78:81], v[152:155], v[208:211], v[78:81]
	s_setprio 0
	s_setprio 1
	v_mfma_f32_16x16x32_bf16 v[118:121], v[164:167], v[180:183], v[118:121]
	v_mfma_f32_16x16x32_bf16 v[118:121], v[168:171], v[184:187], v[118:121]
	v_mfma_f32_16x16x32_bf16 v[114:117], v[172:175], v[180:183], v[114:117]
	v_mfma_f32_16x16x32_bf16 v[114:117], v[176:179], v[184:187], v[114:117]
	v_mfma_f32_16x16x32_bf16 v[98:101], v[172:175], v[188:191], v[98:101]
	v_mfma_f32_16x16x32_bf16 v[98:101], v[176:179], v[192:195], v[98:101]
	v_mfma_f32_16x16x32_bf16 v[102:105], v[164:167], v[188:191], v[102:105]
	v_mfma_f32_16x16x32_bf16 v[102:105], v[168:171], v[192:195], v[102:105]
	v_mfma_f32_16x16x32_bf16 v[86:89], v[164:167], v[196:199], v[86:89]
	v_mfma_f32_16x16x32_bf16 v[86:89], v[168:171], v[200:203], v[86:89]
	v_mfma_f32_16x16x32_bf16 v[82:85], v[172:175], v[196:199], v[82:85]
	v_mfma_f32_16x16x32_bf16 v[82:85], v[176:179], v[200:203], v[82:85]
	v_mfma_f32_16x16x32_bf16 v[66:69], v[172:175], v[204:207], v[66:69]
	v_mfma_f32_16x16x32_bf16 v[66:69], v[176:179], v[208:211], v[66:69]
	s_setprio 2
	s_barrier
	v_mfma_f32_16x16x32_bf16 v[70:73], v[164:167], v[204:207], v[70:73]
	v_mfma_f32_16x16x32_bf16 v[70:73], v[168:171], v[208:211], v[70:73]
	s_setprio 0
	ds_read_b128 v[180:183], v145 offset:49152
	ds_read_b128 v[184:187], v145 offset:50176
	ds_read_b128 v[188:191], v145 offset:51200
	ds_read_b128 v[192:195], v145 offset:52224
	ds_read_b128 v[196:199], v145 offset:53248
	ds_read_b128 v[200:203], v145 offset:54272
	ds_read_b128 v[204:207], v145 offset:55296
	ds_read_b128 v[208:211], v145 offset:56320
	s_add_u32 s22, s20, 0x80
	s_addc_u32 s23, s21, 0
	s_mov_b32 s71, m0
	s_mov_b32 m0, s44
	s_nop 0
	global_load_lds_dwordx4 v139, s[22:23]
	s_mov_b32 m0, s71
	s_add_u32 s20, s20, 0x80080
	s_mov_b32 s71, m0
	s_mov_b32 m0, s45
	s_nop 0
	global_load_lds_dwordx4 v141, s[22:23]
	s_mov_b32 m0, s71
	s_addc_u32 s21, s21, 0
	s_mov_b32 s22, m0
	s_mov_b32 m0, s46
	s_nop 0
	global_load_lds_dwordx4 v139, s[20:21]
	s_mov_b32 m0, s22
	s_nop 0
	s_mov_b32 s22, m0
	s_mov_b32 m0, s47
	s_nop 0
	global_load_lds_dwordx4 v141, s[20:21]
	s_mov_b32 m0, s22
	s_waitcnt vmcnt(4)
	s_waitcnt lgkmcnt(0)
	s_waitcnt lgkmcnt(7)
	v_mfma_f32_16x16x32_bf16 v[62:65], v[148:151], v[180:183], v[62:65]
	v_mfma_f32_16x16x32_bf16 v[62:65], v[152:155], v[184:187], v[62:65]
	s_waitcnt lgkmcnt(5)
	v_mfma_f32_16x16x32_bf16 v[58:61], v[156:159], v[180:183], v[58:61]
	v_mfma_f32_16x16x32_bf16 v[58:61], v[160:163], v[184:187], v[58:61]
	s_barrier
	s_setprio 1
	s_waitcnt lgkmcnt(3)
	v_mfma_f32_16x16x32_bf16 v[42:45], v[156:159], v[188:191], v[42:45]
	v_mfma_f32_16x16x32_bf16 v[42:45], v[160:163], v[192:195], v[42:45]
	s_waitcnt lgkmcnt(1)
	v_mfma_f32_16x16x32_bf16 v[46:49], v[148:151], v[188:191], v[46:49]
	v_mfma_f32_16x16x32_bf16 v[46:49], v[152:155], v[192:195], v[46:49]
	v_mfma_f32_16x16x32_bf16 v[30:33], v[148:151], v[196:199], v[30:33]
	v_mfma_f32_16x16x32_bf16 v[30:33], v[152:155], v[200:203], v[30:33]
	v_mfma_f32_16x16x32_bf16 v[26:29], v[156:159], v[196:199], v[26:29]
	v_mfma_f32_16x16x32_bf16 v[26:29], v[160:163], v[200:203], v[26:29]
	v_mfma_f32_16x16x32_bf16 v[10:13], v[156:159], v[204:207], v[10:13]
	v_mfma_f32_16x16x32_bf16 v[10:13], v[160:163], v[208:211], v[10:13]
	s_waitcnt lgkmcnt(0)
	v_mfma_f32_16x16x32_bf16 v[14:17], v[148:151], v[204:207], v[14:17]
	v_mfma_f32_16x16x32_bf16 v[14:17], v[152:155], v[208:211], v[14:17]
	s_setprio 0
	s_setprio 1
	v_mfma_f32_16x16x32_bf16 v[54:57], v[164:167], v[180:183], v[54:57]
	v_mfma_f32_16x16x32_bf16 v[54:57], v[168:171], v[184:187], v[54:57]
	v_mfma_f32_16x16x32_bf16 v[50:53], v[172:175], v[180:183], v[50:53]
	v_mfma_f32_16x16x32_bf16 v[50:53], v[176:179], v[184:187], v[50:53]
	v_mfma_f32_16x16x32_bf16 v[34:37], v[172:175], v[188:191], v[34:37]
	v_mfma_f32_16x16x32_bf16 v[34:37], v[176:179], v[192:195], v[34:37]
	v_mfma_f32_16x16x32_bf16 v[38:41], v[164:167], v[188:191], v[38:41]
	v_mfma_f32_16x16x32_bf16 v[38:41], v[168:171], v[192:195], v[38:41]
	v_mfma_f32_16x16x32_bf16 v[22:25], v[164:167], v[196:199], v[22:25]
	v_mfma_f32_16x16x32_bf16 v[22:25], v[168:171], v[200:203], v[22:25]
	v_mfma_f32_16x16x32_bf16 v[18:21], v[172:175], v[196:199], v[18:21]
	v_mfma_f32_16x16x32_bf16 v[18:21], v[176:179], v[200:203], v[18:21]
	v_mfma_f32_16x16x32_bf16 v[2:5], v[172:175], v[204:207], v[2:5]
	v_mfma_f32_16x16x32_bf16 v[2:5], v[176:179], v[208:211], v[2:5]
	s_setprio 2
	s_barrier
	v_mfma_f32_16x16x32_bf16 v[6:9], v[164:167], v[204:207], v[6:9]
	v_mfma_f32_16x16x32_bf16 v[6:9], v[168:171], v[208:211], v[6:9]
	s_setprio 0
	s_add_i32 s70, s70, 2
	s_add_u32 s64, s64, 0x100
	s_addc_u32 s65, s65, 0
	s_add_u32 s18, s18, 0x100
	s_addc_u32 s19, s19, 0
	s_add_u32 s66, s66, 0x100
	s_addc_u32 s67, s67, 0
	s_cmp_gt_u32 s70, 29
	s_cbranch_scc0 .LBB0_2594
	s_and_b64 vcc, exec, s[6:7]
	s_cbranch_vccz .LBB0_2597
	s_barrier

.LBB0_2791:
	s_ashr_i32 s21, s20, 31
	s_lshl_b64 s[22:23], s[20:21], 15
	s_add_u32 s22, s37, s22
	s_addc_u32 s23, s40, s23
	s_and_b64 s[24:25], s[2:3], exec
	s_cselect_b32 s21, s23, s31
	s_cselect_b32 s63, s22, s30
	s_ashr_i32 s19, s18, 31
	s_lshl_b64 s[24:25], s[18:19], 15
	s_add_u32 s24, s41, s24
	s_addc_u32 s25, s42, s25
	s_and_b64 s[34:35], s[2:3], exec
	s_cselect_b32 s19, s25, s29
	s_cselect_b32 s64, s24, s28
	s_add_u32 s65, s28, 0x80000
	s_addc_u32 s66, s29, 0
	s_add_u32 s28, s30, 0x204000
	s_addc_u32 s29, s31, 0
	s_add_u32 s67, s30, 0x400000
	s_addc_u32 s68, s31, 0
	s_mov_b32 s69, -2
	s_waitcnt vmcnt(25)
	s_waitcnt vmcnt(24)
	s_waitcnt vmcnt(4)
	s_waitcnt vmcnt(2)
	s_waitcnt vmcnt(1)
	s_waitcnt vmcnt(0)
	ds_read_b128 v[130:133], v181
	ds_read_b128 v[134:137], v181 offset:1024
	ds_read_b128 v[138:141], v181 offset:2048
	ds_read_b128 v[142:145], v181 offset:3072
	ds_read_b128 v[150:153], v182
	ds_read_b128 v[154:157], v182 offset:1024
	ds_read_b128 v[158:161], v182 offset:2048
	ds_read_b128 v[162:165], v182 offset:3072
	s_cmpk_eq_i32 s69, 0x52
	s_cselect_b32 s31, s19, s66
	s_cselect_b32 s30, s64, s65
	s_cselect_b32 s35, s21, s68
	s_cselect_b32 s34, s63, s67
	ds_read_b128 v[166:169], v183
	ds_read_b128 v[170:173], v183 offset:1024
	ds_read_b128 v[186:189], v183 offset:2048
	ds_read_b128 v[190:193], v183 offset:3072
	ds_read_b128 v[194:197], v183 offset:4096
	ds_read_b128 v[198:201], v183 offset:5120
	ds_read_b128 v[202:205], v183 offset:6144
	ds_read_b128 v[206:209], v183 offset:7168
	s_add_u32 s70, s28, 0xffffc000
	s_addc_u32 s71, s29, -1
	s_mov_b32 s73, m0
	s_mov_b32 m0, s57
	s_nop 0
	global_load_lds_dwordx4 v1, s[70:71]
	s_mov_b32 m0, s73
	s_nop 0
	s_mov_b32 s73, m0
	s_mov_b32 m0, s59
	s_nop 0
	global_load_lds_dwordx4 v177, s[70:71]
	s_mov_b32 m0, s73
	s_mov_b32 s70, m0
	s_mov_b32 m0, s58
	s_nop 0
	global_load_lds_dwordx4 v1, s[28:29]
	s_mov_b32 m0, s70
	s_nop 0
	s_mov_b32 s70, m0
	s_mov_b32 m0, s60
	s_nop 0
	global_load_lds_dwordx4 v177, s[28:29]
	s_mov_b32 m0, s70
	s_waitcnt vmcnt(8)
	s_waitcnt lgkmcnt(0)
	s_waitcnt lgkmcnt(7)
	v_mfma_f32_16x16x32_bf16 v[126:129], v[130:133], v[166:169], 0
	v_mfma_f32_16x16x32_bf16 v[126:129], v[134:137], v[170:173], v[126:129]
	s_waitcnt lgkmcnt(5)
	v_mfma_f32_16x16x32_bf16 v[122:125], v[138:141], v[166:169], 0
	v_mfma_f32_16x16x32_bf16 v[122:125], v[142:145], v[170:173], v[122:125]
	s_barrier
	s_setprio 1
	s_waitcnt lgkmcnt(3)
	v_mfma_f32_16x16x32_bf16 v[110:113], v[138:141], v[186:189], 0
	v_mfma_f32_16x16x32_bf16 v[110:113], v[142:145], v[190:193], v[110:113]
	s_waitcnt lgkmcnt(1)
	v_mfma_f32_16x16x32_bf16 v[118:121], v[130:133], v[186:189], 0
	v_mfma_f32_16x16x32_bf16 v[118:121], v[134:137], v[190:193], v[118:121]
	v_mfma_f32_16x16x32_bf16 v[94:97], v[130:133], v[194:197], 0
	v_mfma_f32_16x16x32_bf16 v[94:97], v[134:137], v[198:201], v[94:97]
	v_mfma_f32_16x16x32_bf16 v[90:93], v[138:141], v[194:197], 0
	v_mfma_f32_16x16x32_bf16 v[90:93], v[142:145], v[198:201], v[90:93]
	v_mfma_f32_16x16x32_bf16 v[78:81], v[138:141], v[202:205], 0
	v_mfma_f32_16x16x32_bf16 v[78:81], v[142:145], v[206:209], v[78:81]
	s_waitcnt lgkmcnt(0)
	v_mfma_f32_16x16x32_bf16 v[86:89], v[130:133], v[202:205], 0
	v_mfma_f32_16x16x32_bf16 v[86:89], v[134:137], v[206:209], v[86:89]
	s_setprio 0
	s_setprio 1
	v_mfma_f32_16x16x32_bf16 v[114:117], v[150:153], v[166:169], 0
	v_mfma_f32_16x16x32_bf16 v[114:117], v[154:157], v[170:173], v[114:117]
	v_mfma_f32_16x16x32_bf16 v[106:109], v[158:161], v[166:169], 0
	v_mfma_f32_16x16x32_bf16 v[106:109], v[162:165], v[170:173], v[106:109]
	v_mfma_f32_16x16x32_bf16 v[98:101], v[158:161], v[186:189], 0
	v_mfma_f32_16x16x32_bf16 v[98:101], v[162:165], v[190:193], v[98:101]
	v_mfma_f32_16x16x32_bf16 v[102:105], v[150:153], v[186:189], 0
	v_mfma_f32_16x16x32_bf16 v[102:105], v[154:157], v[190:193], v[102:105]
	v_mfma_f32_16x16x32_bf16 v[82:85], v[150:153], v[194:197], 0
	v_mfma_f32_16x16x32_bf16 v[82:85], v[154:157], v[198:201], v[82:85]
	v_mfma_f32_16x16x32_bf16 v[74:77], v[158:161], v[194:197], 0
	v_mfma_f32_16x16x32_bf16 v[74:77], v[162:165], v[198:201], v[74:77]
	v_mfma_f32_16x16x32_bf16 v[66:69], v[158:161], v[202:205], 0
	v_mfma_f32_16x16x32_bf16 v[66:69], v[162:165], v[206:209], v[66:69]
	s_setprio 2
	s_barrier
	v_mfma_f32_16x16x32_bf16 v[70:73], v[150:153], v[202:205], 0
	v_mfma_f32_16x16x32_bf16 v[70:73], v[154:157], v[206:209], v[70:73]
	s_setprio 0
	ds_read_b128 v[166:169], v183 offset:16384
	ds_read_b128 v[170:173], v183 offset:17408
	ds_read_b128 v[186:189], v183 offset:18432
	ds_read_b128 v[190:193], v183 offset:19456
	ds_read_b128 v[194:197], v183 offset:20480
	ds_read_b128 v[198:201], v183 offset:21504
	ds_read_b128 v[202:205], v183 offset:22528
	ds_read_b128 v[206:209], v183 offset:23552
	s_mov_b32 s70, m0
	s_mov_b32 m0, s27
	s_nop 0
	global_load_lds_dwordx4 v176, s[30:31]
	s_mov_b32 m0, s70
	s_nop 0
	s_mov_b32 s70, m0
	s_mov_b32 m0, s45
	s_nop 0
	global_load_lds_dwordx4 v178, s[30:31]
	s_mov_b32 m0, s70
	s_add_u32 s70, s30, 0x4000
	s_addc_u32 s71, s31, 0
	s_mov_b32 s73, m0
	s_mov_b32 m0, s46
	s_nop 0
	global_load_lds_dwordx4 v176, s[70:71]
	s_mov_b32 m0, s73
	s_nop 0
	s_mov_b32 s73, m0
	s_mov_b32 m0, s47
	s_nop 0
	global_load_lds_dwordx4 v178, s[70:71]
	s_mov_b32 m0, s73
	s_waitcnt vmcnt(4)
	s_waitcnt lgkmcnt(0)
	s_waitcnt lgkmcnt(7)
	v_mfma_f32_16x16x32_bf16 v[62:65], v[130:133], v[166:169], 0
	v_mfma_f32_16x16x32_bf16 v[62:65], v[134:137], v[170:173], v[62:65]
	s_waitcnt lgkmcnt(5)
	v_mfma_f32_16x16x32_bf16 v[58:61], v[138:141], v[166:169], 0
	v_mfma_f32_16x16x32_bf16 v[58:61], v[142:145], v[170:173], v[58:61]
	s_barrier
	s_setprio 1
	s_waitcnt lgkmcnt(3)
	v_mfma_f32_16x16x32_bf16 v[42:45], v[138:141], v[186:189], 0
	v_mfma_f32_16x16x32_bf16 v[42:45], v[142:145], v[190:193], v[42:45]
	s_waitcnt lgkmcnt(1)
	v_mfma_f32_16x16x32_bf16 v[46:49], v[130:133], v[186:189], 0
	v_mfma_f32_16x16x32_bf16 v[46:49], v[134:137], v[190:193], v[46:49]
	v_mfma_f32_16x16x32_bf16 v[30:33], v[130:133], v[194:197], 0
	v_mfma_f32_16x16x32_bf16 v[30:33], v[134:137], v[198:201], v[30:33]
	v_mfma_f32_16x16x32_bf16 v[26:29], v[138:141], v[194:197], 0
	v_mfma_f32_16x16x32_bf16 v[26:29], v[142:145], v[198:201], v[26:29]
	v_mfma_f32_16x16x32_bf16 v[10:13], v[138:141], v[202:205], 0
	v_mfma_f32_16x16x32_bf16 v[10:13], v[142:145], v[206:209], v[10:13]
	s_waitcnt lgkmcnt(0)
	v_mfma_f32_16x16x32_bf16 v[14:17], v[130:133], v[202:205], 0
	v_mfma_f32_16x16x32_bf16 v[14:17], v[134:137], v[206:209], v[14:17]
	s_setprio 0
	s_setprio 1
	v_mfma_f32_16x16x32_bf16 v[54:57], v[150:153], v[166:169], 0
	v_mfma_f32_16x16x32_bf16 v[54:57], v[154:157], v[170:173], v[54:57]
	v_mfma_f32_16x16x32_bf16 v[50:53], v[158:161], v[166:169], 0
	v_mfma_f32_16x16x32_bf16 v[50:53], v[162:165], v[170:173], v[50:53]
	v_mfma_f32_16x16x32_bf16 v[34:37], v[158:161], v[186:189], 0
	v_mfma_f32_16x16x32_bf16 v[34:37], v[162:165], v[190:193], v[34:37]
	v_mfma_f32_16x16x32_bf16 v[38:41], v[150:153], v[186:189], 0
	v_mfma_f32_16x16x32_bf16 v[38:41], v[154:157], v[190:193], v[38:41]
	v_mfma_f32_16x16x32_bf16 v[22:25], v[150:153], v[194:197], 0
	v_mfma_f32_16x16x32_bf16 v[22:25], v[154:157], v[198:201], v[22:25]
	v_mfma_f32_16x16x32_bf16 v[18:21], v[158:161], v[194:197], 0
	v_mfma_f32_16x16x32_bf16 v[18:21], v[162:165], v[198:201], v[18:21]
	v_mfma_f32_16x16x32_bf16 v[2:5], v[158:161], v[202:205], 0
	v_mfma_f32_16x16x32_bf16 v[2:5], v[162:165], v[206:209], v[2:5]
	s_setprio 2
	s_barrier
	v_mfma_f32_16x16x32_bf16 v[6:9], v[150:153], v[202:205], 0
	v_mfma_f32_16x16x32_bf16 v[6:9], v[154:157], v[206:209], v[6:9]
	s_setprio 0
	ds_read_b128 v[130:133], v184
	ds_read_b128 v[134:137], v184 offset:1024
	ds_read_b128 v[138:141], v184 offset:2048
	ds_read_b128 v[142:145], v184 offset:3072
	ds_read_b128 v[150:153], v185
	ds_read_b128 v[154:157], v185 offset:1024
	ds_read_b128 v[158:161], v185 offset:2048
	ds_read_b128 v[162:165], v185 offset:3072
	ds_read_b128 v[166:169], v183 offset:32768
	ds_read_b128 v[170:173], v183 offset:33792
	ds_read_b128 v[186:189], v183 offset:34816
	ds_read_b128 v[190:193], v183 offset:35840
	ds_read_b128 v[194:197], v183 offset:36864
	ds_read_b128 v[198:201], v183 offset:37888
	ds_read_b128 v[202:205], v183 offset:38912
	ds_read_b128 v[206:209], v183 offset:39936
	s_mov_b32 s70, m0
	s_mov_b32 m0, s44
	s_nop 0
	global_load_lds_dwordx4 v1, s[34:35]
	s_mov_b32 m0, s70
	s_nop 0
	s_mov_b32 s70, m0
	s_mov_b32 m0, s48
	s_nop 0
	global_load_lds_dwordx4 v177, s[34:35]
	s_mov_b32 m0, s70
	s_add_u32 s34, s34, 0x4000
	s_addc_u32 s35, s35, 0
	s_mov_b32 s70, m0
	s_mov_b32 m0, s49
	s_nop 0
	global_load_lds_dwordx4 v1, s[34:35]
	s_mov_b32 m0, s70
	s_nop 0
	s_mov_b32 s70, m0
	s_mov_b32 m0, s50
	s_nop 0
	global_load_lds_dwordx4 v177, s[34:35]
	s_mov_b32 m0, s70
	s_waitcnt vmcnt(8)
	s_waitcnt lgkmcnt(0)
	s_waitcnt lgkmcnt(7)
	v_mfma_f32_16x16x32_bf16 v[126:129], v[130:133], v[166:169], v[126:129]
	v_mfma_f32_16x16x32_bf16 v[126:129], v[134:137], v[170:173], v[126:129]
	s_waitcnt lgkmcnt(5)
	v_mfma_f32_16x16x32_bf16 v[122:125], v[138:141], v[166:169], v[122:125]
	v_mfma_f32_16x16x32_bf16 v[122:125], v[142:145], v[170:173], v[122:125]
	s_barrier
	s_setprio 1
	s_waitcnt lgkmcnt(3)
	v_mfma_f32_16x16x32_bf16 v[110:113], v[138:141], v[186:189], v[110:113]
	v_mfma_f32_16x16x32_bf16 v[110:113], v[142:145], v[190:193], v[110:113]
	s_waitcnt lgkmcnt(1)
	v_mfma_f32_16x16x32_bf16 v[118:121], v[130:133], v[186:189], v[118:121]
	v_mfma_f32_16x16x32_bf16 v[118:121], v[134:137], v[190:193], v[118:121]
	v_mfma_f32_16x16x32_bf16 v[94:97], v[130:133], v[194:197], v[94:97]
	v_mfma_f32_16x16x32_bf16 v[94:97], v[134:137], v[198:201], v[94:97]
	v_mfma_f32_16x16x32_bf16 v[90:93], v[138:141], v[194:197], v[90:93]
	v_mfma_f32_16x16x32_bf16 v[90:93], v[142:145], v[198:201], v[90:93]
	v_mfma_f32_16x16x32_bf16 v[78:81], v[138:141], v[202:205], v[78:81]
	v_mfma_f32_16x16x32_bf16 v[78:81], v[142:145], v[206:209], v[78:81]
	s_waitcnt lgkmcnt(0)
	v_mfma_f32_16x16x32_bf16 v[86:89], v[130:133], v[202:205], v[86:89]
	v_mfma_f32_16x16x32_bf16 v[86:89], v[134:137], v[206:209], v[86:89]
	s_setprio 0
	s_setprio 1
	v_mfma_f32_16x16x32_bf16 v[114:117], v[150:153], v[166:169], v[114:117]
	v_mfma_f32_16x16x32_bf16 v[114:117], v[154:157], v[170:173], v[114:117]
	v_mfma_f32_16x16x32_bf16 v[106:109], v[158:161], v[166:169], v[106:109]
	v_mfma_f32_16x16x32_bf16 v[106:109], v[162:165], v[170:173], v[106:109]
	v_mfma_f32_16x16x32_bf16 v[98:101], v[158:161], v[186:189], v[98:101]
	v_mfma_f32_16x16x32_bf16 v[98:101], v[162:165], v[190:193], v[98:101]
	v_mfma_f32_16x16x32_bf16 v[102:105], v[150:153], v[186:189], v[102:105]
	v_mfma_f32_16x16x32_bf16 v[102:105], v[154:157], v[190:193], v[102:105]
	v_mfma_f32_16x16x32_bf16 v[82:85], v[150:153], v[194:197], v[82:85]
	v_mfma_f32_16x16x32_bf16 v[82:85], v[154:157], v[198:201], v[82:85]
	v_mfma_f32_16x16x32_bf16 v[74:77], v[158:161], v[194:197], v[74:77]
	v_mfma_f32_16x16x32_bf16 v[74:77], v[162:165], v[198:201], v[74:77]
	v_mfma_f32_16x16x32_bf16 v[66:69], v[158:161], v[202:205], v[66:69]
	v_mfma_f32_16x16x32_bf16 v[66:69], v[162:165], v[206:209], v[66:69]
	s_setprio 2
	s_barrier
	v_mfma_f32_16x16x32_bf16 v[70:73], v[150:153], v[202:205], v[70:73]
	v_mfma_f32_16x16x32_bf16 v[70:73], v[154:157], v[206:209], v[70:73]
	s_setprio 0
	ds_read_b128 v[166:169], v183 offset:49152
	ds_read_b128 v[170:173], v183 offset:50176
	ds_read_b128 v[186:189], v183 offset:51200
	ds_read_b128 v[190:193], v183 offset:52224
	ds_read_b128 v[194:197], v183 offset:53248
	ds_read_b128 v[198:201], v183 offset:54272
	ds_read_b128 v[202:205], v183 offset:55296
	ds_read_b128 v[206:209], v183 offset:56320
	s_add_u32 s34, s30, 0x40000
	s_addc_u32 s35, s31, 0
	s_mov_b32 s70, m0
	s_mov_b32 m0, s51
	s_nop 0
	global_load_lds_dwordx4 v176, s[34:35]
	s_mov_b32 m0, s70
	s_add_u32 s30, s30, 0x44000
	s_mov_b32 s70, m0
	s_mov_b32 m0, s52
	s_nop 0
	global_load_lds_dwordx4 v178, s[34:35]
	s_mov_b32 m0, s70
	s_addc_u32 s31, s31, 0
	s_mov_b32 s34, m0
	s_mov_b32 m0, s53
	s_nop 0
	global_load_lds_dwordx4 v176, s[30:31]
	s_mov_b32 m0, s34
	s_nop 0
	s_mov_b32 s34, m0
	s_mov_b32 m0, s54
	s_nop 0
	global_load_lds_dwordx4 v178, s[30:31]
	s_mov_b32 m0, s34
	s_waitcnt vmcnt(4)
	s_waitcnt lgkmcnt(0)
	s_waitcnt lgkmcnt(7)
	v_mfma_f32_16x16x32_bf16 v[62:65], v[130:133], v[166:169], v[62:65]
	v_mfma_f32_16x16x32_bf16 v[62:65], v[134:137], v[170:173], v[62:65]
	s_waitcnt lgkmcnt(5)
	v_mfma_f32_16x16x32_bf16 v[58:61], v[138:141], v[166:169], v[58:61]
	v_mfma_f32_16x16x32_bf16 v[58:61], v[142:145], v[170:173], v[58:61]
	s_barrier
	s_setprio 1
	s_waitcnt lgkmcnt(3)
	v_mfma_f32_16x16x32_bf16 v[42:45], v[138:141], v[186:189], v[42:45]
	v_mfma_f32_16x16x32_bf16 v[42:45], v[142:145], v[190:193], v[42:45]
	s_waitcnt lgkmcnt(1)
	v_mfma_f32_16x16x32_bf16 v[46:49], v[130:133], v[186:189], v[46:49]
	v_mfma_f32_16x16x32_bf16 v[46:49], v[134:137], v[190:193], v[46:49]
	v_mfma_f32_16x16x32_bf16 v[30:33], v[130:133], v[194:197], v[30:33]
	v_mfma_f32_16x16x32_bf16 v[30:33], v[134:137], v[198:201], v[30:33]
	v_mfma_f32_16x16x32_bf16 v[26:29], v[138:141], v[194:197], v[26:29]
	v_mfma_f32_16x16x32_bf16 v[26:29], v[142:145], v[198:201], v[26:29]
	v_mfma_f32_16x16x32_bf16 v[10:13], v[138:141], v[202:205], v[10:13]
	v_mfma_f32_16x16x32_bf16 v[10:13], v[142:145], v[206:209], v[10:13]
	s_waitcnt lgkmcnt(0)
	v_mfma_f32_16x16x32_bf16 v[14:17], v[130:133], v[202:205], v[14:17]
	v_mfma_f32_16x16x32_bf16 v[14:17], v[134:137], v[206:209], v[14:17]
	s_setprio 0
	s_setprio 1
	v_mfma_f32_16x16x32_bf16 v[54:57], v[150:153], v[166:169], v[54:57]
	v_mfma_f32_16x16x32_bf16 v[54:57], v[154:157], v[170:173], v[54:57]
	v_mfma_f32_16x16x32_bf16 v[50:53], v[158:161], v[166:169], v[50:53]
	v_mfma_f32_16x16x32_bf16 v[50:53], v[162:165], v[170:173], v[50:53]
	v_mfma_f32_16x16x32_bf16 v[34:37], v[158:161], v[186:189], v[34:37]
	v_mfma_f32_16x16x32_bf16 v[34:37], v[162:165], v[190:193], v[34:37]
	v_mfma_f32_16x16x32_bf16 v[38:41], v[150:153], v[186:189], v[38:41]
	v_mfma_f32_16x16x32_bf16 v[38:41], v[154:157], v[190:193], v[38:41]
	v_mfma_f32_16x16x32_bf16 v[22:25], v[150:153], v[194:197], v[22:25]
	v_mfma_f32_16x16x32_bf16 v[22:25], v[154:157], v[198:201], v[22:25]
	v_mfma_f32_16x16x32_bf16 v[18:21], v[158:161], v[194:197], v[18:21]
	v_mfma_f32_16x16x32_bf16 v[18:21], v[162:165], v[198:201], v[18:21]
	v_mfma_f32_16x16x32_bf16 v[2:5], v[158:161], v[202:205], v[2:5]
	v_mfma_f32_16x16x32_bf16 v[2:5], v[162:165], v[206:209], v[2:5]
	s_setprio 2
	s_barrier
	v_mfma_f32_16x16x32_bf16 v[6:9], v[150:153], v[202:205], v[6:9]
	v_mfma_f32_16x16x32_bf16 v[6:9], v[154:157], v[206:209], v[6:9]
	s_setprio 0
	s_add_i32 s69, s69, 2
	s_add_u32 s65, s65, 0x80000
	s_addc_u32 s66, s66, 0
	s_add_u32 s28, s28, 0x400000
	s_addc_u32 s29, s29, 0
	s_add_u32 s67, s67, 0x400000
	s_addc_u32 s68, s68, 0
	s_cmpk_gt_u32 s69, 0x53
	.p2align 6
.LBB0_2792:
	ds_read_b128 v[130:133], v181
	ds_read_b128 v[134:137], v181 offset:1024
	ds_read_b128 v[138:141], v181 offset:2048
	ds_read_b128 v[142:145], v181 offset:3072
	ds_read_b128 v[150:153], v182
	ds_read_b128 v[154:157], v182 offset:1024
	ds_read_b128 v[158:161], v182 offset:2048
	ds_read_b128 v[162:165], v182 offset:3072
	s_cmpk_eq_i32 s69, 0x52
	s_cselect_b32 s31, s19, s66
	s_cselect_b32 s30, s64, s65
	s_cselect_b32 s35, s21, s68
	s_cselect_b32 s34, s63, s67
	ds_read_b128 v[166:169], v183
	ds_read_b128 v[170:173], v183 offset:1024
	ds_read_b128 v[186:189], v183 offset:2048
	ds_read_b128 v[190:193], v183 offset:3072
	ds_read_b128 v[194:197], v183 offset:4096
	ds_read_b128 v[198:201], v183 offset:5120
	ds_read_b128 v[202:205], v183 offset:6144
	ds_read_b128 v[206:209], v183 offset:7168
	s_add_u32 s70, s28, 0xffffc000
	s_addc_u32 s71, s29, -1
	s_mov_b32 s73, m0
	s_mov_b32 m0, s57
	s_nop 0
	global_load_lds_dwordx4 v1, s[70:71]
	s_mov_b32 m0, s73
	s_nop 0
	s_mov_b32 s73, m0
	s_mov_b32 m0, s59
	s_nop 0
	global_load_lds_dwordx4 v177, s[70:71]
	s_mov_b32 m0, s73
	s_mov_b32 s70, m0
	s_mov_b32 m0, s58
	s_nop 0
	global_load_lds_dwordx4 v1, s[28:29]
	s_mov_b32 m0, s70
	s_nop 0
	s_mov_b32 s70, m0
	s_mov_b32 m0, s60
	s_nop 0
	global_load_lds_dwordx4 v177, s[28:29]
	s_mov_b32 m0, s70
	s_waitcnt vmcnt(8)
	s_waitcnt lgkmcnt(0)
	s_waitcnt lgkmcnt(7)
	v_mfma_f32_16x16x32_bf16 v[126:129], v[130:133], v[166:169], v[126:129]
	v_mfma_f32_16x16x32_bf16 v[126:129], v[134:137], v[170:173], v[126:129]
	s_waitcnt lgkmcnt(5)
	v_mfma_f32_16x16x32_bf16 v[122:125], v[138:141], v[166:169], v[122:125]
	v_mfma_f32_16x16x32_bf16 v[122:125], v[142:145], v[170:173], v[122:125]
	s_barrier
	s_setprio 1
	s_waitcnt lgkmcnt(3)
	v_mfma_f32_16x16x32_bf16 v[110:113], v[138:141], v[186:189], v[110:113]
	v_mfma_f32_16x16x32_bf16 v[110:113], v[142:145], v[190:193], v[110:113]
	s_waitcnt lgkmcnt(1)
	v_mfma_f32_16x16x32_bf16 v[118:121], v[130:133], v[186:189], v[118:121]
	v_mfma_f32_16x16x32_bf16 v[118:121], v[134:137], v[190:193], v[118:121]
	v_mfma_f32_16x16x32_bf16 v[94:97], v[130:133], v[194:197], v[94:97]
	v_mfma_f32_16x16x32_bf16 v[94:97], v[134:137], v[198:201], v[94:97]
	v_mfma_f32_16x16x32_bf16 v[90:93], v[138:141], v[194:197], v[90:93]
	v_mfma_f32_16x16x32_bf16 v[90:93], v[142:145], v[198:201], v[90:93]
	v_mfma_f32_16x16x32_bf16 v[78:81], v[138:141], v[202:205], v[78:81]
	v_mfma_f32_16x16x32_bf16 v[78:81], v[142:145], v[206:209], v[78:81]
	s_waitcnt lgkmcnt(0)
	v_mfma_f32_16x16x32_bf16 v[86:89], v[130:133], v[202:205], v[86:89]
	v_mfma_f32_16x16x32_bf16 v[86:89], v[134:137], v[206:209], v[86:89]
	s_setprio 0
	s_setprio 1
	v_mfma_f32_16x16x32_bf16 v[114:117], v[150:153], v[166:169], v[114:117]
	v_mfma_f32_16x16x32_bf16 v[114:117], v[154:157], v[170:173], v[114:117]
	v_mfma_f32_16x16x32_bf16 v[106:109], v[158:161], v[166:169], v[106:109]
	v_mfma_f32_16x16x32_bf16 v[106:109], v[162:165], v[170:173], v[106:109]
	v_mfma_f32_16x16x32_bf16 v[98:101], v[158:161], v[186:189], v[98:101]
	v_mfma_f32_16x16x32_bf16 v[98:101], v[162:165], v[190:193], v[98:101]
	v_mfma_f32_16x16x32_bf16 v[102:105], v[150:153], v[186:189], v[102:105]
	v_mfma_f32_16x16x32_bf16 v[102:105], v[154:157], v[190:193], v[102:105]
	v_mfma_f32_16x16x32_bf16 v[82:85], v[150:153], v[194:197], v[82:85]
	v_mfma_f32_16x16x32_bf16 v[82:85], v[154:157], v[198:201], v[82:85]
	v_mfma_f32_16x16x32_bf16 v[74:77], v[158:161], v[194:197], v[74:77]
	v_mfma_f32_16x16x32_bf16 v[74:77], v[162:165], v[198:201], v[74:77]
	v_mfma_f32_16x16x32_bf16 v[66:69], v[158:161], v[202:205], v[66:69]
	v_mfma_f32_16x16x32_bf16 v[66:69], v[162:165], v[206:209], v[66:69]
	s_setprio 2
	s_barrier
	v_mfma_f32_16x16x32_bf16 v[70:73], v[150:153], v[202:205], v[70:73]
	v_mfma_f32_16x16x32_bf16 v[70:73], v[154:157], v[206:209], v[70:73]
	s_setprio 0
	ds_read_b128 v[166:169], v183 offset:16384
	ds_read_b128 v[170:173], v183 offset:17408
	ds_read_b128 v[186:189], v183 offset:18432
	ds_read_b128 v[190:193], v183 offset:19456
	ds_read_b128 v[194:197], v183 offset:20480
	ds_read_b128 v[198:201], v183 offset:21504
	ds_read_b128 v[202:205], v183 offset:22528
	ds_read_b128 v[206:209], v183 offset:23552
	s_mov_b32 s70, m0
	s_mov_b32 m0, s27
	s_nop 0
	global_load_lds_dwordx4 v176, s[30:31]
	s_mov_b32 m0, s70
	s_nop 0
	s_mov_b32 s70, m0
	s_mov_b32 m0, s45
	s_nop 0
	global_load_lds_dwordx4 v178, s[30:31]
	s_mov_b32 m0, s70
	s_add_u32 s70, s30, 0x4000
	s_addc_u32 s71, s31, 0
	s_mov_b32 s73, m0
	s_mov_b32 m0, s46
	s_nop 0
	global_load_lds_dwordx4 v176, s[70:71]
	s_mov_b32 m0, s73
	s_nop 0
	s_mov_b32 s73, m0
	s_mov_b32 m0, s47
	s_nop 0
	global_load_lds_dwordx4 v178, s[70:71]
	s_mov_b32 m0, s73
	s_waitcnt vmcnt(4)
	s_waitcnt lgkmcnt(0)
	s_waitcnt lgkmcnt(7)
	v_mfma_f32_16x16x32_bf16 v[62:65], v[130:133], v[166:169], v[62:65]
	v_mfma_f32_16x16x32_bf16 v[62:65], v[134:137], v[170:173], v[62:65]
	s_waitcnt lgkmcnt(5)
	v_mfma_f32_16x16x32_bf16 v[58:61], v[138:141], v[166:169], v[58:61]
	v_mfma_f32_16x16x32_bf16 v[58:61], v[142:145], v[170:173], v[58:61]
	s_barrier
	s_setprio 1
	s_waitcnt lgkmcnt(3)
	v_mfma_f32_16x16x32_bf16 v[42:45], v[138:141], v[186:189], v[42:45]
	v_mfma_f32_16x16x32_bf16 v[42:45], v[142:145], v[190:193], v[42:45]
	s_waitcnt lgkmcnt(1)
	v_mfma_f32_16x16x32_bf16 v[46:49], v[130:133], v[186:189], v[46:49]
	v_mfma_f32_16x16x32_bf16 v[46:49], v[134:137], v[190:193], v[46:49]
	v_mfma_f32_16x16x32_bf16 v[30:33], v[130:133], v[194:197], v[30:33]
	v_mfma_f32_16x16x32_bf16 v[30:33], v[134:137], v[198:201], v[30:33]
	v_mfma_f32_16x16x32_bf16 v[26:29], v[138:141], v[194:197], v[26:29]
	v_mfma_f32_16x16x32_bf16 v[26:29], v[142:145], v[198:201], v[26:29]
	v_mfma_f32_16x16x32_bf16 v[10:13], v[138:141], v[202:205], v[10:13]
	v_mfma_f32_16x16x32_bf16 v[10:13], v[142:145], v[206:209], v[10:13]
	s_waitcnt lgkmcnt(0)
	v_mfma_f32_16x16x32_bf16 v[14:17], v[130:133], v[202:205], v[14:17]
	v_mfma_f32_16x16x32_bf16 v[14:17], v[134:137], v[206:209], v[14:17]
	s_setprio 0
	s_setprio 1
	v_mfma_f32_16x16x32_bf16 v[54:57], v[150:153], v[166:169], v[54:57]
	v_mfma_f32_16x16x32_bf16 v[54:57], v[154:157], v[170:173], v[54:57]
	v_mfma_f32_16x16x32_bf16 v[50:53], v[158:161], v[166:169], v[50:53]
	v_mfma_f32_16x16x32_bf16 v[50:53], v[162:165], v[170:173], v[50:53]
	v_mfma_f32_16x16x32_bf16 v[34:37], v[158:161], v[186:189], v[34:37]
	v_mfma_f32_16x16x32_bf16 v[34:37], v[162:165], v[190:193], v[34:37]
	v_mfma_f32_16x16x32_bf16 v[38:41], v[150:153], v[186:189], v[38:41]
	v_mfma_f32_16x16x32_bf16 v[38:41], v[154:157], v[190:193], v[38:41]
	v_mfma_f32_16x16x32_bf16 v[22:25], v[150:153], v[194:197], v[22:25]
	v_mfma_f32_16x16x32_bf16 v[22:25], v[154:157], v[198:201], v[22:25]
	v_mfma_f32_16x16x32_bf16 v[18:21], v[158:161], v[194:197], v[18:21]
	v_mfma_f32_16x16x32_bf16 v[18:21], v[162:165], v[198:201], v[18:21]
	v_mfma_f32_16x16x32_bf16 v[2:5], v[158:161], v[202:205], v[2:5]
	v_mfma_f32_16x16x32_bf16 v[2:5], v[162:165], v[206:209], v[2:5]
	s_setprio 2
	s_barrier
	v_mfma_f32_16x16x32_bf16 v[6:9], v[150:153], v[202:205], v[6:9]
	v_mfma_f32_16x16x32_bf16 v[6:9], v[154:157], v[206:209], v[6:9]
	s_setprio 0
	ds_read_b128 v[130:133], v184
	ds_read_b128 v[134:137], v184 offset:1024
	ds_read_b128 v[138:141], v184 offset:2048
	ds_read_b128 v[142:145], v184 offset:3072
	ds_read_b128 v[150:153], v185
	ds_read_b128 v[154:157], v185 offset:1024
	ds_read_b128 v[158:161], v185 offset:2048
	ds_read_b128 v[162:165], v185 offset:3072
	ds_read_b128 v[166:169], v183 offset:32768
	ds_read_b128 v[170:173], v183 offset:33792
	ds_read_b128 v[186:189], v183 offset:34816
	ds_read_b128 v[190:193], v183 offset:35840
	ds_read_b128 v[194:197], v183 offset:36864
	ds_read_b128 v[198:201], v183 offset:37888
	ds_read_b128 v[202:205], v183 offset:38912
	ds_read_b128 v[206:209], v183 offset:39936
	s_mov_b32 s70, m0
	s_mov_b32 m0, s44
	s_nop 0
	global_load_lds_dwordx4 v1, s[34:35]
	s_mov_b32 m0, s70
	s_nop 0
	s_mov_b32 s70, m0
	s_mov_b32 m0, s48
	s_nop 0
	global_load_lds_dwordx4 v177, s[34:35]
	s_mov_b32 m0, s70
	s_add_u32 s34, s34, 0x4000
	s_addc_u32 s35, s35, 0
	s_mov_b32 s70, m0
	s_mov_b32 m0, s49
	s_nop 0
	global_load_lds_dwordx4 v1, s[34:35]
	s_mov_b32 m0, s70
	s_nop 0
	s_mov_b32 s70, m0
	s_mov_b32 m0, s50
	s_nop 0
	global_load_lds_dwordx4 v177, s[34:35]
	s_mov_b32 m0, s70
	s_waitcnt vmcnt(8)
	s_waitcnt lgkmcnt(0)
	s_waitcnt lgkmcnt(7)
	v_mfma_f32_16x16x32_bf16 v[126:129], v[130:133], v[166:169], v[126:129]
	v_mfma_f32_16x16x32_bf16 v[126:129], v[134:137], v[170:173], v[126:129]
	s_waitcnt lgkmcnt(5)
	v_mfma_f32_16x16x32_bf16 v[122:125], v[138:141], v[166:169], v[122:125]
	v_mfma_f32_16x16x32_bf16 v[122:125], v[142:145], v[170:173], v[122:125]
	s_barrier
	s_setprio 1
	s_waitcnt lgkmcnt(3)
	v_mfma_f32_16x16x32_bf16 v[110:113], v[138:141], v[186:189], v[110:113]
	v_mfma_f32_16x16x32_bf16 v[110:113], v[142:145], v[190:193], v[110:113]
	s_waitcnt lgkmcnt(1)
	v_mfma_f32_16x16x32_bf16 v[118:121], v[130:133], v[186:189], v[118:121]
	v_mfma_f32_16x16x32_bf16 v[118:121], v[134:137], v[190:193], v[118:121]
	v_mfma_f32_16x16x32_bf16 v[94:97], v[130:133], v[194:197], v[94:97]
	v_mfma_f32_16x16x32_bf16 v[94:97], v[134:137], v[198:201], v[94:97]
	v_mfma_f32_16x16x32_bf16 v[90:93], v[138:141], v[194:197], v[90:93]
	v_mfma_f32_16x16x32_bf16 v[90:93], v[142:145], v[198:201], v[90:93]
	v_mfma_f32_16x16x32_bf16 v[78:81], v[138:141], v[202:205], v[78:81]
	v_mfma_f32_16x16x32_bf16 v[78:81], v[142:145], v[206:209], v[78:81]
	s_waitcnt lgkmcnt(0)
	v_mfma_f32_16x16x32_bf16 v[86:89], v[130:133], v[202:205], v[86:89]
	v_mfma_f32_16x16x32_bf16 v[86:89], v[134:137], v[206:209], v[86:89]
	s_setprio 0
	s_setprio 1
	v_mfma_f32_16x16x32_bf16 v[114:117], v[150:153], v[166:169], v[114:117]
	v_mfma_f32_16x16x32_bf16 v[114:117], v[154:157], v[170:173], v[114:117]
	v_mfma_f32_16x16x32_bf16 v[106:109], v[158:161], v[166:169], v[106:109]
	v_mfma_f32_16x16x32_bf16 v[106:109], v[162:165], v[170:173], v[106:109]
	v_mfma_f32_16x16x32_bf16 v[98:101], v[158:161], v[186:189], v[98:101]
	v_mfma_f32_16x16x32_bf16 v[98:101], v[162:165], v[190:193], v[98:101]
	v_mfma_f32_16x16x32_bf16 v[102:105], v[150:153], v[186:189], v[102:105]
	v_mfma_f32_16x16x32_bf16 v[102:105], v[154:157], v[190:193], v[102:105]
	v_mfma_f32_16x16x32_bf16 v[82:85], v[150:153], v[194:197], v[82:85]
	v_mfma_f32_16x16x32_bf16 v[82:85], v[154:157], v[198:201], v[82:85]
	v_mfma_f32_16x16x32_bf16 v[74:77], v[158:161], v[194:197], v[74:77]
	v_mfma_f32_16x16x32_bf16 v[74:77], v[162:165], v[198:201], v[74:77]
	v_mfma_f32_16x16x32_bf16 v[66:69], v[158:161], v[202:205], v[66:69]
	v_mfma_f32_16x16x32_bf16 v[66:69], v[162:165], v[206:209], v[66:69]
	s_setprio 2
	s_barrier
	v_mfma_f32_16x16x32_bf16 v[70:73], v[150:153], v[202:205], v[70:73]
	v_mfma_f32_16x16x32_bf16 v[70:73], v[154:157], v[206:209], v[70:73]
	s_setprio 0
	ds_read_b128 v[166:169], v183 offset:49152
	ds_read_b128 v[170:173], v183 offset:50176
	ds_read_b128 v[186:189], v183 offset:51200
	ds_read_b128 v[190:193], v183 offset:52224
	ds_read_b128 v[194:197], v183 offset:53248
	ds_read_b128 v[198:201], v183 offset:54272
	ds_read_b128 v[202:205], v183 offset:55296
	ds_read_b128 v[206:209], v183 offset:56320
	s_add_u32 s34, s30, 0x40000
	s_addc_u32 s35, s31, 0
	s_mov_b32 s70, m0
	s_mov_b32 m0, s51
	s_nop 0
	global_load_lds_dwordx4 v176, s[34:35]
	s_mov_b32 m0, s70
	s_add_u32 s30, s30, 0x44000
	s_mov_b32 s70, m0
	s_mov_b32 m0, s52
	s_nop 0
	global_load_lds_dwordx4 v178, s[34:35]
	s_mov_b32 m0, s70
	s_addc_u32 s31, s31, 0
	s_mov_b32 s34, m0
	s_mov_b32 m0, s53
	s_nop 0
	global_load_lds_dwordx4 v176, s[30:31]
	s_mov_b32 m0, s34
	s_nop 0
	s_mov_b32 s34, m0
	s_mov_b32 m0, s54
	s_nop 0
	global_load_lds_dwordx4 v178, s[30:31]
	s_mov_b32 m0, s34
	s_waitcnt vmcnt(4)
	s_waitcnt lgkmcnt(0)
	s_waitcnt lgkmcnt(7)
	v_mfma_f32_16x16x32_bf16 v[62:65], v[130:133], v[166:169], v[62:65]
	v_mfma_f32_16x16x32_bf16 v[62:65], v[134:137], v[170:173], v[62:65]
	s_waitcnt lgkmcnt(5)
	v_mfma_f32_16x16x32_bf16 v[58:61], v[138:141], v[166:169], v[58:61]
	v_mfma_f32_16x16x32_bf16 v[58:61], v[142:145], v[170:173], v[58:61]
	s_barrier
	s_setprio 1
	s_waitcnt lgkmcnt(3)
	v_mfma_f32_16x16x32_bf16 v[42:45], v[138:141], v[186:189], v[42:45]
	v_mfma_f32_16x16x32_bf16 v[42:45], v[142:145], v[190:193], v[42:45]
	s_waitcnt lgkmcnt(1)
	v_mfma_f32_16x16x32_bf16 v[46:49], v[130:133], v[186:189], v[46:49]
	v_mfma_f32_16x16x32_bf16 v[46:49], v[134:137], v[190:193], v[46:49]
	v_mfma_f32_16x16x32_bf16 v[30:33], v[130:133], v[194:197], v[30:33]
	v_mfma_f32_16x16x32_bf16 v[30:33], v[134:137], v[198:201], v[30:33]
	v_mfma_f32_16x16x32_bf16 v[26:29], v[138:141], v[194:197], v[26:29]
	v_mfma_f32_16x16x32_bf16 v[26:29], v[142:145], v[198:201], v[26:29]
	v_mfma_f32_16x16x32_bf16 v[10:13], v[138:141], v[202:205], v[10:13]
	v_mfma_f32_16x16x32_bf16 v[10:13], v[142:145], v[206:209], v[10:13]
	s_waitcnt lgkmcnt(0)
	v_mfma_f32_16x16x32_bf16 v[14:17], v[130:133], v[202:205], v[14:17]
	v_mfma_f32_16x16x32_bf16 v[14:17], v[134:137], v[206:209], v[14:17]
	s_setprio 0
	s_setprio 1
	v_mfma_f32_16x16x32_bf16 v[54:57], v[150:153], v[166:169], v[54:57]
	v_mfma_f32_16x16x32_bf16 v[54:57], v[154:157], v[170:173], v[54:57]
	v_mfma_f32_16x16x32_bf16 v[50:53], v[158:161], v[166:169], v[50:53]
	v_mfma_f32_16x16x32_bf16 v[50:53], v[162:165], v[170:173], v[50:53]
	v_mfma_f32_16x16x32_bf16 v[34:37], v[158:161], v[186:189], v[34:37]
	v_mfma_f32_16x16x32_bf16 v[34:37], v[162:165], v[190:193], v[34:37]
	v_mfma_f32_16x16x32_bf16 v[38:41], v[150:153], v[186:189], v[38:41]
	v_mfma_f32_16x16x32_bf16 v[38:41], v[154:157], v[190:193], v[38:41]
	v_mfma_f32_16x16x32_bf16 v[22:25], v[150:153], v[194:197], v[22:25]
	v_mfma_f32_16x16x32_bf16 v[22:25], v[154:157], v[198:201], v[22:25]
	v_mfma_f32_16x16x32_bf16 v[18:21], v[158:161], v[194:197], v[18:21]
	v_mfma_f32_16x16x32_bf16 v[18:21], v[162:165], v[198:201], v[18:21]
	v_mfma_f32_16x16x32_bf16 v[2:5], v[158:161], v[202:205], v[2:5]
	v_mfma_f32_16x16x32_bf16 v[2:5], v[162:165], v[206:209], v[2:5]
	s_setprio 2
	s_barrier
	v_mfma_f32_16x16x32_bf16 v[6:9], v[150:153], v[202:205], v[6:9]
	v_mfma_f32_16x16x32_bf16 v[6:9], v[154:157], v[206:209], v[6:9]
	s_setprio 0
	s_add_i32 s69, s69, 2
	s_add_u32 s65, s65, 0x80000
	s_addc_u32 s66, s66, 0
	s_add_u32 s28, s28, 0x400000
	s_addc_u32 s29, s29, 0
	s_add_u32 s67, s67, 0x400000
	s_addc_u32 s68, s68, 0
	s_cmpk_gt_u32 s69, 0x53
	s_cbranch_scc0 .LBB0_2792
	s_and_b64 vcc, exec, s[8:9]
	s_cbranch_vccz .LBB0_2795
	s_barrier
